# GEMM k-loops: LDS-DMA staging pieces rebalanced 2/6/2/6 -> 4/4/4/4 across the four sub-phases (15 of 17 loops)
# baseline (speedup 1.0000x reference)
; #define G_STAGE(bufoff, gbase, voff) do { _Pragma("unroll") for (int _i = 0; _i < 2; ++_i) \
;         __builtin_amdgcn_global_load_lds((const unsigned*)((const char*)(gbase) + voff[_i]), (LAS unsigned*)(lds + (bufoff) + ldsw + _i * 8192), 16, 0, 0); } while (0)
; #define G_LDA(dst, b, h) do { _Pragma("unroll") for (int m = 0; m < 4; ++m) _Pragma("unroll") for (int k = 0; k < 2; ++k) dst[m][k] = *(const LAS bf16x8*)(lds + G_SA(b, h) + aoff + m * 2048 + k * 1024); } while (0)
; #define G_LDB(dst, b, h) do { _Pragma("unroll") for (int n = 0; n < 2; ++n) _Pragma("unroll") for (int k = 0; k < 2; ++k) dst[n][k] = *(const LAS bf16x8*)(lds + G_SB(b, h) + boff + n * 2048 + k * 1024); } while (0)
; #define WAIT_V(n) asm volatile("s_waitcnt vmcnt(" #n ")" ::: "memory")
; #define WAIT_L(n) asm volatile("s_waitcnt lgkmcnt(" #n ")" ::: "memory")
; #define BAR __builtin_amdgcn_s_barrier()
; #define SCHED __builtin_amdgcn_sched_barrier(0)
; template <class Get, class Epi>
; DI void gemm_loop(int ntiles, int ld, char* shm, const Get& get, const Epi& epi) {
;     ...
;         for (int t = 0; t < nt; t += 2) {
;             const bool last = (t == nt - 2);
;             const char* a1 = cA + (size_t)(t + 1) * kstep;
;             const char* a2 = last ? nA : cA + (size_t)(t + 2) * kstep; const char* b2 = last ? nB : cB + (size_t)(t + 2) * kstep;
;             const char* a3 = a2 + kstep; const char* b3 = b2 + kstep;
;             G_LDB(B0, 0, 0); G_LDB(B1, 0, 1); SCHED; G_LDA(At, 0, 0); G_STAGE(G_SA(1, 1), a1 + hstep, voffA);
;             WAIT_V(8); WAIT_L(0); BAR; G_MMA(0, 0, At, B0); G_MMA(0, 1, At, B1); BAR; SCHED;
;             G_LDA(At, 0, 1); G_STAGE(G_SB(0, 0), b2, voffB); G_STAGE(G_SB(0, 1), b2 + hstep, voffB); G_STAGE(G_SA(0, 0), a2, voffA);
;             WAIT_V(8); WAIT_L(0); BAR; G_MMA(1, 0, At, B0); G_MMA(1, 1, At, B1); BAR; SCHED;
;             G_LDB(B0, 1, 0); G_LDB(B1, 1, 1); SCHED; G_LDA(At, 1, 0); G_STAGE(G_SA(0, 1), a2 + hstep, voffA);
;             WAIT_V(8); WAIT_L(0); BAR; G_MMA(0, 0, At, B0); G_MMA(0, 1, At, B1); BAR; SCHED;
;             G_LDA(At, 1, 1); G_STAGE(G_SB(1, 0), b3, voffB); G_STAGE(G_SB(1, 1), b3 + hstep, voffB); G_STAGE(G_SA(1, 0), a3, voffA);
;             WAIT_V(8); WAIT_L(0); BAR; G_MMA(1, 0, At, B0); G_MMA(1, 1, At, B1); BAR; SCHED;
.LBB0_528:
	ds_read_b128 v[128:131], v177
	ds_read_b128 v[132:135], v177 offset:1024
	ds_read_b128 v[136:139], v177 offset:2048
	ds_read_b128 v[140:143], v177 offset:3072
	ds_read_b128 v[144:147], v178
	ds_read_b128 v[148:151], v178 offset:1024
	ds_read_b128 v[164:167], v178 offset:2048
	ds_read_b128 v[168:171], v178 offset:3072
	s_add_i32 s83, s14, 2
	s_add_u32 s15, s44, 0xfffc0080
	s_addc_u32 s46, s45, -1
	s_cmp_eq_u32 s54, s14
	s_cselect_b32 s14, s43, s55
	s_cselect_b32 s47, s3, s46
	s_cselect_b32 s46, s35, s15
	s_cselect_b32 s15, s37, s82
	v_lshl_add_u64 v[184:185], s[44:45], 0, v[160:161]
	s_add_i32 m0, s57, 0xc000
	ds_read_b128 v[172:175], v179
	ds_read_b128 v[180:183], v179 offset:1024
	ds_read_b128 v[188:191], v179 offset:2048
	ds_read_b128 v[192:195], v179 offset:3072
	ds_read_b128 v[196:199], v179 offset:4096
	ds_read_b128 v[200:203], v179 offset:5120
	ds_read_b128 v[204:207], v179 offset:6144
	ds_read_b128 v[208:211], v179 offset:7168
	global_load_lds_dwordx4 v[184:185], off
	v_lshl_add_u64 v[184:185], s[44:45], 0, v[162:163]
	s_add_i32 m0, s57, 0xe000
	s_nop 0
	global_load_lds_dwordx4 v[184:185], off
	s_mov_b32 s98, 0xfffc0000
	s_mov_b32 s99, -1
	v_lshl_add_u64 v[184:185], s[44:45], 0, v[160:161]
	v_lshl_add_u64 v[184:185], v[184:185], 0, s[98:99]
	s_add_i32 m0, s57, 0x8000
	s_nop 0
	global_load_lds_dwordx4 v[184:185], off
	v_lshl_add_u64 v[184:185], s[44:45], 0, v[162:163]
	v_lshl_add_u64 v[184:185], v[184:185], 0, s[98:99]
	s_add_i32 m0, s57, 0xa000
	s_nop 0
	global_load_lds_dwordx4 v[184:185], off
	s_waitcnt vmcnt(8)
	s_waitcnt lgkmcnt(0)
	s_barrier
	s_setprio 1
	s_waitcnt lgkmcnt(0)
	v_mfma_f32_16x16x32_bf16 v[124:127], v[128:131], v[172:175], v[124:127]
	v_mfma_f32_16x16x32_bf16 v[120:123], v[136:139], v[172:175], v[120:123]
	v_mfma_f32_16x16x32_bf16 v[116:119], v[128:131], v[188:191], v[116:119]
	v_mfma_f32_16x16x32_bf16 v[112:115], v[136:139], v[188:191], v[112:115]
	v_mfma_f32_16x16x32_bf16 v[108:111], v[128:131], v[196:199], v[108:111]
	v_mfma_f32_16x16x32_bf16 v[104:107], v[136:139], v[196:199], v[104:107]
	v_mfma_f32_16x16x32_bf16 v[100:103], v[128:131], v[204:207], v[100:103]
	v_mfma_f32_16x16x32_bf16 v[96:99], v[136:139], v[204:207], v[96:99]
	v_mfma_f32_16x16x32_bf16 v[124:127], v[132:135], v[180:183], v[124:127]
	v_mfma_f32_16x16x32_bf16 v[120:123], v[140:143], v[180:183], v[120:123]
	v_mfma_f32_16x16x32_bf16 v[116:119], v[132:135], v[192:195], v[116:119]
	v_mfma_f32_16x16x32_bf16 v[112:115], v[140:143], v[192:195], v[112:115]
	v_mfma_f32_16x16x32_bf16 v[108:111], v[132:135], v[200:203], v[108:111]
	v_mfma_f32_16x16x32_bf16 v[104:107], v[140:143], v[200:203], v[104:107]
	v_mfma_f32_16x16x32_bf16 v[100:103], v[132:135], v[208:211], v[100:103]
	v_mfma_f32_16x16x32_bf16 v[96:99], v[140:143], v[208:211], v[96:99]
	s_setprio 0
	s_setprio 1
	v_mfma_f32_16x16x32_bf16 v[60:63], v[144:147], v[172:175], v[60:63]
	v_mfma_f32_16x16x32_bf16 v[56:59], v[164:167], v[172:175], v[56:59]
	v_mfma_f32_16x16x32_bf16 v[52:55], v[144:147], v[188:191], v[52:55]
	v_mfma_f32_16x16x32_bf16 v[48:51], v[164:167], v[188:191], v[48:51]
	v_mfma_f32_16x16x32_bf16 v[44:47], v[144:147], v[196:199], v[44:47]
	v_mfma_f32_16x16x32_bf16 v[40:43], v[164:167], v[196:199], v[40:43]
	v_mfma_f32_16x16x32_bf16 v[36:39], v[144:147], v[204:207], v[36:39]
	v_mfma_f32_16x16x32_bf16 v[32:35], v[164:167], v[204:207], v[32:35]
	v_mfma_f32_16x16x32_bf16 v[60:63], v[148:151], v[180:183], v[60:63]
	v_mfma_f32_16x16x32_bf16 v[56:59], v[168:171], v[180:183], v[56:59]
	v_mfma_f32_16x16x32_bf16 v[52:55], v[148:151], v[192:195], v[52:55]
	v_mfma_f32_16x16x32_bf16 v[48:51], v[168:171], v[192:195], v[48:51]
	v_mfma_f32_16x16x32_bf16 v[44:47], v[148:151], v[200:203], v[44:47]
	v_mfma_f32_16x16x32_bf16 v[40:43], v[168:171], v[200:203], v[40:43]
	v_mfma_f32_16x16x32_bf16 v[36:39], v[148:151], v[208:211], v[36:39]
	v_mfma_f32_16x16x32_bf16 v[32:35], v[168:171], v[208:211], v[32:35]
	s_setprio 0
	s_barrier
	s_add_i32 s84, s78, s56
	v_lshl_add_u64 v[184:185], s[14:15], 0, v[154:155]
	s_mov_b32 m0, s84
	ds_read_b128 v[172:175], v179 offset:16384
	ds_read_b128 v[180:183], v179 offset:17408
	ds_read_b128 v[188:191], v179 offset:18432
	ds_read_b128 v[192:195], v179 offset:19456
	ds_read_b128 v[196:199], v179 offset:20480
	ds_read_b128 v[200:203], v179 offset:21504
	ds_read_b128 v[204:207], v179 offset:22528
	ds_read_b128 v[208:211], v179 offset:23552
	global_load_lds_dwordx4 v[184:185], off
	s_add_i32 m0, s84, 0x2000
	s_add_u32 s84, s14, 0x40000
	v_lshl_add_u64 v[186:187], s[14:15], 0, v[158:159]
	s_addc_u32 s85, s15, 0
	s_add_i32 s86, s79, s56
	global_load_lds_dwordx4 v[186:187], off
	v_lshl_add_u64 v[212:213], s[84:85], 0, v[154:155]
	s_mov_b32 m0, s86
	v_lshl_add_u64 v[214:215], s[46:47], 0, v[156:157]
	global_load_lds_dwordx4 v[212:213], off
	v_lshl_add_u64 v[212:213], s[84:85], 0, v[158:159]
	s_add_i32 m0, s86, 0x2000
	s_nop 0
	global_load_lds_dwordx4 v[212:213], off
	v_lshl_add_u64 v[212:213], s[46:47], 0, v[152:153]
	s_waitcnt vmcnt(4)
	s_waitcnt lgkmcnt(0)
	s_barrier
; #define G_STAGE(bufoff, gbase, voff) do { _Pragma("unroll") for (int _i = 0; _i < 2; ++_i) \
;         __builtin_amdgcn_global_load_lds((const unsigned*)((const char*)(gbase) + voff[_i]), (LAS unsigned*)(lds + (bufoff) + ldsw + _i * 8192), 16, 0, 0); } while (0)
; #define G_LDA(dst, b, h) do { _Pragma("unroll") for (int m = 0; m < 4; ++m) _Pragma("unroll") for (int k = 0; k < 2; ++k) dst[m][k] = *(const LAS bf16x8*)(lds + G_SA(b, h) + aoff + m * 2048 + k * 1024); } while (0)
; #define G_LDB(dst, b, h) do { _Pragma("unroll") for (int n = 0; n < 2; ++n) _Pragma("unroll") for (int k = 0; k < 2; ++k) dst[n][k] = *(const LAS bf16x8*)(lds + G_SB(b, h) + boff + n * 2048 + k * 1024); } while (0)
; #define G_MMA(ai, bj, At_, Bt_) do { __builtin_amdgcn_s_setprio(1); _Pragma("unroll") for (int m = 0; m < 4; ++m) _Pragma("unroll") for (int n = 0; n < 2; ++n) _Pragma("unroll") for (int k = 0; k < 2; ++k) \
;         acc[ai][bj][m][n] = __builtin_amdgcn_mfma_f32_16x16x32_bf16(Bt_[n][k], At_[m][k], acc[ai][bj][m][n], 0, 0, 0); __builtin_amdgcn_s_setprio(0); } while (0)
; #define WAIT_V(n) asm volatile("s_waitcnt vmcnt(" #n ")" ::: "memory")
; #define WAIT_L(n) asm volatile("s_waitcnt lgkmcnt(" #n ")" ::: "memory")
; #define BAR __builtin_amdgcn_s_barrier()
; #define SCHED __builtin_amdgcn_sched_barrier(0)
; template <class Get, class Epi>
; DI void gemm_loop(int ntiles, int ld, char* shm, const Get& get, const Epi& epi) {
;     ...
;             WAIT_V(8); WAIT_L(0); BAR; G_MMA(1, 0, At, B0); G_MMA(1, 1, At, B1); BAR; SCHED;
;             G_LDB(B0, 1, 0); G_LDB(B1, 1, 1); SCHED; G_LDA(At, 1, 0); G_STAGE(G_SA(0, 1), a2 + hstep, voffA);
;             WAIT_V(8); WAIT_L(0); BAR; G_MMA(0, 0, At, B0); G_MMA(0, 1, At, B1); BAR; SCHED;
;             G_LDA(At, 1, 1); G_STAGE(G_SB(1, 0), b3, voffB); G_STAGE(G_SB(1, 1), b3 + hstep, voffB); G_STAGE(G_SA(1, 0), a3, voffA);
	s_setprio 1
	s_waitcnt lgkmcnt(0)
	v_mfma_f32_16x16x32_bf16 v[92:95], v[128:131], v[172:175], v[92:95]
	v_mfma_f32_16x16x32_bf16 v[88:91], v[136:139], v[172:175], v[88:91]
	v_mfma_f32_16x16x32_bf16 v[84:87], v[128:131], v[188:191], v[84:87]
	v_mfma_f32_16x16x32_bf16 v[80:83], v[136:139], v[188:191], v[80:83]
	v_mfma_f32_16x16x32_bf16 v[76:79], v[128:131], v[196:199], v[76:79]
	v_mfma_f32_16x16x32_bf16 v[72:75], v[136:139], v[196:199], v[72:75]
	v_mfma_f32_16x16x32_bf16 v[68:71], v[128:131], v[204:207], v[68:71]
	v_mfma_f32_16x16x32_bf16 v[64:67], v[136:139], v[204:207], v[64:67]
	v_mfma_f32_16x16x32_bf16 v[92:95], v[132:135], v[180:183], v[92:95]
	v_mfma_f32_16x16x32_bf16 v[88:91], v[140:143], v[180:183], v[88:91]
	v_mfma_f32_16x16x32_bf16 v[84:87], v[132:135], v[192:195], v[84:87]
	v_mfma_f32_16x16x32_bf16 v[80:83], v[140:143], v[192:195], v[80:83]
	v_mfma_f32_16x16x32_bf16 v[76:79], v[132:135], v[200:203], v[76:79]
	v_mfma_f32_16x16x32_bf16 v[72:75], v[140:143], v[200:203], v[72:75]
	v_mfma_f32_16x16x32_bf16 v[68:71], v[132:135], v[208:211], v[68:71]
	v_mfma_f32_16x16x32_bf16 v[64:67], v[140:143], v[208:211], v[64:67]
	s_setprio 0
	s_setprio 1
	v_mfma_f32_16x16x32_bf16 v[28:31], v[144:147], v[172:175], v[28:31]
	v_mfma_f32_16x16x32_bf16 v[24:27], v[164:167], v[172:175], v[24:27]
	v_mfma_f32_16x16x32_bf16 v[20:23], v[144:147], v[188:191], v[20:23]
	v_mfma_f32_16x16x32_bf16 v[16:19], v[164:167], v[188:191], v[16:19]
	v_mfma_f32_16x16x32_bf16 v[12:15], v[144:147], v[196:199], v[12:15]
	v_mfma_f32_16x16x32_bf16 v[8:11], v[164:167], v[196:199], v[8:11]
	v_mfma_f32_16x16x32_bf16 v[4:7], v[144:147], v[204:207], v[4:7]
	v_mfma_f32_16x16x32_bf16 v[0:3], v[164:167], v[204:207], v[0:3]
	v_mfma_f32_16x16x32_bf16 v[28:31], v[148:151], v[180:183], v[28:31]
	v_mfma_f32_16x16x32_bf16 v[24:27], v[168:171], v[180:183], v[24:27]
	v_mfma_f32_16x16x32_bf16 v[20:23], v[148:151], v[192:195], v[20:23]
	v_mfma_f32_16x16x32_bf16 v[16:19], v[168:171], v[192:195], v[16:19]
	v_mfma_f32_16x16x32_bf16 v[12:15], v[148:151], v[200:203], v[12:15]
	v_mfma_f32_16x16x32_bf16 v[8:11], v[168:171], v[200:203], v[8:11]
	v_mfma_f32_16x16x32_bf16 v[4:7], v[148:151], v[208:211], v[4:7]
	v_mfma_f32_16x16x32_bf16 v[0:3], v[168:171], v[208:211], v[0:3]
	s_setprio 0
	s_barrier
	s_add_i32 s84, 0, 0x18000
	s_add_i32 s85, 0, 0x1c000
	v_add_u32_e32 v140, s84, v176
	v_add_u32_e32 v168, s85, v176
	ds_read_b128 v[128:131], v140
	ds_read_b128 v[132:135], v140 offset:1024
	ds_read_b128 v[136:139], v140 offset:2048
	ds_read_b128 v[140:143], v140 offset:3072
	ds_read_b128 v[144:147], v168
	ds_read_b128 v[148:151], v168 offset:1024
	ds_read_b128 v[164:167], v168 offset:2048
	ds_read_b128 v[168:171], v168 offset:3072
	s_add_u32 s46, s46, 0x40000
	s_addc_u32 s47, s47, 0
	s_mov_b32 m0, s59
	v_lshl_add_u64 v[216:217], s[46:47], 0, v[152:153]
	ds_read_b128 v[172:175], v179 offset:32768
	ds_read_b128 v[180:183], v179 offset:33792
	ds_read_b128 v[188:191], v179 offset:34816
	ds_read_b128 v[192:195], v179 offset:35840
	ds_read_b128 v[196:199], v179 offset:36864
	ds_read_b128 v[200:203], v179 offset:37888
	ds_read_b128 v[204:207], v179 offset:38912
	ds_read_b128 v[208:211], v179 offset:39936
	global_load_lds_dwordx4 v[216:217], off
	v_lshl_add_u64 v[216:217], s[46:47], 0, v[156:157]
	s_mov_b32 m0, s72
	s_nop 0
	global_load_lds_dwordx4 v[216:217], off
	s_mov_b32 m0, s57
	s_nop 0
	global_load_lds_dwordx4 v[212:213], off
	s_mov_b32 m0, s58
	s_nop 0
	global_load_lds_dwordx4 v[214:215], off
	s_waitcnt vmcnt(8)
	s_waitcnt lgkmcnt(0)
	s_barrier
; #define G_STAGE(bufoff, gbase, voff) do { _Pragma("unroll") for (int _i = 0; _i < 2; ++_i) \
;         __builtin_amdgcn_global_load_lds((const unsigned*)((const char*)(gbase) + voff[_i]), (LAS unsigned*)(lds + (bufoff) + ldsw + _i * 8192), 16, 0, 0); } while (0)
; #define G_LDA(dst, b, h) do { _Pragma("unroll") for (int m = 0; m < 4; ++m) _Pragma("unroll") for (int k = 0; k < 2; ++k) dst[m][k] = *(const LAS bf16x8*)(lds + G_SA(b, h) + aoff + m * 2048 + k * 1024); } while (0)
; #define G_MMA(ai, bj, At_, Bt_) do { __builtin_amdgcn_s_setprio(1); _Pragma("unroll") for (int m = 0; m < 4; ++m) _Pragma("unroll") for (int n = 0; n < 2; ++n) _Pragma("unroll") for (int k = 0; k < 2; ++k) \
;         acc[ai][bj][m][n] = __builtin_amdgcn_mfma_f32_16x16x32_bf16(Bt_[n][k], At_[m][k], acc[ai][bj][m][n], 0, 0, 0); __builtin_amdgcn_s_setprio(0); } while (0)
; #define WAIT_V(n) asm volatile("s_waitcnt vmcnt(" #n ")" ::: "memory")
; #define WAIT_L(n) asm volatile("s_waitcnt lgkmcnt(" #n ")" ::: "memory")
; #define BAR __builtin_amdgcn_s_barrier()
; #define SCHED __builtin_amdgcn_sched_barrier(0)
; template <class Get, class Epi>
; DI void gemm_loop(int ntiles, int ld, char* shm, const Get& get, const Epi& epi) {
;     ...
;             WAIT_V(8); WAIT_L(0); BAR; G_MMA(0, 0, At, B0); G_MMA(0, 1, At, B1); BAR; SCHED;
;             G_LDA(At, 1, 1); G_STAGE(G_SB(1, 0), b3, voffB); G_STAGE(G_SB(1, 1), b3 + hstep, voffB); G_STAGE(G_SA(1, 0), a3, voffA);
;             WAIT_V(8); WAIT_L(0); BAR; G_MMA(1, 0, At, B0); G_MMA(1, 1, At, B1); BAR; SCHED;
	s_setprio 1
	s_waitcnt lgkmcnt(0)
	v_mfma_f32_16x16x32_bf16 v[124:127], v[128:131], v[172:175], v[124:127]
	v_mfma_f32_16x16x32_bf16 v[120:123], v[136:139], v[172:175], v[120:123]
	v_mfma_f32_16x16x32_bf16 v[116:119], v[128:131], v[188:191], v[116:119]
	v_mfma_f32_16x16x32_bf16 v[112:115], v[136:139], v[188:191], v[112:115]
	v_mfma_f32_16x16x32_bf16 v[108:111], v[128:131], v[196:199], v[108:111]
	v_mfma_f32_16x16x32_bf16 v[104:107], v[136:139], v[196:199], v[104:107]
	v_mfma_f32_16x16x32_bf16 v[100:103], v[128:131], v[204:207], v[100:103]
	v_mfma_f32_16x16x32_bf16 v[96:99], v[136:139], v[204:207], v[96:99]
	v_mfma_f32_16x16x32_bf16 v[124:127], v[132:135], v[180:183], v[124:127]
	v_mfma_f32_16x16x32_bf16 v[120:123], v[140:143], v[180:183], v[120:123]
	v_mfma_f32_16x16x32_bf16 v[116:119], v[132:135], v[192:195], v[116:119]
	v_mfma_f32_16x16x32_bf16 v[112:115], v[140:143], v[192:195], v[112:115]
	v_mfma_f32_16x16x32_bf16 v[108:111], v[132:135], v[200:203], v[108:111]
	v_mfma_f32_16x16x32_bf16 v[104:107], v[140:143], v[200:203], v[104:107]
	v_mfma_f32_16x16x32_bf16 v[100:103], v[132:135], v[208:211], v[100:103]
	v_mfma_f32_16x16x32_bf16 v[96:99], v[140:143], v[208:211], v[96:99]
	s_setprio 0
	s_setprio 1
	v_mfma_f32_16x16x32_bf16 v[60:63], v[144:147], v[172:175], v[60:63]
	v_mfma_f32_16x16x32_bf16 v[56:59], v[164:167], v[172:175], v[56:59]
	v_mfma_f32_16x16x32_bf16 v[52:55], v[144:147], v[188:191], v[52:55]
	v_mfma_f32_16x16x32_bf16 v[48:51], v[164:167], v[188:191], v[48:51]
	v_mfma_f32_16x16x32_bf16 v[44:47], v[144:147], v[196:199], v[44:47]
	v_mfma_f32_16x16x32_bf16 v[40:43], v[164:167], v[196:199], v[40:43]
	v_mfma_f32_16x16x32_bf16 v[36:39], v[144:147], v[204:207], v[36:39]
	v_mfma_f32_16x16x32_bf16 v[32:35], v[164:167], v[204:207], v[32:35]
	v_mfma_f32_16x16x32_bf16 v[60:63], v[148:151], v[180:183], v[60:63]
	v_mfma_f32_16x16x32_bf16 v[56:59], v[168:171], v[180:183], v[56:59]
	v_mfma_f32_16x16x32_bf16 v[52:55], v[148:151], v[192:195], v[52:55]
	v_mfma_f32_16x16x32_bf16 v[48:51], v[168:171], v[192:195], v[48:51]
	v_mfma_f32_16x16x32_bf16 v[44:47], v[148:151], v[200:203], v[44:47]
	v_mfma_f32_16x16x32_bf16 v[40:43], v[168:171], v[200:203], v[40:43]
	v_mfma_f32_16x16x32_bf16 v[36:39], v[148:151], v[208:211], v[36:39]
	v_mfma_f32_16x16x32_bf16 v[32:35], v[168:171], v[208:211], v[32:35]
	s_setprio 0
	s_barrier
	s_add_i32 s46, s84, s56
	v_lshl_add_u64 v[184:185], v[184:185], 0, s[10:11]
	s_mov_b32 m0, s46
	ds_read_b128 v[172:175], v179 offset:49152
	ds_read_b128 v[180:183], v179 offset:50176
	ds_read_b128 v[188:191], v179 offset:51200
	ds_read_b128 v[192:195], v179 offset:52224
	ds_read_b128 v[196:199], v179 offset:53248
	ds_read_b128 v[200:203], v179 offset:54272
	ds_read_b128 v[204:207], v179 offset:55296
	ds_read_b128 v[208:211], v179 offset:56320
	global_load_lds_dwordx4 v[184:185], off
	s_add_i32 m0, s46, 0x2000
	s_add_u32 s14, s14, 0x40080
	v_lshl_add_u64 v[184:185], v[186:187], 0, s[10:11]
	s_addc_u32 s15, s15, 0
	s_add_i32 s46, s85, s56
	global_load_lds_dwordx4 v[184:185], off
	v_lshl_add_u64 v[184:185], s[14:15], 0, v[154:155]
	s_mov_b32 m0, s46
	s_nop 0
	global_load_lds_dwordx4 v[184:185], off
	v_lshl_add_u64 v[184:185], s[14:15], 0, v[158:159]
	s_add_i32 m0, s46, 0x2000
	s_nop 0
	global_load_lds_dwordx4 v[184:185], off
	s_waitcnt vmcnt(4)
	s_waitcnt lgkmcnt(0)
	s_barrier
	s_setprio 1
	s_waitcnt lgkmcnt(0)
	v_mfma_f32_16x16x32_bf16 v[92:95], v[128:131], v[172:175], v[92:95]
	v_mfma_f32_16x16x32_bf16 v[88:91], v[136:139], v[172:175], v[88:91]
	v_mfma_f32_16x16x32_bf16 v[84:87], v[128:131], v[188:191], v[84:87]
	v_mfma_f32_16x16x32_bf16 v[80:83], v[136:139], v[188:191], v[80:83]
	v_mfma_f32_16x16x32_bf16 v[76:79], v[128:131], v[196:199], v[76:79]
	v_mfma_f32_16x16x32_bf16 v[72:75], v[136:139], v[196:199], v[72:75]
	v_mfma_f32_16x16x32_bf16 v[68:71], v[128:131], v[204:207], v[68:71]
	v_mfma_f32_16x16x32_bf16 v[64:67], v[136:139], v[204:207], v[64:67]
	v_mfma_f32_16x16x32_bf16 v[92:95], v[132:135], v[180:183], v[92:95]
	v_mfma_f32_16x16x32_bf16 v[88:91], v[140:143], v[180:183], v[88:91]
	v_mfma_f32_16x16x32_bf16 v[84:87], v[132:135], v[192:195], v[84:87]
	v_mfma_f32_16x16x32_bf16 v[80:83], v[140:143], v[192:195], v[80:83]
	v_mfma_f32_16x16x32_bf16 v[76:79], v[132:135], v[200:203], v[76:79]
	v_mfma_f32_16x16x32_bf16 v[72:75], v[140:143], v[200:203], v[72:75]
	v_mfma_f32_16x16x32_bf16 v[68:71], v[132:135], v[208:211], v[68:71]
	v_mfma_f32_16x16x32_bf16 v[64:67], v[140:143], v[208:211], v[64:67]
	s_setprio 0
	s_setprio 1
	v_mfma_f32_16x16x32_bf16 v[28:31], v[144:147], v[172:175], v[28:31]
	v_mfma_f32_16x16x32_bf16 v[24:27], v[164:167], v[172:175], v[24:27]
	v_mfma_f32_16x16x32_bf16 v[20:23], v[144:147], v[188:191], v[20:23]
	v_mfma_f32_16x16x32_bf16 v[16:19], v[164:167], v[188:191], v[16:19]
	v_mfma_f32_16x16x32_bf16 v[12:15], v[144:147], v[196:199], v[12:15]
	v_mfma_f32_16x16x32_bf16 v[8:11], v[164:167], v[196:199], v[8:11]
	v_mfma_f32_16x16x32_bf16 v[4:7], v[144:147], v[204:207], v[4:7]
	v_mfma_f32_16x16x32_bf16 v[0:3], v[164:167], v[204:207], v[0:3]
	v_mfma_f32_16x16x32_bf16 v[28:31], v[148:151], v[180:183], v[28:31]
	v_mfma_f32_16x16x32_bf16 v[24:27], v[168:171], v[180:183], v[24:27]
	v_mfma_f32_16x16x32_bf16 v[20:23], v[148:151], v[192:195], v[20:23]
	v_mfma_f32_16x16x32_bf16 v[16:19], v[168:171], v[192:195], v[16:19]
	v_mfma_f32_16x16x32_bf16 v[12:15], v[148:151], v[200:203], v[12:15]
	v_mfma_f32_16x16x32_bf16 v[8:11], v[168:171], v[200:203], v[8:11]
	v_mfma_f32_16x16x32_bf16 v[4:7], v[148:151], v[208:211], v[4:7]
	v_mfma_f32_16x16x32_bf16 v[0:3], v[168:171], v[208:211], v[0:3]
	s_setprio 0
	s_barrier
	s_add_u32 s44, s44, 0x100
	s_addc_u32 s45, s45, 0
	s_add_u32 s55, s55, 0x100
	s_addc_u32 s82, s82, 0
	s_cmp_ge_u32 s83, s51
	s_mov_b32 s14, s83
	s_cbranch_scc0 .LBB0_528
	s_and_b64 vcc, exec, s[12:13]
	s_cbranch_vccz .LBB0_531
	s_barrier

; #define G_STAGE(bufoff, gbase, voff) do { _Pragma("unroll") for (int _i = 0; _i < 2; ++_i) \
;         __builtin_amdgcn_global_load_lds((const unsigned*)((const char*)(gbase) + voff[_i]), (LAS unsigned*)(lds + (bufoff) + ldsw + _i * 8192), 16, 0, 0); } while (0)
; #define G_LDA(dst, b, h) do { _Pragma("unroll") for (int m = 0; m < 4; ++m) _Pragma("unroll") for (int k = 0; k < 2; ++k) dst[m][k] = *(const LAS bf16x8*)(lds + G_SA(b, h) + aoff + m * 2048 + k * 1024); } while (0)
; #define G_LDB(dst, b, h) do { _Pragma("unroll") for (int n = 0; n < 2; ++n) _Pragma("unroll") for (int k = 0; k < 2; ++k) dst[n][k] = *(const LAS bf16x8*)(lds + G_SB(b, h) + boff + n * 2048 + k * 1024); } while (0)
; #define WAIT_V(n) asm volatile("s_waitcnt vmcnt(" #n ")" ::: "memory")
; #define WAIT_L(n) asm volatile("s_waitcnt lgkmcnt(" #n ")" ::: "memory")
; #define BAR __builtin_amdgcn_s_barrier()
; #define SCHED __builtin_amdgcn_sched_barrier(0)
; template <class Get, class Epi>
; DI void gemm_loop(int ntiles, int ld, char* shm, const Get& get, const Epi& epi) {
;     ...
;         for (int t = 0; t < nt; t += 2) {
;             const bool last = (t == nt - 2);
;             const char* a1 = cA + (size_t)(t + 1) * kstep;
;             const char* a2 = last ? nA : cA + (size_t)(t + 2) * kstep; const char* b2 = last ? nB : cB + (size_t)(t + 2) * kstep;
;             const char* a3 = a2 + kstep; const char* b3 = b2 + kstep;
;             G_LDB(B0, 0, 0); G_LDB(B1, 0, 1); SCHED; G_LDA(At, 0, 0); G_STAGE(G_SA(1, 1), a1 + hstep, voffA);
;             WAIT_V(8); WAIT_L(0); BAR; G_MMA(0, 0, At, B0); G_MMA(0, 1, At, B1); BAR; SCHED;
;             G_LDA(At, 0, 1); G_STAGE(G_SB(0, 0), b2, voffB); G_STAGE(G_SB(0, 1), b2 + hstep, voffB); G_STAGE(G_SA(0, 0), a2, voffA);
;             WAIT_V(8); WAIT_L(0); BAR; G_MMA(1, 0, At, B0); G_MMA(1, 1, At, B1); BAR; SCHED;
;             G_LDB(B0, 1, 0); G_LDB(B1, 1, 1); SCHED; G_LDA(At, 1, 0); G_STAGE(G_SA(0, 1), a2 + hstep, voffA);
;             WAIT_V(8); WAIT_L(0); BAR; G_MMA(0, 0, At, B0); G_MMA(0, 1, At, B1); BAR; SCHED;
;             G_LDA(At, 1, 1); G_STAGE(G_SB(1, 0), b3, voffB); G_STAGE(G_SB(1, 1), b3 + hstep, voffB); G_STAGE(G_SA(1, 0), a3, voffA);
;             WAIT_V(8); WAIT_L(0); BAR; G_MMA(1, 0, At, B0); G_MMA(1, 1, At, B1); BAR; SCHED;
.LBB0_763:
	ds_read_b128 v[144:147], v141
	ds_read_b128 v[148:151], v141 offset:1024
	ds_read_b128 v[152:155], v141 offset:2048
	ds_read_b128 v[156:159], v141 offset:3072
	ds_read_b128 v[160:163], v142
	ds_read_b128 v[164:167], v142 offset:1024
	ds_read_b128 v[168:171], v142 offset:2048
	ds_read_b128 v[172:175], v142 offset:3072
	s_add_u32 s14, s36, 0xfffc0080
	s_addc_u32 s15, s37, -1
	s_cmp_eq_u32 s54, 12
	s_cselect_b32 s39, s9, s15
	s_cselect_b32 s38, s50, s14
	s_cselect_b32 s15, s11, s53
	s_cselect_b32 s14, s51, s52
	v_lshl_add_u64 v[184:185], s[36:37], 0, v[136:137]
	s_add_i32 m0, s31, 0xc000
	ds_read_b128 v[176:179], v143
	ds_read_b128 v[180:183], v143 offset:1024
	ds_read_b128 v[188:191], v143 offset:2048
	ds_read_b128 v[192:195], v143 offset:3072
	ds_read_b128 v[196:199], v143 offset:4096
	ds_read_b128 v[200:203], v143 offset:5120
	ds_read_b128 v[204:207], v143 offset:6144
	ds_read_b128 v[208:211], v143 offset:7168
	global_load_lds_dwordx4 v[184:185], off
	v_lshl_add_u64 v[184:185], s[36:37], 0, v[138:139]
	s_add_i32 m0, s31, 0xe000
	s_nop 0
	global_load_lds_dwordx4 v[184:185], off
	s_mov_b32 s98, 0xfffc0000
	s_mov_b32 s99, -1
	v_lshl_add_u64 v[184:185], s[36:37], 0, v[136:137]
	v_lshl_add_u64 v[184:185], v[184:185], 0, s[98:99]
	s_add_i32 m0, s31, 0x8000
	s_nop 0
	global_load_lds_dwordx4 v[184:185], off
	v_lshl_add_u64 v[184:185], s[36:37], 0, v[138:139]
	v_lshl_add_u64 v[184:185], v[184:185], 0, s[98:99]
	s_add_i32 m0, s31, 0xa000
	s_nop 0
	global_load_lds_dwordx4 v[184:185], off
	s_waitcnt vmcnt(8)
	s_waitcnt lgkmcnt(0)
	s_barrier
	s_setprio 1
	s_waitcnt lgkmcnt(0)
	v_mfma_f32_16x16x32_bf16 v[124:127], v[144:147], v[176:179], v[124:127]
	v_mfma_f32_16x16x32_bf16 v[120:123], v[152:155], v[176:179], v[120:123]
	v_mfma_f32_16x16x32_bf16 v[108:111], v[144:147], v[188:191], v[108:111]
	v_mfma_f32_16x16x32_bf16 v[104:107], v[152:155], v[188:191], v[104:107]
	v_mfma_f32_16x16x32_bf16 v[92:95], v[144:147], v[196:199], v[92:95]
	v_mfma_f32_16x16x32_bf16 v[88:91], v[152:155], v[196:199], v[88:91]
	v_mfma_f32_16x16x32_bf16 v[76:79], v[144:147], v[204:207], v[76:79]
	v_mfma_f32_16x16x32_bf16 v[72:75], v[152:155], v[204:207], v[72:75]
	v_mfma_f32_16x16x32_bf16 v[124:127], v[148:151], v[180:183], v[124:127]
	v_mfma_f32_16x16x32_bf16 v[120:123], v[156:159], v[180:183], v[120:123]
	v_mfma_f32_16x16x32_bf16 v[108:111], v[148:151], v[192:195], v[108:111]
	v_mfma_f32_16x16x32_bf16 v[104:107], v[156:159], v[192:195], v[104:107]
	v_mfma_f32_16x16x32_bf16 v[92:95], v[148:151], v[200:203], v[92:95]
	v_mfma_f32_16x16x32_bf16 v[88:91], v[156:159], v[200:203], v[88:91]
	v_mfma_f32_16x16x32_bf16 v[76:79], v[148:151], v[208:211], v[76:79]
	v_mfma_f32_16x16x32_bf16 v[72:75], v[156:159], v[208:211], v[72:75]
	s_setprio 0
	s_setprio 1
	v_mfma_f32_16x16x32_bf16 v[116:119], v[160:163], v[176:179], v[116:119]
	v_mfma_f32_16x16x32_bf16 v[112:115], v[168:171], v[176:179], v[112:115]
	v_mfma_f32_16x16x32_bf16 v[100:103], v[160:163], v[188:191], v[100:103]
	v_mfma_f32_16x16x32_bf16 v[96:99], v[168:171], v[188:191], v[96:99]
	v_mfma_f32_16x16x32_bf16 v[84:87], v[160:163], v[196:199], v[84:87]
	v_mfma_f32_16x16x32_bf16 v[80:83], v[168:171], v[196:199], v[80:83]
	v_mfma_f32_16x16x32_bf16 v[68:71], v[160:163], v[204:207], v[68:71]
	v_mfma_f32_16x16x32_bf16 v[64:67], v[168:171], v[204:207], v[64:67]
	v_mfma_f32_16x16x32_bf16 v[116:119], v[164:167], v[180:183], v[116:119]
	v_mfma_f32_16x16x32_bf16 v[112:115], v[172:175], v[180:183], v[112:115]
	v_mfma_f32_16x16x32_bf16 v[100:103], v[164:167], v[192:195], v[100:103]
	v_mfma_f32_16x16x32_bf16 v[96:99], v[172:175], v[192:195], v[96:99]
	v_mfma_f32_16x16x32_bf16 v[84:87], v[164:167], v[200:203], v[84:87]
	v_mfma_f32_16x16x32_bf16 v[80:83], v[172:175], v[200:203], v[80:83]
	v_mfma_f32_16x16x32_bf16 v[68:71], v[164:167], v[208:211], v[68:71]
	v_mfma_f32_16x16x32_bf16 v[64:67], v[172:175], v[208:211], v[64:67]
	s_setprio 0
	s_barrier
	s_add_i32 s55, s45, s26
	v_lshl_add_u64 v[184:185], s[14:15], 0, v[132:133]
	s_mov_b32 m0, s55
	ds_read_b128 v[176:179], v143 offset:16384
	ds_read_b128 v[180:183], v143 offset:17408
	ds_read_b128 v[188:191], v143 offset:18432
	ds_read_b128 v[192:195], v143 offset:19456
	ds_read_b128 v[196:199], v143 offset:20480
	ds_read_b128 v[200:203], v143 offset:21504
	ds_read_b128 v[204:207], v143 offset:22528
	ds_read_b128 v[208:211], v143 offset:23552
	global_load_lds_dwordx4 v[184:185], off
	s_add_i32 m0, s55, 0x2000
	s_add_u32 s56, s14, 0x40000
	v_lshl_add_u64 v[186:187], s[14:15], 0, v[128:129]
	s_addc_u32 s57, s15, 0
	s_add_i32 s55, s46, s26
	global_load_lds_dwordx4 v[186:187], off
	v_lshl_add_u64 v[212:213], s[56:57], 0, v[132:133]
	s_mov_b32 m0, s55
	v_lshl_add_u64 v[214:215], s[38:39], 0, v[130:131]
	global_load_lds_dwordx4 v[212:213], off
	v_lshl_add_u64 v[212:213], s[56:57], 0, v[128:129]
	s_add_i32 m0, s55, 0x2000
	s_nop 0
	global_load_lds_dwordx4 v[212:213], off
	v_lshl_add_u64 v[212:213], s[38:39], 0, v[134:135]
	s_waitcnt vmcnt(4)
	s_waitcnt lgkmcnt(0)
	s_barrier
; #define G_STAGE(bufoff, gbase, voff) do { _Pragma("unroll") for (int _i = 0; _i < 2; ++_i) \
;         __builtin_amdgcn_global_load_lds((const unsigned*)((const char*)(gbase) + voff[_i]), (LAS unsigned*)(lds + (bufoff) + ldsw + _i * 8192), 16, 0, 0); } while (0)
; #define G_LDA(dst, b, h) do { _Pragma("unroll") for (int m = 0; m < 4; ++m) _Pragma("unroll") for (int k = 0; k < 2; ++k) dst[m][k] = *(const LAS bf16x8*)(lds + G_SA(b, h) + aoff + m * 2048 + k * 1024); } while (0)
; #define G_LDB(dst, b, h) do { _Pragma("unroll") for (int n = 0; n < 2; ++n) _Pragma("unroll") for (int k = 0; k < 2; ++k) dst[n][k] = *(const LAS bf16x8*)(lds + G_SB(b, h) + boff + n * 2048 + k * 1024); } while (0)
; #define G_MMA(ai, bj, At_, Bt_) do { __builtin_amdgcn_s_setprio(1); _Pragma("unroll") for (int m = 0; m < 4; ++m) _Pragma("unroll") for (int n = 0; n < 2; ++n) _Pragma("unroll") for (int k = 0; k < 2; ++k) \
;         acc[ai][bj][m][n] = __builtin_amdgcn_mfma_f32_16x16x32_bf16(Bt_[n][k], At_[m][k], acc[ai][bj][m][n], 0, 0, 0); __builtin_amdgcn_s_setprio(0); } while (0)
; #define WAIT_V(n) asm volatile("s_waitcnt vmcnt(" #n ")" ::: "memory")
; #define WAIT_L(n) asm volatile("s_waitcnt lgkmcnt(" #n ")" ::: "memory")
; #define BAR __builtin_amdgcn_s_barrier()
; #define SCHED __builtin_amdgcn_sched_barrier(0)
; template <class Get, class Epi>
; DI void gemm_loop(int ntiles, int ld, char* shm, const Get& get, const Epi& epi) {
;     ...
;             WAIT_V(8); WAIT_L(0); BAR; G_MMA(1, 0, At, B0); G_MMA(1, 1, At, B1); BAR; SCHED;
;             G_LDB(B0, 1, 0); G_LDB(B1, 1, 1); SCHED; G_LDA(At, 1, 0); G_STAGE(G_SA(0, 1), a2 + hstep, voffA);
;             WAIT_V(8); WAIT_L(0); BAR; G_MMA(0, 0, At, B0); G_MMA(0, 1, At, B1); BAR; SCHED;
;             G_LDA(At, 1, 1); G_STAGE(G_SB(1, 0), b3, voffB); G_STAGE(G_SB(1, 1), b3 + hstep, voffB); G_STAGE(G_SA(1, 0), a3, voffA);
	s_setprio 1
	s_waitcnt lgkmcnt(0)
	v_mfma_f32_16x16x32_bf16 v[60:63], v[144:147], v[176:179], v[60:63]
	v_mfma_f32_16x16x32_bf16 v[56:59], v[152:155], v[176:179], v[56:59]
	v_mfma_f32_16x16x32_bf16 v[44:47], v[144:147], v[188:191], v[44:47]
	v_mfma_f32_16x16x32_bf16 v[40:43], v[152:155], v[188:191], v[40:43]
	v_mfma_f32_16x16x32_bf16 v[28:31], v[144:147], v[196:199], v[28:31]
	v_mfma_f32_16x16x32_bf16 v[24:27], v[152:155], v[196:199], v[24:27]
	v_mfma_f32_16x16x32_bf16 v[12:15], v[144:147], v[204:207], v[12:15]
	v_mfma_f32_16x16x32_bf16 v[8:11], v[152:155], v[204:207], v[8:11]
	v_mfma_f32_16x16x32_bf16 v[60:63], v[148:151], v[180:183], v[60:63]
	v_mfma_f32_16x16x32_bf16 v[56:59], v[156:159], v[180:183], v[56:59]
	v_mfma_f32_16x16x32_bf16 v[44:47], v[148:151], v[192:195], v[44:47]
	v_mfma_f32_16x16x32_bf16 v[40:43], v[156:159], v[192:195], v[40:43]
	v_mfma_f32_16x16x32_bf16 v[28:31], v[148:151], v[200:203], v[28:31]
	v_mfma_f32_16x16x32_bf16 v[24:27], v[156:159], v[200:203], v[24:27]
	v_mfma_f32_16x16x32_bf16 v[12:15], v[148:151], v[208:211], v[12:15]
	v_mfma_f32_16x16x32_bf16 v[8:11], v[156:159], v[208:211], v[8:11]
	s_setprio 0
	s_setprio 1
	v_mfma_f32_16x16x32_bf16 v[52:55], v[160:163], v[176:179], v[52:55]
	v_mfma_f32_16x16x32_bf16 v[48:51], v[168:171], v[176:179], v[48:51]
	v_mfma_f32_16x16x32_bf16 v[36:39], v[160:163], v[188:191], v[36:39]
	v_mfma_f32_16x16x32_bf16 v[32:35], v[168:171], v[188:191], v[32:35]
	v_mfma_f32_16x16x32_bf16 v[20:23], v[160:163], v[196:199], v[20:23]
	v_mfma_f32_16x16x32_bf16 v[16:19], v[168:171], v[196:199], v[16:19]
	v_mfma_f32_16x16x32_bf16 v[4:7], v[160:163], v[204:207], v[4:7]
	v_mfma_f32_16x16x32_bf16 v[0:3], v[168:171], v[204:207], v[0:3]
	v_mfma_f32_16x16x32_bf16 v[52:55], v[164:167], v[180:183], v[52:55]
	v_mfma_f32_16x16x32_bf16 v[48:51], v[172:175], v[180:183], v[48:51]
	v_mfma_f32_16x16x32_bf16 v[36:39], v[164:167], v[192:195], v[36:39]
	v_mfma_f32_16x16x32_bf16 v[32:35], v[172:175], v[192:195], v[32:35]
	v_mfma_f32_16x16x32_bf16 v[20:23], v[164:167], v[200:203], v[20:23]
	v_mfma_f32_16x16x32_bf16 v[16:19], v[172:175], v[200:203], v[16:19]
	v_mfma_f32_16x16x32_bf16 v[4:7], v[164:167], v[208:211], v[4:7]
	v_mfma_f32_16x16x32_bf16 v[0:3], v[172:175], v[208:211], v[0:3]
	s_setprio 0
	s_barrier
	s_add_i32 s55, 0, 0x18000
	s_add_i32 s56, 0, 0x1c000
	v_add_u32_e32 v156, s55, v140
	v_add_u32_e32 v172, s56, v140
	ds_read_b128 v[144:147], v156
	ds_read_b128 v[148:151], v156 offset:1024
	ds_read_b128 v[152:155], v156 offset:2048
	ds_read_b128 v[156:159], v156 offset:3072
	ds_read_b128 v[160:163], v172
	ds_read_b128 v[164:167], v172 offset:1024
	ds_read_b128 v[168:171], v172 offset:2048
	ds_read_b128 v[172:175], v172 offset:3072
	s_add_u32 s38, s38, 0x40000
	s_addc_u32 s39, s39, 0
	s_mov_b32 m0, s41
	v_lshl_add_u64 v[216:217], s[38:39], 0, v[134:135]
	ds_read_b128 v[176:179], v143 offset:32768
	ds_read_b128 v[180:183], v143 offset:33792
	ds_read_b128 v[188:191], v143 offset:34816
	ds_read_b128 v[192:195], v143 offset:35840
	ds_read_b128 v[196:199], v143 offset:36864
	ds_read_b128 v[200:203], v143 offset:37888
	ds_read_b128 v[204:207], v143 offset:38912
	ds_read_b128 v[208:211], v143 offset:39936
	global_load_lds_dwordx4 v[216:217], off
	v_lshl_add_u64 v[216:217], s[38:39], 0, v[130:131]
	s_mov_b32 m0, s42
	s_nop 0
	global_load_lds_dwordx4 v[216:217], off
	s_mov_b32 m0, s31
	s_nop 0
	global_load_lds_dwordx4 v[212:213], off
	s_mov_b32 m0, s35
	s_nop 0
	global_load_lds_dwordx4 v[214:215], off
	s_waitcnt vmcnt(8)
	s_waitcnt lgkmcnt(0)
	s_barrier
; #define G_STAGE(bufoff, gbase, voff) do { _Pragma("unroll") for (int _i = 0; _i < 2; ++_i) \
;         __builtin_amdgcn_global_load_lds((const unsigned*)((const char*)(gbase) + voff[_i]), (LAS unsigned*)(lds + (bufoff) + ldsw + _i * 8192), 16, 0, 0); } while (0)
; #define G_LDA(dst, b, h) do { _Pragma("unroll") for (int m = 0; m < 4; ++m) _Pragma("unroll") for (int k = 0; k < 2; ++k) dst[m][k] = *(const LAS bf16x8*)(lds + G_SA(b, h) + aoff + m * 2048 + k * 1024); } while (0)
; #define G_MMA(ai, bj, At_, Bt_) do { __builtin_amdgcn_s_setprio(1); _Pragma("unroll") for (int m = 0; m < 4; ++m) _Pragma("unroll") for (int n = 0; n < 2; ++n) _Pragma("unroll") for (int k = 0; k < 2; ++k) \
;         acc[ai][bj][m][n] = __builtin_amdgcn_mfma_f32_16x16x32_bf16(Bt_[n][k], At_[m][k], acc[ai][bj][m][n], 0, 0, 0); __builtin_amdgcn_s_setprio(0); } while (0)
; #define WAIT_V(n) asm volatile("s_waitcnt vmcnt(" #n ")" ::: "memory")
; #define WAIT_L(n) asm volatile("s_waitcnt lgkmcnt(" #n ")" ::: "memory")
; #define BAR __builtin_amdgcn_s_barrier()
; #define SCHED __builtin_amdgcn_sched_barrier(0)
; template <class Get, class Epi>
; DI void gemm_loop(int ntiles, int ld, char* shm, const Get& get, const Epi& epi) {
;     ...
;             WAIT_V(8); WAIT_L(0); BAR; G_MMA(0, 0, At, B0); G_MMA(0, 1, At, B1); BAR; SCHED;
;             G_LDA(At, 1, 1); G_STAGE(G_SB(1, 0), b3, voffB); G_STAGE(G_SB(1, 1), b3 + hstep, voffB); G_STAGE(G_SA(1, 0), a3, voffA);
;             WAIT_V(8); WAIT_L(0); BAR; G_MMA(1, 0, At, B0); G_MMA(1, 1, At, B1); BAR; SCHED;
	s_setprio 1
	s_waitcnt lgkmcnt(0)
	v_mfma_f32_16x16x32_bf16 v[124:127], v[144:147], v[176:179], v[124:127]
	v_mfma_f32_16x16x32_bf16 v[120:123], v[152:155], v[176:179], v[120:123]
	v_mfma_f32_16x16x32_bf16 v[108:111], v[144:147], v[188:191], v[108:111]
	v_mfma_f32_16x16x32_bf16 v[104:107], v[152:155], v[188:191], v[104:107]
	v_mfma_f32_16x16x32_bf16 v[92:95], v[144:147], v[196:199], v[92:95]
	v_mfma_f32_16x16x32_bf16 v[88:91], v[152:155], v[196:199], v[88:91]
	v_mfma_f32_16x16x32_bf16 v[76:79], v[144:147], v[204:207], v[76:79]
	v_mfma_f32_16x16x32_bf16 v[72:75], v[152:155], v[204:207], v[72:75]
	v_mfma_f32_16x16x32_bf16 v[124:127], v[148:151], v[180:183], v[124:127]
	v_mfma_f32_16x16x32_bf16 v[120:123], v[156:159], v[180:183], v[120:123]
	v_mfma_f32_16x16x32_bf16 v[108:111], v[148:151], v[192:195], v[108:111]
	v_mfma_f32_16x16x32_bf16 v[104:107], v[156:159], v[192:195], v[104:107]
	v_mfma_f32_16x16x32_bf16 v[92:95], v[148:151], v[200:203], v[92:95]
	v_mfma_f32_16x16x32_bf16 v[88:91], v[156:159], v[200:203], v[88:91]
	v_mfma_f32_16x16x32_bf16 v[76:79], v[148:151], v[208:211], v[76:79]
	v_mfma_f32_16x16x32_bf16 v[72:75], v[156:159], v[208:211], v[72:75]
	s_setprio 0
	s_setprio 1
	v_mfma_f32_16x16x32_bf16 v[116:119], v[160:163], v[176:179], v[116:119]
	v_mfma_f32_16x16x32_bf16 v[112:115], v[168:171], v[176:179], v[112:115]
	v_mfma_f32_16x16x32_bf16 v[100:103], v[160:163], v[188:191], v[100:103]
	v_mfma_f32_16x16x32_bf16 v[96:99], v[168:171], v[188:191], v[96:99]
	v_mfma_f32_16x16x32_bf16 v[84:87], v[160:163], v[196:199], v[84:87]
	v_mfma_f32_16x16x32_bf16 v[80:83], v[168:171], v[196:199], v[80:83]
	v_mfma_f32_16x16x32_bf16 v[68:71], v[160:163], v[204:207], v[68:71]
	v_mfma_f32_16x16x32_bf16 v[64:67], v[168:171], v[204:207], v[64:67]
	v_mfma_f32_16x16x32_bf16 v[116:119], v[164:167], v[180:183], v[116:119]
	v_mfma_f32_16x16x32_bf16 v[112:115], v[172:175], v[180:183], v[112:115]
	v_mfma_f32_16x16x32_bf16 v[100:103], v[164:167], v[192:195], v[100:103]
	v_mfma_f32_16x16x32_bf16 v[96:99], v[172:175], v[192:195], v[96:99]
	v_mfma_f32_16x16x32_bf16 v[84:87], v[164:167], v[200:203], v[84:87]
	v_mfma_f32_16x16x32_bf16 v[80:83], v[172:175], v[200:203], v[80:83]
	v_mfma_f32_16x16x32_bf16 v[68:71], v[164:167], v[208:211], v[68:71]
	v_mfma_f32_16x16x32_bf16 v[64:67], v[172:175], v[208:211], v[64:67]
	s_setprio 0
	s_barrier
	s_add_i32 s38, s55, s26
	v_lshl_add_u64 v[184:185], v[184:185], 0, s[2:3]
	s_mov_b32 m0, s38
	ds_read_b128 v[176:179], v143 offset:49152
	ds_read_b128 v[180:183], v143 offset:50176
	ds_read_b128 v[188:191], v143 offset:51200
	ds_read_b128 v[192:195], v143 offset:52224
	ds_read_b128 v[196:199], v143 offset:53248
	ds_read_b128 v[200:203], v143 offset:54272
	ds_read_b128 v[204:207], v143 offset:55296
	ds_read_b128 v[208:211], v143 offset:56320
	global_load_lds_dwordx4 v[184:185], off
	s_add_i32 m0, s38, 0x2000
	s_add_u32 s14, s14, 0x40080
	v_lshl_add_u64 v[184:185], v[186:187], 0, s[2:3]
	s_addc_u32 s15, s15, 0
	s_add_i32 s38, s56, s26
	global_load_lds_dwordx4 v[184:185], off
	v_lshl_add_u64 v[184:185], s[14:15], 0, v[132:133]
	s_mov_b32 m0, s38
	s_nop 0
	global_load_lds_dwordx4 v[184:185], off
	v_lshl_add_u64 v[184:185], s[14:15], 0, v[128:129]
	s_add_i32 m0, s38, 0x2000
	s_nop 0
	global_load_lds_dwordx4 v[184:185], off
	s_waitcnt vmcnt(4)
	s_waitcnt lgkmcnt(0)
	s_barrier
	s_setprio 1
	s_waitcnt lgkmcnt(0)
	v_mfma_f32_16x16x32_bf16 v[60:63], v[144:147], v[176:179], v[60:63]
	v_mfma_f32_16x16x32_bf16 v[56:59], v[152:155], v[176:179], v[56:59]
	v_mfma_f32_16x16x32_bf16 v[44:47], v[144:147], v[188:191], v[44:47]
	v_mfma_f32_16x16x32_bf16 v[40:43], v[152:155], v[188:191], v[40:43]
	v_mfma_f32_16x16x32_bf16 v[28:31], v[144:147], v[196:199], v[28:31]
	v_mfma_f32_16x16x32_bf16 v[24:27], v[152:155], v[196:199], v[24:27]
	v_mfma_f32_16x16x32_bf16 v[12:15], v[144:147], v[204:207], v[12:15]
	v_mfma_f32_16x16x32_bf16 v[8:11], v[152:155], v[204:207], v[8:11]
	v_mfma_f32_16x16x32_bf16 v[60:63], v[148:151], v[180:183], v[60:63]
	v_mfma_f32_16x16x32_bf16 v[56:59], v[156:159], v[180:183], v[56:59]
	v_mfma_f32_16x16x32_bf16 v[44:47], v[148:151], v[192:195], v[44:47]
	v_mfma_f32_16x16x32_bf16 v[40:43], v[156:159], v[192:195], v[40:43]
	v_mfma_f32_16x16x32_bf16 v[28:31], v[148:151], v[200:203], v[28:31]
	v_mfma_f32_16x16x32_bf16 v[24:27], v[156:159], v[200:203], v[24:27]
	v_mfma_f32_16x16x32_bf16 v[12:15], v[148:151], v[208:211], v[12:15]
	v_mfma_f32_16x16x32_bf16 v[8:11], v[156:159], v[208:211], v[8:11]
	s_setprio 0
	s_setprio 1
	v_mfma_f32_16x16x32_bf16 v[52:55], v[160:163], v[176:179], v[52:55]
	v_mfma_f32_16x16x32_bf16 v[48:51], v[168:171], v[176:179], v[48:51]
	v_mfma_f32_16x16x32_bf16 v[36:39], v[160:163], v[188:191], v[36:39]
	v_mfma_f32_16x16x32_bf16 v[32:35], v[168:171], v[188:191], v[32:35]
	v_mfma_f32_16x16x32_bf16 v[20:23], v[160:163], v[196:199], v[20:23]
	v_mfma_f32_16x16x32_bf16 v[16:19], v[168:171], v[196:199], v[16:19]
	v_mfma_f32_16x16x32_bf16 v[4:7], v[160:163], v[204:207], v[4:7]
	v_mfma_f32_16x16x32_bf16 v[0:3], v[168:171], v[204:207], v[0:3]
	v_mfma_f32_16x16x32_bf16 v[52:55], v[164:167], v[180:183], v[52:55]
	v_mfma_f32_16x16x32_bf16 v[48:51], v[172:175], v[180:183], v[48:51]
	v_mfma_f32_16x16x32_bf16 v[36:39], v[164:167], v[192:195], v[36:39]
	v_mfma_f32_16x16x32_bf16 v[32:35], v[172:175], v[192:195], v[32:35]
	v_mfma_f32_16x16x32_bf16 v[20:23], v[164:167], v[200:203], v[20:23]
	v_mfma_f32_16x16x32_bf16 v[16:19], v[172:175], v[200:203], v[16:19]
	v_mfma_f32_16x16x32_bf16 v[4:7], v[164:167], v[208:211], v[4:7]
	v_mfma_f32_16x16x32_bf16 v[0:3], v[172:175], v[208:211], v[0:3]
	s_setprio 0
	s_barrier
	s_add_i32 s54, s54, 2
	s_add_u32 s36, s36, 0x100
	s_addc_u32 s37, s37, 0
	s_add_u32 s52, s52, 0x100
	s_addc_u32 s53, s53, 0
	s_cmp_gt_u32 s54, 13
	s_cbranch_scc0 .LBB0_763
	s_and_b64 vcc, exec, s[4:5]
	s_cbranch_vccz .LBB0_766
	s_barrier

; #define G_STAGE(bufoff, gbase, voff) do { _Pragma("unroll") for (int _i = 0; _i < 2; ++_i) \
;         __builtin_amdgcn_global_load_lds((const unsigned*)((const char*)(gbase) + voff[_i]), (LAS unsigned*)(lds + (bufoff) + ldsw + _i * 8192), 16, 0, 0); } while (0)
; #define G_LDA(dst, b, h) do { _Pragma("unroll") for (int m = 0; m < 4; ++m) _Pragma("unroll") for (int k = 0; k < 2; ++k) dst[m][k] = *(const LAS bf16x8*)(lds + G_SA(b, h) + aoff + m * 2048 + k * 1024); } while (0)
; #define G_LDB(dst, b, h) do { _Pragma("unroll") for (int n = 0; n < 2; ++n) _Pragma("unroll") for (int k = 0; k < 2; ++k) dst[n][k] = *(const LAS bf16x8*)(lds + G_SB(b, h) + boff + n * 2048 + k * 1024); } while (0)
; #define WAIT_V(n) asm volatile("s_waitcnt vmcnt(" #n ")" ::: "memory")
; #define WAIT_L(n) asm volatile("s_waitcnt lgkmcnt(" #n ")" ::: "memory")
; #define BAR __builtin_amdgcn_s_barrier()
; #define SCHED __builtin_amdgcn_sched_barrier(0)
; template <class Get, class Epi>
; DI void gemm_loop(int ntiles, int ld, char* shm, const Get& get, const Epi& epi) {
;     ...
;         for (int t = 0; t < nt; t += 2) {
;             const bool last = (t == nt - 2);
;             const char* a1 = cA + (size_t)(t + 1) * kstep;
;             const char* a2 = last ? nA : cA + (size_t)(t + 2) * kstep; const char* b2 = last ? nB : cB + (size_t)(t + 2) * kstep;
;             const char* a3 = a2 + kstep; const char* b3 = b2 + kstep;
;             G_LDB(B0, 0, 0); G_LDB(B1, 0, 1); SCHED; G_LDA(At, 0, 0); G_STAGE(G_SA(1, 1), a1 + hstep, voffA);
;             WAIT_V(8); WAIT_L(0); BAR; G_MMA(0, 0, At, B0); G_MMA(0, 1, At, B1); BAR; SCHED;
;             G_LDA(At, 0, 1); G_STAGE(G_SB(0, 0), b2, voffB); G_STAGE(G_SB(0, 1), b2 + hstep, voffB); G_STAGE(G_SA(0, 0), a2, voffA);
;             WAIT_V(8); WAIT_L(0); BAR; G_MMA(1, 0, At, B0); G_MMA(1, 1, At, B1); BAR; SCHED;
;             G_LDB(B0, 1, 0); G_LDB(B1, 1, 1); SCHED; G_LDA(At, 1, 0); G_STAGE(G_SA(0, 1), a2 + hstep, voffA);
;             WAIT_V(8); WAIT_L(0); BAR; G_MMA(0, 0, At, B0); G_MMA(0, 1, At, B1); BAR; SCHED;
;             G_LDA(At, 1, 1); G_STAGE(G_SB(1, 0), b3, voffB); G_STAGE(G_SB(1, 1), b3 + hstep, voffB); G_STAGE(G_SA(1, 0), a3, voffA);
;             WAIT_V(8); WAIT_L(0); BAR; G_MMA(1, 0, At, B0); G_MMA(1, 1, At, B1); BAR; SCHED;
.LBB0_850:
	ds_read_b128 v[128:131], v169
	ds_read_b128 v[132:135], v169 offset:1024
	ds_read_b128 v[136:139], v169 offset:2048
	ds_read_b128 v[140:143], v169 offset:3072
	ds_read_b128 v[158:161], v170
	ds_read_b128 v[162:165], v170 offset:1024
	ds_read_b128 v[172:175], v170 offset:2048
	ds_read_b128 v[176:179], v170 offset:3072
	s_add_i32 s75, s38, 2
	s_add_u32 s14, s4, 0x100
	s_addc_u32 s15, s5, 0
	s_cmp_eq_u32 s72, s38
	s_cselect_b32 s38, s36, s73
	s_cselect_b32 s41, s35, s15
	s_cselect_b32 s40, s34, s14
	s_cselect_b32 s39, s37, s74
	v_lshl_add_u64 v[144:145], s[4:5], 0, v[154:155]
	s_add_i32 m0, s42, 0xc000
	ds_read_b128 v[180:183], v171
	ds_read_b128 v[188:191], v171 offset:1024
	ds_read_b128 v[192:195], v171 offset:2048
	ds_read_b128 v[196:199], v171 offset:3072
	ds_read_b128 v[200:203], v171 offset:4096
	ds_read_b128 v[204:207], v171 offset:5120
	ds_read_b128 v[208:211], v171 offset:6144
	ds_read_b128 v[212:215], v171 offset:7168
	global_load_lds_dwordx4 v[144:145], off
	v_lshl_add_u64 v[144:145], s[4:5], 0, v[156:157]
	s_add_i32 m0, s42, 0xe000
	s_nop 0
	global_load_lds_dwordx4 v[144:145], off
	s_mov_b32 s98, 0xfff50000
	s_mov_b32 s99, -1
	v_lshl_add_u64 v[144:145], s[4:5], 0, v[154:155]
	v_lshl_add_u64 v[144:145], v[144:145], 0, s[98:99]
	s_add_i32 m0, s42, 0x8000
	s_nop 0
	global_load_lds_dwordx4 v[144:145], off
	v_lshl_add_u64 v[144:145], s[4:5], 0, v[156:157]
	v_lshl_add_u64 v[144:145], v[144:145], 0, s[98:99]
	s_add_i32 m0, s42, 0xa000
	s_nop 0
	global_load_lds_dwordx4 v[144:145], off
	s_waitcnt vmcnt(8)
	s_waitcnt lgkmcnt(0)
	s_barrier
	s_setprio 1
	s_waitcnt lgkmcnt(0)
	v_mfma_f32_16x16x32_bf16 v[124:127], v[128:131], v[180:183], v[124:127]
	v_mfma_f32_16x16x32_bf16 v[120:123], v[136:139], v[180:183], v[120:123]
	v_mfma_f32_16x16x32_bf16 v[116:119], v[128:131], v[192:195], v[116:119]
	v_mfma_f32_16x16x32_bf16 v[112:115], v[136:139], v[192:195], v[112:115]
	v_mfma_f32_16x16x32_bf16 v[108:111], v[128:131], v[200:203], v[108:111]
	v_mfma_f32_16x16x32_bf16 v[104:107], v[136:139], v[200:203], v[104:107]
	v_mfma_f32_16x16x32_bf16 v[100:103], v[128:131], v[208:211], v[100:103]
	v_mfma_f32_16x16x32_bf16 v[96:99], v[136:139], v[208:211], v[96:99]
	v_mfma_f32_16x16x32_bf16 v[124:127], v[132:135], v[188:191], v[124:127]
	v_mfma_f32_16x16x32_bf16 v[120:123], v[140:143], v[188:191], v[120:123]
	v_mfma_f32_16x16x32_bf16 v[116:119], v[132:135], v[196:199], v[116:119]
	v_mfma_f32_16x16x32_bf16 v[112:115], v[140:143], v[196:199], v[112:115]
	v_mfma_f32_16x16x32_bf16 v[108:111], v[132:135], v[204:207], v[108:111]
	v_mfma_f32_16x16x32_bf16 v[104:107], v[140:143], v[204:207], v[104:107]
	v_mfma_f32_16x16x32_bf16 v[100:103], v[132:135], v[212:215], v[100:103]
	v_mfma_f32_16x16x32_bf16 v[96:99], v[140:143], v[212:215], v[96:99]
	s_setprio 0
	s_setprio 1
	v_mfma_f32_16x16x32_bf16 v[60:63], v[158:161], v[180:183], v[60:63]
	v_mfma_f32_16x16x32_bf16 v[56:59], v[172:175], v[180:183], v[56:59]
	v_mfma_f32_16x16x32_bf16 v[52:55], v[158:161], v[192:195], v[52:55]
	v_mfma_f32_16x16x32_bf16 v[48:51], v[172:175], v[192:195], v[48:51]
	v_mfma_f32_16x16x32_bf16 v[44:47], v[158:161], v[200:203], v[44:47]
	v_mfma_f32_16x16x32_bf16 v[40:43], v[172:175], v[200:203], v[40:43]
	v_mfma_f32_16x16x32_bf16 v[36:39], v[158:161], v[208:211], v[36:39]
	v_mfma_f32_16x16x32_bf16 v[32:35], v[172:175], v[208:211], v[32:35]
	v_mfma_f32_16x16x32_bf16 v[60:63], v[162:165], v[188:191], v[60:63]
	v_mfma_f32_16x16x32_bf16 v[56:59], v[176:179], v[188:191], v[56:59]
	v_mfma_f32_16x16x32_bf16 v[52:55], v[162:165], v[196:199], v[52:55]
	v_mfma_f32_16x16x32_bf16 v[48:51], v[176:179], v[196:199], v[48:51]
	v_mfma_f32_16x16x32_bf16 v[44:47], v[162:165], v[204:207], v[44:47]
	v_mfma_f32_16x16x32_bf16 v[40:43], v[176:179], v[204:207], v[40:43]
	v_mfma_f32_16x16x32_bf16 v[36:39], v[162:165], v[212:215], v[36:39]
	v_mfma_f32_16x16x32_bf16 v[32:35], v[176:179], v[212:215], v[32:35]
	s_setprio 0
	s_barrier
	s_add_i32 s4, s50, s26
	v_lshl_add_u64 v[144:145], s[38:39], 0, v[148:149]
	s_mov_b32 m0, s4
	ds_read_b128 v[180:183], v171 offset:16384
	ds_read_b128 v[188:191], v171 offset:17408
	ds_read_b128 v[192:195], v171 offset:18432
	ds_read_b128 v[196:199], v171 offset:19456
	ds_read_b128 v[200:203], v171 offset:20480
	ds_read_b128 v[204:207], v171 offset:21504
	ds_read_b128 v[208:211], v171 offset:22528
	ds_read_b128 v[212:215], v171 offset:23552
	global_load_lds_dwordx4 v[144:145], off
	s_add_i32 m0, s4, 0x2000
	s_add_u32 s4, s38, 0xb0000
	v_lshl_add_u64 v[166:167], s[38:39], 0, v[152:153]
	s_addc_u32 s5, s39, 0
	s_add_i32 s76, s51, s26
	global_load_lds_dwordx4 v[166:167], off
	v_lshl_add_u64 v[184:185], s[4:5], 0, v[148:149]
	s_mov_b32 m0, s76
	v_lshl_add_u64 v[186:187], s[40:41], 0, v[150:151]
	global_load_lds_dwordx4 v[184:185], off
	v_lshl_add_u64 v[184:185], s[4:5], 0, v[152:153]
	s_add_i32 m0, s76, 0x2000
	s_nop 0
	global_load_lds_dwordx4 v[184:185], off
	v_lshl_add_u64 v[184:185], s[40:41], 0, v[146:147]
	s_waitcnt vmcnt(4)
	s_waitcnt lgkmcnt(0)
	s_barrier
; #define G_STAGE(bufoff, gbase, voff) do { _Pragma("unroll") for (int _i = 0; _i < 2; ++_i) \
;         __builtin_amdgcn_global_load_lds((const unsigned*)((const char*)(gbase) + voff[_i]), (LAS unsigned*)(lds + (bufoff) + ldsw + _i * 8192), 16, 0, 0); } while (0)
; #define G_LDA(dst, b, h) do { _Pragma("unroll") for (int m = 0; m < 4; ++m) _Pragma("unroll") for (int k = 0; k < 2; ++k) dst[m][k] = *(const LAS bf16x8*)(lds + G_SA(b, h) + aoff + m * 2048 + k * 1024); } while (0)
; #define G_LDB(dst, b, h) do { _Pragma("unroll") for (int n = 0; n < 2; ++n) _Pragma("unroll") for (int k = 0; k < 2; ++k) dst[n][k] = *(const LAS bf16x8*)(lds + G_SB(b, h) + boff + n * 2048 + k * 1024); } while (0)
; #define G_MMA(ai, bj, At_, Bt_) do { __builtin_amdgcn_s_setprio(1); _Pragma("unroll") for (int m = 0; m < 4; ++m) _Pragma("unroll") for (int n = 0; n < 2; ++n) _Pragma("unroll") for (int k = 0; k < 2; ++k) \
;         acc[ai][bj][m][n] = __builtin_amdgcn_mfma_f32_16x16x32_bf16(Bt_[n][k], At_[m][k], acc[ai][bj][m][n], 0, 0, 0); __builtin_amdgcn_s_setprio(0); } while (0)
; #define WAIT_V(n) asm volatile("s_waitcnt vmcnt(" #n ")" ::: "memory")
; #define WAIT_L(n) asm volatile("s_waitcnt lgkmcnt(" #n ")" ::: "memory")
; #define BAR __builtin_amdgcn_s_barrier()
; #define SCHED __builtin_amdgcn_sched_barrier(0)
; template <class Get, class Epi>
; DI void gemm_loop(int ntiles, int ld, char* shm, const Get& get, const Epi& epi) {
;     ...
;             WAIT_V(8); WAIT_L(0); BAR; G_MMA(1, 0, At, B0); G_MMA(1, 1, At, B1); BAR; SCHED;
;             G_LDB(B0, 1, 0); G_LDB(B1, 1, 1); SCHED; G_LDA(At, 1, 0); G_STAGE(G_SA(0, 1), a2 + hstep, voffA);
;             WAIT_V(8); WAIT_L(0); BAR; G_MMA(0, 0, At, B0); G_MMA(0, 1, At, B1); BAR; SCHED;
;             G_LDA(At, 1, 1); G_STAGE(G_SB(1, 0), b3, voffB); G_STAGE(G_SB(1, 1), b3 + hstep, voffB); G_STAGE(G_SA(1, 0), a3, voffA);
	s_setprio 1
	s_waitcnt lgkmcnt(0)
	v_mfma_f32_16x16x32_bf16 v[92:95], v[128:131], v[180:183], v[92:95]
	v_mfma_f32_16x16x32_bf16 v[88:91], v[136:139], v[180:183], v[88:91]
	v_mfma_f32_16x16x32_bf16 v[84:87], v[128:131], v[192:195], v[84:87]
	v_mfma_f32_16x16x32_bf16 v[80:83], v[136:139], v[192:195], v[80:83]
	v_mfma_f32_16x16x32_bf16 v[76:79], v[128:131], v[200:203], v[76:79]
	v_mfma_f32_16x16x32_bf16 v[72:75], v[136:139], v[200:203], v[72:75]
	v_mfma_f32_16x16x32_bf16 v[68:71], v[128:131], v[208:211], v[68:71]
	v_mfma_f32_16x16x32_bf16 v[64:67], v[136:139], v[208:211], v[64:67]
	v_mfma_f32_16x16x32_bf16 v[92:95], v[132:135], v[188:191], v[92:95]
	v_mfma_f32_16x16x32_bf16 v[88:91], v[140:143], v[188:191], v[88:91]
	v_mfma_f32_16x16x32_bf16 v[84:87], v[132:135], v[196:199], v[84:87]
	v_mfma_f32_16x16x32_bf16 v[80:83], v[140:143], v[196:199], v[80:83]
	v_mfma_f32_16x16x32_bf16 v[76:79], v[132:135], v[204:207], v[76:79]
	v_mfma_f32_16x16x32_bf16 v[72:75], v[140:143], v[204:207], v[72:75]
	v_mfma_f32_16x16x32_bf16 v[68:71], v[132:135], v[212:215], v[68:71]
	v_mfma_f32_16x16x32_bf16 v[64:67], v[140:143], v[212:215], v[64:67]
	s_setprio 0
	s_setprio 1
	v_mfma_f32_16x16x32_bf16 v[28:31], v[158:161], v[180:183], v[28:31]
	v_mfma_f32_16x16x32_bf16 v[24:27], v[172:175], v[180:183], v[24:27]
	v_mfma_f32_16x16x32_bf16 v[20:23], v[158:161], v[192:195], v[20:23]
	v_mfma_f32_16x16x32_bf16 v[16:19], v[172:175], v[192:195], v[16:19]
	v_mfma_f32_16x16x32_bf16 v[12:15], v[158:161], v[200:203], v[12:15]
	v_mfma_f32_16x16x32_bf16 v[8:11], v[172:175], v[200:203], v[8:11]
	v_mfma_f32_16x16x32_bf16 v[4:7], v[158:161], v[208:211], v[4:7]
	v_mfma_f32_16x16x32_bf16 v[0:3], v[172:175], v[208:211], v[0:3]
	v_mfma_f32_16x16x32_bf16 v[28:31], v[162:165], v[188:191], v[28:31]
	v_mfma_f32_16x16x32_bf16 v[24:27], v[176:179], v[188:191], v[24:27]
	v_mfma_f32_16x16x32_bf16 v[20:23], v[162:165], v[196:199], v[20:23]
	v_mfma_f32_16x16x32_bf16 v[16:19], v[176:179], v[196:199], v[16:19]
	v_mfma_f32_16x16x32_bf16 v[12:15], v[162:165], v[204:207], v[12:15]
	v_mfma_f32_16x16x32_bf16 v[8:11], v[176:179], v[204:207], v[8:11]
	v_mfma_f32_16x16x32_bf16 v[4:7], v[162:165], v[212:215], v[4:7]
	v_mfma_f32_16x16x32_bf16 v[0:3], v[176:179], v[212:215], v[0:3]
	s_setprio 0
	s_barrier
	s_add_i32 s76, 0, 0x18000
	s_add_i32 s78, 0, 0x1c000
	v_add_u32_e32 v140, s76, v168
	v_add_u32_e32 v176, s78, v168
	ds_read_b128 v[128:131], v140
	ds_read_b128 v[132:135], v140 offset:1024
	ds_read_b128 v[136:139], v140 offset:2048
	ds_read_b128 v[140:143], v140 offset:3072
	ds_read_b128 v[158:161], v176
	ds_read_b128 v[162:165], v176 offset:1024
	ds_read_b128 v[172:175], v176 offset:2048
	ds_read_b128 v[176:179], v176 offset:3072
	s_add_u32 s4, s40, 0xb0000
	s_addc_u32 s5, s41, 0
	s_mov_b32 m0, s44
	v_lshl_add_u64 v[216:217], s[4:5], 0, v[146:147]
	ds_read_b128 v[180:183], v171 offset:32768
	ds_read_b128 v[188:191], v171 offset:33792
	ds_read_b128 v[192:195], v171 offset:34816
	ds_read_b128 v[196:199], v171 offset:35840
	ds_read_b128 v[200:203], v171 offset:36864
	ds_read_b128 v[204:207], v171 offset:37888
	ds_read_b128 v[208:211], v171 offset:38912
	ds_read_b128 v[212:215], v171 offset:39936
	global_load_lds_dwordx4 v[216:217], off
	v_lshl_add_u64 v[216:217], s[4:5], 0, v[150:151]
	s_mov_b32 m0, s45
	s_nop 0
	global_load_lds_dwordx4 v[216:217], off
	s_mov_b32 m0, s42
	s_nop 0
	global_load_lds_dwordx4 v[184:185], off
	s_mov_b32 m0, s43
	s_nop 0
	global_load_lds_dwordx4 v[186:187], off
	s_waitcnt vmcnt(8)
	s_waitcnt lgkmcnt(0)
	s_barrier
; #define G_STAGE(bufoff, gbase, voff) do { _Pragma("unroll") for (int _i = 0; _i < 2; ++_i) \
;         __builtin_amdgcn_global_load_lds((const unsigned*)((const char*)(gbase) + voff[_i]), (LAS unsigned*)(lds + (bufoff) + ldsw + _i * 8192), 16, 0, 0); } while (0)
; #define G_LDA(dst, b, h) do { _Pragma("unroll") for (int m = 0; m < 4; ++m) _Pragma("unroll") for (int k = 0; k < 2; ++k) dst[m][k] = *(const LAS bf16x8*)(lds + G_SA(b, h) + aoff + m * 2048 + k * 1024); } while (0)
; #define G_MMA(ai, bj, At_, Bt_) do { __builtin_amdgcn_s_setprio(1); _Pragma("unroll") for (int m = 0; m < 4; ++m) _Pragma("unroll") for (int n = 0; n < 2; ++n) _Pragma("unroll") for (int k = 0; k < 2; ++k) \
;         acc[ai][bj][m][n] = __builtin_amdgcn_mfma_f32_16x16x32_bf16(Bt_[n][k], At_[m][k], acc[ai][bj][m][n], 0, 0, 0); __builtin_amdgcn_s_setprio(0); } while (0)
; #define WAIT_V(n) asm volatile("s_waitcnt vmcnt(" #n ")" ::: "memory")
; #define WAIT_L(n) asm volatile("s_waitcnt lgkmcnt(" #n ")" ::: "memory")
; #define BAR __builtin_amdgcn_s_barrier()
; #define SCHED __builtin_amdgcn_sched_barrier(0)
; template <class Get, class Epi>
; DI void gemm_loop(int ntiles, int ld, char* shm, const Get& get, const Epi& epi) {
;     ...
;             WAIT_V(8); WAIT_L(0); BAR; G_MMA(0, 0, At, B0); G_MMA(0, 1, At, B1); BAR; SCHED;
;             G_LDA(At, 1, 1); G_STAGE(G_SB(1, 0), b3, voffB); G_STAGE(G_SB(1, 1), b3 + hstep, voffB); G_STAGE(G_SA(1, 0), a3, voffA);
;             WAIT_V(8); WAIT_L(0); BAR; G_MMA(1, 0, At, B0); G_MMA(1, 1, At, B1); BAR; SCHED;
	s_setprio 1
	s_waitcnt lgkmcnt(0)
	v_mfma_f32_16x16x32_bf16 v[124:127], v[128:131], v[180:183], v[124:127]
	v_mfma_f32_16x16x32_bf16 v[120:123], v[136:139], v[180:183], v[120:123]
	v_mfma_f32_16x16x32_bf16 v[116:119], v[128:131], v[192:195], v[116:119]
	v_mfma_f32_16x16x32_bf16 v[112:115], v[136:139], v[192:195], v[112:115]
	v_mfma_f32_16x16x32_bf16 v[108:111], v[128:131], v[200:203], v[108:111]
	v_mfma_f32_16x16x32_bf16 v[104:107], v[136:139], v[200:203], v[104:107]
	v_mfma_f32_16x16x32_bf16 v[100:103], v[128:131], v[208:211], v[100:103]
	v_mfma_f32_16x16x32_bf16 v[96:99], v[136:139], v[208:211], v[96:99]
	v_mfma_f32_16x16x32_bf16 v[124:127], v[132:135], v[188:191], v[124:127]
	v_mfma_f32_16x16x32_bf16 v[120:123], v[140:143], v[188:191], v[120:123]
	v_mfma_f32_16x16x32_bf16 v[116:119], v[132:135], v[196:199], v[116:119]
	v_mfma_f32_16x16x32_bf16 v[112:115], v[140:143], v[196:199], v[112:115]
	v_mfma_f32_16x16x32_bf16 v[108:111], v[132:135], v[204:207], v[108:111]
	v_mfma_f32_16x16x32_bf16 v[104:107], v[140:143], v[204:207], v[104:107]
	v_mfma_f32_16x16x32_bf16 v[100:103], v[132:135], v[212:215], v[100:103]
	v_mfma_f32_16x16x32_bf16 v[96:99], v[140:143], v[212:215], v[96:99]
	s_setprio 0
	s_setprio 1
	v_mfma_f32_16x16x32_bf16 v[60:63], v[158:161], v[180:183], v[60:63]
	v_mfma_f32_16x16x32_bf16 v[56:59], v[172:175], v[180:183], v[56:59]
	v_mfma_f32_16x16x32_bf16 v[52:55], v[158:161], v[192:195], v[52:55]
	v_mfma_f32_16x16x32_bf16 v[48:51], v[172:175], v[192:195], v[48:51]
	v_mfma_f32_16x16x32_bf16 v[44:47], v[158:161], v[200:203], v[44:47]
	v_mfma_f32_16x16x32_bf16 v[40:43], v[172:175], v[200:203], v[40:43]
	v_mfma_f32_16x16x32_bf16 v[36:39], v[158:161], v[208:211], v[36:39]
	v_mfma_f32_16x16x32_bf16 v[32:35], v[172:175], v[208:211], v[32:35]
	v_mfma_f32_16x16x32_bf16 v[60:63], v[162:165], v[188:191], v[60:63]
	v_mfma_f32_16x16x32_bf16 v[56:59], v[176:179], v[188:191], v[56:59]
	v_mfma_f32_16x16x32_bf16 v[52:55], v[162:165], v[196:199], v[52:55]
	v_mfma_f32_16x16x32_bf16 v[48:51], v[176:179], v[196:199], v[48:51]
	v_mfma_f32_16x16x32_bf16 v[44:47], v[162:165], v[204:207], v[44:47]
	v_mfma_f32_16x16x32_bf16 v[40:43], v[176:179], v[204:207], v[40:43]
	v_mfma_f32_16x16x32_bf16 v[36:39], v[162:165], v[212:215], v[36:39]
	v_mfma_f32_16x16x32_bf16 v[32:35], v[176:179], v[212:215], v[32:35]
	s_setprio 0
	s_barrier
	s_add_i32 s4, s76, s26
	v_lshl_add_u64 v[144:145], v[144:145], 0, s[10:11]
	s_mov_b32 m0, s4
	ds_read_b128 v[180:183], v171 offset:49152
	ds_read_b128 v[188:191], v171 offset:50176
	ds_read_b128 v[192:195], v171 offset:51200
	ds_read_b128 v[196:199], v171 offset:52224
	ds_read_b128 v[200:203], v171 offset:53248
	ds_read_b128 v[204:207], v171 offset:54272
	ds_read_b128 v[208:211], v171 offset:55296
	ds_read_b128 v[212:215], v171 offset:56320
	global_load_lds_dwordx4 v[144:145], off
	s_add_i32 m0, s4, 0x2000
	s_add_u32 s4, s38, 0xb0080
	v_lshl_add_u64 v[144:145], v[166:167], 0, s[10:11]
	s_addc_u32 s5, s39, 0
	s_add_i32 s38, s78, s26
	global_load_lds_dwordx4 v[144:145], off
	v_lshl_add_u64 v[144:145], s[4:5], 0, v[148:149]
	s_mov_b32 m0, s38
	s_nop 0
	global_load_lds_dwordx4 v[144:145], off
	v_lshl_add_u64 v[144:145], s[4:5], 0, v[152:153]
	s_add_i32 m0, s38, 0x2000
	s_nop 0
	global_load_lds_dwordx4 v[144:145], off
	s_waitcnt vmcnt(4)
	s_waitcnt lgkmcnt(0)
	s_barrier
	s_setprio 1
	s_waitcnt lgkmcnt(0)
	v_mfma_f32_16x16x32_bf16 v[92:95], v[128:131], v[180:183], v[92:95]
	v_mfma_f32_16x16x32_bf16 v[88:91], v[136:139], v[180:183], v[88:91]
	v_mfma_f32_16x16x32_bf16 v[84:87], v[128:131], v[192:195], v[84:87]
	v_mfma_f32_16x16x32_bf16 v[80:83], v[136:139], v[192:195], v[80:83]
	v_mfma_f32_16x16x32_bf16 v[76:79], v[128:131], v[200:203], v[76:79]
	v_mfma_f32_16x16x32_bf16 v[72:75], v[136:139], v[200:203], v[72:75]
	v_mfma_f32_16x16x32_bf16 v[68:71], v[128:131], v[208:211], v[68:71]
	v_mfma_f32_16x16x32_bf16 v[64:67], v[136:139], v[208:211], v[64:67]
	v_mfma_f32_16x16x32_bf16 v[92:95], v[132:135], v[188:191], v[92:95]
	v_mfma_f32_16x16x32_bf16 v[88:91], v[140:143], v[188:191], v[88:91]
	v_mfma_f32_16x16x32_bf16 v[84:87], v[132:135], v[196:199], v[84:87]
	v_mfma_f32_16x16x32_bf16 v[80:83], v[140:143], v[196:199], v[80:83]
	v_mfma_f32_16x16x32_bf16 v[76:79], v[132:135], v[204:207], v[76:79]
	v_mfma_f32_16x16x32_bf16 v[72:75], v[140:143], v[204:207], v[72:75]
	v_mfma_f32_16x16x32_bf16 v[68:71], v[132:135], v[212:215], v[68:71]
	v_mfma_f32_16x16x32_bf16 v[64:67], v[140:143], v[212:215], v[64:67]
	s_setprio 0
	s_setprio 1
	v_mfma_f32_16x16x32_bf16 v[28:31], v[158:161], v[180:183], v[28:31]
	v_mfma_f32_16x16x32_bf16 v[24:27], v[172:175], v[180:183], v[24:27]
	v_mfma_f32_16x16x32_bf16 v[20:23], v[158:161], v[192:195], v[20:23]
	v_mfma_f32_16x16x32_bf16 v[16:19], v[172:175], v[192:195], v[16:19]
	v_mfma_f32_16x16x32_bf16 v[12:15], v[158:161], v[200:203], v[12:15]
	v_mfma_f32_16x16x32_bf16 v[8:11], v[172:175], v[200:203], v[8:11]
	v_mfma_f32_16x16x32_bf16 v[4:7], v[158:161], v[208:211], v[4:7]
	v_mfma_f32_16x16x32_bf16 v[0:3], v[172:175], v[208:211], v[0:3]
	v_mfma_f32_16x16x32_bf16 v[28:31], v[162:165], v[188:191], v[28:31]
	v_mfma_f32_16x16x32_bf16 v[24:27], v[176:179], v[188:191], v[24:27]
	v_mfma_f32_16x16x32_bf16 v[20:23], v[162:165], v[196:199], v[20:23]
	v_mfma_f32_16x16x32_bf16 v[16:19], v[176:179], v[196:199], v[16:19]
	v_mfma_f32_16x16x32_bf16 v[12:15], v[162:165], v[204:207], v[12:15]
	v_mfma_f32_16x16x32_bf16 v[8:11], v[176:179], v[204:207], v[8:11]
	v_mfma_f32_16x16x32_bf16 v[4:7], v[162:165], v[212:215], v[4:7]
	v_mfma_f32_16x16x32_bf16 v[0:3], v[176:179], v[212:215], v[0:3]
	s_setprio 0
	s_barrier
	s_add_u32 s73, s73, 0x100
	s_addc_u32 s74, s74, 0
	s_cmp_ge_u32 s75, s59
	s_mov_b64 s[4:5], s[14:15]
	s_mov_b32 s38, s75
	s_cbranch_scc0 .LBB0_850
	s_and_b64 vcc, exec, s[12:13]
	s_cbranch_vccz .LBB0_853
	s_barrier

; #define G_STAGE(bufoff, gbase, voff) do { _Pragma("unroll") for (int _i = 0; _i < 2; ++_i) \
;         __builtin_amdgcn_global_load_lds((const unsigned*)((const char*)(gbase) + voff[_i]), (LAS unsigned*)(lds + (bufoff) + ldsw + _i * 8192), 16, 0, 0); } while (0)
; #define G_LDA(dst, b, h) do { _Pragma("unroll") for (int m = 0; m < 4; ++m) _Pragma("unroll") for (int k = 0; k < 2; ++k) dst[m][k] = *(const LAS bf16x8*)(lds + G_SA(b, h) + aoff + m * 2048 + k * 1024); } while (0)
; #define G_LDB(dst, b, h) do { _Pragma("unroll") for (int n = 0; n < 2; ++n) _Pragma("unroll") for (int k = 0; k < 2; ++k) dst[n][k] = *(const LAS bf16x8*)(lds + G_SB(b, h) + boff + n * 2048 + k * 1024); } while (0)
; #define WAIT_V(n) asm volatile("s_waitcnt vmcnt(" #n ")" ::: "memory")
; #define WAIT_L(n) asm volatile("s_waitcnt lgkmcnt(" #n ")" ::: "memory")
; #define BAR __builtin_amdgcn_s_barrier()
; #define SCHED __builtin_amdgcn_sched_barrier(0)
; template <class Get, class Epi>
; DI void gemm_loop(int ntiles, int ld, char* shm, const Get& get, const Epi& epi) {
;     ...
;         for (int t = 0; t < nt; t += 2) {
;             const bool last = (t == nt - 2);
;             const char* a1 = cA + (size_t)(t + 1) * kstep;
;             const char* a2 = last ? nA : cA + (size_t)(t + 2) * kstep; const char* b2 = last ? nB : cB + (size_t)(t + 2) * kstep;
;             const char* a3 = a2 + kstep; const char* b3 = b2 + kstep;
;             G_LDB(B0, 0, 0); G_LDB(B1, 0, 1); SCHED; G_LDA(At, 0, 0); G_STAGE(G_SA(1, 1), a1 + hstep, voffA);
;             WAIT_V(8); WAIT_L(0); BAR; G_MMA(0, 0, At, B0); G_MMA(0, 1, At, B1); BAR; SCHED;
;             G_LDA(At, 0, 1); G_STAGE(G_SB(0, 0), b2, voffB); G_STAGE(G_SB(0, 1), b2 + hstep, voffB); G_STAGE(G_SA(0, 0), a2, voffA);
;             WAIT_V(8); WAIT_L(0); BAR; G_MMA(1, 0, At, B0); G_MMA(1, 1, At, B1); BAR; SCHED;
;             G_LDB(B0, 1, 0); G_LDB(B1, 1, 1); SCHED; G_LDA(At, 1, 0); G_STAGE(G_SA(0, 1), a2 + hstep, voffA);
;             WAIT_V(8); WAIT_L(0); BAR; G_MMA(0, 0, At, B0); G_MMA(0, 1, At, B1); BAR; SCHED;
;             G_LDA(At, 1, 1); G_STAGE(G_SB(1, 0), b3, voffB); G_STAGE(G_SB(1, 1), b3 + hstep, voffB); G_STAGE(G_SA(1, 0), a3, voffA);
;             WAIT_V(8); WAIT_L(0); BAR; G_MMA(1, 0, At, B0); G_MMA(1, 1, At, B1); BAR; SCHED;
.LBB0_1099:
	ds_read_b128 v[140:143], v145
	ds_read_b128 v[148:151], v145 offset:1024
	ds_read_b128 v[152:155], v145 offset:2048
	ds_read_b128 v[156:159], v145 offset:3072
	ds_read_b128 v[160:163], v146
	ds_read_b128 v[164:167], v146 offset:1024
	ds_read_b128 v[168:171], v146 offset:2048
	ds_read_b128 v[172:175], v146 offset:3072
	s_add_u32 s14, s52, 0xfffc0080
	s_addc_u32 s15, s53, -1
	s_cmp_eq_u32 s76, 12
	s_cselect_b32 s47, s39, s15
	s_cselect_b32 s46, s72, s14
	s_cselect_b32 s15, s37, s75
	s_cselect_b32 s14, s73, s74
	v_lshl_add_u64 v[208:209], s[52:53], 0, v[136:137]
	s_add_i32 m0, s45, 0xc000
	ds_read_b128 v[176:179], v147
	ds_read_b128 v[180:183], v147 offset:1024
	ds_read_b128 v[184:187], v147 offset:2048
	ds_read_b128 v[188:191], v147 offset:3072
	ds_read_b128 v[192:195], v147 offset:4096
	ds_read_b128 v[196:199], v147 offset:5120
	ds_read_b128 v[200:203], v147 offset:6144
	ds_read_b128 v[204:207], v147 offset:7168
	global_load_lds_dwordx4 v[208:209], off
	v_lshl_add_u64 v[208:209], s[52:53], 0, v[138:139]
	s_add_i32 m0, s45, 0xe000
	s_nop 0
	global_load_lds_dwordx4 v[208:209], off
	s_mov_b32 s98, 0xfffc0000
	s_mov_b32 s99, -1
	v_lshl_add_u64 v[208:209], s[52:53], 0, v[136:137]
	v_lshl_add_u64 v[208:209], v[208:209], 0, s[98:99]
	s_add_i32 m0, s45, 0x8000
	s_nop 0
	global_load_lds_dwordx4 v[208:209], off
	v_lshl_add_u64 v[208:209], s[52:53], 0, v[138:139]
	v_lshl_add_u64 v[208:209], v[208:209], 0, s[98:99]
	s_add_i32 m0, s45, 0xa000
	s_nop 0
	global_load_lds_dwordx4 v[208:209], off
	s_waitcnt vmcnt(8)
	s_waitcnt lgkmcnt(0)
	s_barrier
	s_setprio 1
	s_waitcnt lgkmcnt(0)
	v_mfma_f32_16x16x32_bf16 v[124:127], v[140:143], v[176:179], v[124:127]
	v_mfma_f32_16x16x32_bf16 v[120:123], v[152:155], v[176:179], v[120:123]
	v_mfma_f32_16x16x32_bf16 v[116:119], v[140:143], v[184:187], v[116:119]
	v_mfma_f32_16x16x32_bf16 v[112:115], v[152:155], v[184:187], v[112:115]
	v_mfma_f32_16x16x32_bf16 v[108:111], v[140:143], v[192:195], v[108:111]
	v_mfma_f32_16x16x32_bf16 v[100:103], v[152:155], v[192:195], v[100:103]
	v_mfma_f32_16x16x32_bf16 v[92:95], v[140:143], v[200:203], v[92:95]
	v_mfma_f32_16x16x32_bf16 v[84:87], v[152:155], v[200:203], v[84:87]
	v_mfma_f32_16x16x32_bf16 v[124:127], v[148:151], v[180:183], v[124:127]
	v_mfma_f32_16x16x32_bf16 v[120:123], v[156:159], v[180:183], v[120:123]
	v_mfma_f32_16x16x32_bf16 v[116:119], v[148:151], v[188:191], v[116:119]
	v_mfma_f32_16x16x32_bf16 v[112:115], v[156:159], v[188:191], v[112:115]
	v_mfma_f32_16x16x32_bf16 v[108:111], v[148:151], v[196:199], v[108:111]
	v_mfma_f32_16x16x32_bf16 v[100:103], v[156:159], v[196:199], v[100:103]
	v_mfma_f32_16x16x32_bf16 v[92:95], v[148:151], v[204:207], v[92:95]
	v_mfma_f32_16x16x32_bf16 v[84:87], v[156:159], v[204:207], v[84:87]
	s_setprio 0
	s_setprio 1
	v_mfma_f32_16x16x32_bf16 v[104:107], v[160:163], v[176:179], v[104:107]
	v_mfma_f32_16x16x32_bf16 v[96:99], v[168:171], v[176:179], v[96:99]
	v_mfma_f32_16x16x32_bf16 v[88:91], v[160:163], v[184:187], v[88:91]
	v_mfma_f32_16x16x32_bf16 v[80:83], v[168:171], v[184:187], v[80:83]
	v_mfma_f32_16x16x32_bf16 v[76:79], v[160:163], v[192:195], v[76:79]
	v_mfma_f32_16x16x32_bf16 v[72:75], v[168:171], v[192:195], v[72:75]
	v_mfma_f32_16x16x32_bf16 v[68:71], v[160:163], v[200:203], v[68:71]
	v_mfma_f32_16x16x32_bf16 v[64:67], v[168:171], v[200:203], v[64:67]
	v_mfma_f32_16x16x32_bf16 v[104:107], v[164:167], v[180:183], v[104:107]
	v_mfma_f32_16x16x32_bf16 v[96:99], v[172:175], v[180:183], v[96:99]
	v_mfma_f32_16x16x32_bf16 v[88:91], v[164:167], v[188:191], v[88:91]
	v_mfma_f32_16x16x32_bf16 v[80:83], v[172:175], v[188:191], v[80:83]
	v_mfma_f32_16x16x32_bf16 v[76:79], v[164:167], v[196:199], v[76:79]
	v_mfma_f32_16x16x32_bf16 v[72:75], v[172:175], v[196:199], v[72:75]
	v_mfma_f32_16x16x32_bf16 v[68:71], v[164:167], v[204:207], v[68:71]
	v_mfma_f32_16x16x32_bf16 v[64:67], v[172:175], v[204:207], v[64:67]
	s_setprio 0
	s_barrier
	s_add_i32 s77, s57, s7
	v_lshl_add_u64 v[208:209], s[14:15], 0, v[130:131]
	s_mov_b32 m0, s77
	ds_read_b128 v[176:179], v147 offset:16384
	ds_read_b128 v[180:183], v147 offset:17408
	ds_read_b128 v[184:187], v147 offset:18432
	ds_read_b128 v[188:191], v147 offset:19456
	ds_read_b128 v[192:195], v147 offset:20480
	ds_read_b128 v[196:199], v147 offset:21504
	ds_read_b128 v[200:203], v147 offset:22528
	ds_read_b128 v[204:207], v147 offset:23552
	global_load_lds_dwordx4 v[208:209], off
	s_add_i32 m0, s77, 0x2000
	s_add_u32 s78, s14, 0x40000
	v_lshl_add_u64 v[210:211], s[14:15], 0, v[134:135]
	s_addc_u32 s79, s15, 0
	s_add_i32 s77, s58, s7
	global_load_lds_dwordx4 v[210:211], off
	v_lshl_add_u64 v[212:213], s[78:79], 0, v[130:131]
	s_mov_b32 m0, s77
	v_lshl_add_u64 v[214:215], s[46:47], 0, v[132:133]
	global_load_lds_dwordx4 v[212:213], off
	v_lshl_add_u64 v[212:213], s[78:79], 0, v[134:135]
	s_add_i32 m0, s77, 0x2000
	s_nop 0
	global_load_lds_dwordx4 v[212:213], off
	v_lshl_add_u64 v[212:213], s[46:47], 0, v[128:129]
	s_waitcnt vmcnt(4)
	s_waitcnt lgkmcnt(0)
	s_barrier
; #define G_STAGE(bufoff, gbase, voff) do { _Pragma("unroll") for (int _i = 0; _i < 2; ++_i) \
;         __builtin_amdgcn_global_load_lds((const unsigned*)((const char*)(gbase) + voff[_i]), (LAS unsigned*)(lds + (bufoff) + ldsw + _i * 8192), 16, 0, 0); } while (0)
; #define G_LDA(dst, b, h) do { _Pragma("unroll") for (int m = 0; m < 4; ++m) _Pragma("unroll") for (int k = 0; k < 2; ++k) dst[m][k] = *(const LAS bf16x8*)(lds + G_SA(b, h) + aoff + m * 2048 + k * 1024); } while (0)
; #define G_LDB(dst, b, h) do { _Pragma("unroll") for (int n = 0; n < 2; ++n) _Pragma("unroll") for (int k = 0; k < 2; ++k) dst[n][k] = *(const LAS bf16x8*)(lds + G_SB(b, h) + boff + n * 2048 + k * 1024); } while (0)
; #define G_MMA(ai, bj, At_, Bt_) do { __builtin_amdgcn_s_setprio(1); _Pragma("unroll") for (int m = 0; m < 4; ++m) _Pragma("unroll") for (int n = 0; n < 2; ++n) _Pragma("unroll") for (int k = 0; k < 2; ++k) \
;         acc[ai][bj][m][n] = __builtin_amdgcn_mfma_f32_16x16x32_bf16(Bt_[n][k], At_[m][k], acc[ai][bj][m][n], 0, 0, 0); __builtin_amdgcn_s_setprio(0); } while (0)
; #define WAIT_V(n) asm volatile("s_waitcnt vmcnt(" #n ")" ::: "memory")
; #define WAIT_L(n) asm volatile("s_waitcnt lgkmcnt(" #n ")" ::: "memory")
; #define BAR __builtin_amdgcn_s_barrier()
; #define SCHED __builtin_amdgcn_sched_barrier(0)
; template <class Get, class Epi>
; DI void gemm_loop(int ntiles, int ld, char* shm, const Get& get, const Epi& epi) {
;     ...
;             WAIT_V(8); WAIT_L(0); BAR; G_MMA(1, 0, At, B0); G_MMA(1, 1, At, B1); BAR; SCHED;
;             G_LDB(B0, 1, 0); G_LDB(B1, 1, 1); SCHED; G_LDA(At, 1, 0); G_STAGE(G_SA(0, 1), a2 + hstep, voffA);
;             WAIT_V(8); WAIT_L(0); BAR; G_MMA(0, 0, At, B0); G_MMA(0, 1, At, B1); BAR; SCHED;
;             G_LDA(At, 1, 1); G_STAGE(G_SB(1, 0), b3, voffB); G_STAGE(G_SB(1, 1), b3 + hstep, voffB); G_STAGE(G_SA(1, 0), a3, voffA);
	s_setprio 1
	s_waitcnt lgkmcnt(0)
	v_mfma_f32_16x16x32_bf16 v[60:63], v[140:143], v[176:179], v[60:63]
	v_mfma_f32_16x16x32_bf16 v[56:59], v[152:155], v[176:179], v[56:59]
	v_mfma_f32_16x16x32_bf16 v[52:55], v[140:143], v[184:187], v[52:55]
	v_mfma_f32_16x16x32_bf16 v[48:51], v[152:155], v[184:187], v[48:51]
	v_mfma_f32_16x16x32_bf16 v[44:47], v[140:143], v[192:195], v[44:47]
	v_mfma_f32_16x16x32_bf16 v[36:39], v[152:155], v[192:195], v[36:39]
	v_mfma_f32_16x16x32_bf16 v[28:31], v[140:143], v[200:203], v[28:31]
	v_mfma_f32_16x16x32_bf16 v[20:23], v[152:155], v[200:203], v[20:23]
	v_mfma_f32_16x16x32_bf16 v[60:63], v[148:151], v[180:183], v[60:63]
	v_mfma_f32_16x16x32_bf16 v[56:59], v[156:159], v[180:183], v[56:59]
	v_mfma_f32_16x16x32_bf16 v[52:55], v[148:151], v[188:191], v[52:55]
	v_mfma_f32_16x16x32_bf16 v[48:51], v[156:159], v[188:191], v[48:51]
	v_mfma_f32_16x16x32_bf16 v[44:47], v[148:151], v[196:199], v[44:47]
	v_mfma_f32_16x16x32_bf16 v[36:39], v[156:159], v[196:199], v[36:39]
	v_mfma_f32_16x16x32_bf16 v[28:31], v[148:151], v[204:207], v[28:31]
	v_mfma_f32_16x16x32_bf16 v[20:23], v[156:159], v[204:207], v[20:23]
	s_setprio 0
	s_setprio 1
	v_mfma_f32_16x16x32_bf16 v[40:43], v[160:163], v[176:179], v[40:43]
	v_mfma_f32_16x16x32_bf16 v[32:35], v[168:171], v[176:179], v[32:35]
	v_mfma_f32_16x16x32_bf16 v[24:27], v[160:163], v[184:187], v[24:27]
	v_mfma_f32_16x16x32_bf16 v[16:19], v[168:171], v[184:187], v[16:19]
	v_mfma_f32_16x16x32_bf16 v[12:15], v[160:163], v[192:195], v[12:15]
	v_mfma_f32_16x16x32_bf16 v[8:11], v[168:171], v[192:195], v[8:11]
	v_mfma_f32_16x16x32_bf16 v[4:7], v[160:163], v[200:203], v[4:7]
	v_mfma_f32_16x16x32_bf16 v[0:3], v[168:171], v[200:203], v[0:3]
	v_mfma_f32_16x16x32_bf16 v[40:43], v[164:167], v[180:183], v[40:43]
	v_mfma_f32_16x16x32_bf16 v[32:35], v[172:175], v[180:183], v[32:35]
	v_mfma_f32_16x16x32_bf16 v[24:27], v[164:167], v[188:191], v[24:27]
	v_mfma_f32_16x16x32_bf16 v[16:19], v[172:175], v[188:191], v[16:19]
	v_mfma_f32_16x16x32_bf16 v[12:15], v[164:167], v[196:199], v[12:15]
	v_mfma_f32_16x16x32_bf16 v[8:11], v[172:175], v[196:199], v[8:11]
	v_mfma_f32_16x16x32_bf16 v[4:7], v[164:167], v[204:207], v[4:7]
	v_mfma_f32_16x16x32_bf16 v[0:3], v[172:175], v[204:207], v[0:3]
	s_setprio 0
	s_barrier
	s_add_i32 s77, 0, 0x18000
	s_add_i32 s78, 0, 0x1c000
	v_add_u32_e32 v156, s77, v144
	v_add_u32_e32 v172, s78, v144
	ds_read_b128 v[140:143], v156
	ds_read_b128 v[148:151], v156 offset:1024
	ds_read_b128 v[152:155], v156 offset:2048
	ds_read_b128 v[156:159], v156 offset:3072
	ds_read_b128 v[160:163], v172
	ds_read_b128 v[164:167], v172 offset:1024
	ds_read_b128 v[168:171], v172 offset:2048
	ds_read_b128 v[172:175], v172 offset:3072
	s_add_u32 s46, s46, 0x40000
	s_addc_u32 s47, s47, 0
	s_mov_b32 m0, s50
	v_lshl_add_u64 v[216:217], s[46:47], 0, v[128:129]
	ds_read_b128 v[176:179], v147 offset:32768
	ds_read_b128 v[180:183], v147 offset:33792
	ds_read_b128 v[184:187], v147 offset:34816
	ds_read_b128 v[188:191], v147 offset:35840
	ds_read_b128 v[192:195], v147 offset:36864
	ds_read_b128 v[196:199], v147 offset:37888
	ds_read_b128 v[200:203], v147 offset:38912
	ds_read_b128 v[204:207], v147 offset:39936
	global_load_lds_dwordx4 v[216:217], off
	v_lshl_add_u64 v[216:217], s[46:47], 0, v[132:133]
	s_mov_b32 m0, s51
	s_nop 0
	global_load_lds_dwordx4 v[216:217], off
	s_mov_b32 m0, s45
	s_nop 0
	global_load_lds_dwordx4 v[212:213], off
	s_mov_b32 m0, s49
	s_nop 0
	global_load_lds_dwordx4 v[214:215], off
	s_waitcnt vmcnt(8)
	s_waitcnt lgkmcnt(0)
	s_barrier
; #define G_STAGE(bufoff, gbase, voff) do { _Pragma("unroll") for (int _i = 0; _i < 2; ++_i) \
;         __builtin_amdgcn_global_load_lds((const unsigned*)((const char*)(gbase) + voff[_i]), (LAS unsigned*)(lds + (bufoff) + ldsw + _i * 8192), 16, 0, 0); } while (0)
; #define G_LDA(dst, b, h) do { _Pragma("unroll") for (int m = 0; m < 4; ++m) _Pragma("unroll") for (int k = 0; k < 2; ++k) dst[m][k] = *(const LAS bf16x8*)(lds + G_SA(b, h) + aoff + m * 2048 + k * 1024); } while (0)
; #define G_MMA(ai, bj, At_, Bt_) do { __builtin_amdgcn_s_setprio(1); _Pragma("unroll") for (int m = 0; m < 4; ++m) _Pragma("unroll") for (int n = 0; n < 2; ++n) _Pragma("unroll") for (int k = 0; k < 2; ++k) \
;         acc[ai][bj][m][n] = __builtin_amdgcn_mfma_f32_16x16x32_bf16(Bt_[n][k], At_[m][k], acc[ai][bj][m][n], 0, 0, 0); __builtin_amdgcn_s_setprio(0); } while (0)
; #define WAIT_V(n) asm volatile("s_waitcnt vmcnt(" #n ")" ::: "memory")
; #define WAIT_L(n) asm volatile("s_waitcnt lgkmcnt(" #n ")" ::: "memory")
; #define BAR __builtin_amdgcn_s_barrier()
; #define SCHED __builtin_amdgcn_sched_barrier(0)
; template <class Get, class Epi>
; DI void gemm_loop(int ntiles, int ld, char* shm, const Get& get, const Epi& epi) {
;     ...
;             WAIT_V(8); WAIT_L(0); BAR; G_MMA(0, 0, At, B0); G_MMA(0, 1, At, B1); BAR; SCHED;
;             G_LDA(At, 1, 1); G_STAGE(G_SB(1, 0), b3, voffB); G_STAGE(G_SB(1, 1), b3 + hstep, voffB); G_STAGE(G_SA(1, 0), a3, voffA);
;             WAIT_V(8); WAIT_L(0); BAR; G_MMA(1, 0, At, B0); G_MMA(1, 1, At, B1); BAR; SCHED;
	s_setprio 1
	s_waitcnt lgkmcnt(0)
	v_mfma_f32_16x16x32_bf16 v[124:127], v[140:143], v[176:179], v[124:127]
	v_mfma_f32_16x16x32_bf16 v[120:123], v[152:155], v[176:179], v[120:123]
	v_mfma_f32_16x16x32_bf16 v[116:119], v[140:143], v[184:187], v[116:119]
	v_mfma_f32_16x16x32_bf16 v[112:115], v[152:155], v[184:187], v[112:115]
	v_mfma_f32_16x16x32_bf16 v[108:111], v[140:143], v[192:195], v[108:111]
	v_mfma_f32_16x16x32_bf16 v[100:103], v[152:155], v[192:195], v[100:103]
	v_mfma_f32_16x16x32_bf16 v[92:95], v[140:143], v[200:203], v[92:95]
	v_mfma_f32_16x16x32_bf16 v[84:87], v[152:155], v[200:203], v[84:87]
	v_mfma_f32_16x16x32_bf16 v[124:127], v[148:151], v[180:183], v[124:127]
	v_mfma_f32_16x16x32_bf16 v[120:123], v[156:159], v[180:183], v[120:123]
	v_mfma_f32_16x16x32_bf16 v[116:119], v[148:151], v[188:191], v[116:119]
	v_mfma_f32_16x16x32_bf16 v[112:115], v[156:159], v[188:191], v[112:115]
	v_mfma_f32_16x16x32_bf16 v[108:111], v[148:151], v[196:199], v[108:111]
	v_mfma_f32_16x16x32_bf16 v[100:103], v[156:159], v[196:199], v[100:103]
	v_mfma_f32_16x16x32_bf16 v[92:95], v[148:151], v[204:207], v[92:95]
	v_mfma_f32_16x16x32_bf16 v[84:87], v[156:159], v[204:207], v[84:87]
	s_setprio 0
	s_setprio 1
	v_mfma_f32_16x16x32_bf16 v[104:107], v[160:163], v[176:179], v[104:107]
	v_mfma_f32_16x16x32_bf16 v[96:99], v[168:171], v[176:179], v[96:99]
	v_mfma_f32_16x16x32_bf16 v[88:91], v[160:163], v[184:187], v[88:91]
	v_mfma_f32_16x16x32_bf16 v[80:83], v[168:171], v[184:187], v[80:83]
	v_mfma_f32_16x16x32_bf16 v[76:79], v[160:163], v[192:195], v[76:79]
	v_mfma_f32_16x16x32_bf16 v[72:75], v[168:171], v[192:195], v[72:75]
	v_mfma_f32_16x16x32_bf16 v[68:71], v[160:163], v[200:203], v[68:71]
	v_mfma_f32_16x16x32_bf16 v[64:67], v[168:171], v[200:203], v[64:67]
	v_mfma_f32_16x16x32_bf16 v[104:107], v[164:167], v[180:183], v[104:107]
	v_mfma_f32_16x16x32_bf16 v[96:99], v[172:175], v[180:183], v[96:99]
	v_mfma_f32_16x16x32_bf16 v[88:91], v[164:167], v[188:191], v[88:91]
	v_mfma_f32_16x16x32_bf16 v[80:83], v[172:175], v[188:191], v[80:83]
	v_mfma_f32_16x16x32_bf16 v[76:79], v[164:167], v[196:199], v[76:79]
	v_mfma_f32_16x16x32_bf16 v[72:75], v[172:175], v[196:199], v[72:75]
	v_mfma_f32_16x16x32_bf16 v[68:71], v[164:167], v[204:207], v[68:71]
	v_mfma_f32_16x16x32_bf16 v[64:67], v[172:175], v[204:207], v[64:67]
	s_setprio 0
	s_barrier
	s_add_i32 s46, s77, s7
	v_lshl_add_u64 v[208:209], v[208:209], 0, s[10:11]
	s_mov_b32 m0, s46
	ds_read_b128 v[176:179], v147 offset:49152
	ds_read_b128 v[180:183], v147 offset:50176
	ds_read_b128 v[184:187], v147 offset:51200
	ds_read_b128 v[188:191], v147 offset:52224
	ds_read_b128 v[192:195], v147 offset:53248
	ds_read_b128 v[196:199], v147 offset:54272
	ds_read_b128 v[200:203], v147 offset:55296
	ds_read_b128 v[204:207], v147 offset:56320
	global_load_lds_dwordx4 v[208:209], off
	s_add_i32 m0, s46, 0x2000
	s_add_u32 s14, s14, 0x40080
	v_lshl_add_u64 v[208:209], v[210:211], 0, s[10:11]
	s_addc_u32 s15, s15, 0
	s_add_i32 s46, s78, s7
	global_load_lds_dwordx4 v[208:209], off
	v_lshl_add_u64 v[208:209], s[14:15], 0, v[130:131]
	s_mov_b32 m0, s46
	s_nop 0
	global_load_lds_dwordx4 v[208:209], off
	v_lshl_add_u64 v[208:209], s[14:15], 0, v[134:135]
	s_add_i32 m0, s46, 0x2000
	s_nop 0
	global_load_lds_dwordx4 v[208:209], off
	s_waitcnt vmcnt(4)
	s_waitcnt lgkmcnt(0)
	s_barrier
	s_setprio 1
	s_waitcnt lgkmcnt(0)
	v_mfma_f32_16x16x32_bf16 v[60:63], v[140:143], v[176:179], v[60:63]
	v_mfma_f32_16x16x32_bf16 v[56:59], v[152:155], v[176:179], v[56:59]
	v_mfma_f32_16x16x32_bf16 v[52:55], v[140:143], v[184:187], v[52:55]
	v_mfma_f32_16x16x32_bf16 v[48:51], v[152:155], v[184:187], v[48:51]
	v_mfma_f32_16x16x32_bf16 v[44:47], v[140:143], v[192:195], v[44:47]
	v_mfma_f32_16x16x32_bf16 v[36:39], v[152:155], v[192:195], v[36:39]
	v_mfma_f32_16x16x32_bf16 v[28:31], v[140:143], v[200:203], v[28:31]
	v_mfma_f32_16x16x32_bf16 v[20:23], v[152:155], v[200:203], v[20:23]
	v_mfma_f32_16x16x32_bf16 v[60:63], v[148:151], v[180:183], v[60:63]
	v_mfma_f32_16x16x32_bf16 v[56:59], v[156:159], v[180:183], v[56:59]
	v_mfma_f32_16x16x32_bf16 v[52:55], v[148:151], v[188:191], v[52:55]
	v_mfma_f32_16x16x32_bf16 v[48:51], v[156:159], v[188:191], v[48:51]
	v_mfma_f32_16x16x32_bf16 v[44:47], v[148:151], v[196:199], v[44:47]
	v_mfma_f32_16x16x32_bf16 v[36:39], v[156:159], v[196:199], v[36:39]
	v_mfma_f32_16x16x32_bf16 v[28:31], v[148:151], v[204:207], v[28:31]
	v_mfma_f32_16x16x32_bf16 v[20:23], v[156:159], v[204:207], v[20:23]
	s_setprio 0
	s_setprio 1
	v_mfma_f32_16x16x32_bf16 v[40:43], v[160:163], v[176:179], v[40:43]
	v_mfma_f32_16x16x32_bf16 v[32:35], v[168:171], v[176:179], v[32:35]
	v_mfma_f32_16x16x32_bf16 v[24:27], v[160:163], v[184:187], v[24:27]
	v_mfma_f32_16x16x32_bf16 v[16:19], v[168:171], v[184:187], v[16:19]
	v_mfma_f32_16x16x32_bf16 v[12:15], v[160:163], v[192:195], v[12:15]
	v_mfma_f32_16x16x32_bf16 v[8:11], v[168:171], v[192:195], v[8:11]
	v_mfma_f32_16x16x32_bf16 v[4:7], v[160:163], v[200:203], v[4:7]
	v_mfma_f32_16x16x32_bf16 v[0:3], v[168:171], v[200:203], v[0:3]
	v_mfma_f32_16x16x32_bf16 v[40:43], v[164:167], v[180:183], v[40:43]
	v_mfma_f32_16x16x32_bf16 v[32:35], v[172:175], v[180:183], v[32:35]
	v_mfma_f32_16x16x32_bf16 v[24:27], v[164:167], v[188:191], v[24:27]
	v_mfma_f32_16x16x32_bf16 v[16:19], v[172:175], v[188:191], v[16:19]
	v_mfma_f32_16x16x32_bf16 v[12:15], v[164:167], v[196:199], v[12:15]
	v_mfma_f32_16x16x32_bf16 v[8:11], v[172:175], v[196:199], v[8:11]
	v_mfma_f32_16x16x32_bf16 v[4:7], v[164:167], v[204:207], v[4:7]
	v_mfma_f32_16x16x32_bf16 v[0:3], v[172:175], v[204:207], v[0:3]
	s_setprio 0
	s_barrier
	s_add_i32 s76, s76, 2
	s_add_u32 s52, s52, 0x100
	s_addc_u32 s53, s53, 0
	s_add_u32 s74, s74, 0x100
	s_addc_u32 s75, s75, 0
	s_cmp_gt_u32 s76, 13
	s_cbranch_scc0 .LBB0_1099
	s_and_b64 vcc, exec, s[12:13]
	s_cbranch_vccz .LBB0_1102
	s_barrier

; #define G_STAGE(bufoff, gbase, voff) do { _Pragma("unroll") for (int _i = 0; _i < 2; ++_i) \
;         __builtin_amdgcn_global_load_lds((const unsigned*)((const char*)(gbase) + voff[_i]), (LAS unsigned*)(lds + (bufoff) + ldsw + _i * 8192), 16, 0, 0); } while (0)
; #define G_LDA(dst, b, h) do { _Pragma("unroll") for (int m = 0; m < 4; ++m) _Pragma("unroll") for (int k = 0; k < 2; ++k) dst[m][k] = *(const LAS bf16x8*)(lds + G_SA(b, h) + aoff + m * 2048 + k * 1024); } while (0)
; #define G_LDB(dst, b, h) do { _Pragma("unroll") for (int n = 0; n < 2; ++n) _Pragma("unroll") for (int k = 0; k < 2; ++k) dst[n][k] = *(const LAS bf16x8*)(lds + G_SB(b, h) + boff + n * 2048 + k * 1024); } while (0)
; #define WAIT_V(n) asm volatile("s_waitcnt vmcnt(" #n ")" ::: "memory")
; #define WAIT_L(n) asm volatile("s_waitcnt lgkmcnt(" #n ")" ::: "memory")
; #define BAR __builtin_amdgcn_s_barrier()
; #define SCHED __builtin_amdgcn_sched_barrier(0)
; template <class Get, class Epi>
; DI void gemm_loop(int ntiles, int ld, char* shm, const Get& get, const Epi& epi) {
;     ...
;         for (int t = 0; t < nt; t += 2) {
;             const bool last = (t == nt - 2);
;             const char* a1 = cA + (size_t)(t + 1) * kstep;
;             const char* a2 = last ? nA : cA + (size_t)(t + 2) * kstep; const char* b2 = last ? nB : cB + (size_t)(t + 2) * kstep;
;             const char* a3 = a2 + kstep; const char* b3 = b2 + kstep;
;             G_LDB(B0, 0, 0); G_LDB(B1, 0, 1); SCHED; G_LDA(At, 0, 0); G_STAGE(G_SA(1, 1), a1 + hstep, voffA);
;             WAIT_V(8); WAIT_L(0); BAR; G_MMA(0, 0, At, B0); G_MMA(0, 1, At, B1); BAR; SCHED;
;             G_LDA(At, 0, 1); G_STAGE(G_SB(0, 0), b2, voffB); G_STAGE(G_SB(0, 1), b2 + hstep, voffB); G_STAGE(G_SA(0, 0), a2, voffA);
;             WAIT_V(8); WAIT_L(0); BAR; G_MMA(1, 0, At, B0); G_MMA(1, 1, At, B1); BAR; SCHED;
;             G_LDB(B0, 1, 0); G_LDB(B1, 1, 1); SCHED; G_LDA(At, 1, 0); G_STAGE(G_SA(0, 1), a2 + hstep, voffA);
;             WAIT_V(8); WAIT_L(0); BAR; G_MMA(0, 0, At, B0); G_MMA(0, 1, At, B1); BAR; SCHED;
;             G_LDA(At, 1, 1); G_STAGE(G_SB(1, 0), b3, voffB); G_STAGE(G_SB(1, 1), b3 + hstep, voffB); G_STAGE(G_SA(1, 0), a3, voffA);
;             WAIT_V(8); WAIT_L(0); BAR; G_MMA(1, 0, At, B0); G_MMA(1, 1, At, B1); BAR; SCHED;
.LBB0_1463:
	ds_read_b128 v[128:131], v169
	ds_read_b128 v[132:135], v169 offset:1024
	ds_read_b128 v[136:139], v169 offset:2048
	ds_read_b128 v[140:143], v169 offset:3072
	ds_read_b128 v[158:161], v170
	ds_read_b128 v[162:165], v170 offset:1024
	ds_read_b128 v[172:175], v170 offset:2048
	ds_read_b128 v[176:179], v170 offset:3072
	s_add_i32 s78, s14, 2
	s_add_u32 s15, s48, 0xfffc0080
	s_addc_u32 s46, s49, -1
	s_cmp_eq_u32 s75, s14
	s_cselect_b32 s14, s73, s76
	s_cselect_b32 s47, s3, s46
	s_cselect_b32 s46, s37, s15
	s_cselect_b32 s15, s39, s77
	v_lshl_add_u64 v[144:145], s[48:49], 0, v[154:155]
	s_add_i32 m0, s45, 0xc000
	ds_read_b128 v[180:183], v171
	ds_read_b128 v[184:187], v171 offset:1024
	ds_read_b128 v[188:191], v171 offset:2048
	ds_read_b128 v[192:195], v171 offset:3072
	ds_read_b128 v[196:199], v171 offset:4096
	ds_read_b128 v[200:203], v171 offset:5120
	ds_read_b128 v[204:207], v171 offset:6144
	ds_read_b128 v[208:211], v171 offset:7168
	global_load_lds_dwordx4 v[144:145], off
	v_lshl_add_u64 v[144:145], s[48:49], 0, v[156:157]
	s_add_i32 m0, s45, 0xe000
	s_nop 0
	global_load_lds_dwordx4 v[144:145], off
	s_mov_b32 s98, 0xfffc0000
	s_mov_b32 s99, -1
	v_lshl_add_u64 v[144:145], s[48:49], 0, v[154:155]
	v_lshl_add_u64 v[144:145], v[144:145], 0, s[98:99]
	s_add_i32 m0, s45, 0x8000
	s_nop 0
	global_load_lds_dwordx4 v[144:145], off
	v_lshl_add_u64 v[144:145], s[48:49], 0, v[156:157]
	v_lshl_add_u64 v[144:145], v[144:145], 0, s[98:99]
	s_add_i32 m0, s45, 0xa000
	s_nop 0
	global_load_lds_dwordx4 v[144:145], off
	s_waitcnt vmcnt(8)
	s_waitcnt lgkmcnt(0)
	s_barrier
	s_setprio 1
	s_waitcnt lgkmcnt(0)
	v_mfma_f32_16x16x32_bf16 v[124:127], v[128:131], v[180:183], v[124:127]
	v_mfma_f32_16x16x32_bf16 v[120:123], v[136:139], v[180:183], v[120:123]
	v_mfma_f32_16x16x32_bf16 v[116:119], v[128:131], v[188:191], v[116:119]
	v_mfma_f32_16x16x32_bf16 v[112:115], v[136:139], v[188:191], v[112:115]
	v_mfma_f32_16x16x32_bf16 v[108:111], v[128:131], v[196:199], v[108:111]
	v_mfma_f32_16x16x32_bf16 v[104:107], v[136:139], v[196:199], v[104:107]
	v_mfma_f32_16x16x32_bf16 v[100:103], v[128:131], v[204:207], v[100:103]
	v_mfma_f32_16x16x32_bf16 v[96:99], v[136:139], v[204:207], v[96:99]
	v_mfma_f32_16x16x32_bf16 v[124:127], v[132:135], v[184:187], v[124:127]
	v_mfma_f32_16x16x32_bf16 v[120:123], v[140:143], v[184:187], v[120:123]
	v_mfma_f32_16x16x32_bf16 v[116:119], v[132:135], v[192:195], v[116:119]
	v_mfma_f32_16x16x32_bf16 v[112:115], v[140:143], v[192:195], v[112:115]
	v_mfma_f32_16x16x32_bf16 v[108:111], v[132:135], v[200:203], v[108:111]
	v_mfma_f32_16x16x32_bf16 v[104:107], v[140:143], v[200:203], v[104:107]
	v_mfma_f32_16x16x32_bf16 v[100:103], v[132:135], v[208:211], v[100:103]
	v_mfma_f32_16x16x32_bf16 v[96:99], v[140:143], v[208:211], v[96:99]
	s_setprio 0
	s_setprio 1
	v_mfma_f32_16x16x32_bf16 v[60:63], v[158:161], v[180:183], v[60:63]
	v_mfma_f32_16x16x32_bf16 v[56:59], v[172:175], v[180:183], v[56:59]
	v_mfma_f32_16x16x32_bf16 v[52:55], v[158:161], v[188:191], v[52:55]
	v_mfma_f32_16x16x32_bf16 v[48:51], v[172:175], v[188:191], v[48:51]
	v_mfma_f32_16x16x32_bf16 v[44:47], v[158:161], v[196:199], v[44:47]
	v_mfma_f32_16x16x32_bf16 v[40:43], v[172:175], v[196:199], v[40:43]
	v_mfma_f32_16x16x32_bf16 v[36:39], v[158:161], v[204:207], v[36:39]
	v_mfma_f32_16x16x32_bf16 v[32:35], v[172:175], v[204:207], v[32:35]
	v_mfma_f32_16x16x32_bf16 v[60:63], v[162:165], v[184:187], v[60:63]
	v_mfma_f32_16x16x32_bf16 v[56:59], v[176:179], v[184:187], v[56:59]
	v_mfma_f32_16x16x32_bf16 v[52:55], v[162:165], v[192:195], v[52:55]
	v_mfma_f32_16x16x32_bf16 v[48:51], v[176:179], v[192:195], v[48:51]
	v_mfma_f32_16x16x32_bf16 v[44:47], v[162:165], v[200:203], v[44:47]
	v_mfma_f32_16x16x32_bf16 v[40:43], v[176:179], v[200:203], v[40:43]
	v_mfma_f32_16x16x32_bf16 v[36:39], v[162:165], v[208:211], v[36:39]
	v_mfma_f32_16x16x32_bf16 v[32:35], v[176:179], v[208:211], v[32:35]
	s_setprio 0
	s_barrier
	s_add_i32 s79, s57, s7
	v_lshl_add_u64 v[144:145], s[14:15], 0, v[148:149]
	s_mov_b32 m0, s79
	ds_read_b128 v[180:183], v171 offset:16384
	ds_read_b128 v[184:187], v171 offset:17408
	ds_read_b128 v[188:191], v171 offset:18432
	ds_read_b128 v[192:195], v171 offset:19456
	ds_read_b128 v[196:199], v171 offset:20480
	ds_read_b128 v[200:203], v171 offset:21504
	ds_read_b128 v[204:207], v171 offset:22528
	ds_read_b128 v[208:211], v171 offset:23552
	global_load_lds_dwordx4 v[144:145], off
	s_add_i32 m0, s79, 0x2000
	s_add_u32 s80, s14, 0x40000
	v_lshl_add_u64 v[166:167], s[14:15], 0, v[152:153]
	s_addc_u32 s81, s15, 0
	s_add_i32 s79, s58, s7
	global_load_lds_dwordx4 v[166:167], off
	v_lshl_add_u64 v[212:213], s[80:81], 0, v[148:149]
	s_mov_b32 m0, s79
	v_lshl_add_u64 v[214:215], s[46:47], 0, v[150:151]
	global_load_lds_dwordx4 v[212:213], off
	v_lshl_add_u64 v[212:213], s[80:81], 0, v[152:153]
	s_add_i32 m0, s79, 0x2000
	s_nop 0
	global_load_lds_dwordx4 v[212:213], off
	v_lshl_add_u64 v[212:213], s[46:47], 0, v[146:147]
	s_waitcnt vmcnt(4)
	s_waitcnt lgkmcnt(0)
	s_barrier
; #define G_STAGE(bufoff, gbase, voff) do { _Pragma("unroll") for (int _i = 0; _i < 2; ++_i) \
;         __builtin_amdgcn_global_load_lds((const unsigned*)((const char*)(gbase) + voff[_i]), (LAS unsigned*)(lds + (bufoff) + ldsw + _i * 8192), 16, 0, 0); } while (0)
; #define G_LDA(dst, b, h) do { _Pragma("unroll") for (int m = 0; m < 4; ++m) _Pragma("unroll") for (int k = 0; k < 2; ++k) dst[m][k] = *(const LAS bf16x8*)(lds + G_SA(b, h) + aoff + m * 2048 + k * 1024); } while (0)
; #define G_LDB(dst, b, h) do { _Pragma("unroll") for (int n = 0; n < 2; ++n) _Pragma("unroll") for (int k = 0; k < 2; ++k) dst[n][k] = *(const LAS bf16x8*)(lds + G_SB(b, h) + boff + n * 2048 + k * 1024); } while (0)
; #define G_MMA(ai, bj, At_, Bt_) do { __builtin_amdgcn_s_setprio(1); _Pragma("unroll") for (int m = 0; m < 4; ++m) _Pragma("unroll") for (int n = 0; n < 2; ++n) _Pragma("unroll") for (int k = 0; k < 2; ++k) \
;         acc[ai][bj][m][n] = __builtin_amdgcn_mfma_f32_16x16x32_bf16(Bt_[n][k], At_[m][k], acc[ai][bj][m][n], 0, 0, 0); __builtin_amdgcn_s_setprio(0); } while (0)
; #define WAIT_V(n) asm volatile("s_waitcnt vmcnt(" #n ")" ::: "memory")
; #define WAIT_L(n) asm volatile("s_waitcnt lgkmcnt(" #n ")" ::: "memory")
; #define BAR __builtin_amdgcn_s_barrier()
; #define SCHED __builtin_amdgcn_sched_barrier(0)
; template <class Get, class Epi>
; DI void gemm_loop(int ntiles, int ld, char* shm, const Get& get, const Epi& epi) {
;     ...
;             WAIT_V(8); WAIT_L(0); BAR; G_MMA(1, 0, At, B0); G_MMA(1, 1, At, B1); BAR; SCHED;
;             G_LDB(B0, 1, 0); G_LDB(B1, 1, 1); SCHED; G_LDA(At, 1, 0); G_STAGE(G_SA(0, 1), a2 + hstep, voffA);
;             WAIT_V(8); WAIT_L(0); BAR; G_MMA(0, 0, At, B0); G_MMA(0, 1, At, B1); BAR; SCHED;
;             G_LDA(At, 1, 1); G_STAGE(G_SB(1, 0), b3, voffB); G_STAGE(G_SB(1, 1), b3 + hstep, voffB); G_STAGE(G_SA(1, 0), a3, voffA);
	s_setprio 1
	s_waitcnt lgkmcnt(0)
	v_mfma_f32_16x16x32_bf16 v[92:95], v[128:131], v[180:183], v[92:95]
	v_mfma_f32_16x16x32_bf16 v[88:91], v[136:139], v[180:183], v[88:91]
	v_mfma_f32_16x16x32_bf16 v[84:87], v[128:131], v[188:191], v[84:87]
	v_mfma_f32_16x16x32_bf16 v[80:83], v[136:139], v[188:191], v[80:83]
	v_mfma_f32_16x16x32_bf16 v[76:79], v[128:131], v[196:199], v[76:79]
	v_mfma_f32_16x16x32_bf16 v[72:75], v[136:139], v[196:199], v[72:75]
	v_mfma_f32_16x16x32_bf16 v[68:71], v[128:131], v[204:207], v[68:71]
	v_mfma_f32_16x16x32_bf16 v[64:67], v[136:139], v[204:207], v[64:67]
	v_mfma_f32_16x16x32_bf16 v[92:95], v[132:135], v[184:187], v[92:95]
	v_mfma_f32_16x16x32_bf16 v[88:91], v[140:143], v[184:187], v[88:91]
	v_mfma_f32_16x16x32_bf16 v[84:87], v[132:135], v[192:195], v[84:87]
	v_mfma_f32_16x16x32_bf16 v[80:83], v[140:143], v[192:195], v[80:83]
	v_mfma_f32_16x16x32_bf16 v[76:79], v[132:135], v[200:203], v[76:79]
	v_mfma_f32_16x16x32_bf16 v[72:75], v[140:143], v[200:203], v[72:75]
	v_mfma_f32_16x16x32_bf16 v[68:71], v[132:135], v[208:211], v[68:71]
	v_mfma_f32_16x16x32_bf16 v[64:67], v[140:143], v[208:211], v[64:67]
	s_setprio 0
	s_setprio 1
	v_mfma_f32_16x16x32_bf16 v[28:31], v[158:161], v[180:183], v[28:31]
	v_mfma_f32_16x16x32_bf16 v[24:27], v[172:175], v[180:183], v[24:27]
	v_mfma_f32_16x16x32_bf16 v[20:23], v[158:161], v[188:191], v[20:23]
	v_mfma_f32_16x16x32_bf16 v[16:19], v[172:175], v[188:191], v[16:19]
	v_mfma_f32_16x16x32_bf16 v[12:15], v[158:161], v[196:199], v[12:15]
	v_mfma_f32_16x16x32_bf16 v[8:11], v[172:175], v[196:199], v[8:11]
	v_mfma_f32_16x16x32_bf16 v[4:7], v[158:161], v[204:207], v[4:7]
	v_mfma_f32_16x16x32_bf16 v[0:3], v[172:175], v[204:207], v[0:3]
	v_mfma_f32_16x16x32_bf16 v[28:31], v[162:165], v[184:187], v[28:31]
	v_mfma_f32_16x16x32_bf16 v[24:27], v[176:179], v[184:187], v[24:27]
	v_mfma_f32_16x16x32_bf16 v[20:23], v[162:165], v[192:195], v[20:23]
	v_mfma_f32_16x16x32_bf16 v[16:19], v[176:179], v[192:195], v[16:19]
	v_mfma_f32_16x16x32_bf16 v[12:15], v[162:165], v[200:203], v[12:15]
	v_mfma_f32_16x16x32_bf16 v[8:11], v[176:179], v[200:203], v[8:11]
	v_mfma_f32_16x16x32_bf16 v[4:7], v[162:165], v[208:211], v[4:7]
	v_mfma_f32_16x16x32_bf16 v[0:3], v[176:179], v[208:211], v[0:3]
	s_setprio 0
	s_barrier
	s_add_i32 s79, 0, 0x18000
	s_add_i32 s80, 0, 0x1c000
	v_add_u32_e32 v140, s79, v168
	v_add_u32_e32 v176, s80, v168
	ds_read_b128 v[128:131], v140
	ds_read_b128 v[132:135], v140 offset:1024
	ds_read_b128 v[136:139], v140 offset:2048
	ds_read_b128 v[140:143], v140 offset:3072
	ds_read_b128 v[158:161], v176
	ds_read_b128 v[162:165], v176 offset:1024
	ds_read_b128 v[172:175], v176 offset:2048
	ds_read_b128 v[176:179], v176 offset:3072
	s_add_u32 s46, s46, 0x40000
	s_addc_u32 s47, s47, 0
	s_mov_b32 m0, s51
	v_lshl_add_u64 v[216:217], s[46:47], 0, v[146:147]
	ds_read_b128 v[180:183], v171 offset:32768
	ds_read_b128 v[184:187], v171 offset:33792
	ds_read_b128 v[188:191], v171 offset:34816
	ds_read_b128 v[192:195], v171 offset:35840
	ds_read_b128 v[196:199], v171 offset:36864
	ds_read_b128 v[200:203], v171 offset:37888
	ds_read_b128 v[204:207], v171 offset:38912
	ds_read_b128 v[208:211], v171 offset:39936
	global_load_lds_dwordx4 v[216:217], off
	v_lshl_add_u64 v[216:217], s[46:47], 0, v[150:151]
	s_mov_b32 m0, s52
	s_nop 0
	global_load_lds_dwordx4 v[216:217], off
	s_mov_b32 m0, s45
	s_nop 0
	global_load_lds_dwordx4 v[212:213], off
	s_mov_b32 m0, s50
	s_nop 0
	global_load_lds_dwordx4 v[214:215], off
	s_waitcnt vmcnt(8)
	s_waitcnt lgkmcnt(0)
	s_barrier
; #define G_STAGE(bufoff, gbase, voff) do { _Pragma("unroll") for (int _i = 0; _i < 2; ++_i) \
;         __builtin_amdgcn_global_load_lds((const unsigned*)((const char*)(gbase) + voff[_i]), (LAS unsigned*)(lds + (bufoff) + ldsw + _i * 8192), 16, 0, 0); } while (0)
; #define G_LDA(dst, b, h) do { _Pragma("unroll") for (int m = 0; m < 4; ++m) _Pragma("unroll") for (int k = 0; k < 2; ++k) dst[m][k] = *(const LAS bf16x8*)(lds + G_SA(b, h) + aoff + m * 2048 + k * 1024); } while (0)
; #define G_MMA(ai, bj, At_, Bt_) do { __builtin_amdgcn_s_setprio(1); _Pragma("unroll") for (int m = 0; m < 4; ++m) _Pragma("unroll") for (int n = 0; n < 2; ++n) _Pragma("unroll") for (int k = 0; k < 2; ++k) \
;         acc[ai][bj][m][n] = __builtin_amdgcn_mfma_f32_16x16x32_bf16(Bt_[n][k], At_[m][k], acc[ai][bj][m][n], 0, 0, 0); __builtin_amdgcn_s_setprio(0); } while (0)
; #define WAIT_V(n) asm volatile("s_waitcnt vmcnt(" #n ")" ::: "memory")
; #define WAIT_L(n) asm volatile("s_waitcnt lgkmcnt(" #n ")" ::: "memory")
; #define BAR __builtin_amdgcn_s_barrier()
; #define SCHED __builtin_amdgcn_sched_barrier(0)
; template <class Get, class Epi>
; DI void gemm_loop(int ntiles, int ld, char* shm, const Get& get, const Epi& epi) {
;     ...
;             WAIT_V(8); WAIT_L(0); BAR; G_MMA(0, 0, At, B0); G_MMA(0, 1, At, B1); BAR; SCHED;
;             G_LDA(At, 1, 1); G_STAGE(G_SB(1, 0), b3, voffB); G_STAGE(G_SB(1, 1), b3 + hstep, voffB); G_STAGE(G_SA(1, 0), a3, voffA);
;             WAIT_V(8); WAIT_L(0); BAR; G_MMA(1, 0, At, B0); G_MMA(1, 1, At, B1); BAR; SCHED;
	s_setprio 1
	s_waitcnt lgkmcnt(0)
	v_mfma_f32_16x16x32_bf16 v[124:127], v[128:131], v[180:183], v[124:127]
	v_mfma_f32_16x16x32_bf16 v[120:123], v[136:139], v[180:183], v[120:123]
	v_mfma_f32_16x16x32_bf16 v[116:119], v[128:131], v[188:191], v[116:119]
	v_mfma_f32_16x16x32_bf16 v[112:115], v[136:139], v[188:191], v[112:115]
	v_mfma_f32_16x16x32_bf16 v[108:111], v[128:131], v[196:199], v[108:111]
	v_mfma_f32_16x16x32_bf16 v[104:107], v[136:139], v[196:199], v[104:107]
	v_mfma_f32_16x16x32_bf16 v[100:103], v[128:131], v[204:207], v[100:103]
	v_mfma_f32_16x16x32_bf16 v[96:99], v[136:139], v[204:207], v[96:99]
	v_mfma_f32_16x16x32_bf16 v[124:127], v[132:135], v[184:187], v[124:127]
	v_mfma_f32_16x16x32_bf16 v[120:123], v[140:143], v[184:187], v[120:123]
	v_mfma_f32_16x16x32_bf16 v[116:119], v[132:135], v[192:195], v[116:119]
	v_mfma_f32_16x16x32_bf16 v[112:115], v[140:143], v[192:195], v[112:115]
	v_mfma_f32_16x16x32_bf16 v[108:111], v[132:135], v[200:203], v[108:111]
	v_mfma_f32_16x16x32_bf16 v[104:107], v[140:143], v[200:203], v[104:107]
	v_mfma_f32_16x16x32_bf16 v[100:103], v[132:135], v[208:211], v[100:103]
	v_mfma_f32_16x16x32_bf16 v[96:99], v[140:143], v[208:211], v[96:99]
	s_setprio 0
	s_setprio 1
	v_mfma_f32_16x16x32_bf16 v[60:63], v[158:161], v[180:183], v[60:63]
	v_mfma_f32_16x16x32_bf16 v[56:59], v[172:175], v[180:183], v[56:59]
	v_mfma_f32_16x16x32_bf16 v[52:55], v[158:161], v[188:191], v[52:55]
	v_mfma_f32_16x16x32_bf16 v[48:51], v[172:175], v[188:191], v[48:51]
	v_mfma_f32_16x16x32_bf16 v[44:47], v[158:161], v[196:199], v[44:47]
	v_mfma_f32_16x16x32_bf16 v[40:43], v[172:175], v[196:199], v[40:43]
	v_mfma_f32_16x16x32_bf16 v[36:39], v[158:161], v[204:207], v[36:39]
	v_mfma_f32_16x16x32_bf16 v[32:35], v[172:175], v[204:207], v[32:35]
	v_mfma_f32_16x16x32_bf16 v[60:63], v[162:165], v[184:187], v[60:63]
	v_mfma_f32_16x16x32_bf16 v[56:59], v[176:179], v[184:187], v[56:59]
	v_mfma_f32_16x16x32_bf16 v[52:55], v[162:165], v[192:195], v[52:55]
	v_mfma_f32_16x16x32_bf16 v[48:51], v[176:179], v[192:195], v[48:51]
	v_mfma_f32_16x16x32_bf16 v[44:47], v[162:165], v[200:203], v[44:47]
	v_mfma_f32_16x16x32_bf16 v[40:43], v[176:179], v[200:203], v[40:43]
	v_mfma_f32_16x16x32_bf16 v[36:39], v[162:165], v[208:211], v[36:39]
	v_mfma_f32_16x16x32_bf16 v[32:35], v[176:179], v[208:211], v[32:35]
	s_setprio 0
	s_barrier
	s_add_i32 s46, s79, s7
	v_lshl_add_u64 v[144:145], v[144:145], 0, s[10:11]
	s_mov_b32 m0, s46
	ds_read_b128 v[180:183], v171 offset:49152
	ds_read_b128 v[184:187], v171 offset:50176
	ds_read_b128 v[188:191], v171 offset:51200
	ds_read_b128 v[192:195], v171 offset:52224
	ds_read_b128 v[196:199], v171 offset:53248
	ds_read_b128 v[200:203], v171 offset:54272
	ds_read_b128 v[204:207], v171 offset:55296
	ds_read_b128 v[208:211], v171 offset:56320
	global_load_lds_dwordx4 v[144:145], off
	s_add_i32 m0, s46, 0x2000
	s_add_u32 s14, s14, 0x40080
	v_lshl_add_u64 v[144:145], v[166:167], 0, s[10:11]
	s_addc_u32 s15, s15, 0
	s_add_i32 s46, s80, s7
	global_load_lds_dwordx4 v[144:145], off
	v_lshl_add_u64 v[144:145], s[14:15], 0, v[148:149]
	s_mov_b32 m0, s46
	s_nop 0
	global_load_lds_dwordx4 v[144:145], off
	v_lshl_add_u64 v[144:145], s[14:15], 0, v[152:153]
	s_add_i32 m0, s46, 0x2000
	s_nop 0
	global_load_lds_dwordx4 v[144:145], off
	s_waitcnt vmcnt(4)
	s_waitcnt lgkmcnt(0)
	s_barrier
	s_setprio 1
	s_waitcnt lgkmcnt(0)
	v_mfma_f32_16x16x32_bf16 v[92:95], v[128:131], v[180:183], v[92:95]
	v_mfma_f32_16x16x32_bf16 v[88:91], v[136:139], v[180:183], v[88:91]
	v_mfma_f32_16x16x32_bf16 v[84:87], v[128:131], v[188:191], v[84:87]
	v_mfma_f32_16x16x32_bf16 v[80:83], v[136:139], v[188:191], v[80:83]
	v_mfma_f32_16x16x32_bf16 v[76:79], v[128:131], v[196:199], v[76:79]
	v_mfma_f32_16x16x32_bf16 v[72:75], v[136:139], v[196:199], v[72:75]
	v_mfma_f32_16x16x32_bf16 v[68:71], v[128:131], v[204:207], v[68:71]
	v_mfma_f32_16x16x32_bf16 v[64:67], v[136:139], v[204:207], v[64:67]
	v_mfma_f32_16x16x32_bf16 v[92:95], v[132:135], v[184:187], v[92:95]
	v_mfma_f32_16x16x32_bf16 v[88:91], v[140:143], v[184:187], v[88:91]
	v_mfma_f32_16x16x32_bf16 v[84:87], v[132:135], v[192:195], v[84:87]
	v_mfma_f32_16x16x32_bf16 v[80:83], v[140:143], v[192:195], v[80:83]
	v_mfma_f32_16x16x32_bf16 v[76:79], v[132:135], v[200:203], v[76:79]
	v_mfma_f32_16x16x32_bf16 v[72:75], v[140:143], v[200:203], v[72:75]
	v_mfma_f32_16x16x32_bf16 v[68:71], v[132:135], v[208:211], v[68:71]
	v_mfma_f32_16x16x32_bf16 v[64:67], v[140:143], v[208:211], v[64:67]
	s_setprio 0
	s_setprio 1
	v_mfma_f32_16x16x32_bf16 v[28:31], v[158:161], v[180:183], v[28:31]
	v_mfma_f32_16x16x32_bf16 v[24:27], v[172:175], v[180:183], v[24:27]
	v_mfma_f32_16x16x32_bf16 v[20:23], v[158:161], v[188:191], v[20:23]
	v_mfma_f32_16x16x32_bf16 v[16:19], v[172:175], v[188:191], v[16:19]
	v_mfma_f32_16x16x32_bf16 v[12:15], v[158:161], v[196:199], v[12:15]
	v_mfma_f32_16x16x32_bf16 v[8:11], v[172:175], v[196:199], v[8:11]
	v_mfma_f32_16x16x32_bf16 v[4:7], v[158:161], v[204:207], v[4:7]
	v_mfma_f32_16x16x32_bf16 v[0:3], v[172:175], v[204:207], v[0:3]
	v_mfma_f32_16x16x32_bf16 v[28:31], v[162:165], v[184:187], v[28:31]
	v_mfma_f32_16x16x32_bf16 v[24:27], v[176:179], v[184:187], v[24:27]
	v_mfma_f32_16x16x32_bf16 v[20:23], v[162:165], v[192:195], v[20:23]
	v_mfma_f32_16x16x32_bf16 v[16:19], v[176:179], v[192:195], v[16:19]
	v_mfma_f32_16x16x32_bf16 v[12:15], v[162:165], v[200:203], v[12:15]
	v_mfma_f32_16x16x32_bf16 v[8:11], v[176:179], v[200:203], v[8:11]
	v_mfma_f32_16x16x32_bf16 v[4:7], v[162:165], v[208:211], v[4:7]
	v_mfma_f32_16x16x32_bf16 v[0:3], v[176:179], v[208:211], v[0:3]
	s_setprio 0
	s_barrier
	s_add_u32 s48, s48, 0x100
	s_addc_u32 s49, s49, 0
	s_add_u32 s76, s76, 0x100
	s_addc_u32 s77, s77, 0
	s_cmp_ge_u32 s78, s74
	s_mov_b32 s14, s78
	s_cbranch_scc0 .LBB0_1463
	s_and_b64 vcc, exec, s[12:13]
	s_cbranch_vccz .LBB0_1466
	s_barrier

; #define G_STAGE(bufoff, gbase, voff) do { _Pragma("unroll") for (int _i = 0; _i < 2; ++_i) \
;         __builtin_amdgcn_global_load_lds((const unsigned*)((const char*)(gbase) + voff[_i]), (LAS unsigned*)(lds + (bufoff) + ldsw + _i * 8192), 16, 0, 0); } while (0)
; #define G_LDA(dst, b, h) do { _Pragma("unroll") for (int m = 0; m < 4; ++m) _Pragma("unroll") for (int k = 0; k < 2; ++k) dst[m][k] = *(const LAS bf16x8*)(lds + G_SA(b, h) + aoff + m * 2048 + k * 1024); } while (0)
; #define G_LDB(dst, b, h) do { _Pragma("unroll") for (int n = 0; n < 2; ++n) _Pragma("unroll") for (int k = 0; k < 2; ++k) dst[n][k] = *(const LAS bf16x8*)(lds + G_SB(b, h) + boff + n * 2048 + k * 1024); } while (0)
; #define G_MMA(ai, bj, At_, Bt_) do { __builtin_amdgcn_s_setprio(1); _Pragma("unroll") for (int m = 0; m < 4; ++m) _Pragma("unroll") for (int n = 0; n < 2; ++n) _Pragma("unroll") for (int k = 0; k < 2; ++k) \
;         acc[ai][bj][m][n] = __builtin_amdgcn_mfma_f32_16x16x32_bf16(Bt_[n][k], At_[m][k], acc[ai][bj][m][n], 0, 0, 0); __builtin_amdgcn_s_setprio(0); } while (0)
; #define WAIT_V(n) asm volatile("s_waitcnt vmcnt(" #n ")" ::: "memory")
; #define WAIT_L(n) asm volatile("s_waitcnt lgkmcnt(" #n ")" ::: "memory")
; #define BAR __builtin_amdgcn_s_barrier()
; #define SCHED __builtin_amdgcn_sched_barrier(0)
; template <class Get, class Epi>
; DI void gemm_loop(int ntiles, int ld, char* shm, const Get& get, const Epi& epi) {
;     ...
;         for (int t = 0; t < nt; t += 2) {
;             const bool last = (t == nt - 2);
;             const char* a1 = cA + (size_t)(t + 1) * kstep;
;             const char* a2 = last ? nA : cA + (size_t)(t + 2) * kstep; const char* b2 = last ? nB : cB + (size_t)(t + 2) * kstep;
;             const char* a3 = a2 + kstep; const char* b3 = b2 + kstep;
;             G_LDB(B0, 0, 0); G_LDB(B1, 0, 1); SCHED; G_LDA(At, 0, 0); G_STAGE(G_SA(1, 1), a1 + hstep, voffA);
;             WAIT_V(8); WAIT_L(0); BAR; G_MMA(0, 0, At, B0); G_MMA(0, 1, At, B1); BAR; SCHED;
;             G_LDA(At, 0, 1); G_STAGE(G_SB(0, 0), b2, voffB); G_STAGE(G_SB(0, 1), b2 + hstep, voffB); G_STAGE(G_SA(0, 0), a2, voffA);
;             WAIT_V(8); WAIT_L(0); BAR; G_MMA(1, 0, At, B0); G_MMA(1, 1, At, B1); BAR; SCHED;
.LBB0_1694:
	ds_read_b128 v[144:147], v141
	ds_read_b128 v[148:151], v141 offset:1024
	ds_read_b128 v[152:155], v141 offset:2048
	ds_read_b128 v[156:159], v141 offset:3072
	ds_read_b128 v[160:163], v142
	ds_read_b128 v[164:167], v142 offset:1024
	ds_read_b128 v[168:171], v142 offset:2048
	ds_read_b128 v[172:175], v142 offset:3072
	s_add_u32 s14, s38, 0xfffc0080
	s_addc_u32 s15, s39, -1
	s_cmp_eq_u32 s57, 12
	s_cselect_b32 s41, s9, s15
	s_cselect_b32 s40, s53, s14
	s_cselect_b32 s15, s11, s56
	s_cselect_b32 s14, s54, s55
	v_lshl_add_u64 v[208:209], s[38:39], 0, v[136:137]
	s_add_i32 m0, s35, 0xc000
	ds_read_b128 v[176:179], v143
	ds_read_b128 v[180:183], v143 offset:1024
	ds_read_b128 v[184:187], v143 offset:2048
	ds_read_b128 v[188:191], v143 offset:3072
	ds_read_b128 v[192:195], v143 offset:4096
	ds_read_b128 v[196:199], v143 offset:5120
	ds_read_b128 v[200:203], v143 offset:6144
	ds_read_b128 v[204:207], v143 offset:7168
	global_load_lds_dwordx4 v[208:209], off
	v_lshl_add_u64 v[208:209], s[38:39], 0, v[138:139]
	s_add_i32 m0, s35, 0xe000
	s_nop 0
	global_load_lds_dwordx4 v[208:209], off
	s_mov_b32 s98, 0xfffc0000
	s_mov_b32 s99, -1
	v_lshl_add_u64 v[208:209], s[38:39], 0, v[136:137]
	v_lshl_add_u64 v[208:209], v[208:209], 0, s[98:99]
	s_add_i32 m0, s35, 0x8000
	s_nop 0
	global_load_lds_dwordx4 v[208:209], off
	v_lshl_add_u64 v[208:209], s[38:39], 0, v[138:139]
	v_lshl_add_u64 v[208:209], v[208:209], 0, s[98:99]
	s_add_i32 m0, s35, 0xa000
	s_nop 0
	global_load_lds_dwordx4 v[208:209], off
	s_waitcnt vmcnt(8)
	s_waitcnt lgkmcnt(0)
	s_barrier
	s_setprio 1
	s_waitcnt lgkmcnt(0)
	v_mfma_f32_16x16x32_bf16 v[124:127], v[144:147], v[176:179], v[124:127]
	v_mfma_f32_16x16x32_bf16 v[120:123], v[152:155], v[176:179], v[120:123]
	v_mfma_f32_16x16x32_bf16 v[108:111], v[144:147], v[184:187], v[108:111]
	v_mfma_f32_16x16x32_bf16 v[104:107], v[152:155], v[184:187], v[104:107]
	v_mfma_f32_16x16x32_bf16 v[92:95], v[144:147], v[192:195], v[92:95]
	v_mfma_f32_16x16x32_bf16 v[88:91], v[152:155], v[192:195], v[88:91]
	v_mfma_f32_16x16x32_bf16 v[76:79], v[144:147], v[200:203], v[76:79]
	v_mfma_f32_16x16x32_bf16 v[72:75], v[152:155], v[200:203], v[72:75]
	v_mfma_f32_16x16x32_bf16 v[124:127], v[148:151], v[180:183], v[124:127]
	v_mfma_f32_16x16x32_bf16 v[120:123], v[156:159], v[180:183], v[120:123]
	v_mfma_f32_16x16x32_bf16 v[108:111], v[148:151], v[188:191], v[108:111]
	v_mfma_f32_16x16x32_bf16 v[104:107], v[156:159], v[188:191], v[104:107]
	v_mfma_f32_16x16x32_bf16 v[92:95], v[148:151], v[196:199], v[92:95]
	v_mfma_f32_16x16x32_bf16 v[88:91], v[156:159], v[196:199], v[88:91]
	v_mfma_f32_16x16x32_bf16 v[76:79], v[148:151], v[204:207], v[76:79]
	v_mfma_f32_16x16x32_bf16 v[72:75], v[156:159], v[204:207], v[72:75]
	s_setprio 0
	s_setprio 1
	v_mfma_f32_16x16x32_bf16 v[116:119], v[160:163], v[176:179], v[116:119]
	v_mfma_f32_16x16x32_bf16 v[112:115], v[168:171], v[176:179], v[112:115]
	v_mfma_f32_16x16x32_bf16 v[100:103], v[160:163], v[184:187], v[100:103]
	v_mfma_f32_16x16x32_bf16 v[96:99], v[168:171], v[184:187], v[96:99]
	v_mfma_f32_16x16x32_bf16 v[84:87], v[160:163], v[192:195], v[84:87]
	v_mfma_f32_16x16x32_bf16 v[80:83], v[168:171], v[192:195], v[80:83]
	v_mfma_f32_16x16x32_bf16 v[68:71], v[160:163], v[200:203], v[68:71]
	v_mfma_f32_16x16x32_bf16 v[64:67], v[168:171], v[200:203], v[64:67]
	v_mfma_f32_16x16x32_bf16 v[116:119], v[164:167], v[180:183], v[116:119]
	v_mfma_f32_16x16x32_bf16 v[112:115], v[172:175], v[180:183], v[112:115]
	v_mfma_f32_16x16x32_bf16 v[100:103], v[164:167], v[188:191], v[100:103]
	v_mfma_f32_16x16x32_bf16 v[96:99], v[172:175], v[188:191], v[96:99]
	v_mfma_f32_16x16x32_bf16 v[84:87], v[164:167], v[196:199], v[84:87]
	v_mfma_f32_16x16x32_bf16 v[80:83], v[172:175], v[196:199], v[80:83]
	v_mfma_f32_16x16x32_bf16 v[68:71], v[164:167], v[204:207], v[68:71]
	v_mfma_f32_16x16x32_bf16 v[64:67], v[172:175], v[204:207], v[64:67]
	s_setprio 0
	s_barrier
	s_add_i32 s58, s48, s42
	v_lshl_add_u64 v[208:209], s[14:15], 0, v[132:133]
	s_mov_b32 m0, s58
	ds_read_b128 v[176:179], v143 offset:16384
	ds_read_b128 v[180:183], v143 offset:17408
	ds_read_b128 v[184:187], v143 offset:18432
	ds_read_b128 v[188:191], v143 offset:19456
	ds_read_b128 v[192:195], v143 offset:20480
	ds_read_b128 v[196:199], v143 offset:21504
	ds_read_b128 v[200:203], v143 offset:22528
	ds_read_b128 v[204:207], v143 offset:23552
	global_load_lds_dwordx4 v[208:209], off
	s_add_i32 m0, s58, 0x2000
	s_add_u32 s58, s14, 0x40000
	v_lshl_add_u64 v[210:211], s[14:15], 0, v[128:129]
	s_addc_u32 s59, s15, 0
	s_add_i32 s71, s49, s42
	global_load_lds_dwordx4 v[210:211], off
	v_lshl_add_u64 v[212:213], s[58:59], 0, v[132:133]
	s_mov_b32 m0, s71
	v_lshl_add_u64 v[214:215], s[40:41], 0, v[130:131]
	global_load_lds_dwordx4 v[212:213], off
	v_lshl_add_u64 v[212:213], s[58:59], 0, v[128:129]
	s_add_i32 m0, s71, 0x2000
	s_nop 0
	global_load_lds_dwordx4 v[212:213], off
	v_lshl_add_u64 v[212:213], s[40:41], 0, v[134:135]
	s_waitcnt vmcnt(4)
	s_waitcnt lgkmcnt(0)
	s_barrier
; #define G_STAGE(bufoff, gbase, voff) do { _Pragma("unroll") for (int _i = 0; _i < 2; ++_i) \
;         __builtin_amdgcn_global_load_lds((const unsigned*)((const char*)(gbase) + voff[_i]), (LAS unsigned*)(lds + (bufoff) + ldsw + _i * 8192), 16, 0, 0); } while (0)
; #define G_LDA(dst, b, h) do { _Pragma("unroll") for (int m = 0; m < 4; ++m) _Pragma("unroll") for (int k = 0; k < 2; ++k) dst[m][k] = *(const LAS bf16x8*)(lds + G_SA(b, h) + aoff + m * 2048 + k * 1024); } while (0)
; #define G_LDB(dst, b, h) do { _Pragma("unroll") for (int n = 0; n < 2; ++n) _Pragma("unroll") for (int k = 0; k < 2; ++k) dst[n][k] = *(const LAS bf16x8*)(lds + G_SB(b, h) + boff + n * 2048 + k * 1024); } while (0)
; #define G_MMA(ai, bj, At_, Bt_) do { __builtin_amdgcn_s_setprio(1); _Pragma("unroll") for (int m = 0; m < 4; ++m) _Pragma("unroll") for (int n = 0; n < 2; ++n) _Pragma("unroll") for (int k = 0; k < 2; ++k) \
;         acc[ai][bj][m][n] = __builtin_amdgcn_mfma_f32_16x16x32_bf16(Bt_[n][k], At_[m][k], acc[ai][bj][m][n], 0, 0, 0); __builtin_amdgcn_s_setprio(0); } while (0)
; #define WAIT_V(n) asm volatile("s_waitcnt vmcnt(" #n ")" ::: "memory")
; #define WAIT_L(n) asm volatile("s_waitcnt lgkmcnt(" #n ")" ::: "memory")
; #define BAR __builtin_amdgcn_s_barrier()
; #define SCHED __builtin_amdgcn_sched_barrier(0)
; template <class Get, class Epi>
; DI void gemm_loop(int ntiles, int ld, char* shm, const Get& get, const Epi& epi) {
;     ...
;             WAIT_V(8); WAIT_L(0); BAR; G_MMA(1, 0, At, B0); G_MMA(1, 1, At, B1); BAR; SCHED;
;             G_LDB(B0, 1, 0); G_LDB(B1, 1, 1); SCHED; G_LDA(At, 1, 0); G_STAGE(G_SA(0, 1), a2 + hstep, voffA);
;             WAIT_V(8); WAIT_L(0); BAR; G_MMA(0, 0, At, B0); G_MMA(0, 1, At, B1); BAR; SCHED;
	s_setprio 1
	s_waitcnt lgkmcnt(0)
	v_mfma_f32_16x16x32_bf16 v[60:63], v[144:147], v[176:179], v[60:63]
	v_mfma_f32_16x16x32_bf16 v[56:59], v[152:155], v[176:179], v[56:59]
	v_mfma_f32_16x16x32_bf16 v[44:47], v[144:147], v[184:187], v[44:47]
	v_mfma_f32_16x16x32_bf16 v[40:43], v[152:155], v[184:187], v[40:43]
	v_mfma_f32_16x16x32_bf16 v[28:31], v[144:147], v[192:195], v[28:31]
	v_mfma_f32_16x16x32_bf16 v[24:27], v[152:155], v[192:195], v[24:27]
	v_mfma_f32_16x16x32_bf16 v[12:15], v[144:147], v[200:203], v[12:15]
	v_mfma_f32_16x16x32_bf16 v[8:11], v[152:155], v[200:203], v[8:11]
	v_mfma_f32_16x16x32_bf16 v[60:63], v[148:151], v[180:183], v[60:63]
	v_mfma_f32_16x16x32_bf16 v[56:59], v[156:159], v[180:183], v[56:59]
	v_mfma_f32_16x16x32_bf16 v[44:47], v[148:151], v[188:191], v[44:47]
	v_mfma_f32_16x16x32_bf16 v[40:43], v[156:159], v[188:191], v[40:43]
	v_mfma_f32_16x16x32_bf16 v[28:31], v[148:151], v[196:199], v[28:31]
	v_mfma_f32_16x16x32_bf16 v[24:27], v[156:159], v[196:199], v[24:27]
	v_mfma_f32_16x16x32_bf16 v[12:15], v[148:151], v[204:207], v[12:15]
	v_mfma_f32_16x16x32_bf16 v[8:11], v[156:159], v[204:207], v[8:11]
	s_setprio 0
	s_setprio 1
	v_mfma_f32_16x16x32_bf16 v[52:55], v[160:163], v[176:179], v[52:55]
	v_mfma_f32_16x16x32_bf16 v[48:51], v[168:171], v[176:179], v[48:51]
	v_mfma_f32_16x16x32_bf16 v[36:39], v[160:163], v[184:187], v[36:39]
	v_mfma_f32_16x16x32_bf16 v[32:35], v[168:171], v[184:187], v[32:35]
	v_mfma_f32_16x16x32_bf16 v[20:23], v[160:163], v[192:195], v[20:23]
	v_mfma_f32_16x16x32_bf16 v[16:19], v[168:171], v[192:195], v[16:19]
	v_mfma_f32_16x16x32_bf16 v[4:7], v[160:163], v[200:203], v[4:7]
	v_mfma_f32_16x16x32_bf16 v[0:3], v[168:171], v[200:203], v[0:3]
	v_mfma_f32_16x16x32_bf16 v[52:55], v[164:167], v[180:183], v[52:55]
	v_mfma_f32_16x16x32_bf16 v[48:51], v[172:175], v[180:183], v[48:51]
	v_mfma_f32_16x16x32_bf16 v[36:39], v[164:167], v[188:191], v[36:39]
	v_mfma_f32_16x16x32_bf16 v[32:35], v[172:175], v[188:191], v[32:35]
	v_mfma_f32_16x16x32_bf16 v[20:23], v[164:167], v[196:199], v[20:23]
	v_mfma_f32_16x16x32_bf16 v[16:19], v[172:175], v[196:199], v[16:19]
	v_mfma_f32_16x16x32_bf16 v[4:7], v[164:167], v[204:207], v[4:7]
	v_mfma_f32_16x16x32_bf16 v[0:3], v[172:175], v[204:207], v[0:3]
	s_setprio 0
	s_barrier
	s_add_i32 s58, 0, 0x18000
	s_add_i32 s59, 0, 0x1c000
	v_add_u32_e32 v156, s58, v140
	v_add_u32_e32 v172, s59, v140
	ds_read_b128 v[144:147], v156
	ds_read_b128 v[148:151], v156 offset:1024
	ds_read_b128 v[152:155], v156 offset:2048
	ds_read_b128 v[156:159], v156 offset:3072
	ds_read_b128 v[160:163], v172
	ds_read_b128 v[164:167], v172 offset:1024
	ds_read_b128 v[168:171], v172 offset:2048
	ds_read_b128 v[172:175], v172 offset:3072
	s_add_u32 s40, s40, 0x40000
	s_addc_u32 s41, s41, 0
	s_mov_b32 m0, s44
	v_lshl_add_u64 v[216:217], s[40:41], 0, v[134:135]
	ds_read_b128 v[176:179], v143 offset:32768
	ds_read_b128 v[180:183], v143 offset:33792
	ds_read_b128 v[184:187], v143 offset:34816
	ds_read_b128 v[188:191], v143 offset:35840
	ds_read_b128 v[192:195], v143 offset:36864
	ds_read_b128 v[196:199], v143 offset:37888
	ds_read_b128 v[200:203], v143 offset:38912
	ds_read_b128 v[204:207], v143 offset:39936
	global_load_lds_dwordx4 v[216:217], off
	v_lshl_add_u64 v[216:217], s[40:41], 0, v[130:131]
	s_mov_b32 m0, s45
	s_nop 0
	global_load_lds_dwordx4 v[216:217], off
	s_mov_b32 m0, s35
	s_nop 0
	global_load_lds_dwordx4 v[212:213], off
	s_mov_b32 m0, s37
	s_nop 0
	global_load_lds_dwordx4 v[214:215], off
	s_waitcnt vmcnt(8)
	s_waitcnt lgkmcnt(0)
	s_barrier
; #define G_STAGE(bufoff, gbase, voff) do { _Pragma("unroll") for (int _i = 0; _i < 2; ++_i) \
;         __builtin_amdgcn_global_load_lds((const unsigned*)((const char*)(gbase) + voff[_i]), (LAS unsigned*)(lds + (bufoff) + ldsw + _i * 8192), 16, 0, 0); } while (0)
; #define G_LDA(dst, b, h) do { _Pragma("unroll") for (int m = 0; m < 4; ++m) _Pragma("unroll") for (int k = 0; k < 2; ++k) dst[m][k] = *(const LAS bf16x8*)(lds + G_SA(b, h) + aoff + m * 2048 + k * 1024); } while (0)
; #define G_MMA(ai, bj, At_, Bt_) do { __builtin_amdgcn_s_setprio(1); _Pragma("unroll") for (int m = 0; m < 4; ++m) _Pragma("unroll") for (int n = 0; n < 2; ++n) _Pragma("unroll") for (int k = 0; k < 2; ++k) \
;         acc[ai][bj][m][n] = __builtin_amdgcn_mfma_f32_16x16x32_bf16(Bt_[n][k], At_[m][k], acc[ai][bj][m][n], 0, 0, 0); __builtin_amdgcn_s_setprio(0); } while (0)
; #define WAIT_V(n) asm volatile("s_waitcnt vmcnt(" #n ")" ::: "memory")
; #define WAIT_L(n) asm volatile("s_waitcnt lgkmcnt(" #n ")" ::: "memory")
; #define BAR __builtin_amdgcn_s_barrier()
; #define SCHED __builtin_amdgcn_sched_barrier(0)
; template <class Get, class Epi>
; DI void gemm_loop(int ntiles, int ld, char* shm, const Get& get, const Epi& epi) {
;     ...
;             WAIT_V(8); WAIT_L(0); BAR; G_MMA(0, 0, At, B0); G_MMA(0, 1, At, B1); BAR; SCHED;
;             G_LDA(At, 1, 1); G_STAGE(G_SB(1, 0), b3, voffB); G_STAGE(G_SB(1, 1), b3 + hstep, voffB); G_STAGE(G_SA(1, 0), a3, voffA);
;             WAIT_V(8); WAIT_L(0); BAR; G_MMA(1, 0, At, B0); G_MMA(1, 1, At, B1); BAR; SCHED;
;         }
	s_setprio 1
	s_waitcnt lgkmcnt(0)
	v_mfma_f32_16x16x32_bf16 v[124:127], v[144:147], v[176:179], v[124:127]
	v_mfma_f32_16x16x32_bf16 v[120:123], v[152:155], v[176:179], v[120:123]
	v_mfma_f32_16x16x32_bf16 v[108:111], v[144:147], v[184:187], v[108:111]
	v_mfma_f32_16x16x32_bf16 v[104:107], v[152:155], v[184:187], v[104:107]
	v_mfma_f32_16x16x32_bf16 v[92:95], v[144:147], v[192:195], v[92:95]
	v_mfma_f32_16x16x32_bf16 v[88:91], v[152:155], v[192:195], v[88:91]
	v_mfma_f32_16x16x32_bf16 v[76:79], v[144:147], v[200:203], v[76:79]
	v_mfma_f32_16x16x32_bf16 v[72:75], v[152:155], v[200:203], v[72:75]
	v_mfma_f32_16x16x32_bf16 v[124:127], v[148:151], v[180:183], v[124:127]
	v_mfma_f32_16x16x32_bf16 v[120:123], v[156:159], v[180:183], v[120:123]
	v_mfma_f32_16x16x32_bf16 v[108:111], v[148:151], v[188:191], v[108:111]
	v_mfma_f32_16x16x32_bf16 v[104:107], v[156:159], v[188:191], v[104:107]
	v_mfma_f32_16x16x32_bf16 v[92:95], v[148:151], v[196:199], v[92:95]
	v_mfma_f32_16x16x32_bf16 v[88:91], v[156:159], v[196:199], v[88:91]
	v_mfma_f32_16x16x32_bf16 v[76:79], v[148:151], v[204:207], v[76:79]
	v_mfma_f32_16x16x32_bf16 v[72:75], v[156:159], v[204:207], v[72:75]
	s_setprio 0
	s_setprio 1
	v_mfma_f32_16x16x32_bf16 v[116:119], v[160:163], v[176:179], v[116:119]
	v_mfma_f32_16x16x32_bf16 v[112:115], v[168:171], v[176:179], v[112:115]
	v_mfma_f32_16x16x32_bf16 v[100:103], v[160:163], v[184:187], v[100:103]
	v_mfma_f32_16x16x32_bf16 v[96:99], v[168:171], v[184:187], v[96:99]
	v_mfma_f32_16x16x32_bf16 v[84:87], v[160:163], v[192:195], v[84:87]
	v_mfma_f32_16x16x32_bf16 v[80:83], v[168:171], v[192:195], v[80:83]
	v_mfma_f32_16x16x32_bf16 v[68:71], v[160:163], v[200:203], v[68:71]
	v_mfma_f32_16x16x32_bf16 v[64:67], v[168:171], v[200:203], v[64:67]
	v_mfma_f32_16x16x32_bf16 v[116:119], v[164:167], v[180:183], v[116:119]
	v_mfma_f32_16x16x32_bf16 v[112:115], v[172:175], v[180:183], v[112:115]
	v_mfma_f32_16x16x32_bf16 v[100:103], v[164:167], v[188:191], v[100:103]
	v_mfma_f32_16x16x32_bf16 v[96:99], v[172:175], v[188:191], v[96:99]
	v_mfma_f32_16x16x32_bf16 v[84:87], v[164:167], v[196:199], v[84:87]
	v_mfma_f32_16x16x32_bf16 v[80:83], v[172:175], v[196:199], v[80:83]
	v_mfma_f32_16x16x32_bf16 v[68:71], v[164:167], v[204:207], v[68:71]
	v_mfma_f32_16x16x32_bf16 v[64:67], v[172:175], v[204:207], v[64:67]
	s_setprio 0
	s_barrier
	s_add_i32 s40, s58, s42
	v_lshl_add_u64 v[208:209], v[208:209], 0, s[2:3]
	s_mov_b32 m0, s40
	ds_read_b128 v[176:179], v143 offset:49152
	ds_read_b128 v[180:183], v143 offset:50176
	ds_read_b128 v[184:187], v143 offset:51200
	ds_read_b128 v[188:191], v143 offset:52224
	ds_read_b128 v[192:195], v143 offset:53248
	ds_read_b128 v[196:199], v143 offset:54272
	ds_read_b128 v[200:203], v143 offset:55296
	ds_read_b128 v[204:207], v143 offset:56320
	global_load_lds_dwordx4 v[208:209], off
	s_add_i32 m0, s40, 0x2000
	s_add_u32 s14, s14, 0x40080
	v_lshl_add_u64 v[208:209], v[210:211], 0, s[2:3]
	s_addc_u32 s15, s15, 0
	s_add_i32 s40, s59, s42
	global_load_lds_dwordx4 v[208:209], off
	v_lshl_add_u64 v[208:209], s[14:15], 0, v[132:133]
	s_mov_b32 m0, s40
	s_nop 0
	global_load_lds_dwordx4 v[208:209], off
	v_lshl_add_u64 v[208:209], s[14:15], 0, v[128:129]
	s_add_i32 m0, s40, 0x2000
	s_nop 0
	global_load_lds_dwordx4 v[208:209], off
	s_waitcnt vmcnt(4)
	s_waitcnt lgkmcnt(0)
	s_barrier
	s_setprio 1
	s_waitcnt lgkmcnt(0)
	v_mfma_f32_16x16x32_bf16 v[60:63], v[144:147], v[176:179], v[60:63]
	v_mfma_f32_16x16x32_bf16 v[56:59], v[152:155], v[176:179], v[56:59]
	v_mfma_f32_16x16x32_bf16 v[44:47], v[144:147], v[184:187], v[44:47]
	v_mfma_f32_16x16x32_bf16 v[40:43], v[152:155], v[184:187], v[40:43]
	v_mfma_f32_16x16x32_bf16 v[28:31], v[144:147], v[192:195], v[28:31]
	v_mfma_f32_16x16x32_bf16 v[24:27], v[152:155], v[192:195], v[24:27]
	v_mfma_f32_16x16x32_bf16 v[12:15], v[144:147], v[200:203], v[12:15]
	v_mfma_f32_16x16x32_bf16 v[8:11], v[152:155], v[200:203], v[8:11]
	v_mfma_f32_16x16x32_bf16 v[60:63], v[148:151], v[180:183], v[60:63]
	v_mfma_f32_16x16x32_bf16 v[56:59], v[156:159], v[180:183], v[56:59]
	v_mfma_f32_16x16x32_bf16 v[44:47], v[148:151], v[188:191], v[44:47]
	v_mfma_f32_16x16x32_bf16 v[40:43], v[156:159], v[188:191], v[40:43]
	v_mfma_f32_16x16x32_bf16 v[28:31], v[148:151], v[196:199], v[28:31]
	v_mfma_f32_16x16x32_bf16 v[24:27], v[156:159], v[196:199], v[24:27]
	v_mfma_f32_16x16x32_bf16 v[12:15], v[148:151], v[204:207], v[12:15]
	v_mfma_f32_16x16x32_bf16 v[8:11], v[156:159], v[204:207], v[8:11]
	s_setprio 0
	s_setprio 1
	v_mfma_f32_16x16x32_bf16 v[52:55], v[160:163], v[176:179], v[52:55]
	v_mfma_f32_16x16x32_bf16 v[48:51], v[168:171], v[176:179], v[48:51]
	v_mfma_f32_16x16x32_bf16 v[36:39], v[160:163], v[184:187], v[36:39]
	v_mfma_f32_16x16x32_bf16 v[32:35], v[168:171], v[184:187], v[32:35]
	v_mfma_f32_16x16x32_bf16 v[20:23], v[160:163], v[192:195], v[20:23]
	v_mfma_f32_16x16x32_bf16 v[16:19], v[168:171], v[192:195], v[16:19]
	v_mfma_f32_16x16x32_bf16 v[4:7], v[160:163], v[200:203], v[4:7]
	v_mfma_f32_16x16x32_bf16 v[0:3], v[168:171], v[200:203], v[0:3]
	v_mfma_f32_16x16x32_bf16 v[52:55], v[164:167], v[180:183], v[52:55]
	v_mfma_f32_16x16x32_bf16 v[48:51], v[172:175], v[180:183], v[48:51]
	v_mfma_f32_16x16x32_bf16 v[36:39], v[164:167], v[188:191], v[36:39]
	v_mfma_f32_16x16x32_bf16 v[32:35], v[172:175], v[188:191], v[32:35]
	v_mfma_f32_16x16x32_bf16 v[20:23], v[164:167], v[196:199], v[20:23]
	v_mfma_f32_16x16x32_bf16 v[16:19], v[172:175], v[196:199], v[16:19]
	v_mfma_f32_16x16x32_bf16 v[4:7], v[164:167], v[204:207], v[4:7]
	v_mfma_f32_16x16x32_bf16 v[0:3], v[172:175], v[204:207], v[0:3]
	s_setprio 0
	s_barrier
	s_add_i32 s57, s57, 2
	s_add_u32 s38, s38, 0x100
	s_addc_u32 s39, s39, 0
	s_add_u32 s55, s55, 0x100
	s_addc_u32 s56, s56, 0
	s_cmp_gt_u32 s57, 13
	s_cbranch_scc0 .LBB0_1694
	s_and_b64 vcc, exec, s[4:5]
	s_cbranch_vccz .LBB0_1697
	s_barrier

; #define G_STAGE(bufoff, gbase, voff) do { _Pragma("unroll") for (int _i = 0; _i < 2; ++_i) \
;         __builtin_amdgcn_global_load_lds((const unsigned*)((const char*)(gbase) + voff[_i]), (LAS unsigned*)(lds + (bufoff) + ldsw + _i * 8192), 16, 0, 0); } while (0)
; #define G_LDA(dst, b, h) do { _Pragma("unroll") for (int m = 0; m < 4; ++m) _Pragma("unroll") for (int k = 0; k < 2; ++k) dst[m][k] = *(const LAS bf16x8*)(lds + G_SA(b, h) + aoff + m * 2048 + k * 1024); } while (0)
; #define G_LDB(dst, b, h) do { _Pragma("unroll") for (int n = 0; n < 2; ++n) _Pragma("unroll") for (int k = 0; k < 2; ++k) dst[n][k] = *(const LAS bf16x8*)(lds + G_SB(b, h) + boff + n * 2048 + k * 1024); } while (0)
; #define G_MMA(ai, bj, At_, Bt_) do { __builtin_amdgcn_s_setprio(1); _Pragma("unroll") for (int m = 0; m < 4; ++m) _Pragma("unroll") for (int n = 0; n < 2; ++n) _Pragma("unroll") for (int k = 0; k < 2; ++k) \
;         acc[ai][bj][m][n] = __builtin_amdgcn_mfma_f32_16x16x32_bf16(Bt_[n][k], At_[m][k], acc[ai][bj][m][n], 0, 0, 0); __builtin_amdgcn_s_setprio(0); } while (0)
; #define WAIT_V(n) asm volatile("s_waitcnt vmcnt(" #n ")" ::: "memory")
; #define WAIT_L(n) asm volatile("s_waitcnt lgkmcnt(" #n ")" ::: "memory")
; #define BAR __builtin_amdgcn_s_barrier()
; #define SCHED __builtin_amdgcn_sched_barrier(0)
; template <class Get, class Epi>
; DI void gemm_loop(int ntiles, int ld, char* shm, const Get& get, const Epi& epi) {
;     ...
;         for (int t = 0; t < nt; t += 2) {
;             const bool last = (t == nt - 2);
;             const char* a1 = cA + (size_t)(t + 1) * kstep;
;             const char* a2 = last ? nA : cA + (size_t)(t + 2) * kstep; const char* b2 = last ? nB : cB + (size_t)(t + 2) * kstep;
;             const char* a3 = a2 + kstep; const char* b3 = b2 + kstep;
;             G_LDB(B0, 0, 0); G_LDB(B1, 0, 1); SCHED; G_LDA(At, 0, 0); G_STAGE(G_SA(1, 1), a1 + hstep, voffA);
;             WAIT_V(8); WAIT_L(0); BAR; G_MMA(0, 0, At, B0); G_MMA(0, 1, At, B1); BAR; SCHED;
;             G_LDA(At, 0, 1); G_STAGE(G_SB(0, 0), b2, voffB); G_STAGE(G_SB(0, 1), b2 + hstep, voffB); G_STAGE(G_SA(0, 0), a2, voffA);
;             WAIT_V(8); WAIT_L(0); BAR; G_MMA(1, 0, At, B0); G_MMA(1, 1, At, B1); BAR; SCHED;
.LBB0_1781:
	ds_read_b128 v[128:131], v169
	ds_read_b128 v[132:135], v169 offset:1024
	ds_read_b128 v[136:139], v169 offset:2048
	ds_read_b128 v[140:143], v169 offset:3072
	ds_read_b128 v[158:161], v170
	ds_read_b128 v[162:165], v170 offset:1024
	ds_read_b128 v[172:175], v170 offset:2048
	ds_read_b128 v[176:179], v170 offset:3072
	s_add_i32 s77, s40, 2
	s_add_u32 s14, s4, 0x100
	s_addc_u32 s15, s5, 0
	s_cmp_eq_u32 s74, s40
	s_cselect_b32 s40, s38, s75
	s_cselect_b32 s43, s37, s15
	s_cselect_b32 s42, s36, s14
	s_cselect_b32 s41, s39, s76
	v_lshl_add_u64 v[144:145], s[4:5], 0, v[154:155]
	s_add_i32 m0, s45, 0xc000
	ds_read_b128 v[180:183], v171
	ds_read_b128 v[184:187], v171 offset:1024
	ds_read_b128 v[188:191], v171 offset:2048
	ds_read_b128 v[192:195], v171 offset:3072
	ds_read_b128 v[196:199], v171 offset:4096
	ds_read_b128 v[200:203], v171 offset:5120
	ds_read_b128 v[204:207], v171 offset:6144
	ds_read_b128 v[208:211], v171 offset:7168
	global_load_lds_dwordx4 v[144:145], off
	v_lshl_add_u64 v[144:145], s[4:5], 0, v[156:157]
	s_add_i32 m0, s45, 0xe000
	s_nop 0
	global_load_lds_dwordx4 v[144:145], off
	s_mov_b32 s98, 0xfff50000
	s_mov_b32 s99, -1
	v_lshl_add_u64 v[144:145], s[4:5], 0, v[154:155]
	v_lshl_add_u64 v[144:145], v[144:145], 0, s[98:99]
	s_add_i32 m0, s45, 0x8000
	s_nop 0
	global_load_lds_dwordx4 v[144:145], off
	v_lshl_add_u64 v[144:145], s[4:5], 0, v[156:157]
	v_lshl_add_u64 v[144:145], v[144:145], 0, s[98:99]
	s_add_i32 m0, s45, 0xa000
	s_nop 0
	global_load_lds_dwordx4 v[144:145], off
	s_waitcnt vmcnt(8)
	s_waitcnt lgkmcnt(0)
	s_barrier
	s_setprio 1
	s_waitcnt lgkmcnt(0)
	v_mfma_f32_16x16x32_bf16 v[124:127], v[128:131], v[180:183], v[124:127]
	v_mfma_f32_16x16x32_bf16 v[120:123], v[136:139], v[180:183], v[120:123]
	v_mfma_f32_16x16x32_bf16 v[116:119], v[128:131], v[188:191], v[116:119]
	v_mfma_f32_16x16x32_bf16 v[112:115], v[136:139], v[188:191], v[112:115]
	v_mfma_f32_16x16x32_bf16 v[108:111], v[128:131], v[196:199], v[108:111]
	v_mfma_f32_16x16x32_bf16 v[104:107], v[136:139], v[196:199], v[104:107]
	v_mfma_f32_16x16x32_bf16 v[100:103], v[128:131], v[204:207], v[100:103]
	v_mfma_f32_16x16x32_bf16 v[96:99], v[136:139], v[204:207], v[96:99]
	v_mfma_f32_16x16x32_bf16 v[124:127], v[132:135], v[184:187], v[124:127]
	v_mfma_f32_16x16x32_bf16 v[120:123], v[140:143], v[184:187], v[120:123]
	v_mfma_f32_16x16x32_bf16 v[116:119], v[132:135], v[192:195], v[116:119]
	v_mfma_f32_16x16x32_bf16 v[112:115], v[140:143], v[192:195], v[112:115]
	v_mfma_f32_16x16x32_bf16 v[108:111], v[132:135], v[200:203], v[108:111]
	v_mfma_f32_16x16x32_bf16 v[104:107], v[140:143], v[200:203], v[104:107]
	v_mfma_f32_16x16x32_bf16 v[100:103], v[132:135], v[208:211], v[100:103]
	v_mfma_f32_16x16x32_bf16 v[96:99], v[140:143], v[208:211], v[96:99]
	s_setprio 0
	s_setprio 1
	v_mfma_f32_16x16x32_bf16 v[60:63], v[158:161], v[180:183], v[60:63]
	v_mfma_f32_16x16x32_bf16 v[56:59], v[172:175], v[180:183], v[56:59]
	v_mfma_f32_16x16x32_bf16 v[52:55], v[158:161], v[188:191], v[52:55]
	v_mfma_f32_16x16x32_bf16 v[48:51], v[172:175], v[188:191], v[48:51]
	v_mfma_f32_16x16x32_bf16 v[44:47], v[158:161], v[196:199], v[44:47]
	v_mfma_f32_16x16x32_bf16 v[40:43], v[172:175], v[196:199], v[40:43]
	v_mfma_f32_16x16x32_bf16 v[36:39], v[158:161], v[204:207], v[36:39]
	v_mfma_f32_16x16x32_bf16 v[32:35], v[172:175], v[204:207], v[32:35]
	v_mfma_f32_16x16x32_bf16 v[60:63], v[162:165], v[184:187], v[60:63]
	v_mfma_f32_16x16x32_bf16 v[56:59], v[176:179], v[184:187], v[56:59]
	v_mfma_f32_16x16x32_bf16 v[52:55], v[162:165], v[192:195], v[52:55]
	v_mfma_f32_16x16x32_bf16 v[48:51], v[176:179], v[192:195], v[48:51]
	v_mfma_f32_16x16x32_bf16 v[44:47], v[162:165], v[200:203], v[44:47]
	v_mfma_f32_16x16x32_bf16 v[40:43], v[176:179], v[200:203], v[40:43]
	v_mfma_f32_16x16x32_bf16 v[36:39], v[162:165], v[208:211], v[36:39]
	v_mfma_f32_16x16x32_bf16 v[32:35], v[176:179], v[208:211], v[32:35]
	s_setprio 0
	s_barrier
	s_add_i32 s4, s53, s44
	v_lshl_add_u64 v[144:145], s[40:41], 0, v[148:149]
	s_mov_b32 m0, s4
	ds_read_b128 v[180:183], v171 offset:16384
	ds_read_b128 v[184:187], v171 offset:17408
	ds_read_b128 v[188:191], v171 offset:18432
	ds_read_b128 v[192:195], v171 offset:19456
	ds_read_b128 v[196:199], v171 offset:20480
	ds_read_b128 v[200:203], v171 offset:21504
	ds_read_b128 v[204:207], v171 offset:22528
	ds_read_b128 v[208:211], v171 offset:23552
	global_load_lds_dwordx4 v[144:145], off
	s_add_i32 m0, s4, 0x2000
	s_add_u32 s4, s40, 0xb0000
	v_lshl_add_u64 v[166:167], s[40:41], 0, v[152:153]
	s_addc_u32 s5, s41, 0
	s_add_i32 s78, s54, s44
	global_load_lds_dwordx4 v[166:167], off
	v_lshl_add_u64 v[212:213], s[4:5], 0, v[148:149]
	s_mov_b32 m0, s78
	v_lshl_add_u64 v[214:215], s[42:43], 0, v[150:151]
	global_load_lds_dwordx4 v[212:213], off
	v_lshl_add_u64 v[212:213], s[4:5], 0, v[152:153]
	s_add_i32 m0, s78, 0x2000
	s_nop 0
	global_load_lds_dwordx4 v[212:213], off
	v_lshl_add_u64 v[212:213], s[42:43], 0, v[146:147]
	s_waitcnt vmcnt(4)
	s_waitcnt lgkmcnt(0)
	s_barrier
; #define G_STAGE(bufoff, gbase, voff) do { _Pragma("unroll") for (int _i = 0; _i < 2; ++_i) \
;         __builtin_amdgcn_global_load_lds((const unsigned*)((const char*)(gbase) + voff[_i]), (LAS unsigned*)(lds + (bufoff) + ldsw + _i * 8192), 16, 0, 0); } while (0)
; #define G_LDA(dst, b, h) do { _Pragma("unroll") for (int m = 0; m < 4; ++m) _Pragma("unroll") for (int k = 0; k < 2; ++k) dst[m][k] = *(const LAS bf16x8*)(lds + G_SA(b, h) + aoff + m * 2048 + k * 1024); } while (0)
; #define G_LDB(dst, b, h) do { _Pragma("unroll") for (int n = 0; n < 2; ++n) _Pragma("unroll") for (int k = 0; k < 2; ++k) dst[n][k] = *(const LAS bf16x8*)(lds + G_SB(b, h) + boff + n * 2048 + k * 1024); } while (0)
; #define G_MMA(ai, bj, At_, Bt_) do { __builtin_amdgcn_s_setprio(1); _Pragma("unroll") for (int m = 0; m < 4; ++m) _Pragma("unroll") for (int n = 0; n < 2; ++n) _Pragma("unroll") for (int k = 0; k < 2; ++k) \
;         acc[ai][bj][m][n] = __builtin_amdgcn_mfma_f32_16x16x32_bf16(Bt_[n][k], At_[m][k], acc[ai][bj][m][n], 0, 0, 0); __builtin_amdgcn_s_setprio(0); } while (0)
; #define WAIT_V(n) asm volatile("s_waitcnt vmcnt(" #n ")" ::: "memory")
; #define WAIT_L(n) asm volatile("s_waitcnt lgkmcnt(" #n ")" ::: "memory")
; #define BAR __builtin_amdgcn_s_barrier()
; #define SCHED __builtin_amdgcn_sched_barrier(0)
; template <class Get, class Epi>
; DI void gemm_loop(int ntiles, int ld, char* shm, const Get& get, const Epi& epi) {
;     ...
;             WAIT_V(8); WAIT_L(0); BAR; G_MMA(1, 0, At, B0); G_MMA(1, 1, At, B1); BAR; SCHED;
;             G_LDB(B0, 1, 0); G_LDB(B1, 1, 1); SCHED; G_LDA(At, 1, 0); G_STAGE(G_SA(0, 1), a2 + hstep, voffA);
;             WAIT_V(8); WAIT_L(0); BAR; G_MMA(0, 0, At, B0); G_MMA(0, 1, At, B1); BAR; SCHED;
	s_setprio 1
	s_waitcnt lgkmcnt(0)
	v_mfma_f32_16x16x32_bf16 v[92:95], v[128:131], v[180:183], v[92:95]
	v_mfma_f32_16x16x32_bf16 v[88:91], v[136:139], v[180:183], v[88:91]
	v_mfma_f32_16x16x32_bf16 v[84:87], v[128:131], v[188:191], v[84:87]
	v_mfma_f32_16x16x32_bf16 v[80:83], v[136:139], v[188:191], v[80:83]
	v_mfma_f32_16x16x32_bf16 v[76:79], v[128:131], v[196:199], v[76:79]
	v_mfma_f32_16x16x32_bf16 v[72:75], v[136:139], v[196:199], v[72:75]
	v_mfma_f32_16x16x32_bf16 v[68:71], v[128:131], v[204:207], v[68:71]
	v_mfma_f32_16x16x32_bf16 v[64:67], v[136:139], v[204:207], v[64:67]
	v_mfma_f32_16x16x32_bf16 v[92:95], v[132:135], v[184:187], v[92:95]
	v_mfma_f32_16x16x32_bf16 v[88:91], v[140:143], v[184:187], v[88:91]
	v_mfma_f32_16x16x32_bf16 v[84:87], v[132:135], v[192:195], v[84:87]
	v_mfma_f32_16x16x32_bf16 v[80:83], v[140:143], v[192:195], v[80:83]
	v_mfma_f32_16x16x32_bf16 v[76:79], v[132:135], v[200:203], v[76:79]
	v_mfma_f32_16x16x32_bf16 v[72:75], v[140:143], v[200:203], v[72:75]
	v_mfma_f32_16x16x32_bf16 v[68:71], v[132:135], v[208:211], v[68:71]
	v_mfma_f32_16x16x32_bf16 v[64:67], v[140:143], v[208:211], v[64:67]
	s_setprio 0
	s_setprio 1
	v_mfma_f32_16x16x32_bf16 v[28:31], v[158:161], v[180:183], v[28:31]
	v_mfma_f32_16x16x32_bf16 v[24:27], v[172:175], v[180:183], v[24:27]
	v_mfma_f32_16x16x32_bf16 v[20:23], v[158:161], v[188:191], v[20:23]
	v_mfma_f32_16x16x32_bf16 v[16:19], v[172:175], v[188:191], v[16:19]
	v_mfma_f32_16x16x32_bf16 v[12:15], v[158:161], v[196:199], v[12:15]
	v_mfma_f32_16x16x32_bf16 v[8:11], v[172:175], v[196:199], v[8:11]
	v_mfma_f32_16x16x32_bf16 v[4:7], v[158:161], v[204:207], v[4:7]
	v_mfma_f32_16x16x32_bf16 v[0:3], v[172:175], v[204:207], v[0:3]
	v_mfma_f32_16x16x32_bf16 v[28:31], v[162:165], v[184:187], v[28:31]
	v_mfma_f32_16x16x32_bf16 v[24:27], v[176:179], v[184:187], v[24:27]
	v_mfma_f32_16x16x32_bf16 v[20:23], v[162:165], v[192:195], v[20:23]
	v_mfma_f32_16x16x32_bf16 v[16:19], v[176:179], v[192:195], v[16:19]
	v_mfma_f32_16x16x32_bf16 v[12:15], v[162:165], v[200:203], v[12:15]
	v_mfma_f32_16x16x32_bf16 v[8:11], v[176:179], v[200:203], v[8:11]
	v_mfma_f32_16x16x32_bf16 v[4:7], v[162:165], v[208:211], v[4:7]
	v_mfma_f32_16x16x32_bf16 v[0:3], v[176:179], v[208:211], v[0:3]
	s_setprio 0
	s_barrier
	s_add_i32 s78, 0, 0x18000
	s_add_i32 s79, 0, 0x1c000
	v_add_u32_e32 v140, s78, v168
	v_add_u32_e32 v176, s79, v168
	ds_read_b128 v[128:131], v140
	ds_read_b128 v[132:135], v140 offset:1024
	ds_read_b128 v[136:139], v140 offset:2048
	ds_read_b128 v[140:143], v140 offset:3072
	ds_read_b128 v[158:161], v176
	ds_read_b128 v[162:165], v176 offset:1024
	ds_read_b128 v[172:175], v176 offset:2048
	ds_read_b128 v[176:179], v176 offset:3072
	s_add_u32 s4, s42, 0xb0000
	s_addc_u32 s5, s43, 0
	s_mov_b32 m0, s47
	v_lshl_add_u64 v[216:217], s[4:5], 0, v[146:147]
	ds_read_b128 v[180:183], v171 offset:32768
	ds_read_b128 v[184:187], v171 offset:33792
	ds_read_b128 v[188:191], v171 offset:34816
	ds_read_b128 v[192:195], v171 offset:35840
	ds_read_b128 v[196:199], v171 offset:36864
	ds_read_b128 v[200:203], v171 offset:37888
	ds_read_b128 v[204:207], v171 offset:38912
	ds_read_b128 v[208:211], v171 offset:39936
	global_load_lds_dwordx4 v[216:217], off
	v_lshl_add_u64 v[216:217], s[4:5], 0, v[150:151]
	s_mov_b32 m0, s48
	s_nop 0
	global_load_lds_dwordx4 v[216:217], off
	s_mov_b32 m0, s45
	s_nop 0
	global_load_lds_dwordx4 v[212:213], off
	s_mov_b32 m0, s46
	s_nop 0
	global_load_lds_dwordx4 v[214:215], off
	s_waitcnt vmcnt(8)
	s_waitcnt lgkmcnt(0)
	s_barrier
; #define G_STAGE(bufoff, gbase, voff) do { _Pragma("unroll") for (int _i = 0; _i < 2; ++_i) \
;         __builtin_amdgcn_global_load_lds((const unsigned*)((const char*)(gbase) + voff[_i]), (LAS unsigned*)(lds + (bufoff) + ldsw + _i * 8192), 16, 0, 0); } while (0)
; #define G_LDA(dst, b, h) do { _Pragma("unroll") for (int m = 0; m < 4; ++m) _Pragma("unroll") for (int k = 0; k < 2; ++k) dst[m][k] = *(const LAS bf16x8*)(lds + G_SA(b, h) + aoff + m * 2048 + k * 1024); } while (0)
; #define G_MMA(ai, bj, At_, Bt_) do { __builtin_amdgcn_s_setprio(1); _Pragma("unroll") for (int m = 0; m < 4; ++m) _Pragma("unroll") for (int n = 0; n < 2; ++n) _Pragma("unroll") for (int k = 0; k < 2; ++k) \
;         acc[ai][bj][m][n] = __builtin_amdgcn_mfma_f32_16x16x32_bf16(Bt_[n][k], At_[m][k], acc[ai][bj][m][n], 0, 0, 0); __builtin_amdgcn_s_setprio(0); } while (0)
; #define WAIT_V(n) asm volatile("s_waitcnt vmcnt(" #n ")" ::: "memory")
; #define WAIT_L(n) asm volatile("s_waitcnt lgkmcnt(" #n ")" ::: "memory")
; #define BAR __builtin_amdgcn_s_barrier()
; #define SCHED __builtin_amdgcn_sched_barrier(0)
; template <class Get, class Epi>
; DI void gemm_loop(int ntiles, int ld, char* shm, const Get& get, const Epi& epi) {
;     ...
;             WAIT_V(8); WAIT_L(0); BAR; G_MMA(0, 0, At, B0); G_MMA(0, 1, At, B1); BAR; SCHED;
;             G_LDA(At, 1, 1); G_STAGE(G_SB(1, 0), b3, voffB); G_STAGE(G_SB(1, 1), b3 + hstep, voffB); G_STAGE(G_SA(1, 0), a3, voffA);
;             WAIT_V(8); WAIT_L(0); BAR; G_MMA(1, 0, At, B0); G_MMA(1, 1, At, B1); BAR; SCHED;
;         }
;         if (wr == 0) BAR;
	s_setprio 1
	s_waitcnt lgkmcnt(0)
	v_mfma_f32_16x16x32_bf16 v[124:127], v[128:131], v[180:183], v[124:127]
	v_mfma_f32_16x16x32_bf16 v[120:123], v[136:139], v[180:183], v[120:123]
	v_mfma_f32_16x16x32_bf16 v[116:119], v[128:131], v[188:191], v[116:119]
	v_mfma_f32_16x16x32_bf16 v[112:115], v[136:139], v[188:191], v[112:115]
	v_mfma_f32_16x16x32_bf16 v[108:111], v[128:131], v[196:199], v[108:111]
	v_mfma_f32_16x16x32_bf16 v[104:107], v[136:139], v[196:199], v[104:107]
	v_mfma_f32_16x16x32_bf16 v[100:103], v[128:131], v[204:207], v[100:103]
	v_mfma_f32_16x16x32_bf16 v[96:99], v[136:139], v[204:207], v[96:99]
	v_mfma_f32_16x16x32_bf16 v[124:127], v[132:135], v[184:187], v[124:127]
	v_mfma_f32_16x16x32_bf16 v[120:123], v[140:143], v[184:187], v[120:123]
	v_mfma_f32_16x16x32_bf16 v[116:119], v[132:135], v[192:195], v[116:119]
	v_mfma_f32_16x16x32_bf16 v[112:115], v[140:143], v[192:195], v[112:115]
	v_mfma_f32_16x16x32_bf16 v[108:111], v[132:135], v[200:203], v[108:111]
	v_mfma_f32_16x16x32_bf16 v[104:107], v[140:143], v[200:203], v[104:107]
	v_mfma_f32_16x16x32_bf16 v[100:103], v[132:135], v[208:211], v[100:103]
	v_mfma_f32_16x16x32_bf16 v[96:99], v[140:143], v[208:211], v[96:99]
	s_setprio 0
	s_setprio 1
	v_mfma_f32_16x16x32_bf16 v[60:63], v[158:161], v[180:183], v[60:63]
	v_mfma_f32_16x16x32_bf16 v[56:59], v[172:175], v[180:183], v[56:59]
	v_mfma_f32_16x16x32_bf16 v[52:55], v[158:161], v[188:191], v[52:55]
	v_mfma_f32_16x16x32_bf16 v[48:51], v[172:175], v[188:191], v[48:51]
	v_mfma_f32_16x16x32_bf16 v[44:47], v[158:161], v[196:199], v[44:47]
	v_mfma_f32_16x16x32_bf16 v[40:43], v[172:175], v[196:199], v[40:43]
	v_mfma_f32_16x16x32_bf16 v[36:39], v[158:161], v[204:207], v[36:39]
	v_mfma_f32_16x16x32_bf16 v[32:35], v[172:175], v[204:207], v[32:35]
	v_mfma_f32_16x16x32_bf16 v[60:63], v[162:165], v[184:187], v[60:63]
	v_mfma_f32_16x16x32_bf16 v[56:59], v[176:179], v[184:187], v[56:59]
	v_mfma_f32_16x16x32_bf16 v[52:55], v[162:165], v[192:195], v[52:55]
	v_mfma_f32_16x16x32_bf16 v[48:51], v[176:179], v[192:195], v[48:51]
	v_mfma_f32_16x16x32_bf16 v[44:47], v[162:165], v[200:203], v[44:47]
	v_mfma_f32_16x16x32_bf16 v[40:43], v[176:179], v[200:203], v[40:43]
	v_mfma_f32_16x16x32_bf16 v[36:39], v[162:165], v[208:211], v[36:39]
	v_mfma_f32_16x16x32_bf16 v[32:35], v[176:179], v[208:211], v[32:35]
	s_setprio 0
	s_barrier
	s_add_i32 s4, s78, s44
	v_lshl_add_u64 v[144:145], v[144:145], 0, s[10:11]
	s_mov_b32 m0, s4
	ds_read_b128 v[180:183], v171 offset:49152
	ds_read_b128 v[184:187], v171 offset:50176
	ds_read_b128 v[188:191], v171 offset:51200
	ds_read_b128 v[192:195], v171 offset:52224
	ds_read_b128 v[196:199], v171 offset:53248
	ds_read_b128 v[200:203], v171 offset:54272
	ds_read_b128 v[204:207], v171 offset:55296
	ds_read_b128 v[208:211], v171 offset:56320
	global_load_lds_dwordx4 v[144:145], off
	s_add_i32 m0, s4, 0x2000
	s_add_u32 s4, s40, 0xb0080
	v_lshl_add_u64 v[144:145], v[166:167], 0, s[10:11]
	s_addc_u32 s5, s41, 0
	s_add_i32 s40, s79, s44
	global_load_lds_dwordx4 v[144:145], off
	v_lshl_add_u64 v[144:145], s[4:5], 0, v[148:149]
	s_mov_b32 m0, s40
	s_nop 0
	global_load_lds_dwordx4 v[144:145], off
	v_lshl_add_u64 v[144:145], s[4:5], 0, v[152:153]
	s_add_i32 m0, s40, 0x2000
	s_nop 0
	global_load_lds_dwordx4 v[144:145], off
	s_waitcnt vmcnt(4)
	s_waitcnt lgkmcnt(0)
	s_barrier
	s_setprio 1
	s_waitcnt lgkmcnt(0)
	v_mfma_f32_16x16x32_bf16 v[92:95], v[128:131], v[180:183], v[92:95]
	v_mfma_f32_16x16x32_bf16 v[88:91], v[136:139], v[180:183], v[88:91]
	v_mfma_f32_16x16x32_bf16 v[84:87], v[128:131], v[188:191], v[84:87]
	v_mfma_f32_16x16x32_bf16 v[80:83], v[136:139], v[188:191], v[80:83]
	v_mfma_f32_16x16x32_bf16 v[76:79], v[128:131], v[196:199], v[76:79]
	v_mfma_f32_16x16x32_bf16 v[72:75], v[136:139], v[196:199], v[72:75]
	v_mfma_f32_16x16x32_bf16 v[68:71], v[128:131], v[204:207], v[68:71]
	v_mfma_f32_16x16x32_bf16 v[64:67], v[136:139], v[204:207], v[64:67]
	v_mfma_f32_16x16x32_bf16 v[92:95], v[132:135], v[184:187], v[92:95]
	v_mfma_f32_16x16x32_bf16 v[88:91], v[140:143], v[184:187], v[88:91]
	v_mfma_f32_16x16x32_bf16 v[84:87], v[132:135], v[192:195], v[84:87]
	v_mfma_f32_16x16x32_bf16 v[80:83], v[140:143], v[192:195], v[80:83]
	v_mfma_f32_16x16x32_bf16 v[76:79], v[132:135], v[200:203], v[76:79]
	v_mfma_f32_16x16x32_bf16 v[72:75], v[140:143], v[200:203], v[72:75]
	v_mfma_f32_16x16x32_bf16 v[68:71], v[132:135], v[208:211], v[68:71]
	v_mfma_f32_16x16x32_bf16 v[64:67], v[140:143], v[208:211], v[64:67]
	s_setprio 0
	s_setprio 1
	v_mfma_f32_16x16x32_bf16 v[28:31], v[158:161], v[180:183], v[28:31]
	v_mfma_f32_16x16x32_bf16 v[24:27], v[172:175], v[180:183], v[24:27]
	v_mfma_f32_16x16x32_bf16 v[20:23], v[158:161], v[188:191], v[20:23]
	v_mfma_f32_16x16x32_bf16 v[16:19], v[172:175], v[188:191], v[16:19]
	v_mfma_f32_16x16x32_bf16 v[12:15], v[158:161], v[196:199], v[12:15]
	v_mfma_f32_16x16x32_bf16 v[8:11], v[172:175], v[196:199], v[8:11]
	v_mfma_f32_16x16x32_bf16 v[4:7], v[158:161], v[204:207], v[4:7]
	v_mfma_f32_16x16x32_bf16 v[0:3], v[172:175], v[204:207], v[0:3]
	v_mfma_f32_16x16x32_bf16 v[28:31], v[162:165], v[184:187], v[28:31]
	v_mfma_f32_16x16x32_bf16 v[24:27], v[176:179], v[184:187], v[24:27]
	v_mfma_f32_16x16x32_bf16 v[20:23], v[162:165], v[192:195], v[20:23]
	v_mfma_f32_16x16x32_bf16 v[16:19], v[176:179], v[192:195], v[16:19]
	v_mfma_f32_16x16x32_bf16 v[12:15], v[162:165], v[200:203], v[12:15]
	v_mfma_f32_16x16x32_bf16 v[8:11], v[176:179], v[200:203], v[8:11]
	v_mfma_f32_16x16x32_bf16 v[4:7], v[162:165], v[208:211], v[4:7]
	v_mfma_f32_16x16x32_bf16 v[0:3], v[176:179], v[208:211], v[0:3]
	s_setprio 0
	s_barrier
	s_add_u32 s75, s75, 0x100
	s_addc_u32 s76, s76, 0
	s_cmp_ge_u32 s77, s73
	s_mov_b64 s[4:5], s[14:15]
	s_mov_b32 s40, s77
	s_cbranch_scc0 .LBB0_1781
	s_and_b64 vcc, exec, s[12:13]
	s_cbranch_vccz .LBB0_1784
	s_barrier

; #define G_STAGE(bufoff, gbase, voff) do { _Pragma("unroll") for (int _i = 0; _i < 2; ++_i) \
;         __builtin_amdgcn_global_load_lds((const unsigned*)((const char*)(gbase) + voff[_i]), (LAS unsigned*)(lds + (bufoff) + ldsw + _i * 8192), 16, 0, 0); } while (0)
; #define G_LDA(dst, b, h) do { _Pragma("unroll") for (int m = 0; m < 4; ++m) _Pragma("unroll") for (int k = 0; k < 2; ++k) dst[m][k] = *(const LAS bf16x8*)(lds + G_SA(b, h) + aoff + m * 2048 + k * 1024); } while (0)
; #define G_LDB(dst, b, h) do { _Pragma("unroll") for (int n = 0; n < 2; ++n) _Pragma("unroll") for (int k = 0; k < 2; ++k) dst[n][k] = *(const LAS bf16x8*)(lds + G_SB(b, h) + boff + n * 2048 + k * 1024); } while (0)
; #define G_MMA(ai, bj, At_, Bt_) do { __builtin_amdgcn_s_setprio(1); _Pragma("unroll") for (int m = 0; m < 4; ++m) _Pragma("unroll") for (int n = 0; n < 2; ++n) _Pragma("unroll") for (int k = 0; k < 2; ++k) \
;         acc[ai][bj][m][n] = __builtin_amdgcn_mfma_f32_16x16x32_bf16(Bt_[n][k], At_[m][k], acc[ai][bj][m][n], 0, 0, 0); __builtin_amdgcn_s_setprio(0); } while (0)
; #define WAIT_V(n) asm volatile("s_waitcnt vmcnt(" #n ")" ::: "memory")
; #define WAIT_L(n) asm volatile("s_waitcnt lgkmcnt(" #n ")" ::: "memory")
; #define BAR __builtin_amdgcn_s_barrier()
; #define SCHED __builtin_amdgcn_sched_barrier(0)
; template <class Get, class Epi>
; DI void gemm_loop(int ntiles, int ld, char* shm, const Get& get, const Epi& epi) {
;     ...
;         for (int t = 0; t < nt; t += 2) {
;             const bool last = (t == nt - 2);
;             const char* a1 = cA + (size_t)(t + 1) * kstep;
;             const char* a2 = last ? nA : cA + (size_t)(t + 2) * kstep; const char* b2 = last ? nB : cB + (size_t)(t + 2) * kstep;
;             const char* a3 = a2 + kstep; const char* b3 = b2 + kstep;
;             G_LDB(B0, 0, 0); G_LDB(B1, 0, 1); SCHED; G_LDA(At, 0, 0); G_STAGE(G_SA(1, 1), a1 + hstep, voffA);
;             WAIT_V(8); WAIT_L(0); BAR; G_MMA(0, 0, At, B0); G_MMA(0, 1, At, B1); BAR; SCHED;
;             G_LDA(At, 0, 1); G_STAGE(G_SB(0, 0), b2, voffB); G_STAGE(G_SB(0, 1), b2 + hstep, voffB); G_STAGE(G_SA(0, 0), a2, voffA);
;             WAIT_V(8); WAIT_L(0); BAR; G_MMA(1, 0, At, B0); G_MMA(1, 1, At, B1); BAR; SCHED;
.LBB0_2022:
	ds_read_b128 v[96:99], v173
	ds_read_b128 v[108:111], v173 offset:1024
	ds_read_b128 v[150:153], v173 offset:2048
	ds_read_b128 v[154:157], v173 offset:3072
	ds_read_b128 v[158:161], v174
	ds_read_b128 v[162:165], v174 offset:1024
	ds_read_b128 v[166:169], v174 offset:2048
	ds_read_b128 v[180:183], v174 offset:3072
	s_add_u32 s6, s4, 0xfffc0080
	s_addc_u32 s7, s5, -1
	s_cmp_eq_u32 s56, 12
	s_cselect_b32 s15, s3, s7
	s_cselect_b32 s14, s41, s6
	s_cselect_b32 s7, s43, s55
	s_cselect_b32 s6, s53, s54
	v_lshl_add_u64 v[170:171], s[4:5], 0, v[146:147]
	s_add_i32 m0, s50, 0xc000
	ds_read_b128 v[184:187], v175
	ds_read_b128 v[188:191], v175 offset:1024
	ds_read_b128 v[192:195], v175 offset:2048
	ds_read_b128 v[196:199], v175 offset:3072
	ds_read_b128 v[200:203], v175 offset:4096
	ds_read_b128 v[204:207], v175 offset:5120
	ds_read_b128 v[208:211], v175 offset:6144
	ds_read_b128 v[212:215], v175 offset:7168
	global_load_lds_dwordx4 v[170:171], off
	v_lshl_add_u64 v[170:171], s[4:5], 0, v[148:149]
	s_add_i32 m0, s50, 0xe000
	s_nop 0
	global_load_lds_dwordx4 v[170:171], off
	s_mov_b32 s98, 0xfffc0000
	s_mov_b32 s99, -1
	v_lshl_add_u64 v[170:171], s[4:5], 0, v[146:147]
	v_lshl_add_u64 v[170:171], v[170:171], 0, s[98:99]
	s_add_i32 m0, s50, 0x8000
	s_nop 0
	global_load_lds_dwordx4 v[170:171], off
	v_lshl_add_u64 v[170:171], s[4:5], 0, v[148:149]
	v_lshl_add_u64 v[170:171], v[170:171], 0, s[98:99]
	s_add_i32 m0, s50, 0xa000
	s_nop 0
	global_load_lds_dwordx4 v[170:171], off
	s_waitcnt vmcnt(8)
	s_waitcnt lgkmcnt(0)
	s_barrier
	s_setprio 1
	s_waitcnt lgkmcnt(0)
	v_mfma_f32_16x16x32_bf16 v[132:135], v[96:99], v[184:187], v[132:135]
	v_mfma_f32_16x16x32_bf16 v[124:127], v[150:153], v[184:187], v[124:127]
	v_mfma_f32_16x16x32_bf16 v[128:131], v[96:99], v[192:195], v[128:131]
	v_mfma_f32_16x16x32_bf16 v[120:123], v[150:153], v[192:195], v[120:123]
	v_mfma_f32_16x16x32_bf16 v[116:119], v[96:99], v[200:203], v[116:119]
	v_mfma_f32_16x16x32_bf16 v[104:107], v[150:153], v[200:203], v[104:107]
	v_mfma_f32_16x16x32_bf16 v[112:115], v[96:99], v[208:211], v[112:115]
	v_mfma_f32_16x16x32_bf16 v[100:103], v[150:153], v[208:211], v[100:103]
	v_mfma_f32_16x16x32_bf16 v[132:135], v[108:111], v[188:191], v[132:135]
	v_mfma_f32_16x16x32_bf16 v[124:127], v[154:157], v[188:191], v[124:127]
	v_mfma_f32_16x16x32_bf16 v[128:131], v[108:111], v[196:199], v[128:131]
	v_mfma_f32_16x16x32_bf16 v[120:123], v[154:157], v[196:199], v[120:123]
	v_mfma_f32_16x16x32_bf16 v[116:119], v[108:111], v[204:207], v[116:119]
	v_mfma_f32_16x16x32_bf16 v[104:107], v[154:157], v[204:207], v[104:107]
	v_mfma_f32_16x16x32_bf16 v[112:115], v[108:111], v[212:215], v[112:115]
	v_mfma_f32_16x16x32_bf16 v[100:103], v[154:157], v[212:215], v[100:103]
	s_setprio 0
	s_setprio 1
	v_mfma_f32_16x16x32_bf16 v[60:63], v[158:161], v[184:187], v[60:63]
	v_mfma_f32_16x16x32_bf16 v[52:55], v[166:169], v[184:187], v[52:55]
	v_mfma_f32_16x16x32_bf16 v[56:59], v[158:161], v[192:195], v[56:59]
	v_mfma_f32_16x16x32_bf16 v[48:51], v[166:169], v[192:195], v[48:51]
	v_mfma_f32_16x16x32_bf16 v[44:47], v[158:161], v[200:203], v[44:47]
	v_mfma_f32_16x16x32_bf16 v[36:39], v[166:169], v[200:203], v[36:39]
	v_mfma_f32_16x16x32_bf16 v[40:43], v[158:161], v[208:211], v[40:43]
	v_mfma_f32_16x16x32_bf16 v[32:35], v[166:169], v[208:211], v[32:35]
	v_mfma_f32_16x16x32_bf16 v[60:63], v[162:165], v[188:191], v[60:63]
	v_mfma_f32_16x16x32_bf16 v[52:55], v[180:183], v[188:191], v[52:55]
	v_mfma_f32_16x16x32_bf16 v[56:59], v[162:165], v[196:199], v[56:59]
	v_mfma_f32_16x16x32_bf16 v[48:51], v[180:183], v[196:199], v[48:51]
	v_mfma_f32_16x16x32_bf16 v[44:47], v[162:165], v[204:207], v[44:47]
	v_mfma_f32_16x16x32_bf16 v[36:39], v[180:183], v[204:207], v[36:39]
	v_mfma_f32_16x16x32_bf16 v[40:43], v[162:165], v[212:215], v[40:43]
	v_mfma_f32_16x16x32_bf16 v[32:35], v[180:183], v[212:215], v[32:35]
	s_setprio 0
	s_barrier
	s_add_i32 s57, s75, s46
	v_lshl_add_u64 v[170:171], s[6:7], 0, v[140:141]
	s_mov_b32 m0, s57
	ds_read_b128 v[184:187], v175 offset:16384
	ds_read_b128 v[188:191], v175 offset:17408
	ds_read_b128 v[192:195], v175 offset:18432
	ds_read_b128 v[196:199], v175 offset:19456
	ds_read_b128 v[200:203], v175 offset:20480
	ds_read_b128 v[204:207], v175 offset:21504
	ds_read_b128 v[208:211], v175 offset:22528
	ds_read_b128 v[212:215], v175 offset:23552
	global_load_lds_dwordx4 v[170:171], off
	s_add_i32 m0, s57, 0x2000
	s_add_u32 s58, s6, 0x40000
	v_lshl_add_u64 v[216:217], s[6:7], 0, v[136:137]
	s_addc_u32 s59, s7, 0
	s_add_i32 s57, s76, s46
	global_load_lds_dwordx4 v[216:217], off
	v_lshl_add_u64 v[218:219], s[58:59], 0, v[140:141]
	s_mov_b32 m0, s57
	v_lshl_add_u64 v[220:221], s[14:15], 0, v[138:139]
	global_load_lds_dwordx4 v[218:219], off
	v_lshl_add_u64 v[218:219], s[58:59], 0, v[136:137]
	s_add_i32 m0, s57, 0x2000
	s_nop 0
	global_load_lds_dwordx4 v[218:219], off
	v_lshl_add_u64 v[218:219], s[14:15], 0, v[142:143]
	s_waitcnt vmcnt(4)
	s_waitcnt lgkmcnt(0)
	s_barrier
; #define G_STAGE(bufoff, gbase, voff) do { _Pragma("unroll") for (int _i = 0; _i < 2; ++_i) \
;         __builtin_amdgcn_global_load_lds((const unsigned*)((const char*)(gbase) + voff[_i]), (LAS unsigned*)(lds + (bufoff) + ldsw + _i * 8192), 16, 0, 0); } while (0)
; #define G_LDA(dst, b, h) do { _Pragma("unroll") for (int m = 0; m < 4; ++m) _Pragma("unroll") for (int k = 0; k < 2; ++k) dst[m][k] = *(const LAS bf16x8*)(lds + G_SA(b, h) + aoff + m * 2048 + k * 1024); } while (0)
; #define G_LDB(dst, b, h) do { _Pragma("unroll") for (int n = 0; n < 2; ++n) _Pragma("unroll") for (int k = 0; k < 2; ++k) dst[n][k] = *(const LAS bf16x8*)(lds + G_SB(b, h) + boff + n * 2048 + k * 1024); } while (0)
; #define G_MMA(ai, bj, At_, Bt_) do { __builtin_amdgcn_s_setprio(1); _Pragma("unroll") for (int m = 0; m < 4; ++m) _Pragma("unroll") for (int n = 0; n < 2; ++n) _Pragma("unroll") for (int k = 0; k < 2; ++k) \
;         acc[ai][bj][m][n] = __builtin_amdgcn_mfma_f32_16x16x32_bf16(Bt_[n][k], At_[m][k], acc[ai][bj][m][n], 0, 0, 0); __builtin_amdgcn_s_setprio(0); } while (0)
; #define WAIT_V(n) asm volatile("s_waitcnt vmcnt(" #n ")" ::: "memory")
; #define WAIT_L(n) asm volatile("s_waitcnt lgkmcnt(" #n ")" ::: "memory")
; #define BAR __builtin_amdgcn_s_barrier()
; #define SCHED __builtin_amdgcn_sched_barrier(0)
; template <class Get, class Epi>
; DI void gemm_loop(int ntiles, int ld, char* shm, const Get& get, const Epi& epi) {
;     ...
;             WAIT_V(8); WAIT_L(0); BAR; G_MMA(1, 0, At, B0); G_MMA(1, 1, At, B1); BAR; SCHED;
;             G_LDB(B0, 1, 0); G_LDB(B1, 1, 1); SCHED; G_LDA(At, 1, 0); G_STAGE(G_SA(0, 1), a2 + hstep, voffA);
;             WAIT_V(8); WAIT_L(0); BAR; G_MMA(0, 0, At, B0); G_MMA(0, 1, At, B1); BAR; SCHED;
	s_setprio 1
	s_waitcnt lgkmcnt(0)
	v_mfma_f32_16x16x32_bf16 v[92:95], v[96:99], v[184:187], v[92:95]
	v_mfma_f32_16x16x32_bf16 v[84:87], v[150:153], v[184:187], v[84:87]
	v_mfma_f32_16x16x32_bf16 v[88:91], v[96:99], v[192:195], v[88:91]
	v_mfma_f32_16x16x32_bf16 v[80:83], v[150:153], v[192:195], v[80:83]
	v_mfma_f32_16x16x32_bf16 v[76:79], v[96:99], v[200:203], v[76:79]
	v_mfma_f32_16x16x32_bf16 v[68:71], v[150:153], v[200:203], v[68:71]
	v_mfma_f32_16x16x32_bf16 v[72:75], v[96:99], v[208:211], v[72:75]
	v_mfma_f32_16x16x32_bf16 v[64:67], v[150:153], v[208:211], v[64:67]
	v_mfma_f32_16x16x32_bf16 v[92:95], v[108:111], v[188:191], v[92:95]
	v_mfma_f32_16x16x32_bf16 v[84:87], v[154:157], v[188:191], v[84:87]
	v_mfma_f32_16x16x32_bf16 v[88:91], v[108:111], v[196:199], v[88:91]
	v_mfma_f32_16x16x32_bf16 v[80:83], v[154:157], v[196:199], v[80:83]
	v_mfma_f32_16x16x32_bf16 v[76:79], v[108:111], v[204:207], v[76:79]
	v_mfma_f32_16x16x32_bf16 v[68:71], v[154:157], v[204:207], v[68:71]
	v_mfma_f32_16x16x32_bf16 v[72:75], v[108:111], v[212:215], v[72:75]
	v_mfma_f32_16x16x32_bf16 v[64:67], v[154:157], v[212:215], v[64:67]
	s_setprio 0
	s_setprio 1
	v_mfma_f32_16x16x32_bf16 v[28:31], v[158:161], v[184:187], v[28:31]
	v_mfma_f32_16x16x32_bf16 v[20:23], v[166:169], v[184:187], v[20:23]
	v_mfma_f32_16x16x32_bf16 v[24:27], v[158:161], v[192:195], v[24:27]
	v_mfma_f32_16x16x32_bf16 v[16:19], v[166:169], v[192:195], v[16:19]
	v_mfma_f32_16x16x32_bf16 v[12:15], v[158:161], v[200:203], v[12:15]
	v_mfma_f32_16x16x32_bf16 v[4:7], v[166:169], v[200:203], v[4:7]
	v_mfma_f32_16x16x32_bf16 v[8:11], v[158:161], v[208:211], v[8:11]
	v_mfma_f32_16x16x32_bf16 v[0:3], v[166:169], v[208:211], v[0:3]
	v_mfma_f32_16x16x32_bf16 v[28:31], v[162:165], v[188:191], v[28:31]
	v_mfma_f32_16x16x32_bf16 v[20:23], v[180:183], v[188:191], v[20:23]
	v_mfma_f32_16x16x32_bf16 v[24:27], v[162:165], v[196:199], v[24:27]
	v_mfma_f32_16x16x32_bf16 v[16:19], v[180:183], v[196:199], v[16:19]
	v_mfma_f32_16x16x32_bf16 v[12:15], v[162:165], v[204:207], v[12:15]
	v_mfma_f32_16x16x32_bf16 v[4:7], v[180:183], v[204:207], v[4:7]
	v_mfma_f32_16x16x32_bf16 v[8:11], v[162:165], v[212:215], v[8:11]
	v_mfma_f32_16x16x32_bf16 v[0:3], v[180:183], v[212:215], v[0:3]
	s_setprio 0
	s_barrier
	s_add_i32 s57, 0, 0x18000
	v_add_u32_e32 v144, s57, v172
	s_add_i32 s58, 0, 0x1c000
	ds_read_b128 v[96:99], v144
	ds_read_b128 v[108:111], v144 offset:1024
	ds_read_b128 v[150:153], v144 offset:2048
	ds_read_b128 v[154:157], v144 offset:3072
	v_add_u32_e32 v144, s58, v172
	ds_read_b128 v[158:161], v144
	ds_read_b128 v[162:165], v144 offset:1024
	ds_read_b128 v[166:169], v144 offset:2048
	ds_read_b128 v[180:183], v144 offset:3072
	s_add_u32 s14, s14, 0x40000
	s_addc_u32 s15, s15, 0
	s_mov_b32 m0, s71
	v_lshl_add_u64 v[222:223], s[14:15], 0, v[142:143]
	ds_read_b128 v[184:187], v175 offset:32768
	ds_read_b128 v[188:191], v175 offset:33792
	ds_read_b128 v[192:195], v175 offset:34816
	ds_read_b128 v[196:199], v175 offset:35840
	ds_read_b128 v[200:203], v175 offset:36864
	ds_read_b128 v[204:207], v175 offset:37888
	ds_read_b128 v[208:211], v175 offset:38912
	ds_read_b128 v[212:215], v175 offset:39936
	global_load_lds_dwordx4 v[222:223], off
	v_lshl_add_u64 v[222:223], s[14:15], 0, v[138:139]
	s_mov_b32 m0, s72
	s_nop 0
	global_load_lds_dwordx4 v[222:223], off
	s_mov_b32 m0, s50
	s_nop 0
	global_load_lds_dwordx4 v[218:219], off
	s_mov_b32 m0, s51
	s_nop 0
	global_load_lds_dwordx4 v[220:221], off
	s_waitcnt vmcnt(8)
	s_waitcnt lgkmcnt(0)
	s_barrier
; #define G_STAGE(bufoff, gbase, voff) do { _Pragma("unroll") for (int _i = 0; _i < 2; ++_i) \
;         __builtin_amdgcn_global_load_lds((const unsigned*)((const char*)(gbase) + voff[_i]), (LAS unsigned*)(lds + (bufoff) + ldsw + _i * 8192), 16, 0, 0); } while (0)
; #define G_LDA(dst, b, h) do { _Pragma("unroll") for (int m = 0; m < 4; ++m) _Pragma("unroll") for (int k = 0; k < 2; ++k) dst[m][k] = *(const LAS bf16x8*)(lds + G_SA(b, h) + aoff + m * 2048 + k * 1024); } while (0)
; #define G_MMA(ai, bj, At_, Bt_) do { __builtin_amdgcn_s_setprio(1); _Pragma("unroll") for (int m = 0; m < 4; ++m) _Pragma("unroll") for (int n = 0; n < 2; ++n) _Pragma("unroll") for (int k = 0; k < 2; ++k) \
;         acc[ai][bj][m][n] = __builtin_amdgcn_mfma_f32_16x16x32_bf16(Bt_[n][k], At_[m][k], acc[ai][bj][m][n], 0, 0, 0); __builtin_amdgcn_s_setprio(0); } while (0)
; #define WAIT_V(n) asm volatile("s_waitcnt vmcnt(" #n ")" ::: "memory")
; #define WAIT_L(n) asm volatile("s_waitcnt lgkmcnt(" #n ")" ::: "memory")
; #define BAR __builtin_amdgcn_s_barrier()
; #define SCHED __builtin_amdgcn_sched_barrier(0)
; template <class Get, class Epi>
; DI void gemm_loop(int ntiles, int ld, char* shm, const Get& get, const Epi& epi) {
;     ...
;             WAIT_V(8); WAIT_L(0); BAR; G_MMA(0, 0, At, B0); G_MMA(0, 1, At, B1); BAR; SCHED;
;             G_LDA(At, 1, 1); G_STAGE(G_SB(1, 0), b3, voffB); G_STAGE(G_SB(1, 1), b3 + hstep, voffB); G_STAGE(G_SA(1, 0), a3, voffA);
;             WAIT_V(8); WAIT_L(0); BAR; G_MMA(1, 0, At, B0); G_MMA(1, 1, At, B1); BAR; SCHED;
;         }
;         if (wr == 0) BAR;
	s_setprio 1
	s_waitcnt lgkmcnt(0)
	v_mfma_f32_16x16x32_bf16 v[132:135], v[96:99], v[184:187], v[132:135]
	v_mfma_f32_16x16x32_bf16 v[124:127], v[150:153], v[184:187], v[124:127]
	v_mfma_f32_16x16x32_bf16 v[128:131], v[96:99], v[192:195], v[128:131]
	v_mfma_f32_16x16x32_bf16 v[120:123], v[150:153], v[192:195], v[120:123]
	v_mfma_f32_16x16x32_bf16 v[116:119], v[96:99], v[200:203], v[116:119]
	v_mfma_f32_16x16x32_bf16 v[104:107], v[150:153], v[200:203], v[104:107]
	v_mfma_f32_16x16x32_bf16 v[112:115], v[96:99], v[208:211], v[112:115]
	v_mfma_f32_16x16x32_bf16 v[100:103], v[150:153], v[208:211], v[100:103]
	v_mfma_f32_16x16x32_bf16 v[132:135], v[108:111], v[188:191], v[132:135]
	v_mfma_f32_16x16x32_bf16 v[124:127], v[154:157], v[188:191], v[124:127]
	v_mfma_f32_16x16x32_bf16 v[128:131], v[108:111], v[196:199], v[128:131]
	v_mfma_f32_16x16x32_bf16 v[120:123], v[154:157], v[196:199], v[120:123]
	v_mfma_f32_16x16x32_bf16 v[116:119], v[108:111], v[204:207], v[116:119]
	v_mfma_f32_16x16x32_bf16 v[104:107], v[154:157], v[204:207], v[104:107]
	v_mfma_f32_16x16x32_bf16 v[112:115], v[108:111], v[212:215], v[112:115]
	v_mfma_f32_16x16x32_bf16 v[100:103], v[154:157], v[212:215], v[100:103]
	s_setprio 0
	s_setprio 1
	v_mfma_f32_16x16x32_bf16 v[60:63], v[158:161], v[184:187], v[60:63]
	v_mfma_f32_16x16x32_bf16 v[52:55], v[166:169], v[184:187], v[52:55]
	v_mfma_f32_16x16x32_bf16 v[56:59], v[158:161], v[192:195], v[56:59]
	v_mfma_f32_16x16x32_bf16 v[48:51], v[166:169], v[192:195], v[48:51]
	v_mfma_f32_16x16x32_bf16 v[44:47], v[158:161], v[200:203], v[44:47]
	v_mfma_f32_16x16x32_bf16 v[36:39], v[166:169], v[200:203], v[36:39]
	v_mfma_f32_16x16x32_bf16 v[40:43], v[158:161], v[208:211], v[40:43]
	v_mfma_f32_16x16x32_bf16 v[32:35], v[166:169], v[208:211], v[32:35]
	v_mfma_f32_16x16x32_bf16 v[60:63], v[162:165], v[188:191], v[60:63]
	v_mfma_f32_16x16x32_bf16 v[52:55], v[180:183], v[188:191], v[52:55]
	v_mfma_f32_16x16x32_bf16 v[56:59], v[162:165], v[196:199], v[56:59]
	v_mfma_f32_16x16x32_bf16 v[48:51], v[180:183], v[196:199], v[48:51]
	v_mfma_f32_16x16x32_bf16 v[44:47], v[162:165], v[204:207], v[44:47]
	v_mfma_f32_16x16x32_bf16 v[36:39], v[180:183], v[204:207], v[36:39]
	v_mfma_f32_16x16x32_bf16 v[40:43], v[162:165], v[212:215], v[40:43]
	v_mfma_f32_16x16x32_bf16 v[32:35], v[180:183], v[212:215], v[32:35]
	s_setprio 0
	s_barrier
	s_add_i32 s14, s57, s46
	v_lshl_add_u64 v[170:171], v[170:171], 0, s[10:11]
	s_mov_b32 m0, s14
	ds_read_b128 v[184:187], v175 offset:49152
	ds_read_b128 v[188:191], v175 offset:50176
	ds_read_b128 v[192:195], v175 offset:51200
	ds_read_b128 v[196:199], v175 offset:52224
	ds_read_b128 v[200:203], v175 offset:53248
	ds_read_b128 v[204:207], v175 offset:54272
	ds_read_b128 v[208:211], v175 offset:55296
	ds_read_b128 v[212:215], v175 offset:56320
	global_load_lds_dwordx4 v[170:171], off
	s_add_i32 m0, s14, 0x2000
	s_add_u32 s6, s6, 0x40080
	v_lshl_add_u64 v[170:171], v[216:217], 0, s[10:11]
	s_addc_u32 s7, s7, 0
	s_add_i32 s14, s58, s46
	global_load_lds_dwordx4 v[170:171], off
	v_lshl_add_u64 v[170:171], s[6:7], 0, v[140:141]
	s_mov_b32 m0, s14
	s_nop 0
	global_load_lds_dwordx4 v[170:171], off
	v_lshl_add_u64 v[170:171], s[6:7], 0, v[136:137]
	s_add_i32 m0, s14, 0x2000
	s_nop 0
	global_load_lds_dwordx4 v[170:171], off
	s_waitcnt vmcnt(4)
	s_waitcnt lgkmcnt(0)
	s_barrier
	s_setprio 1
	s_waitcnt lgkmcnt(0)
	v_mfma_f32_16x16x32_bf16 v[92:95], v[96:99], v[184:187], v[92:95]
	v_mfma_f32_16x16x32_bf16 v[84:87], v[150:153], v[184:187], v[84:87]
	v_mfma_f32_16x16x32_bf16 v[88:91], v[96:99], v[192:195], v[88:91]
	v_mfma_f32_16x16x32_bf16 v[80:83], v[150:153], v[192:195], v[80:83]
	v_mfma_f32_16x16x32_bf16 v[76:79], v[96:99], v[200:203], v[76:79]
	v_mfma_f32_16x16x32_bf16 v[68:71], v[150:153], v[200:203], v[68:71]
	v_mfma_f32_16x16x32_bf16 v[72:75], v[96:99], v[208:211], v[72:75]
	v_mfma_f32_16x16x32_bf16 v[64:67], v[150:153], v[208:211], v[64:67]
	v_mfma_f32_16x16x32_bf16 v[92:95], v[108:111], v[188:191], v[92:95]
	v_mfma_f32_16x16x32_bf16 v[84:87], v[154:157], v[188:191], v[84:87]
	v_mfma_f32_16x16x32_bf16 v[88:91], v[108:111], v[196:199], v[88:91]
	v_mfma_f32_16x16x32_bf16 v[80:83], v[154:157], v[196:199], v[80:83]
	v_mfma_f32_16x16x32_bf16 v[76:79], v[108:111], v[204:207], v[76:79]
	v_mfma_f32_16x16x32_bf16 v[68:71], v[154:157], v[204:207], v[68:71]
	v_mfma_f32_16x16x32_bf16 v[72:75], v[108:111], v[212:215], v[72:75]
	v_mfma_f32_16x16x32_bf16 v[64:67], v[154:157], v[212:215], v[64:67]
	s_setprio 0
	s_setprio 1
	v_mfma_f32_16x16x32_bf16 v[28:31], v[158:161], v[184:187], v[28:31]
	v_mfma_f32_16x16x32_bf16 v[20:23], v[166:169], v[184:187], v[20:23]
	v_mfma_f32_16x16x32_bf16 v[24:27], v[158:161], v[192:195], v[24:27]
	v_mfma_f32_16x16x32_bf16 v[16:19], v[166:169], v[192:195], v[16:19]
	v_mfma_f32_16x16x32_bf16 v[12:15], v[158:161], v[200:203], v[12:15]
	v_mfma_f32_16x16x32_bf16 v[4:7], v[166:169], v[200:203], v[4:7]
	v_mfma_f32_16x16x32_bf16 v[8:11], v[158:161], v[208:211], v[8:11]
	v_mfma_f32_16x16x32_bf16 v[0:3], v[166:169], v[208:211], v[0:3]
	v_mfma_f32_16x16x32_bf16 v[28:31], v[162:165], v[188:191], v[28:31]
	v_mfma_f32_16x16x32_bf16 v[20:23], v[180:183], v[188:191], v[20:23]
	v_mfma_f32_16x16x32_bf16 v[24:27], v[162:165], v[196:199], v[24:27]
	v_mfma_f32_16x16x32_bf16 v[16:19], v[180:183], v[196:199], v[16:19]
	v_mfma_f32_16x16x32_bf16 v[12:15], v[162:165], v[204:207], v[12:15]
	v_mfma_f32_16x16x32_bf16 v[4:7], v[180:183], v[204:207], v[4:7]
	v_mfma_f32_16x16x32_bf16 v[8:11], v[162:165], v[212:215], v[8:11]
	v_mfma_f32_16x16x32_bf16 v[0:3], v[180:183], v[212:215], v[0:3]
	s_setprio 0
	s_barrier
	s_add_i32 s56, s56, 2
	s_add_u32 s4, s4, 0x100
	s_addc_u32 s5, s5, 0
	s_add_u32 s54, s54, 0x100
	s_addc_u32 s55, s55, 0
	s_cmp_gt_u32 s56, 13
	s_cbranch_scc0 .LBB0_2022
	s_and_b64 vcc, exec, s[36:37]
	s_cbranch_vccz .LBB0_2025
	s_barrier

; #define G_STAGE(bufoff, gbase, voff) do { _Pragma("unroll") for (int _i = 0; _i < 2; ++_i) \
;         __builtin_amdgcn_global_load_lds((const unsigned*)((const char*)(gbase) + voff[_i]), (LAS unsigned*)(lds + (bufoff) + ldsw + _i * 8192), 16, 0, 0); } while (0)
; #define G_LDA(dst, b, h) do { _Pragma("unroll") for (int m = 0; m < 4; ++m) _Pragma("unroll") for (int k = 0; k < 2; ++k) dst[m][k] = *(const LAS bf16x8*)(lds + G_SA(b, h) + aoff + m * 2048 + k * 1024); } while (0)
; #define G_LDB(dst, b, h) do { _Pragma("unroll") for (int n = 0; n < 2; ++n) _Pragma("unroll") for (int k = 0; k < 2; ++k) dst[n][k] = *(const LAS bf16x8*)(lds + G_SB(b, h) + boff + n * 2048 + k * 1024); } while (0)
; #define G_MMA(ai, bj, At_, Bt_) do { __builtin_amdgcn_s_setprio(1); _Pragma("unroll") for (int m = 0; m < 4; ++m) _Pragma("unroll") for (int n = 0; n < 2; ++n) _Pragma("unroll") for (int k = 0; k < 2; ++k) \
;         acc[ai][bj][m][n] = __builtin_amdgcn_mfma_f32_16x16x32_bf16(Bt_[n][k], At_[m][k], acc[ai][bj][m][n], 0, 0, 0); __builtin_amdgcn_s_setprio(0); } while (0)
; #define WAIT_V(n) asm volatile("s_waitcnt vmcnt(" #n ")" ::: "memory")
; #define WAIT_L(n) asm volatile("s_waitcnt lgkmcnt(" #n ")" ::: "memory")
; #define BAR __builtin_amdgcn_s_barrier()
; #define SCHED __builtin_amdgcn_sched_barrier(0)
; template <class Get, class Epi>
; DI void gemm_loop(int ntiles, int ld, char* shm, const Get& get, const Epi& epi) {
;     ...
;         for (int t = 0; t < nt; t += 2) {
;             const bool last = (t == nt - 2);
;             const char* a1 = cA + (size_t)(t + 1) * kstep;
;             const char* a2 = last ? nA : cA + (size_t)(t + 2) * kstep; const char* b2 = last ? nB : cB + (size_t)(t + 2) * kstep;
;             const char* a3 = a2 + kstep; const char* b3 = b2 + kstep;
;             G_LDB(B0, 0, 0); G_LDB(B1, 0, 1); SCHED; G_LDA(At, 0, 0); G_STAGE(G_SA(1, 1), a1 + hstep, voffA);
;             WAIT_V(8); WAIT_L(0); BAR; G_MMA(0, 0, At, B0); G_MMA(0, 1, At, B1); BAR; SCHED;
;             G_LDA(At, 0, 1); G_STAGE(G_SB(0, 0), b2, voffB); G_STAGE(G_SB(0, 1), b2 + hstep, voffB); G_STAGE(G_SA(0, 0), a2, voffA);
;             WAIT_V(8); WAIT_L(0); BAR; G_MMA(1, 0, At, B0); G_MMA(1, 1, At, B1); BAR; SCHED;
.LBB0_2574:
	ds_read_b128 v[128:131], v169
	ds_read_b128 v[132:135], v169 offset:1024
	ds_read_b128 v[136:139], v169 offset:2048
	ds_read_b128 v[140:143], v169 offset:3072
	ds_read_b128 v[158:161], v170
	ds_read_b128 v[162:165], v170 offset:1024
	ds_read_b128 v[172:175], v170 offset:2048
	ds_read_b128 v[176:179], v170 offset:3072
	s_add_i32 s82, s14, 2
	s_add_u32 s15, s52, 0xfffc0080
	s_addc_u32 s46, s53, -1
	s_cmp_eq_u32 s79, s14
	s_cselect_b32 s14, s77, s80
	s_cselect_b32 s47, s3, s46
	s_cselect_b32 s46, s41, s15
	s_cselect_b32 s15, s43, s81
	v_lshl_add_u64 v[144:145], s[52:53], 0, v[154:155]
	s_add_i32 m0, s51, 0xc000
	ds_read_b128 v[180:183], v171
	ds_read_b128 v[184:187], v171 offset:1024
	ds_read_b128 v[188:191], v171 offset:2048
	ds_read_b128 v[192:195], v171 offset:3072
	ds_read_b128 v[196:199], v171 offset:4096
	ds_read_b128 v[200:203], v171 offset:5120
	ds_read_b128 v[204:207], v171 offset:6144
	ds_read_b128 v[208:211], v171 offset:7168
	global_load_lds_dwordx4 v[144:145], off
	v_lshl_add_u64 v[144:145], s[52:53], 0, v[156:157]
	s_add_i32 m0, s51, 0xe000
	s_nop 0
	global_load_lds_dwordx4 v[144:145], off
	s_mov_b32 s98, 0xfffc0000
	s_mov_b32 s99, -1
	v_lshl_add_u64 v[144:145], s[52:53], 0, v[154:155]
	v_lshl_add_u64 v[144:145], v[144:145], 0, s[98:99]
	s_add_i32 m0, s51, 0x8000
	s_nop 0
	global_load_lds_dwordx4 v[144:145], off
	v_lshl_add_u64 v[144:145], s[52:53], 0, v[156:157]
	v_lshl_add_u64 v[144:145], v[144:145], 0, s[98:99]
	s_add_i32 m0, s51, 0xa000
	s_nop 0
	global_load_lds_dwordx4 v[144:145], off
	s_waitcnt vmcnt(8)
	s_waitcnt lgkmcnt(0)
	s_barrier
	s_setprio 1
	s_waitcnt lgkmcnt(0)
	v_mfma_f32_16x16x32_bf16 v[124:127], v[128:131], v[180:183], v[124:127]
	v_mfma_f32_16x16x32_bf16 v[120:123], v[136:139], v[180:183], v[120:123]
	v_mfma_f32_16x16x32_bf16 v[116:119], v[128:131], v[188:191], v[116:119]
	v_mfma_f32_16x16x32_bf16 v[112:115], v[136:139], v[188:191], v[112:115]
	v_mfma_f32_16x16x32_bf16 v[108:111], v[128:131], v[196:199], v[108:111]
	v_mfma_f32_16x16x32_bf16 v[104:107], v[136:139], v[196:199], v[104:107]
	v_mfma_f32_16x16x32_bf16 v[100:103], v[128:131], v[204:207], v[100:103]
	v_mfma_f32_16x16x32_bf16 v[96:99], v[136:139], v[204:207], v[96:99]
	v_mfma_f32_16x16x32_bf16 v[124:127], v[132:135], v[184:187], v[124:127]
	v_mfma_f32_16x16x32_bf16 v[120:123], v[140:143], v[184:187], v[120:123]
	v_mfma_f32_16x16x32_bf16 v[116:119], v[132:135], v[192:195], v[116:119]
	v_mfma_f32_16x16x32_bf16 v[112:115], v[140:143], v[192:195], v[112:115]
	v_mfma_f32_16x16x32_bf16 v[108:111], v[132:135], v[200:203], v[108:111]
	v_mfma_f32_16x16x32_bf16 v[104:107], v[140:143], v[200:203], v[104:107]
	v_mfma_f32_16x16x32_bf16 v[100:103], v[132:135], v[208:211], v[100:103]
	v_mfma_f32_16x16x32_bf16 v[96:99], v[140:143], v[208:211], v[96:99]
	s_setprio 0
	s_setprio 1
	v_mfma_f32_16x16x32_bf16 v[60:63], v[158:161], v[180:183], v[60:63]
	v_mfma_f32_16x16x32_bf16 v[56:59], v[172:175], v[180:183], v[56:59]
	v_mfma_f32_16x16x32_bf16 v[52:55], v[158:161], v[188:191], v[52:55]
	v_mfma_f32_16x16x32_bf16 v[48:51], v[172:175], v[188:191], v[48:51]
	v_mfma_f32_16x16x32_bf16 v[44:47], v[158:161], v[196:199], v[44:47]
	v_mfma_f32_16x16x32_bf16 v[40:43], v[172:175], v[196:199], v[40:43]
	v_mfma_f32_16x16x32_bf16 v[36:39], v[158:161], v[204:207], v[36:39]
	v_mfma_f32_16x16x32_bf16 v[32:35], v[172:175], v[204:207], v[32:35]
	v_mfma_f32_16x16x32_bf16 v[60:63], v[162:165], v[184:187], v[60:63]
	v_mfma_f32_16x16x32_bf16 v[56:59], v[176:179], v[184:187], v[56:59]
	v_mfma_f32_16x16x32_bf16 v[52:55], v[162:165], v[192:195], v[52:55]
	v_mfma_f32_16x16x32_bf16 v[48:51], v[176:179], v[192:195], v[48:51]
	v_mfma_f32_16x16x32_bf16 v[44:47], v[162:165], v[200:203], v[44:47]
	v_mfma_f32_16x16x32_bf16 v[40:43], v[176:179], v[200:203], v[40:43]
	v_mfma_f32_16x16x32_bf16 v[36:39], v[162:165], v[208:211], v[36:39]
	v_mfma_f32_16x16x32_bf16 v[32:35], v[176:179], v[208:211], v[32:35]
	s_setprio 0
	s_barrier
	s_add_i32 s83, s72, s31
	v_lshl_add_u64 v[144:145], s[14:15], 0, v[148:149]
	s_mov_b32 m0, s83
	ds_read_b128 v[180:183], v171 offset:16384
	ds_read_b128 v[184:187], v171 offset:17408
	ds_read_b128 v[188:191], v171 offset:18432
	ds_read_b128 v[192:195], v171 offset:19456
	ds_read_b128 v[196:199], v171 offset:20480
	ds_read_b128 v[200:203], v171 offset:21504
	ds_read_b128 v[204:207], v171 offset:22528
	ds_read_b128 v[208:211], v171 offset:23552
	global_load_lds_dwordx4 v[144:145], off
	s_add_i32 m0, s83, 0x2000
	s_add_u32 s84, s14, 0x40000
	v_lshl_add_u64 v[166:167], s[14:15], 0, v[152:153]
	s_addc_u32 s85, s15, 0
	s_add_i32 s83, s73, s31
	global_load_lds_dwordx4 v[166:167], off
	v_lshl_add_u64 v[212:213], s[84:85], 0, v[148:149]
	s_mov_b32 m0, s83
	v_lshl_add_u64 v[214:215], s[46:47], 0, v[150:151]
	global_load_lds_dwordx4 v[212:213], off
	v_lshl_add_u64 v[212:213], s[84:85], 0, v[152:153]
	s_add_i32 m0, s83, 0x2000
	s_nop 0
	global_load_lds_dwordx4 v[212:213], off
	v_lshl_add_u64 v[212:213], s[46:47], 0, v[146:147]
	s_waitcnt vmcnt(4)
	s_waitcnt lgkmcnt(0)
	s_barrier
; #define G_STAGE(bufoff, gbase, voff) do { _Pragma("unroll") for (int _i = 0; _i < 2; ++_i) \
;         __builtin_amdgcn_global_load_lds((const unsigned*)((const char*)(gbase) + voff[_i]), (LAS unsigned*)(lds + (bufoff) + ldsw + _i * 8192), 16, 0, 0); } while (0)
; #define G_LDA(dst, b, h) do { _Pragma("unroll") for (int m = 0; m < 4; ++m) _Pragma("unroll") for (int k = 0; k < 2; ++k) dst[m][k] = *(const LAS bf16x8*)(lds + G_SA(b, h) + aoff + m * 2048 + k * 1024); } while (0)
; #define G_LDB(dst, b, h) do { _Pragma("unroll") for (int n = 0; n < 2; ++n) _Pragma("unroll") for (int k = 0; k < 2; ++k) dst[n][k] = *(const LAS bf16x8*)(lds + G_SB(b, h) + boff + n * 2048 + k * 1024); } while (0)
; #define G_MMA(ai, bj, At_, Bt_) do { __builtin_amdgcn_s_setprio(1); _Pragma("unroll") for (int m = 0; m < 4; ++m) _Pragma("unroll") for (int n = 0; n < 2; ++n) _Pragma("unroll") for (int k = 0; k < 2; ++k) \
;         acc[ai][bj][m][n] = __builtin_amdgcn_mfma_f32_16x16x32_bf16(Bt_[n][k], At_[m][k], acc[ai][bj][m][n], 0, 0, 0); __builtin_amdgcn_s_setprio(0); } while (0)
; #define WAIT_V(n) asm volatile("s_waitcnt vmcnt(" #n ")" ::: "memory")
; #define WAIT_L(n) asm volatile("s_waitcnt lgkmcnt(" #n ")" ::: "memory")
; #define BAR __builtin_amdgcn_s_barrier()
; #define SCHED __builtin_amdgcn_sched_barrier(0)
; template <class Get, class Epi>
; DI void gemm_loop(int ntiles, int ld, char* shm, const Get& get, const Epi& epi) {
;     ...
;             WAIT_V(8); WAIT_L(0); BAR; G_MMA(1, 0, At, B0); G_MMA(1, 1, At, B1); BAR; SCHED;
;             G_LDB(B0, 1, 0); G_LDB(B1, 1, 1); SCHED; G_LDA(At, 1, 0); G_STAGE(G_SA(0, 1), a2 + hstep, voffA);
;             WAIT_V(8); WAIT_L(0); BAR; G_MMA(0, 0, At, B0); G_MMA(0, 1, At, B1); BAR; SCHED;
	s_setprio 1
	s_waitcnt lgkmcnt(0)
	v_mfma_f32_16x16x32_bf16 v[92:95], v[128:131], v[180:183], v[92:95]
	v_mfma_f32_16x16x32_bf16 v[88:91], v[136:139], v[180:183], v[88:91]
	v_mfma_f32_16x16x32_bf16 v[84:87], v[128:131], v[188:191], v[84:87]
	v_mfma_f32_16x16x32_bf16 v[80:83], v[136:139], v[188:191], v[80:83]
	v_mfma_f32_16x16x32_bf16 v[76:79], v[128:131], v[196:199], v[76:79]
	v_mfma_f32_16x16x32_bf16 v[72:75], v[136:139], v[196:199], v[72:75]
	v_mfma_f32_16x16x32_bf16 v[68:71], v[128:131], v[204:207], v[68:71]
	v_mfma_f32_16x16x32_bf16 v[64:67], v[136:139], v[204:207], v[64:67]
	v_mfma_f32_16x16x32_bf16 v[92:95], v[132:135], v[184:187], v[92:95]
	v_mfma_f32_16x16x32_bf16 v[88:91], v[140:143], v[184:187], v[88:91]
	v_mfma_f32_16x16x32_bf16 v[84:87], v[132:135], v[192:195], v[84:87]
	v_mfma_f32_16x16x32_bf16 v[80:83], v[140:143], v[192:195], v[80:83]
	v_mfma_f32_16x16x32_bf16 v[76:79], v[132:135], v[200:203], v[76:79]
	v_mfma_f32_16x16x32_bf16 v[72:75], v[140:143], v[200:203], v[72:75]
	v_mfma_f32_16x16x32_bf16 v[68:71], v[132:135], v[208:211], v[68:71]
	v_mfma_f32_16x16x32_bf16 v[64:67], v[140:143], v[208:211], v[64:67]
	s_setprio 0
	s_setprio 1
	v_mfma_f32_16x16x32_bf16 v[28:31], v[158:161], v[180:183], v[28:31]
	v_mfma_f32_16x16x32_bf16 v[24:27], v[172:175], v[180:183], v[24:27]
	v_mfma_f32_16x16x32_bf16 v[20:23], v[158:161], v[188:191], v[20:23]
	v_mfma_f32_16x16x32_bf16 v[16:19], v[172:175], v[188:191], v[16:19]
	v_mfma_f32_16x16x32_bf16 v[12:15], v[158:161], v[196:199], v[12:15]
	v_mfma_f32_16x16x32_bf16 v[8:11], v[172:175], v[196:199], v[8:11]
	v_mfma_f32_16x16x32_bf16 v[4:7], v[158:161], v[204:207], v[4:7]
	v_mfma_f32_16x16x32_bf16 v[0:3], v[172:175], v[204:207], v[0:3]
	v_mfma_f32_16x16x32_bf16 v[28:31], v[162:165], v[184:187], v[28:31]
	v_mfma_f32_16x16x32_bf16 v[24:27], v[176:179], v[184:187], v[24:27]
	v_mfma_f32_16x16x32_bf16 v[20:23], v[162:165], v[192:195], v[20:23]
	v_mfma_f32_16x16x32_bf16 v[16:19], v[176:179], v[192:195], v[16:19]
	v_mfma_f32_16x16x32_bf16 v[12:15], v[162:165], v[200:203], v[12:15]
	v_mfma_f32_16x16x32_bf16 v[8:11], v[176:179], v[200:203], v[8:11]
	v_mfma_f32_16x16x32_bf16 v[4:7], v[162:165], v[208:211], v[4:7]
	v_mfma_f32_16x16x32_bf16 v[0:3], v[176:179], v[208:211], v[0:3]
	s_setprio 0
	s_barrier
	s_add_i32 s83, 0, 0x18000
	s_add_i32 s84, 0, 0x1c000
	v_add_u32_e32 v140, s83, v168
	v_add_u32_e32 v176, s84, v168
	ds_read_b128 v[128:131], v140
	ds_read_b128 v[132:135], v140 offset:1024
	ds_read_b128 v[136:139], v140 offset:2048
	ds_read_b128 v[140:143], v140 offset:3072
	ds_read_b128 v[158:161], v176
	ds_read_b128 v[162:165], v176 offset:1024
	ds_read_b128 v[172:175], v176 offset:2048
	ds_read_b128 v[176:179], v176 offset:3072
	s_add_u32 s46, s46, 0x40000
	s_addc_u32 s47, s47, 0
	s_mov_b32 m0, s55
	v_lshl_add_u64 v[216:217], s[46:47], 0, v[146:147]
	ds_read_b128 v[180:183], v171 offset:32768
	ds_read_b128 v[184:187], v171 offset:33792
	ds_read_b128 v[188:191], v171 offset:34816
	ds_read_b128 v[192:195], v171 offset:35840
	ds_read_b128 v[196:199], v171 offset:36864
	ds_read_b128 v[200:203], v171 offset:37888
	ds_read_b128 v[204:207], v171 offset:38912
	ds_read_b128 v[208:211], v171 offset:39936
	global_load_lds_dwordx4 v[216:217], off
	v_lshl_add_u64 v[216:217], s[46:47], 0, v[150:151]
	s_mov_b32 m0, s56
	s_nop 0
	global_load_lds_dwordx4 v[216:217], off
	s_mov_b32 m0, s51
	s_nop 0
	global_load_lds_dwordx4 v[212:213], off
	s_mov_b32 m0, s54
	s_nop 0
	global_load_lds_dwordx4 v[214:215], off
	s_waitcnt vmcnt(8)
	s_waitcnt lgkmcnt(0)
	s_barrier
; #define G_STAGE(bufoff, gbase, voff) do { _Pragma("unroll") for (int _i = 0; _i < 2; ++_i) \
;         __builtin_amdgcn_global_load_lds((const unsigned*)((const char*)(gbase) + voff[_i]), (LAS unsigned*)(lds + (bufoff) + ldsw + _i * 8192), 16, 0, 0); } while (0)
; #define G_LDA(dst, b, h) do { _Pragma("unroll") for (int m = 0; m < 4; ++m) _Pragma("unroll") for (int k = 0; k < 2; ++k) dst[m][k] = *(const LAS bf16x8*)(lds + G_SA(b, h) + aoff + m * 2048 + k * 1024); } while (0)
; #define G_MMA(ai, bj, At_, Bt_) do { __builtin_amdgcn_s_setprio(1); _Pragma("unroll") for (int m = 0; m < 4; ++m) _Pragma("unroll") for (int n = 0; n < 2; ++n) _Pragma("unroll") for (int k = 0; k < 2; ++k) \
;         acc[ai][bj][m][n] = __builtin_amdgcn_mfma_f32_16x16x32_bf16(Bt_[n][k], At_[m][k], acc[ai][bj][m][n], 0, 0, 0); __builtin_amdgcn_s_setprio(0); } while (0)
; #define WAIT_V(n) asm volatile("s_waitcnt vmcnt(" #n ")" ::: "memory")
; #define WAIT_L(n) asm volatile("s_waitcnt lgkmcnt(" #n ")" ::: "memory")
; #define BAR __builtin_amdgcn_s_barrier()
; #define SCHED __builtin_amdgcn_sched_barrier(0)
; template <class Get, class Epi>
; DI void gemm_loop(int ntiles, int ld, char* shm, const Get& get, const Epi& epi) {
;     ...
;             WAIT_V(8); WAIT_L(0); BAR; G_MMA(0, 0, At, B0); G_MMA(0, 1, At, B1); BAR; SCHED;
;             G_LDA(At, 1, 1); G_STAGE(G_SB(1, 0), b3, voffB); G_STAGE(G_SB(1, 1), b3 + hstep, voffB); G_STAGE(G_SA(1, 0), a3, voffA);
;             WAIT_V(8); WAIT_L(0); BAR; G_MMA(1, 0, At, B0); G_MMA(1, 1, At, B1); BAR; SCHED;
;         }
;         if (wr == 0) BAR;
	s_setprio 1
	s_waitcnt lgkmcnt(0)
	v_mfma_f32_16x16x32_bf16 v[124:127], v[128:131], v[180:183], v[124:127]
	v_mfma_f32_16x16x32_bf16 v[120:123], v[136:139], v[180:183], v[120:123]
	v_mfma_f32_16x16x32_bf16 v[116:119], v[128:131], v[188:191], v[116:119]
	v_mfma_f32_16x16x32_bf16 v[112:115], v[136:139], v[188:191], v[112:115]
	v_mfma_f32_16x16x32_bf16 v[108:111], v[128:131], v[196:199], v[108:111]
	v_mfma_f32_16x16x32_bf16 v[104:107], v[136:139], v[196:199], v[104:107]
	v_mfma_f32_16x16x32_bf16 v[100:103], v[128:131], v[204:207], v[100:103]
	v_mfma_f32_16x16x32_bf16 v[96:99], v[136:139], v[204:207], v[96:99]
	v_mfma_f32_16x16x32_bf16 v[124:127], v[132:135], v[184:187], v[124:127]
	v_mfma_f32_16x16x32_bf16 v[120:123], v[140:143], v[184:187], v[120:123]
	v_mfma_f32_16x16x32_bf16 v[116:119], v[132:135], v[192:195], v[116:119]
	v_mfma_f32_16x16x32_bf16 v[112:115], v[140:143], v[192:195], v[112:115]
	v_mfma_f32_16x16x32_bf16 v[108:111], v[132:135], v[200:203], v[108:111]
	v_mfma_f32_16x16x32_bf16 v[104:107], v[140:143], v[200:203], v[104:107]
	v_mfma_f32_16x16x32_bf16 v[100:103], v[132:135], v[208:211], v[100:103]
	v_mfma_f32_16x16x32_bf16 v[96:99], v[140:143], v[208:211], v[96:99]
	s_setprio 0
	s_setprio 1
	v_mfma_f32_16x16x32_bf16 v[60:63], v[158:161], v[180:183], v[60:63]
	v_mfma_f32_16x16x32_bf16 v[56:59], v[172:175], v[180:183], v[56:59]
	v_mfma_f32_16x16x32_bf16 v[52:55], v[158:161], v[188:191], v[52:55]
	v_mfma_f32_16x16x32_bf16 v[48:51], v[172:175], v[188:191], v[48:51]
	v_mfma_f32_16x16x32_bf16 v[44:47], v[158:161], v[196:199], v[44:47]
	v_mfma_f32_16x16x32_bf16 v[40:43], v[172:175], v[196:199], v[40:43]
	v_mfma_f32_16x16x32_bf16 v[36:39], v[158:161], v[204:207], v[36:39]
	v_mfma_f32_16x16x32_bf16 v[32:35], v[172:175], v[204:207], v[32:35]
	v_mfma_f32_16x16x32_bf16 v[60:63], v[162:165], v[184:187], v[60:63]
	v_mfma_f32_16x16x32_bf16 v[56:59], v[176:179], v[184:187], v[56:59]
	v_mfma_f32_16x16x32_bf16 v[52:55], v[162:165], v[192:195], v[52:55]
	v_mfma_f32_16x16x32_bf16 v[48:51], v[176:179], v[192:195], v[48:51]
	v_mfma_f32_16x16x32_bf16 v[44:47], v[162:165], v[200:203], v[44:47]
	v_mfma_f32_16x16x32_bf16 v[40:43], v[176:179], v[200:203], v[40:43]
	v_mfma_f32_16x16x32_bf16 v[36:39], v[162:165], v[208:211], v[36:39]
	v_mfma_f32_16x16x32_bf16 v[32:35], v[176:179], v[208:211], v[32:35]
	s_setprio 0
	s_barrier
	s_add_i32 s46, s83, s31
	v_lshl_add_u64 v[144:145], v[144:145], 0, s[8:9]
	s_mov_b32 m0, s46
	ds_read_b128 v[180:183], v171 offset:49152
	ds_read_b128 v[184:187], v171 offset:50176
	ds_read_b128 v[188:191], v171 offset:51200
	ds_read_b128 v[192:195], v171 offset:52224
	ds_read_b128 v[196:199], v171 offset:53248
	ds_read_b128 v[200:203], v171 offset:54272
	ds_read_b128 v[204:207], v171 offset:55296
	ds_read_b128 v[208:211], v171 offset:56320
	global_load_lds_dwordx4 v[144:145], off
	s_add_i32 m0, s46, 0x2000
	s_add_u32 s14, s14, 0x40080
	v_lshl_add_u64 v[144:145], v[166:167], 0, s[8:9]
	s_addc_u32 s15, s15, 0
	s_add_i32 s46, s84, s31
	global_load_lds_dwordx4 v[144:145], off
	v_lshl_add_u64 v[144:145], s[14:15], 0, v[148:149]
	s_mov_b32 m0, s46
	s_nop 0
	global_load_lds_dwordx4 v[144:145], off
	v_lshl_add_u64 v[144:145], s[14:15], 0, v[152:153]
	s_add_i32 m0, s46, 0x2000
	s_nop 0
	global_load_lds_dwordx4 v[144:145], off
	s_waitcnt vmcnt(4)
	s_waitcnt lgkmcnt(0)
	s_barrier
	s_setprio 1
	s_waitcnt lgkmcnt(0)
	v_mfma_f32_16x16x32_bf16 v[92:95], v[128:131], v[180:183], v[92:95]
	v_mfma_f32_16x16x32_bf16 v[88:91], v[136:139], v[180:183], v[88:91]
	v_mfma_f32_16x16x32_bf16 v[84:87], v[128:131], v[188:191], v[84:87]
	v_mfma_f32_16x16x32_bf16 v[80:83], v[136:139], v[188:191], v[80:83]
	v_mfma_f32_16x16x32_bf16 v[76:79], v[128:131], v[196:199], v[76:79]
	v_mfma_f32_16x16x32_bf16 v[72:75], v[136:139], v[196:199], v[72:75]
	v_mfma_f32_16x16x32_bf16 v[68:71], v[128:131], v[204:207], v[68:71]
	v_mfma_f32_16x16x32_bf16 v[64:67], v[136:139], v[204:207], v[64:67]
	v_mfma_f32_16x16x32_bf16 v[92:95], v[132:135], v[184:187], v[92:95]
	v_mfma_f32_16x16x32_bf16 v[88:91], v[140:143], v[184:187], v[88:91]
	v_mfma_f32_16x16x32_bf16 v[84:87], v[132:135], v[192:195], v[84:87]
	v_mfma_f32_16x16x32_bf16 v[80:83], v[140:143], v[192:195], v[80:83]
	v_mfma_f32_16x16x32_bf16 v[76:79], v[132:135], v[200:203], v[76:79]
	v_mfma_f32_16x16x32_bf16 v[72:75], v[140:143], v[200:203], v[72:75]
	v_mfma_f32_16x16x32_bf16 v[68:71], v[132:135], v[208:211], v[68:71]
	v_mfma_f32_16x16x32_bf16 v[64:67], v[140:143], v[208:211], v[64:67]
	s_setprio 0
	s_setprio 1
	v_mfma_f32_16x16x32_bf16 v[28:31], v[158:161], v[180:183], v[28:31]
	v_mfma_f32_16x16x32_bf16 v[24:27], v[172:175], v[180:183], v[24:27]
	v_mfma_f32_16x16x32_bf16 v[20:23], v[158:161], v[188:191], v[20:23]
	v_mfma_f32_16x16x32_bf16 v[16:19], v[172:175], v[188:191], v[16:19]
	v_mfma_f32_16x16x32_bf16 v[12:15], v[158:161], v[196:199], v[12:15]
	v_mfma_f32_16x16x32_bf16 v[8:11], v[172:175], v[196:199], v[8:11]
	v_mfma_f32_16x16x32_bf16 v[4:7], v[158:161], v[204:207], v[4:7]
	v_mfma_f32_16x16x32_bf16 v[0:3], v[172:175], v[204:207], v[0:3]
	v_mfma_f32_16x16x32_bf16 v[28:31], v[162:165], v[184:187], v[28:31]
	v_mfma_f32_16x16x32_bf16 v[24:27], v[176:179], v[184:187], v[24:27]
	v_mfma_f32_16x16x32_bf16 v[20:23], v[162:165], v[192:195], v[20:23]
	v_mfma_f32_16x16x32_bf16 v[16:19], v[176:179], v[192:195], v[16:19]
	v_mfma_f32_16x16x32_bf16 v[12:15], v[162:165], v[200:203], v[12:15]
	v_mfma_f32_16x16x32_bf16 v[8:11], v[176:179], v[200:203], v[8:11]
	v_mfma_f32_16x16x32_bf16 v[4:7], v[162:165], v[208:211], v[4:7]
	v_mfma_f32_16x16x32_bf16 v[0:3], v[176:179], v[208:211], v[0:3]
	s_setprio 0
	s_barrier
	s_add_u32 s52, s52, 0x100
	s_addc_u32 s53, s53, 0
	s_add_u32 s80, s80, 0x100
	s_addc_u32 s81, s81, 0
	s_cmp_ge_u32 s82, s78
	s_mov_b32 s14, s82
	s_cbranch_scc0 .LBB0_2574
	s_and_b64 vcc, exec, s[10:11]
	s_cbranch_vccz .LBB0_2577
	s_barrier

; #define G_STAGE(bufoff, gbase, voff) do { _Pragma("unroll") for (int _i = 0; _i < 2; ++_i) \
;         __builtin_amdgcn_global_load_lds((const unsigned*)((const char*)(gbase) + voff[_i]), (LAS unsigned*)(lds + (bufoff) + ldsw + _i * 8192), 16, 0, 0); } while (0)
; #define G_LDA(dst, b, h) do { _Pragma("unroll") for (int m = 0; m < 4; ++m) _Pragma("unroll") for (int k = 0; k < 2; ++k) dst[m][k] = *(const LAS bf16x8*)(lds + G_SA(b, h) + aoff + m * 2048 + k * 1024); } while (0)
; #define G_LDB(dst, b, h) do { _Pragma("unroll") for (int n = 0; n < 2; ++n) _Pragma("unroll") for (int k = 0; k < 2; ++k) dst[n][k] = *(const LAS bf16x8*)(lds + G_SB(b, h) + boff + n * 2048 + k * 1024); } while (0)
; #define G_MMA(ai, bj, At_, Bt_) do { __builtin_amdgcn_s_setprio(1); _Pragma("unroll") for (int m = 0; m < 4; ++m) _Pragma("unroll") for (int n = 0; n < 2; ++n) _Pragma("unroll") for (int k = 0; k < 2; ++k) \
;         acc[ai][bj][m][n] = __builtin_amdgcn_mfma_f32_16x16x32_bf16(Bt_[n][k], At_[m][k], acc[ai][bj][m][n], 0, 0, 0); __builtin_amdgcn_s_setprio(0); } while (0)
; #define WAIT_V(n) asm volatile("s_waitcnt vmcnt(" #n ")" ::: "memory")
; #define WAIT_L(n) asm volatile("s_waitcnt lgkmcnt(" #n ")" ::: "memory")
; #define BAR __builtin_amdgcn_s_barrier()
; #define SCHED __builtin_amdgcn_sched_barrier(0)
; template <class Get, class Epi>
; DI void gemm_loop(int ntiles, int ld, char* shm, const Get& get, const Epi& epi) {
;     ...
;         for (int t = 0; t < nt; t += 2) {
;             const bool last = (t == nt - 2);
;             const char* a1 = cA + (size_t)(t + 1) * kstep;
;             const char* a2 = last ? nA : cA + (size_t)(t + 2) * kstep; const char* b2 = last ? nB : cB + (size_t)(t + 2) * kstep;
;             const char* a3 = a2 + kstep; const char* b3 = b2 + kstep;
;             G_LDB(B0, 0, 0); G_LDB(B1, 0, 1); SCHED; G_LDA(At, 0, 0); G_STAGE(G_SA(1, 1), a1 + hstep, voffA);
;             WAIT_V(8); WAIT_L(0); BAR; G_MMA(0, 0, At, B0); G_MMA(0, 1, At, B1); BAR; SCHED;
;             G_LDA(At, 0, 1); G_STAGE(G_SB(0, 0), b2, voffB); G_STAGE(G_SB(0, 1), b2 + hstep, voffB); G_STAGE(G_SA(0, 0), a2, voffA);
;             WAIT_V(8); WAIT_L(0); BAR; G_MMA(1, 0, At, B0); G_MMA(1, 1, At, B1); BAR; SCHED;
.LBB0_2892:
	ds_read_b128 v[128:131], v169
	ds_read_b128 v[132:135], v169 offset:1024
	ds_read_b128 v[136:139], v169 offset:2048
	ds_read_b128 v[140:143], v169 offset:3072
	ds_read_b128 v[158:161], v170
	ds_read_b128 v[162:165], v170 offset:1024
	ds_read_b128 v[172:175], v170 offset:2048
	ds_read_b128 v[176:179], v170 offset:3072
	s_add_i32 s83, s44, 2
	s_add_u32 s14, s4, 0x100
	s_addc_u32 s15, s5, 0
	s_cmp_eq_u32 s80, s44
	s_cselect_b32 s44, s42, s81
	s_cselect_b32 s47, s41, s15
	s_cselect_b32 s46, s40, s14
	s_cselect_b32 s45, s43, s82
	v_lshl_add_u64 v[144:145], s[4:5], 0, v[154:155]
	s_add_i32 m0, s49, 0xc000
	ds_read_b128 v[180:183], v171
	ds_read_b128 v[184:187], v171 offset:1024
	ds_read_b128 v[188:191], v171 offset:2048
	ds_read_b128 v[192:195], v171 offset:3072
	ds_read_b128 v[196:199], v171 offset:4096
	ds_read_b128 v[200:203], v171 offset:5120
	ds_read_b128 v[204:207], v171 offset:6144
	ds_read_b128 v[208:211], v171 offset:7168
	global_load_lds_dwordx4 v[144:145], off
	v_lshl_add_u64 v[144:145], s[4:5], 0, v[156:157]
	s_add_i32 m0, s49, 0xe000
	s_nop 0
	global_load_lds_dwordx4 v[144:145], off
	s_mov_b32 s98, 0xfff50000
	s_mov_b32 s99, -1
	v_lshl_add_u64 v[144:145], s[4:5], 0, v[154:155]
	v_lshl_add_u64 v[144:145], v[144:145], 0, s[98:99]
	s_add_i32 m0, s49, 0x8000
	s_nop 0
	global_load_lds_dwordx4 v[144:145], off
	v_lshl_add_u64 v[144:145], s[4:5], 0, v[156:157]
	v_lshl_add_u64 v[144:145], v[144:145], 0, s[98:99]
	s_add_i32 m0, s49, 0xa000
	s_nop 0
	global_load_lds_dwordx4 v[144:145], off
	s_waitcnt vmcnt(8)
	s_waitcnt lgkmcnt(0)
	s_barrier
	s_setprio 1
	s_waitcnt lgkmcnt(0)
	v_mfma_f32_16x16x32_bf16 v[124:127], v[128:131], v[180:183], v[124:127]
	v_mfma_f32_16x16x32_bf16 v[120:123], v[136:139], v[180:183], v[120:123]
	v_mfma_f32_16x16x32_bf16 v[116:119], v[128:131], v[188:191], v[116:119]
	v_mfma_f32_16x16x32_bf16 v[112:115], v[136:139], v[188:191], v[112:115]
	v_mfma_f32_16x16x32_bf16 v[108:111], v[128:131], v[196:199], v[108:111]
	v_mfma_f32_16x16x32_bf16 v[104:107], v[136:139], v[196:199], v[104:107]
	v_mfma_f32_16x16x32_bf16 v[100:103], v[128:131], v[204:207], v[100:103]
	v_mfma_f32_16x16x32_bf16 v[96:99], v[136:139], v[204:207], v[96:99]
	v_mfma_f32_16x16x32_bf16 v[124:127], v[132:135], v[184:187], v[124:127]
	v_mfma_f32_16x16x32_bf16 v[120:123], v[140:143], v[184:187], v[120:123]
	v_mfma_f32_16x16x32_bf16 v[116:119], v[132:135], v[192:195], v[116:119]
	v_mfma_f32_16x16x32_bf16 v[112:115], v[140:143], v[192:195], v[112:115]
	v_mfma_f32_16x16x32_bf16 v[108:111], v[132:135], v[200:203], v[108:111]
	v_mfma_f32_16x16x32_bf16 v[104:107], v[140:143], v[200:203], v[104:107]
	v_mfma_f32_16x16x32_bf16 v[100:103], v[132:135], v[208:211], v[100:103]
	v_mfma_f32_16x16x32_bf16 v[96:99], v[140:143], v[208:211], v[96:99]
	s_setprio 0
	s_setprio 1
	v_mfma_f32_16x16x32_bf16 v[60:63], v[158:161], v[180:183], v[60:63]
	v_mfma_f32_16x16x32_bf16 v[56:59], v[172:175], v[180:183], v[56:59]
	v_mfma_f32_16x16x32_bf16 v[52:55], v[158:161], v[188:191], v[52:55]
	v_mfma_f32_16x16x32_bf16 v[48:51], v[172:175], v[188:191], v[48:51]
	v_mfma_f32_16x16x32_bf16 v[44:47], v[158:161], v[196:199], v[44:47]
	v_mfma_f32_16x16x32_bf16 v[40:43], v[172:175], v[196:199], v[40:43]
	v_mfma_f32_16x16x32_bf16 v[36:39], v[158:161], v[204:207], v[36:39]
	v_mfma_f32_16x16x32_bf16 v[32:35], v[172:175], v[204:207], v[32:35]
	v_mfma_f32_16x16x32_bf16 v[60:63], v[162:165], v[184:187], v[60:63]
	v_mfma_f32_16x16x32_bf16 v[56:59], v[176:179], v[184:187], v[56:59]
	v_mfma_f32_16x16x32_bf16 v[52:55], v[162:165], v[192:195], v[52:55]
	v_mfma_f32_16x16x32_bf16 v[48:51], v[176:179], v[192:195], v[48:51]
	v_mfma_f32_16x16x32_bf16 v[44:47], v[162:165], v[200:203], v[44:47]
	v_mfma_f32_16x16x32_bf16 v[40:43], v[176:179], v[200:203], v[40:43]
	v_mfma_f32_16x16x32_bf16 v[36:39], v[162:165], v[208:211], v[36:39]
	v_mfma_f32_16x16x32_bf16 v[32:35], v[176:179], v[208:211], v[32:35]
	s_setprio 0
	s_barrier
	s_add_i32 s4, s58, s48
	v_lshl_add_u64 v[144:145], s[44:45], 0, v[148:149]
	s_mov_b32 m0, s4
	ds_read_b128 v[180:183], v171 offset:16384
	ds_read_b128 v[184:187], v171 offset:17408
	ds_read_b128 v[188:191], v171 offset:18432
	ds_read_b128 v[192:195], v171 offset:19456
	ds_read_b128 v[196:199], v171 offset:20480
	ds_read_b128 v[200:203], v171 offset:21504
	ds_read_b128 v[204:207], v171 offset:22528
	ds_read_b128 v[208:211], v171 offset:23552
	global_load_lds_dwordx4 v[144:145], off
	s_add_i32 m0, s4, 0x2000
	s_add_u32 s4, s44, 0xb0000
	v_lshl_add_u64 v[166:167], s[44:45], 0, v[152:153]
	s_addc_u32 s5, s45, 0
	s_add_i32 s84, s59, s48
	global_load_lds_dwordx4 v[166:167], off
	v_lshl_add_u64 v[212:213], s[4:5], 0, v[148:149]
	s_mov_b32 m0, s84
	v_lshl_add_u64 v[214:215], s[46:47], 0, v[150:151]
	global_load_lds_dwordx4 v[212:213], off
	v_lshl_add_u64 v[212:213], s[4:5], 0, v[152:153]
	s_add_i32 m0, s84, 0x2000
	s_nop 0
	global_load_lds_dwordx4 v[212:213], off
	v_lshl_add_u64 v[212:213], s[46:47], 0, v[146:147]
	s_waitcnt vmcnt(4)
	s_waitcnt lgkmcnt(0)
	s_barrier
; #define G_STAGE(bufoff, gbase, voff) do { _Pragma("unroll") for (int _i = 0; _i < 2; ++_i) \
;         __builtin_amdgcn_global_load_lds((const unsigned*)((const char*)(gbase) + voff[_i]), (LAS unsigned*)(lds + (bufoff) + ldsw + _i * 8192), 16, 0, 0); } while (0)
; #define G_LDA(dst, b, h) do { _Pragma("unroll") for (int m = 0; m < 4; ++m) _Pragma("unroll") for (int k = 0; k < 2; ++k) dst[m][k] = *(const LAS bf16x8*)(lds + G_SA(b, h) + aoff + m * 2048 + k * 1024); } while (0)
; #define G_LDB(dst, b, h) do { _Pragma("unroll") for (int n = 0; n < 2; ++n) _Pragma("unroll") for (int k = 0; k < 2; ++k) dst[n][k] = *(const LAS bf16x8*)(lds + G_SB(b, h) + boff + n * 2048 + k * 1024); } while (0)
; #define G_MMA(ai, bj, At_, Bt_) do { __builtin_amdgcn_s_setprio(1); _Pragma("unroll") for (int m = 0; m < 4; ++m) _Pragma("unroll") for (int n = 0; n < 2; ++n) _Pragma("unroll") for (int k = 0; k < 2; ++k) \
;         acc[ai][bj][m][n] = __builtin_amdgcn_mfma_f32_16x16x32_bf16(Bt_[n][k], At_[m][k], acc[ai][bj][m][n], 0, 0, 0); __builtin_amdgcn_s_setprio(0); } while (0)
; #define WAIT_V(n) asm volatile("s_waitcnt vmcnt(" #n ")" ::: "memory")
; #define WAIT_L(n) asm volatile("s_waitcnt lgkmcnt(" #n ")" ::: "memory")
; #define BAR __builtin_amdgcn_s_barrier()
; #define SCHED __builtin_amdgcn_sched_barrier(0)
; template <class Get, class Epi>
; DI void gemm_loop(int ntiles, int ld, char* shm, const Get& get, const Epi& epi) {
;     ...
;             WAIT_V(8); WAIT_L(0); BAR; G_MMA(1, 0, At, B0); G_MMA(1, 1, At, B1); BAR; SCHED;
;             G_LDB(B0, 1, 0); G_LDB(B1, 1, 1); SCHED; G_LDA(At, 1, 0); G_STAGE(G_SA(0, 1), a2 + hstep, voffA);
;             WAIT_V(8); WAIT_L(0); BAR; G_MMA(0, 0, At, B0); G_MMA(0, 1, At, B1); BAR; SCHED;
	s_setprio 1
	s_waitcnt lgkmcnt(0)
	v_mfma_f32_16x16x32_bf16 v[92:95], v[128:131], v[180:183], v[92:95]
	v_mfma_f32_16x16x32_bf16 v[88:91], v[136:139], v[180:183], v[88:91]
	v_mfma_f32_16x16x32_bf16 v[84:87], v[128:131], v[188:191], v[84:87]
	v_mfma_f32_16x16x32_bf16 v[80:83], v[136:139], v[188:191], v[80:83]
	v_mfma_f32_16x16x32_bf16 v[76:79], v[128:131], v[196:199], v[76:79]
	v_mfma_f32_16x16x32_bf16 v[72:75], v[136:139], v[196:199], v[72:75]
	v_mfma_f32_16x16x32_bf16 v[68:71], v[128:131], v[204:207], v[68:71]
	v_mfma_f32_16x16x32_bf16 v[64:67], v[136:139], v[204:207], v[64:67]
	v_mfma_f32_16x16x32_bf16 v[92:95], v[132:135], v[184:187], v[92:95]
	v_mfma_f32_16x16x32_bf16 v[88:91], v[140:143], v[184:187], v[88:91]
	v_mfma_f32_16x16x32_bf16 v[84:87], v[132:135], v[192:195], v[84:87]
	v_mfma_f32_16x16x32_bf16 v[80:83], v[140:143], v[192:195], v[80:83]
	v_mfma_f32_16x16x32_bf16 v[76:79], v[132:135], v[200:203], v[76:79]
	v_mfma_f32_16x16x32_bf16 v[72:75], v[140:143], v[200:203], v[72:75]
	v_mfma_f32_16x16x32_bf16 v[68:71], v[132:135], v[208:211], v[68:71]
	v_mfma_f32_16x16x32_bf16 v[64:67], v[140:143], v[208:211], v[64:67]
	s_setprio 0
	s_setprio 1
	v_mfma_f32_16x16x32_bf16 v[28:31], v[158:161], v[180:183], v[28:31]
	v_mfma_f32_16x16x32_bf16 v[24:27], v[172:175], v[180:183], v[24:27]
	v_mfma_f32_16x16x32_bf16 v[20:23], v[158:161], v[188:191], v[20:23]
	v_mfma_f32_16x16x32_bf16 v[16:19], v[172:175], v[188:191], v[16:19]
	v_mfma_f32_16x16x32_bf16 v[12:15], v[158:161], v[196:199], v[12:15]
	v_mfma_f32_16x16x32_bf16 v[8:11], v[172:175], v[196:199], v[8:11]
	v_mfma_f32_16x16x32_bf16 v[4:7], v[158:161], v[204:207], v[4:7]
	v_mfma_f32_16x16x32_bf16 v[0:3], v[172:175], v[204:207], v[0:3]
	v_mfma_f32_16x16x32_bf16 v[28:31], v[162:165], v[184:187], v[28:31]
	v_mfma_f32_16x16x32_bf16 v[24:27], v[176:179], v[184:187], v[24:27]
	v_mfma_f32_16x16x32_bf16 v[20:23], v[162:165], v[192:195], v[20:23]
	v_mfma_f32_16x16x32_bf16 v[16:19], v[176:179], v[192:195], v[16:19]
	v_mfma_f32_16x16x32_bf16 v[12:15], v[162:165], v[200:203], v[12:15]
	v_mfma_f32_16x16x32_bf16 v[8:11], v[176:179], v[200:203], v[8:11]
	v_mfma_f32_16x16x32_bf16 v[4:7], v[162:165], v[208:211], v[4:7]
	v_mfma_f32_16x16x32_bf16 v[0:3], v[176:179], v[208:211], v[0:3]
	s_setprio 0
	s_barrier
	s_add_i32 s84, 0, 0x18000
	s_add_i32 s85, 0, 0x1c000
	v_add_u32_e32 v140, s84, v168
	v_add_u32_e32 v176, s85, v168
	ds_read_b128 v[128:131], v140
	ds_read_b128 v[132:135], v140 offset:1024
	ds_read_b128 v[136:139], v140 offset:2048
	ds_read_b128 v[140:143], v140 offset:3072
	ds_read_b128 v[158:161], v176
	ds_read_b128 v[162:165], v176 offset:1024
	ds_read_b128 v[172:175], v176 offset:2048
	ds_read_b128 v[176:179], v176 offset:3072
	s_add_u32 s4, s46, 0xb0000
	s_addc_u32 s5, s47, 0
	s_mov_b32 m0, s51
	v_lshl_add_u64 v[216:217], s[4:5], 0, v[146:147]
	ds_read_b128 v[180:183], v171 offset:32768
	ds_read_b128 v[184:187], v171 offset:33792
	ds_read_b128 v[188:191], v171 offset:34816
	ds_read_b128 v[192:195], v171 offset:35840
	ds_read_b128 v[196:199], v171 offset:36864
	ds_read_b128 v[200:203], v171 offset:37888
	ds_read_b128 v[204:207], v171 offset:38912
	ds_read_b128 v[208:211], v171 offset:39936
	global_load_lds_dwordx4 v[216:217], off
	v_lshl_add_u64 v[216:217], s[4:5], 0, v[150:151]
	s_mov_b32 m0, s52
	s_nop 0
	global_load_lds_dwordx4 v[216:217], off
	s_mov_b32 m0, s49
	s_nop 0
	global_load_lds_dwordx4 v[212:213], off
	s_mov_b32 m0, s50
	s_nop 0
	global_load_lds_dwordx4 v[214:215], off
	s_waitcnt vmcnt(8)
	s_waitcnt lgkmcnt(0)
	s_barrier
; #define G_STAGE(bufoff, gbase, voff) do { _Pragma("unroll") for (int _i = 0; _i < 2; ++_i) \
;         __builtin_amdgcn_global_load_lds((const unsigned*)((const char*)(gbase) + voff[_i]), (LAS unsigned*)(lds + (bufoff) + ldsw + _i * 8192), 16, 0, 0); } while (0)
; #define G_LDA(dst, b, h) do { _Pragma("unroll") for (int m = 0; m < 4; ++m) _Pragma("unroll") for (int k = 0; k < 2; ++k) dst[m][k] = *(const LAS bf16x8*)(lds + G_SA(b, h) + aoff + m * 2048 + k * 1024); } while (0)
; #define G_MMA(ai, bj, At_, Bt_) do { __builtin_amdgcn_s_setprio(1); _Pragma("unroll") for (int m = 0; m < 4; ++m) _Pragma("unroll") for (int n = 0; n < 2; ++n) _Pragma("unroll") for (int k = 0; k < 2; ++k) \
;         acc[ai][bj][m][n] = __builtin_amdgcn_mfma_f32_16x16x32_bf16(Bt_[n][k], At_[m][k], acc[ai][bj][m][n], 0, 0, 0); __builtin_amdgcn_s_setprio(0); } while (0)
; #define WAIT_V(n) asm volatile("s_waitcnt vmcnt(" #n ")" ::: "memory")
; #define WAIT_L(n) asm volatile("s_waitcnt lgkmcnt(" #n ")" ::: "memory")
; #define BAR __builtin_amdgcn_s_barrier()
; #define SCHED __builtin_amdgcn_sched_barrier(0)
; template <class Get, class Epi>
; DI void gemm_loop(int ntiles, int ld, char* shm, const Get& get, const Epi& epi) {
;     ...
;             WAIT_V(8); WAIT_L(0); BAR; G_MMA(0, 0, At, B0); G_MMA(0, 1, At, B1); BAR; SCHED;
;             G_LDA(At, 1, 1); G_STAGE(G_SB(1, 0), b3, voffB); G_STAGE(G_SB(1, 1), b3 + hstep, voffB); G_STAGE(G_SA(1, 0), a3, voffA);
;             WAIT_V(8); WAIT_L(0); BAR; G_MMA(1, 0, At, B0); G_MMA(1, 1, At, B1); BAR; SCHED;
;         }
;         if (wr == 0) BAR;
	s_setprio 1
	s_waitcnt lgkmcnt(0)
	v_mfma_f32_16x16x32_bf16 v[124:127], v[128:131], v[180:183], v[124:127]
	v_mfma_f32_16x16x32_bf16 v[120:123], v[136:139], v[180:183], v[120:123]
	v_mfma_f32_16x16x32_bf16 v[116:119], v[128:131], v[188:191], v[116:119]
	v_mfma_f32_16x16x32_bf16 v[112:115], v[136:139], v[188:191], v[112:115]
	v_mfma_f32_16x16x32_bf16 v[108:111], v[128:131], v[196:199], v[108:111]
	v_mfma_f32_16x16x32_bf16 v[104:107], v[136:139], v[196:199], v[104:107]
	v_mfma_f32_16x16x32_bf16 v[100:103], v[128:131], v[204:207], v[100:103]
	v_mfma_f32_16x16x32_bf16 v[96:99], v[136:139], v[204:207], v[96:99]
	v_mfma_f32_16x16x32_bf16 v[124:127], v[132:135], v[184:187], v[124:127]
	v_mfma_f32_16x16x32_bf16 v[120:123], v[140:143], v[184:187], v[120:123]
	v_mfma_f32_16x16x32_bf16 v[116:119], v[132:135], v[192:195], v[116:119]
	v_mfma_f32_16x16x32_bf16 v[112:115], v[140:143], v[192:195], v[112:115]
	v_mfma_f32_16x16x32_bf16 v[108:111], v[132:135], v[200:203], v[108:111]
	v_mfma_f32_16x16x32_bf16 v[104:107], v[140:143], v[200:203], v[104:107]
	v_mfma_f32_16x16x32_bf16 v[100:103], v[132:135], v[208:211], v[100:103]
	v_mfma_f32_16x16x32_bf16 v[96:99], v[140:143], v[208:211], v[96:99]
	s_setprio 0
	s_setprio 1
	v_mfma_f32_16x16x32_bf16 v[60:63], v[158:161], v[180:183], v[60:63]
	v_mfma_f32_16x16x32_bf16 v[56:59], v[172:175], v[180:183], v[56:59]
	v_mfma_f32_16x16x32_bf16 v[52:55], v[158:161], v[188:191], v[52:55]
	v_mfma_f32_16x16x32_bf16 v[48:51], v[172:175], v[188:191], v[48:51]
	v_mfma_f32_16x16x32_bf16 v[44:47], v[158:161], v[196:199], v[44:47]
	v_mfma_f32_16x16x32_bf16 v[40:43], v[172:175], v[196:199], v[40:43]
	v_mfma_f32_16x16x32_bf16 v[36:39], v[158:161], v[204:207], v[36:39]
	v_mfma_f32_16x16x32_bf16 v[32:35], v[172:175], v[204:207], v[32:35]
	v_mfma_f32_16x16x32_bf16 v[60:63], v[162:165], v[184:187], v[60:63]
	v_mfma_f32_16x16x32_bf16 v[56:59], v[176:179], v[184:187], v[56:59]
	v_mfma_f32_16x16x32_bf16 v[52:55], v[162:165], v[192:195], v[52:55]
	v_mfma_f32_16x16x32_bf16 v[48:51], v[176:179], v[192:195], v[48:51]
	v_mfma_f32_16x16x32_bf16 v[44:47], v[162:165], v[200:203], v[44:47]
	v_mfma_f32_16x16x32_bf16 v[40:43], v[176:179], v[200:203], v[40:43]
	v_mfma_f32_16x16x32_bf16 v[36:39], v[162:165], v[208:211], v[36:39]
	v_mfma_f32_16x16x32_bf16 v[32:35], v[176:179], v[208:211], v[32:35]
	s_setprio 0
	s_barrier
	s_add_i32 s4, s84, s48
	v_lshl_add_u64 v[144:145], v[144:145], 0, s[10:11]
	s_mov_b32 m0, s4
	ds_read_b128 v[180:183], v171 offset:49152
	ds_read_b128 v[184:187], v171 offset:50176
	ds_read_b128 v[188:191], v171 offset:51200
	ds_read_b128 v[192:195], v171 offset:52224
	ds_read_b128 v[196:199], v171 offset:53248
	ds_read_b128 v[200:203], v171 offset:54272
	ds_read_b128 v[204:207], v171 offset:55296
	ds_read_b128 v[208:211], v171 offset:56320
	global_load_lds_dwordx4 v[144:145], off
	s_add_i32 m0, s4, 0x2000
	s_add_u32 s4, s44, 0xb0080
	v_lshl_add_u64 v[144:145], v[166:167], 0, s[10:11]
	s_addc_u32 s5, s45, 0
	s_add_i32 s44, s85, s48
	global_load_lds_dwordx4 v[144:145], off
	v_lshl_add_u64 v[144:145], s[4:5], 0, v[148:149]
	s_mov_b32 m0, s44
	s_nop 0
	global_load_lds_dwordx4 v[144:145], off
	v_lshl_add_u64 v[144:145], s[4:5], 0, v[152:153]
	s_add_i32 m0, s44, 0x2000
	s_nop 0
	global_load_lds_dwordx4 v[144:145], off
	s_waitcnt vmcnt(4)
	s_waitcnt lgkmcnt(0)
	s_barrier
	s_setprio 1
	s_waitcnt lgkmcnt(0)
	v_mfma_f32_16x16x32_bf16 v[92:95], v[128:131], v[180:183], v[92:95]
	v_mfma_f32_16x16x32_bf16 v[88:91], v[136:139], v[180:183], v[88:91]
	v_mfma_f32_16x16x32_bf16 v[84:87], v[128:131], v[188:191], v[84:87]
	v_mfma_f32_16x16x32_bf16 v[80:83], v[136:139], v[188:191], v[80:83]
	v_mfma_f32_16x16x32_bf16 v[76:79], v[128:131], v[196:199], v[76:79]
	v_mfma_f32_16x16x32_bf16 v[72:75], v[136:139], v[196:199], v[72:75]
	v_mfma_f32_16x16x32_bf16 v[68:71], v[128:131], v[204:207], v[68:71]
	v_mfma_f32_16x16x32_bf16 v[64:67], v[136:139], v[204:207], v[64:67]
	v_mfma_f32_16x16x32_bf16 v[92:95], v[132:135], v[184:187], v[92:95]
	v_mfma_f32_16x16x32_bf16 v[88:91], v[140:143], v[184:187], v[88:91]
	v_mfma_f32_16x16x32_bf16 v[84:87], v[132:135], v[192:195], v[84:87]
	v_mfma_f32_16x16x32_bf16 v[80:83], v[140:143], v[192:195], v[80:83]
	v_mfma_f32_16x16x32_bf16 v[76:79], v[132:135], v[200:203], v[76:79]
	v_mfma_f32_16x16x32_bf16 v[72:75], v[140:143], v[200:203], v[72:75]
	v_mfma_f32_16x16x32_bf16 v[68:71], v[132:135], v[208:211], v[68:71]
	v_mfma_f32_16x16x32_bf16 v[64:67], v[140:143], v[208:211], v[64:67]
	s_setprio 0
	s_setprio 1
	v_mfma_f32_16x16x32_bf16 v[28:31], v[158:161], v[180:183], v[28:31]
	v_mfma_f32_16x16x32_bf16 v[24:27], v[172:175], v[180:183], v[24:27]
	v_mfma_f32_16x16x32_bf16 v[20:23], v[158:161], v[188:191], v[20:23]
	v_mfma_f32_16x16x32_bf16 v[16:19], v[172:175], v[188:191], v[16:19]
	v_mfma_f32_16x16x32_bf16 v[12:15], v[158:161], v[196:199], v[12:15]
	v_mfma_f32_16x16x32_bf16 v[8:11], v[172:175], v[196:199], v[8:11]
	v_mfma_f32_16x16x32_bf16 v[4:7], v[158:161], v[204:207], v[4:7]
	v_mfma_f32_16x16x32_bf16 v[0:3], v[172:175], v[204:207], v[0:3]
	v_mfma_f32_16x16x32_bf16 v[28:31], v[162:165], v[184:187], v[28:31]
	v_mfma_f32_16x16x32_bf16 v[24:27], v[176:179], v[184:187], v[24:27]
	v_mfma_f32_16x16x32_bf16 v[20:23], v[162:165], v[192:195], v[20:23]
	v_mfma_f32_16x16x32_bf16 v[16:19], v[176:179], v[192:195], v[16:19]
	v_mfma_f32_16x16x32_bf16 v[12:15], v[162:165], v[200:203], v[12:15]
	v_mfma_f32_16x16x32_bf16 v[8:11], v[176:179], v[200:203], v[8:11]
	v_mfma_f32_16x16x32_bf16 v[4:7], v[162:165], v[208:211], v[4:7]
	v_mfma_f32_16x16x32_bf16 v[0:3], v[176:179], v[208:211], v[0:3]
	s_setprio 0
	s_barrier
	s_add_u32 s81, s81, 0x100
	s_addc_u32 s82, s82, 0
	s_cmp_ge_u32 s83, s79
	s_mov_b64 s[4:5], s[14:15]
	s_mov_b32 s44, s83
	s_cbranch_scc0 .LBB0_2892
	s_and_b64 vcc, exec, s[12:13]
	s_cbranch_vccz .LBB0_2895
	s_barrier

; #define G_STAGE(bufoff, gbase, voff) do { _Pragma("unroll") for (int _i = 0; _i < 2; ++_i) \
;         __builtin_amdgcn_global_load_lds((const unsigned*)((const char*)(gbase) + voff[_i]), (LAS unsigned*)(lds + (bufoff) + ldsw + _i * 8192), 16, 0, 0); } while (0)
; #define G_LDA(dst, b, h) do { _Pragma("unroll") for (int m = 0; m < 4; ++m) _Pragma("unroll") for (int k = 0; k < 2; ++k) dst[m][k] = *(const LAS bf16x8*)(lds + G_SA(b, h) + aoff + m * 2048 + k * 1024); } while (0)
; #define G_LDB(dst, b, h) do { _Pragma("unroll") for (int n = 0; n < 2; ++n) _Pragma("unroll") for (int k = 0; k < 2; ++k) dst[n][k] = *(const LAS bf16x8*)(lds + G_SB(b, h) + boff + n * 2048 + k * 1024); } while (0)
; #define G_MMA(ai, bj, At_, Bt_) do { __builtin_amdgcn_s_setprio(1); _Pragma("unroll") for (int m = 0; m < 4; ++m) _Pragma("unroll") for (int n = 0; n < 2; ++n) _Pragma("unroll") for (int k = 0; k < 2; ++k) \
;         acc[ai][bj][m][n] = __builtin_amdgcn_mfma_f32_16x16x32_bf16(Bt_[n][k], At_[m][k], acc[ai][bj][m][n], 0, 0, 0); __builtin_amdgcn_s_setprio(0); } while (0)
; #define WAIT_V(n) asm volatile("s_waitcnt vmcnt(" #n ")" ::: "memory")
; #define WAIT_L(n) asm volatile("s_waitcnt lgkmcnt(" #n ")" ::: "memory")
; #define BAR __builtin_amdgcn_s_barrier()
; #define SCHED __builtin_amdgcn_sched_barrier(0)
; template <class Get, class Epi>
; DI void gemm_loop(int ntiles, int ld, char* shm, const Get& get, const Epi& epi) {
;     ...
;         for (int t = 0; t < nt; t += 2) {
;             const bool last = (t == nt - 2);
;             const char* a1 = cA + (size_t)(t + 1) * kstep;
;             const char* a2 = last ? nA : cA + (size_t)(t + 2) * kstep; const char* b2 = last ? nB : cB + (size_t)(t + 2) * kstep;
;             const char* a3 = a2 + kstep; const char* b3 = b2 + kstep;
;             G_LDB(B0, 0, 0); G_LDB(B1, 0, 1); SCHED; G_LDA(At, 0, 0); G_STAGE(G_SA(1, 1), a1 + hstep, voffA);
;             WAIT_V(8); WAIT_L(0); BAR; G_MMA(0, 0, At, B0); G_MMA(0, 1, At, B1); BAR; SCHED;
;             G_LDA(At, 0, 1); G_STAGE(G_SB(0, 0), b2, voffB); G_STAGE(G_SB(0, 1), b2 + hstep, voffB); G_STAGE(G_SA(0, 0), a2, voffA);
;             WAIT_V(8); WAIT_L(0); BAR; G_MMA(1, 0, At, B0); G_MMA(1, 1, At, B1); BAR; SCHED;
.LBB0_3141:
	ds_read_b128 v[144:147], v141
	ds_read_b128 v[148:151], v141 offset:1024
	ds_read_b128 v[152:155], v141 offset:2048
	ds_read_b128 v[156:159], v141 offset:3072
	ds_read_b128 v[160:163], v142
	ds_read_b128 v[164:167], v142 offset:1024
	ds_read_b128 v[168:171], v142 offset:2048
	ds_read_b128 v[172:175], v142 offset:3072
	s_add_u32 s14, s48, 0xfffc0080
	s_addc_u32 s15, s49, -1
	s_cmp_eq_u32 s70, 12
	s_cselect_b32 s47, s11, s15
	s_cselect_b32 s46, s39, s14
	s_cselect_b32 s15, s41, s65
	s_cselect_b32 s14, s63, s64
	v_lshl_add_u64 v[208:209], s[48:49], 0, v[136:137]
	s_add_i32 m0, s35, 0xc000
	ds_read_b128 v[176:179], v143
	ds_read_b128 v[180:183], v143 offset:1024
	ds_read_b128 v[184:187], v143 offset:2048
	ds_read_b128 v[188:191], v143 offset:3072
	ds_read_b128 v[192:195], v143 offset:4096
	ds_read_b128 v[196:199], v143 offset:5120
	ds_read_b128 v[200:203], v143 offset:6144
	ds_read_b128 v[204:207], v143 offset:7168
	global_load_lds_dwordx4 v[208:209], off
	v_lshl_add_u64 v[208:209], s[48:49], 0, v[138:139]
	s_add_i32 m0, s35, 0xe000
	s_nop 0
	global_load_lds_dwordx4 v[208:209], off
	s_mov_b32 s98, 0xfffc0000
	s_mov_b32 s99, -1
	v_lshl_add_u64 v[208:209], s[48:49], 0, v[136:137]
	v_lshl_add_u64 v[208:209], v[208:209], 0, s[98:99]
	s_add_i32 m0, s35, 0x8000
	s_nop 0
	global_load_lds_dwordx4 v[208:209], off
	v_lshl_add_u64 v[208:209], s[48:49], 0, v[138:139]
	v_lshl_add_u64 v[208:209], v[208:209], 0, s[98:99]
	s_add_i32 m0, s35, 0xa000
	s_nop 0
	global_load_lds_dwordx4 v[208:209], off
	s_waitcnt vmcnt(8)
	s_waitcnt lgkmcnt(0)
	s_barrier
	s_setprio 1
	s_waitcnt lgkmcnt(0)
	v_mfma_f32_16x16x32_bf16 v[124:127], v[144:147], v[176:179], v[124:127]
	v_mfma_f32_16x16x32_bf16 v[120:123], v[152:155], v[176:179], v[120:123]
	v_mfma_f32_16x16x32_bf16 v[116:119], v[144:147], v[184:187], v[116:119]
	v_mfma_f32_16x16x32_bf16 v[112:115], v[152:155], v[184:187], v[112:115]
	v_mfma_f32_16x16x32_bf16 v[100:103], v[144:147], v[192:195], v[100:103]
	v_mfma_f32_16x16x32_bf16 v[96:99], v[152:155], v[192:195], v[96:99]
	v_mfma_f32_16x16x32_bf16 v[84:87], v[144:147], v[200:203], v[84:87]
	v_mfma_f32_16x16x32_bf16 v[80:83], v[152:155], v[200:203], v[80:83]
	v_mfma_f32_16x16x32_bf16 v[124:127], v[148:151], v[180:183], v[124:127]
	v_mfma_f32_16x16x32_bf16 v[120:123], v[156:159], v[180:183], v[120:123]
	v_mfma_f32_16x16x32_bf16 v[116:119], v[148:151], v[188:191], v[116:119]
	v_mfma_f32_16x16x32_bf16 v[112:115], v[156:159], v[188:191], v[112:115]
	v_mfma_f32_16x16x32_bf16 v[100:103], v[148:151], v[196:199], v[100:103]
	v_mfma_f32_16x16x32_bf16 v[96:99], v[156:159], v[196:199], v[96:99]
	v_mfma_f32_16x16x32_bf16 v[84:87], v[148:151], v[204:207], v[84:87]
	v_mfma_f32_16x16x32_bf16 v[80:83], v[156:159], v[204:207], v[80:83]
	s_setprio 0
	s_setprio 1
	v_mfma_f32_16x16x32_bf16 v[108:111], v[160:163], v[176:179], v[108:111]
	v_mfma_f32_16x16x32_bf16 v[104:107], v[168:171], v[176:179], v[104:107]
	v_mfma_f32_16x16x32_bf16 v[92:95], v[160:163], v[184:187], v[92:95]
	v_mfma_f32_16x16x32_bf16 v[88:91], v[168:171], v[184:187], v[88:91]
	v_mfma_f32_16x16x32_bf16 v[76:79], v[160:163], v[192:195], v[76:79]
	v_mfma_f32_16x16x32_bf16 v[72:75], v[168:171], v[192:195], v[72:75]
	v_mfma_f32_16x16x32_bf16 v[68:71], v[160:163], v[200:203], v[68:71]
	v_mfma_f32_16x16x32_bf16 v[64:67], v[168:171], v[200:203], v[64:67]
	v_mfma_f32_16x16x32_bf16 v[108:111], v[164:167], v[180:183], v[108:111]
	v_mfma_f32_16x16x32_bf16 v[104:107], v[172:175], v[180:183], v[104:107]
	v_mfma_f32_16x16x32_bf16 v[92:95], v[164:167], v[188:191], v[92:95]
	v_mfma_f32_16x16x32_bf16 v[88:91], v[172:175], v[188:191], v[88:91]
	v_mfma_f32_16x16x32_bf16 v[76:79], v[164:167], v[196:199], v[76:79]
	v_mfma_f32_16x16x32_bf16 v[72:75], v[172:175], v[196:199], v[72:75]
	v_mfma_f32_16x16x32_bf16 v[68:71], v[164:167], v[204:207], v[68:71]
	v_mfma_f32_16x16x32_bf16 v[64:67], v[172:175], v[204:207], v[64:67]
	s_setprio 0
	s_barrier
	s_add_i32 s71, s57, s50
	v_lshl_add_u64 v[208:209], s[14:15], 0, v[130:131]
	s_mov_b32 m0, s71
	ds_read_b128 v[176:179], v143 offset:16384
	ds_read_b128 v[180:183], v143 offset:17408
	ds_read_b128 v[184:187], v143 offset:18432
	ds_read_b128 v[188:191], v143 offset:19456
	ds_read_b128 v[192:195], v143 offset:20480
	ds_read_b128 v[196:199], v143 offset:21504
	ds_read_b128 v[200:203], v143 offset:22528
	ds_read_b128 v[204:207], v143 offset:23552
	global_load_lds_dwordx4 v[208:209], off
	s_add_i32 m0, s71, 0x2000
	s_add_u32 s72, s14, 0x40000
	v_lshl_add_u64 v[210:211], s[14:15], 0, v[134:135]
	s_addc_u32 s73, s15, 0
	s_add_i32 s71, s58, s50
	global_load_lds_dwordx4 v[210:211], off
	v_lshl_add_u64 v[212:213], s[72:73], 0, v[130:131]
	s_mov_b32 m0, s71
	v_lshl_add_u64 v[214:215], s[46:47], 0, v[132:133]
	global_load_lds_dwordx4 v[212:213], off
	v_lshl_add_u64 v[212:213], s[72:73], 0, v[134:135]
	s_add_i32 m0, s71, 0x2000
	s_nop 0
	global_load_lds_dwordx4 v[212:213], off
	v_lshl_add_u64 v[212:213], s[46:47], 0, v[128:129]
	s_waitcnt vmcnt(4)
	s_waitcnt lgkmcnt(0)
	s_barrier
; #define G_STAGE(bufoff, gbase, voff) do { _Pragma("unroll") for (int _i = 0; _i < 2; ++_i) \
;         __builtin_amdgcn_global_load_lds((const unsigned*)((const char*)(gbase) + voff[_i]), (LAS unsigned*)(lds + (bufoff) + ldsw + _i * 8192), 16, 0, 0); } while (0)
; #define G_LDA(dst, b, h) do { _Pragma("unroll") for (int m = 0; m < 4; ++m) _Pragma("unroll") for (int k = 0; k < 2; ++k) dst[m][k] = *(const LAS bf16x8*)(lds + G_SA(b, h) + aoff + m * 2048 + k * 1024); } while (0)
; #define G_LDB(dst, b, h) do { _Pragma("unroll") for (int n = 0; n < 2; ++n) _Pragma("unroll") for (int k = 0; k < 2; ++k) dst[n][k] = *(const LAS bf16x8*)(lds + G_SB(b, h) + boff + n * 2048 + k * 1024); } while (0)
; #define G_MMA(ai, bj, At_, Bt_) do { __builtin_amdgcn_s_setprio(1); _Pragma("unroll") for (int m = 0; m < 4; ++m) _Pragma("unroll") for (int n = 0; n < 2; ++n) _Pragma("unroll") for (int k = 0; k < 2; ++k) \
;         acc[ai][bj][m][n] = __builtin_amdgcn_mfma_f32_16x16x32_bf16(Bt_[n][k], At_[m][k], acc[ai][bj][m][n], 0, 0, 0); __builtin_amdgcn_s_setprio(0); } while (0)
; #define WAIT_V(n) asm volatile("s_waitcnt vmcnt(" #n ")" ::: "memory")
; #define WAIT_L(n) asm volatile("s_waitcnt lgkmcnt(" #n ")" ::: "memory")
; #define BAR __builtin_amdgcn_s_barrier()
; #define SCHED __builtin_amdgcn_sched_barrier(0)
; template <class Get, class Epi>
; DI void gemm_loop(int ntiles, int ld, char* shm, const Get& get, const Epi& epi) {
;     ...
;             WAIT_V(8); WAIT_L(0); BAR; G_MMA(1, 0, At, B0); G_MMA(1, 1, At, B1); BAR; SCHED;
;             G_LDB(B0, 1, 0); G_LDB(B1, 1, 1); SCHED; G_LDA(At, 1, 0); G_STAGE(G_SA(0, 1), a2 + hstep, voffA);
;             WAIT_V(8); WAIT_L(0); BAR; G_MMA(0, 0, At, B0); G_MMA(0, 1, At, B1); BAR; SCHED;
	s_setprio 1
	s_waitcnt lgkmcnt(0)
	v_mfma_f32_16x16x32_bf16 v[60:63], v[144:147], v[176:179], v[60:63]
	v_mfma_f32_16x16x32_bf16 v[56:59], v[152:155], v[176:179], v[56:59]
	v_mfma_f32_16x16x32_bf16 v[52:55], v[144:147], v[184:187], v[52:55]
	v_mfma_f32_16x16x32_bf16 v[48:51], v[152:155], v[184:187], v[48:51]
	v_mfma_f32_16x16x32_bf16 v[36:39], v[144:147], v[192:195], v[36:39]
	v_mfma_f32_16x16x32_bf16 v[32:35], v[152:155], v[192:195], v[32:35]
	v_mfma_f32_16x16x32_bf16 v[20:23], v[144:147], v[200:203], v[20:23]
	v_mfma_f32_16x16x32_bf16 v[16:19], v[152:155], v[200:203], v[16:19]
	v_mfma_f32_16x16x32_bf16 v[60:63], v[148:151], v[180:183], v[60:63]
	v_mfma_f32_16x16x32_bf16 v[56:59], v[156:159], v[180:183], v[56:59]
	v_mfma_f32_16x16x32_bf16 v[52:55], v[148:151], v[188:191], v[52:55]
	v_mfma_f32_16x16x32_bf16 v[48:51], v[156:159], v[188:191], v[48:51]
	v_mfma_f32_16x16x32_bf16 v[36:39], v[148:151], v[196:199], v[36:39]
	v_mfma_f32_16x16x32_bf16 v[32:35], v[156:159], v[196:199], v[32:35]
	v_mfma_f32_16x16x32_bf16 v[20:23], v[148:151], v[204:207], v[20:23]
	v_mfma_f32_16x16x32_bf16 v[16:19], v[156:159], v[204:207], v[16:19]
	s_setprio 0
	s_setprio 1
	v_mfma_f32_16x16x32_bf16 v[44:47], v[160:163], v[176:179], v[44:47]
	v_mfma_f32_16x16x32_bf16 v[40:43], v[168:171], v[176:179], v[40:43]
	v_mfma_f32_16x16x32_bf16 v[28:31], v[160:163], v[184:187], v[28:31]
	v_mfma_f32_16x16x32_bf16 v[24:27], v[168:171], v[184:187], v[24:27]
	v_mfma_f32_16x16x32_bf16 v[12:15], v[160:163], v[192:195], v[12:15]
	v_mfma_f32_16x16x32_bf16 v[8:11], v[168:171], v[192:195], v[8:11]
	v_mfma_f32_16x16x32_bf16 v[4:7], v[160:163], v[200:203], v[4:7]
	v_mfma_f32_16x16x32_bf16 v[0:3], v[168:171], v[200:203], v[0:3]
	v_mfma_f32_16x16x32_bf16 v[44:47], v[164:167], v[180:183], v[44:47]
	v_mfma_f32_16x16x32_bf16 v[40:43], v[172:175], v[180:183], v[40:43]
	v_mfma_f32_16x16x32_bf16 v[28:31], v[164:167], v[188:191], v[28:31]
	v_mfma_f32_16x16x32_bf16 v[24:27], v[172:175], v[188:191], v[24:27]
	v_mfma_f32_16x16x32_bf16 v[12:15], v[164:167], v[196:199], v[12:15]
	v_mfma_f32_16x16x32_bf16 v[8:11], v[172:175], v[196:199], v[8:11]
	v_mfma_f32_16x16x32_bf16 v[4:7], v[164:167], v[204:207], v[4:7]
	v_mfma_f32_16x16x32_bf16 v[0:3], v[172:175], v[204:207], v[0:3]
	s_setprio 0
	s_barrier
	s_add_i32 s71, 0, 0x18000
	s_add_i32 s72, 0, 0x1c000
	v_add_u32_e32 v156, s71, v140
	v_add_u32_e32 v172, s72, v140
	ds_read_b128 v[144:147], v156
	ds_read_b128 v[148:151], v156 offset:1024
	ds_read_b128 v[152:155], v156 offset:2048
	ds_read_b128 v[156:159], v156 offset:3072
	ds_read_b128 v[160:163], v172
	ds_read_b128 v[164:167], v172 offset:1024
	ds_read_b128 v[168:171], v172 offset:2048
	ds_read_b128 v[172:175], v172 offset:3072
	s_add_u32 s46, s46, 0x40000
	s_addc_u32 s47, s47, 0
	s_mov_b32 m0, s52
	v_lshl_add_u64 v[216:217], s[46:47], 0, v[128:129]
	ds_read_b128 v[176:179], v143 offset:32768
	ds_read_b128 v[180:183], v143 offset:33792
	ds_read_b128 v[184:187], v143 offset:34816
	ds_read_b128 v[188:191], v143 offset:35840
	ds_read_b128 v[192:195], v143 offset:36864
	ds_read_b128 v[196:199], v143 offset:37888
	ds_read_b128 v[200:203], v143 offset:38912
	ds_read_b128 v[204:207], v143 offset:39936
	global_load_lds_dwordx4 v[216:217], off
	v_lshl_add_u64 v[216:217], s[46:47], 0, v[132:133]
	s_mov_b32 m0, s53
	s_nop 0
	global_load_lds_dwordx4 v[216:217], off
	s_mov_b32 m0, s35
	s_nop 0
	global_load_lds_dwordx4 v[212:213], off
	s_mov_b32 m0, s51
	s_nop 0
	global_load_lds_dwordx4 v[214:215], off
	s_waitcnt vmcnt(8)
	s_waitcnt lgkmcnt(0)
	s_barrier
; #define G_STAGE(bufoff, gbase, voff) do { _Pragma("unroll") for (int _i = 0; _i < 2; ++_i) \
;         __builtin_amdgcn_global_load_lds((const unsigned*)((const char*)(gbase) + voff[_i]), (LAS unsigned*)(lds + (bufoff) + ldsw + _i * 8192), 16, 0, 0); } while (0)
; #define G_LDA(dst, b, h) do { _Pragma("unroll") for (int m = 0; m < 4; ++m) _Pragma("unroll") for (int k = 0; k < 2; ++k) dst[m][k] = *(const LAS bf16x8*)(lds + G_SA(b, h) + aoff + m * 2048 + k * 1024); } while (0)
; #define G_MMA(ai, bj, At_, Bt_) do { __builtin_amdgcn_s_setprio(1); _Pragma("unroll") for (int m = 0; m < 4; ++m) _Pragma("unroll") for (int n = 0; n < 2; ++n) _Pragma("unroll") for (int k = 0; k < 2; ++k) \
;         acc[ai][bj][m][n] = __builtin_amdgcn_mfma_f32_16x16x32_bf16(Bt_[n][k], At_[m][k], acc[ai][bj][m][n], 0, 0, 0); __builtin_amdgcn_s_setprio(0); } while (0)
; #define WAIT_V(n) asm volatile("s_waitcnt vmcnt(" #n ")" ::: "memory")
; #define WAIT_L(n) asm volatile("s_waitcnt lgkmcnt(" #n ")" ::: "memory")
; #define BAR __builtin_amdgcn_s_barrier()
; #define SCHED __builtin_amdgcn_sched_barrier(0)
; template <class Get, class Epi>
; DI void gemm_loop(int ntiles, int ld, char* shm, const Get& get, const Epi& epi) {
;     ...
;             WAIT_V(8); WAIT_L(0); BAR; G_MMA(0, 0, At, B0); G_MMA(0, 1, At, B1); BAR; SCHED;
;             G_LDA(At, 1, 1); G_STAGE(G_SB(1, 0), b3, voffB); G_STAGE(G_SB(1, 1), b3 + hstep, voffB); G_STAGE(G_SA(1, 0), a3, voffA);
;             WAIT_V(8); WAIT_L(0); BAR; G_MMA(1, 0, At, B0); G_MMA(1, 1, At, B1); BAR; SCHED;
;         }
;         if (wr == 0) BAR;
	s_setprio 1
	s_waitcnt lgkmcnt(0)
	v_mfma_f32_16x16x32_bf16 v[124:127], v[144:147], v[176:179], v[124:127]
	v_mfma_f32_16x16x32_bf16 v[120:123], v[152:155], v[176:179], v[120:123]
	v_mfma_f32_16x16x32_bf16 v[116:119], v[144:147], v[184:187], v[116:119]
	v_mfma_f32_16x16x32_bf16 v[112:115], v[152:155], v[184:187], v[112:115]
	v_mfma_f32_16x16x32_bf16 v[100:103], v[144:147], v[192:195], v[100:103]
	v_mfma_f32_16x16x32_bf16 v[96:99], v[152:155], v[192:195], v[96:99]
	v_mfma_f32_16x16x32_bf16 v[84:87], v[144:147], v[200:203], v[84:87]
	v_mfma_f32_16x16x32_bf16 v[80:83], v[152:155], v[200:203], v[80:83]
	v_mfma_f32_16x16x32_bf16 v[124:127], v[148:151], v[180:183], v[124:127]
	v_mfma_f32_16x16x32_bf16 v[120:123], v[156:159], v[180:183], v[120:123]
	v_mfma_f32_16x16x32_bf16 v[116:119], v[148:151], v[188:191], v[116:119]
	v_mfma_f32_16x16x32_bf16 v[112:115], v[156:159], v[188:191], v[112:115]
	v_mfma_f32_16x16x32_bf16 v[100:103], v[148:151], v[196:199], v[100:103]
	v_mfma_f32_16x16x32_bf16 v[96:99], v[156:159], v[196:199], v[96:99]
	v_mfma_f32_16x16x32_bf16 v[84:87], v[148:151], v[204:207], v[84:87]
	v_mfma_f32_16x16x32_bf16 v[80:83], v[156:159], v[204:207], v[80:83]
	s_setprio 0
	s_setprio 1
	v_mfma_f32_16x16x32_bf16 v[108:111], v[160:163], v[176:179], v[108:111]
	v_mfma_f32_16x16x32_bf16 v[104:107], v[168:171], v[176:179], v[104:107]
	v_mfma_f32_16x16x32_bf16 v[92:95], v[160:163], v[184:187], v[92:95]
	v_mfma_f32_16x16x32_bf16 v[88:91], v[168:171], v[184:187], v[88:91]
	v_mfma_f32_16x16x32_bf16 v[76:79], v[160:163], v[192:195], v[76:79]
	v_mfma_f32_16x16x32_bf16 v[72:75], v[168:171], v[192:195], v[72:75]
	v_mfma_f32_16x16x32_bf16 v[68:71], v[160:163], v[200:203], v[68:71]
	v_mfma_f32_16x16x32_bf16 v[64:67], v[168:171], v[200:203], v[64:67]
	v_mfma_f32_16x16x32_bf16 v[108:111], v[164:167], v[180:183], v[108:111]
	v_mfma_f32_16x16x32_bf16 v[104:107], v[172:175], v[180:183], v[104:107]
	v_mfma_f32_16x16x32_bf16 v[92:95], v[164:167], v[188:191], v[92:95]
	v_mfma_f32_16x16x32_bf16 v[88:91], v[172:175], v[188:191], v[88:91]
	v_mfma_f32_16x16x32_bf16 v[76:79], v[164:167], v[196:199], v[76:79]
	v_mfma_f32_16x16x32_bf16 v[72:75], v[172:175], v[196:199], v[72:75]
	v_mfma_f32_16x16x32_bf16 v[68:71], v[164:167], v[204:207], v[68:71]
	v_mfma_f32_16x16x32_bf16 v[64:67], v[172:175], v[204:207], v[64:67]
	s_setprio 0
	s_barrier
	s_add_i32 s46, s71, s50
	v_lshl_add_u64 v[208:209], v[208:209], 0, s[8:9]
	s_mov_b32 m0, s46
	ds_read_b128 v[176:179], v143 offset:49152
	ds_read_b128 v[180:183], v143 offset:50176
	ds_read_b128 v[184:187], v143 offset:51200
	ds_read_b128 v[188:191], v143 offset:52224
	ds_read_b128 v[192:195], v143 offset:53248
	ds_read_b128 v[196:199], v143 offset:54272
	ds_read_b128 v[200:203], v143 offset:55296
	ds_read_b128 v[204:207], v143 offset:56320
	global_load_lds_dwordx4 v[208:209], off
	s_add_i32 m0, s46, 0x2000
	s_add_u32 s14, s14, 0x40080
	v_lshl_add_u64 v[208:209], v[210:211], 0, s[8:9]
	s_addc_u32 s15, s15, 0
	s_add_i32 s46, s72, s50
	global_load_lds_dwordx4 v[208:209], off
	v_lshl_add_u64 v[208:209], s[14:15], 0, v[130:131]
	s_mov_b32 m0, s46
	s_nop 0
	global_load_lds_dwordx4 v[208:209], off
	v_lshl_add_u64 v[208:209], s[14:15], 0, v[134:135]
	s_add_i32 m0, s46, 0x2000
	s_nop 0
	global_load_lds_dwordx4 v[208:209], off
	s_waitcnt vmcnt(4)
	s_waitcnt lgkmcnt(0)
	s_barrier
	s_setprio 1
	s_waitcnt lgkmcnt(0)
	v_mfma_f32_16x16x32_bf16 v[60:63], v[144:147], v[176:179], v[60:63]
	v_mfma_f32_16x16x32_bf16 v[56:59], v[152:155], v[176:179], v[56:59]
	v_mfma_f32_16x16x32_bf16 v[52:55], v[144:147], v[184:187], v[52:55]
	v_mfma_f32_16x16x32_bf16 v[48:51], v[152:155], v[184:187], v[48:51]
	v_mfma_f32_16x16x32_bf16 v[36:39], v[144:147], v[192:195], v[36:39]
	v_mfma_f32_16x16x32_bf16 v[32:35], v[152:155], v[192:195], v[32:35]
	v_mfma_f32_16x16x32_bf16 v[20:23], v[144:147], v[200:203], v[20:23]
	v_mfma_f32_16x16x32_bf16 v[16:19], v[152:155], v[200:203], v[16:19]
	v_mfma_f32_16x16x32_bf16 v[60:63], v[148:151], v[180:183], v[60:63]
	v_mfma_f32_16x16x32_bf16 v[56:59], v[156:159], v[180:183], v[56:59]
	v_mfma_f32_16x16x32_bf16 v[52:55], v[148:151], v[188:191], v[52:55]
	v_mfma_f32_16x16x32_bf16 v[48:51], v[156:159], v[188:191], v[48:51]
	v_mfma_f32_16x16x32_bf16 v[36:39], v[148:151], v[196:199], v[36:39]
	v_mfma_f32_16x16x32_bf16 v[32:35], v[156:159], v[196:199], v[32:35]
	v_mfma_f32_16x16x32_bf16 v[20:23], v[148:151], v[204:207], v[20:23]
	v_mfma_f32_16x16x32_bf16 v[16:19], v[156:159], v[204:207], v[16:19]
	s_setprio 0
	s_setprio 1
	v_mfma_f32_16x16x32_bf16 v[44:47], v[160:163], v[176:179], v[44:47]
	v_mfma_f32_16x16x32_bf16 v[40:43], v[168:171], v[176:179], v[40:43]
	v_mfma_f32_16x16x32_bf16 v[28:31], v[160:163], v[184:187], v[28:31]
	v_mfma_f32_16x16x32_bf16 v[24:27], v[168:171], v[184:187], v[24:27]
	v_mfma_f32_16x16x32_bf16 v[12:15], v[160:163], v[192:195], v[12:15]
	v_mfma_f32_16x16x32_bf16 v[8:11], v[168:171], v[192:195], v[8:11]
	v_mfma_f32_16x16x32_bf16 v[4:7], v[160:163], v[200:203], v[4:7]
	v_mfma_f32_16x16x32_bf16 v[0:3], v[168:171], v[200:203], v[0:3]
	v_mfma_f32_16x16x32_bf16 v[44:47], v[164:167], v[180:183], v[44:47]
	v_mfma_f32_16x16x32_bf16 v[40:43], v[172:175], v[180:183], v[40:43]
	v_mfma_f32_16x16x32_bf16 v[28:31], v[164:167], v[188:191], v[28:31]
	v_mfma_f32_16x16x32_bf16 v[24:27], v[172:175], v[188:191], v[24:27]
	v_mfma_f32_16x16x32_bf16 v[12:15], v[164:167], v[196:199], v[12:15]
	v_mfma_f32_16x16x32_bf16 v[8:11], v[172:175], v[196:199], v[8:11]
	v_mfma_f32_16x16x32_bf16 v[4:7], v[164:167], v[204:207], v[4:7]
	v_mfma_f32_16x16x32_bf16 v[0:3], v[172:175], v[204:207], v[0:3]
	s_setprio 0
	s_barrier
	s_add_i32 s70, s70, 2
	s_add_u32 s48, s48, 0x100
	s_addc_u32 s49, s49, 0
	s_add_u32 s64, s64, 0x100
	s_addc_u32 s65, s65, 0
	s_cmp_gt_u32 s70, 13
	s_cbranch_scc0 .LBB0_3141
	s_and_b64 vcc, exec, s[12:13]
	s_cbranch_vccz .LBB0_3144
	s_barrier

; #define G_STAGE(bufoff, gbase, voff) do { _Pragma("unroll") for (int _i = 0; _i < 2; ++_i) \
;         __builtin_amdgcn_global_load_lds((const unsigned*)((const char*)(gbase) + voff[_i]), (LAS unsigned*)(lds + (bufoff) + ldsw + _i * 8192), 16, 0, 0); } while (0)
; #define G_LDA(dst, b, h) do { _Pragma("unroll") for (int m = 0; m < 4; ++m) _Pragma("unroll") for (int k = 0; k < 2; ++k) dst[m][k] = *(const LAS bf16x8*)(lds + G_SA(b, h) + aoff + m * 2048 + k * 1024); } while (0)
; #define G_LDB(dst, b, h) do { _Pragma("unroll") for (int n = 0; n < 2; ++n) _Pragma("unroll") for (int k = 0; k < 2; ++k) dst[n][k] = *(const LAS bf16x8*)(lds + G_SB(b, h) + boff + n * 2048 + k * 1024); } while (0)
; #define G_MMA(ai, bj, At_, Bt_) do { __builtin_amdgcn_s_setprio(1); _Pragma("unroll") for (int m = 0; m < 4; ++m) _Pragma("unroll") for (int n = 0; n < 2; ++n) _Pragma("unroll") for (int k = 0; k < 2; ++k) \
;         acc[ai][bj][m][n] = __builtin_amdgcn_mfma_f32_16x16x32_bf16(Bt_[n][k], At_[m][k], acc[ai][bj][m][n], 0, 0, 0); __builtin_amdgcn_s_setprio(0); } while (0)
; #define WAIT_V(n) asm volatile("s_waitcnt vmcnt(" #n ")" ::: "memory")
; #define WAIT_L(n) asm volatile("s_waitcnt lgkmcnt(" #n ")" ::: "memory")
; #define BAR __builtin_amdgcn_s_barrier()
; #define SCHED __builtin_amdgcn_sched_barrier(0)
; template <class Get, class Epi>
; DI void gemm_loop(int ntiles, int ld, char* shm, const Get& get, const Epi& epi) {
;     ...
;         for (int t = 0; t < nt; t += 2) {
;             const bool last = (t == nt - 2);
;             const char* a1 = cA + (size_t)(t + 1) * kstep;
;             const char* a2 = last ? nA : cA + (size_t)(t + 2) * kstep; const char* b2 = last ? nB : cB + (size_t)(t + 2) * kstep;
;             const char* a3 = a2 + kstep; const char* b3 = b2 + kstep;
;             G_LDB(B0, 0, 0); G_LDB(B1, 0, 1); SCHED; G_LDA(At, 0, 0); G_STAGE(G_SA(1, 1), a1 + hstep, voffA);
;             WAIT_V(8); WAIT_L(0); BAR; G_MMA(0, 0, At, B0); G_MMA(0, 1, At, B1); BAR; SCHED;
;             G_LDA(At, 0, 1); G_STAGE(G_SB(0, 0), b2, voffB); G_STAGE(G_SB(0, 1), b2 + hstep, voffB); G_STAGE(G_SA(0, 0), a2, voffA);
;             WAIT_V(8); WAIT_L(0); BAR; G_MMA(1, 0, At, B0); G_MMA(1, 1, At, B1); BAR; SCHED;
.LBB0_3466:
	ds_read_b128 v[128:131], v169
	ds_read_b128 v[132:135], v169 offset:1024
	ds_read_b128 v[136:139], v169 offset:2048
	ds_read_b128 v[140:143], v169 offset:3072
	ds_read_b128 v[158:161], v170
	ds_read_b128 v[162:165], v170 offset:1024
	ds_read_b128 v[172:175], v170 offset:2048
	ds_read_b128 v[176:179], v170 offset:3072
	s_add_u32 s14, s44, 0xfffc0080
	s_addc_u32 s15, s45, -1
	s_cmp_eq_u32 s71, 12
	s_cselect_b32 s47, s3, s15
	s_cselect_b32 s46, s35, s14
	s_cselect_b32 s15, s37, s70
	s_cselect_b32 s14, s64, s65
	v_lshl_add_u64 v[144:145], s[44:45], 0, v[154:155]
	s_add_i32 m0, s43, 0xc000
	ds_read_b128 v[180:183], v171
	ds_read_b128 v[184:187], v171 offset:1024
	ds_read_b128 v[188:191], v171 offset:2048
	ds_read_b128 v[192:195], v171 offset:3072
	ds_read_b128 v[196:199], v171 offset:4096
	ds_read_b128 v[200:203], v171 offset:5120
	ds_read_b128 v[204:207], v171 offset:6144
	ds_read_b128 v[208:211], v171 offset:7168
	global_load_lds_dwordx4 v[144:145], off
	v_lshl_add_u64 v[144:145], s[44:45], 0, v[156:157]
	s_add_i32 m0, s43, 0xe000
	s_nop 0
	global_load_lds_dwordx4 v[144:145], off
	s_mov_b32 s98, 0xfffc0000
	s_mov_b32 s99, -1
	v_lshl_add_u64 v[144:145], s[44:45], 0, v[154:155]
	v_lshl_add_u64 v[144:145], v[144:145], 0, s[98:99]
	s_add_i32 m0, s43, 0x8000
	s_nop 0
	global_load_lds_dwordx4 v[144:145], off
	v_lshl_add_u64 v[144:145], s[44:45], 0, v[156:157]
	v_lshl_add_u64 v[144:145], v[144:145], 0, s[98:99]
	s_add_i32 m0, s43, 0xa000
	s_nop 0
	global_load_lds_dwordx4 v[144:145], off
	s_waitcnt vmcnt(8)
	s_waitcnt lgkmcnt(0)
	s_barrier
	s_setprio 1
	s_waitcnt lgkmcnt(0)
	v_mfma_f32_16x16x32_bf16 v[124:127], v[128:131], v[180:183], v[124:127]
	v_mfma_f32_16x16x32_bf16 v[120:123], v[136:139], v[180:183], v[120:123]
	v_mfma_f32_16x16x32_bf16 v[116:119], v[128:131], v[188:191], v[116:119]
	v_mfma_f32_16x16x32_bf16 v[112:115], v[136:139], v[188:191], v[112:115]
	v_mfma_f32_16x16x32_bf16 v[108:111], v[128:131], v[196:199], v[108:111]
	v_mfma_f32_16x16x32_bf16 v[104:107], v[136:139], v[196:199], v[104:107]
	v_mfma_f32_16x16x32_bf16 v[100:103], v[128:131], v[204:207], v[100:103]
	v_mfma_f32_16x16x32_bf16 v[96:99], v[136:139], v[204:207], v[96:99]
	v_mfma_f32_16x16x32_bf16 v[124:127], v[132:135], v[184:187], v[124:127]
	v_mfma_f32_16x16x32_bf16 v[120:123], v[140:143], v[184:187], v[120:123]
	v_mfma_f32_16x16x32_bf16 v[116:119], v[132:135], v[192:195], v[116:119]
	v_mfma_f32_16x16x32_bf16 v[112:115], v[140:143], v[192:195], v[112:115]
	v_mfma_f32_16x16x32_bf16 v[108:111], v[132:135], v[200:203], v[108:111]
	v_mfma_f32_16x16x32_bf16 v[104:107], v[140:143], v[200:203], v[104:107]
	v_mfma_f32_16x16x32_bf16 v[100:103], v[132:135], v[208:211], v[100:103]
	v_mfma_f32_16x16x32_bf16 v[96:99], v[140:143], v[208:211], v[96:99]
	s_setprio 0
	s_setprio 1
	v_mfma_f32_16x16x32_bf16 v[60:63], v[158:161], v[180:183], v[60:63]
	v_mfma_f32_16x16x32_bf16 v[56:59], v[172:175], v[180:183], v[56:59]
	v_mfma_f32_16x16x32_bf16 v[52:55], v[158:161], v[188:191], v[52:55]
	v_mfma_f32_16x16x32_bf16 v[48:51], v[172:175], v[188:191], v[48:51]
	v_mfma_f32_16x16x32_bf16 v[44:47], v[158:161], v[196:199], v[44:47]
	v_mfma_f32_16x16x32_bf16 v[40:43], v[172:175], v[196:199], v[40:43]
	v_mfma_f32_16x16x32_bf16 v[36:39], v[158:161], v[204:207], v[36:39]
	v_mfma_f32_16x16x32_bf16 v[32:35], v[172:175], v[204:207], v[32:35]
	v_mfma_f32_16x16x32_bf16 v[60:63], v[162:165], v[184:187], v[60:63]
	v_mfma_f32_16x16x32_bf16 v[56:59], v[176:179], v[184:187], v[56:59]
	v_mfma_f32_16x16x32_bf16 v[52:55], v[162:165], v[192:195], v[52:55]
	v_mfma_f32_16x16x32_bf16 v[48:51], v[176:179], v[192:195], v[48:51]
	v_mfma_f32_16x16x32_bf16 v[44:47], v[162:165], v[200:203], v[44:47]
	v_mfma_f32_16x16x32_bf16 v[40:43], v[176:179], v[200:203], v[40:43]
	v_mfma_f32_16x16x32_bf16 v[36:39], v[162:165], v[208:211], v[36:39]
	v_mfma_f32_16x16x32_bf16 v[32:35], v[176:179], v[208:211], v[32:35]
	s_setprio 0
	s_barrier
	s_add_i32 s72, s56, s48
	v_lshl_add_u64 v[144:145], s[14:15], 0, v[148:149]
	s_mov_b32 m0, s72
	ds_read_b128 v[180:183], v171 offset:16384
	ds_read_b128 v[184:187], v171 offset:17408
	ds_read_b128 v[188:191], v171 offset:18432
	ds_read_b128 v[192:195], v171 offset:19456
	ds_read_b128 v[196:199], v171 offset:20480
	ds_read_b128 v[200:203], v171 offset:21504
	ds_read_b128 v[204:207], v171 offset:22528
	ds_read_b128 v[208:211], v171 offset:23552
	global_load_lds_dwordx4 v[144:145], off
	s_add_i32 m0, s72, 0x2000
	s_add_u32 s72, s14, 0x40000
	v_lshl_add_u64 v[166:167], s[14:15], 0, v[152:153]
	s_addc_u32 s73, s15, 0
	s_add_i32 s74, s57, s48
	global_load_lds_dwordx4 v[166:167], off
	v_lshl_add_u64 v[212:213], s[72:73], 0, v[148:149]
	s_mov_b32 m0, s74
	v_lshl_add_u64 v[214:215], s[46:47], 0, v[150:151]
	global_load_lds_dwordx4 v[212:213], off
	v_lshl_add_u64 v[212:213], s[72:73], 0, v[152:153]
	s_add_i32 m0, s74, 0x2000
	s_nop 0
	global_load_lds_dwordx4 v[212:213], off
	v_lshl_add_u64 v[212:213], s[46:47], 0, v[146:147]
	s_waitcnt vmcnt(4)
	s_waitcnt lgkmcnt(0)
	s_barrier
; #define G_STAGE(bufoff, gbase, voff) do { _Pragma("unroll") for (int _i = 0; _i < 2; ++_i) \
;         __builtin_amdgcn_global_load_lds((const unsigned*)((const char*)(gbase) + voff[_i]), (LAS unsigned*)(lds + (bufoff) + ldsw + _i * 8192), 16, 0, 0); } while (0)
; #define G_LDA(dst, b, h) do { _Pragma("unroll") for (int m = 0; m < 4; ++m) _Pragma("unroll") for (int k = 0; k < 2; ++k) dst[m][k] = *(const LAS bf16x8*)(lds + G_SA(b, h) + aoff + m * 2048 + k * 1024); } while (0)
; #define G_LDB(dst, b, h) do { _Pragma("unroll") for (int n = 0; n < 2; ++n) _Pragma("unroll") for (int k = 0; k < 2; ++k) dst[n][k] = *(const LAS bf16x8*)(lds + G_SB(b, h) + boff + n * 2048 + k * 1024); } while (0)
; #define G_MMA(ai, bj, At_, Bt_) do { __builtin_amdgcn_s_setprio(1); _Pragma("unroll") for (int m = 0; m < 4; ++m) _Pragma("unroll") for (int n = 0; n < 2; ++n) _Pragma("unroll") for (int k = 0; k < 2; ++k) \
;         acc[ai][bj][m][n] = __builtin_amdgcn_mfma_f32_16x16x32_bf16(Bt_[n][k], At_[m][k], acc[ai][bj][m][n], 0, 0, 0); __builtin_amdgcn_s_setprio(0); } while (0)
; #define WAIT_V(n) asm volatile("s_waitcnt vmcnt(" #n ")" ::: "memory")
; #define WAIT_L(n) asm volatile("s_waitcnt lgkmcnt(" #n ")" ::: "memory")
; #define BAR __builtin_amdgcn_s_barrier()
; #define SCHED __builtin_amdgcn_sched_barrier(0)
; template <class Get, class Epi>
; DI void gemm_loop(int ntiles, int ld, char* shm, const Get& get, const Epi& epi) {
;     ...
;             WAIT_V(8); WAIT_L(0); BAR; G_MMA(1, 0, At, B0); G_MMA(1, 1, At, B1); BAR; SCHED;
;             G_LDB(B0, 1, 0); G_LDB(B1, 1, 1); SCHED; G_LDA(At, 1, 0); G_STAGE(G_SA(0, 1), a2 + hstep, voffA);
;             WAIT_V(8); WAIT_L(0); BAR; G_MMA(0, 0, At, B0); G_MMA(0, 1, At, B1); BAR; SCHED;
	s_setprio 1
	s_waitcnt lgkmcnt(0)
	v_mfma_f32_16x16x32_bf16 v[92:95], v[128:131], v[180:183], v[92:95]
	v_mfma_f32_16x16x32_bf16 v[88:91], v[136:139], v[180:183], v[88:91]
	v_mfma_f32_16x16x32_bf16 v[84:87], v[128:131], v[188:191], v[84:87]
	v_mfma_f32_16x16x32_bf16 v[80:83], v[136:139], v[188:191], v[80:83]
	v_mfma_f32_16x16x32_bf16 v[76:79], v[128:131], v[196:199], v[76:79]
	v_mfma_f32_16x16x32_bf16 v[72:75], v[136:139], v[196:199], v[72:75]
	v_mfma_f32_16x16x32_bf16 v[68:71], v[128:131], v[204:207], v[68:71]
	v_mfma_f32_16x16x32_bf16 v[64:67], v[136:139], v[204:207], v[64:67]
	v_mfma_f32_16x16x32_bf16 v[92:95], v[132:135], v[184:187], v[92:95]
	v_mfma_f32_16x16x32_bf16 v[88:91], v[140:143], v[184:187], v[88:91]
	v_mfma_f32_16x16x32_bf16 v[84:87], v[132:135], v[192:195], v[84:87]
	v_mfma_f32_16x16x32_bf16 v[80:83], v[140:143], v[192:195], v[80:83]
	v_mfma_f32_16x16x32_bf16 v[76:79], v[132:135], v[200:203], v[76:79]
	v_mfma_f32_16x16x32_bf16 v[72:75], v[140:143], v[200:203], v[72:75]
	v_mfma_f32_16x16x32_bf16 v[68:71], v[132:135], v[208:211], v[68:71]
	v_mfma_f32_16x16x32_bf16 v[64:67], v[140:143], v[208:211], v[64:67]
	s_setprio 0
	s_setprio 1
	v_mfma_f32_16x16x32_bf16 v[28:31], v[158:161], v[180:183], v[28:31]
	v_mfma_f32_16x16x32_bf16 v[24:27], v[172:175], v[180:183], v[24:27]
	v_mfma_f32_16x16x32_bf16 v[20:23], v[158:161], v[188:191], v[20:23]
	v_mfma_f32_16x16x32_bf16 v[16:19], v[172:175], v[188:191], v[16:19]
	v_mfma_f32_16x16x32_bf16 v[12:15], v[158:161], v[196:199], v[12:15]
	v_mfma_f32_16x16x32_bf16 v[8:11], v[172:175], v[196:199], v[8:11]
	v_mfma_f32_16x16x32_bf16 v[4:7], v[158:161], v[204:207], v[4:7]
	v_mfma_f32_16x16x32_bf16 v[0:3], v[172:175], v[204:207], v[0:3]
	v_mfma_f32_16x16x32_bf16 v[28:31], v[162:165], v[184:187], v[28:31]
	v_mfma_f32_16x16x32_bf16 v[24:27], v[176:179], v[184:187], v[24:27]
	v_mfma_f32_16x16x32_bf16 v[20:23], v[162:165], v[192:195], v[20:23]
	v_mfma_f32_16x16x32_bf16 v[16:19], v[176:179], v[192:195], v[16:19]
	v_mfma_f32_16x16x32_bf16 v[12:15], v[162:165], v[200:203], v[12:15]
	v_mfma_f32_16x16x32_bf16 v[8:11], v[176:179], v[200:203], v[8:11]
	v_mfma_f32_16x16x32_bf16 v[4:7], v[162:165], v[208:211], v[4:7]
	v_mfma_f32_16x16x32_bf16 v[0:3], v[176:179], v[208:211], v[0:3]
	s_setprio 0
	s_barrier
	s_add_i32 s72, 0, 0x18000
	s_add_i32 s73, 0, 0x1c000
	v_add_u32_e32 v140, s72, v168
	v_add_u32_e32 v176, s73, v168
	ds_read_b128 v[128:131], v140
	ds_read_b128 v[132:135], v140 offset:1024
	ds_read_b128 v[136:139], v140 offset:2048
	ds_read_b128 v[140:143], v140 offset:3072
	ds_read_b128 v[158:161], v176
	ds_read_b128 v[162:165], v176 offset:1024
	ds_read_b128 v[172:175], v176 offset:2048
	ds_read_b128 v[176:179], v176 offset:3072
	s_add_u32 s46, s46, 0x40000
	s_addc_u32 s47, s47, 0
	s_mov_b32 m0, s50
	v_lshl_add_u64 v[216:217], s[46:47], 0, v[146:147]
	ds_read_b128 v[180:183], v171 offset:32768
	ds_read_b128 v[184:187], v171 offset:33792
	ds_read_b128 v[188:191], v171 offset:34816
	ds_read_b128 v[192:195], v171 offset:35840
	ds_read_b128 v[196:199], v171 offset:36864
	ds_read_b128 v[200:203], v171 offset:37888
	ds_read_b128 v[204:207], v171 offset:38912
	ds_read_b128 v[208:211], v171 offset:39936
	global_load_lds_dwordx4 v[216:217], off
	v_lshl_add_u64 v[216:217], s[46:47], 0, v[150:151]
	s_mov_b32 m0, s51
	s_nop 0
	global_load_lds_dwordx4 v[216:217], off
	s_mov_b32 m0, s43
	s_nop 0
	global_load_lds_dwordx4 v[212:213], off
	s_mov_b32 m0, s49
	s_nop 0
	global_load_lds_dwordx4 v[214:215], off
	s_waitcnt vmcnt(8)
	s_waitcnt lgkmcnt(0)
	s_barrier
; #define G_STAGE(bufoff, gbase, voff) do { _Pragma("unroll") for (int _i = 0; _i < 2; ++_i) \
;         __builtin_amdgcn_global_load_lds((const unsigned*)((const char*)(gbase) + voff[_i]), (LAS unsigned*)(lds + (bufoff) + ldsw + _i * 8192), 16, 0, 0); } while (0)
; #define G_LDA(dst, b, h) do { _Pragma("unroll") for (int m = 0; m < 4; ++m) _Pragma("unroll") for (int k = 0; k < 2; ++k) dst[m][k] = *(const LAS bf16x8*)(lds + G_SA(b, h) + aoff + m * 2048 + k * 1024); } while (0)
; #define G_MMA(ai, bj, At_, Bt_) do { __builtin_amdgcn_s_setprio(1); _Pragma("unroll") for (int m = 0; m < 4; ++m) _Pragma("unroll") for (int n = 0; n < 2; ++n) _Pragma("unroll") for (int k = 0; k < 2; ++k) \
;         acc[ai][bj][m][n] = __builtin_amdgcn_mfma_f32_16x16x32_bf16(Bt_[n][k], At_[m][k], acc[ai][bj][m][n], 0, 0, 0); __builtin_amdgcn_s_setprio(0); } while (0)
; #define WAIT_V(n) asm volatile("s_waitcnt vmcnt(" #n ")" ::: "memory")
; #define WAIT_L(n) asm volatile("s_waitcnt lgkmcnt(" #n ")" ::: "memory")
; #define BAR __builtin_amdgcn_s_barrier()
; #define SCHED __builtin_amdgcn_sched_barrier(0)
; template <class Get, class Epi>
; DI void gemm_loop(int ntiles, int ld, char* shm, const Get& get, const Epi& epi) {
;     ...
;             WAIT_V(8); WAIT_L(0); BAR; G_MMA(0, 0, At, B0); G_MMA(0, 1, At, B1); BAR; SCHED;
;             G_LDA(At, 1, 1); G_STAGE(G_SB(1, 0), b3, voffB); G_STAGE(G_SB(1, 1), b3 + hstep, voffB); G_STAGE(G_SA(1, 0), a3, voffA);
;             WAIT_V(8); WAIT_L(0); BAR; G_MMA(1, 0, At, B0); G_MMA(1, 1, At, B1); BAR; SCHED;
;         }
;         if (wr == 0) BAR;
	s_setprio 1
	s_waitcnt lgkmcnt(0)
	v_mfma_f32_16x16x32_bf16 v[124:127], v[128:131], v[180:183], v[124:127]
	v_mfma_f32_16x16x32_bf16 v[120:123], v[136:139], v[180:183], v[120:123]
	v_mfma_f32_16x16x32_bf16 v[116:119], v[128:131], v[188:191], v[116:119]
	v_mfma_f32_16x16x32_bf16 v[112:115], v[136:139], v[188:191], v[112:115]
	v_mfma_f32_16x16x32_bf16 v[108:111], v[128:131], v[196:199], v[108:111]
	v_mfma_f32_16x16x32_bf16 v[104:107], v[136:139], v[196:199], v[104:107]
	v_mfma_f32_16x16x32_bf16 v[100:103], v[128:131], v[204:207], v[100:103]
	v_mfma_f32_16x16x32_bf16 v[96:99], v[136:139], v[204:207], v[96:99]
	v_mfma_f32_16x16x32_bf16 v[124:127], v[132:135], v[184:187], v[124:127]
	v_mfma_f32_16x16x32_bf16 v[120:123], v[140:143], v[184:187], v[120:123]
	v_mfma_f32_16x16x32_bf16 v[116:119], v[132:135], v[192:195], v[116:119]
	v_mfma_f32_16x16x32_bf16 v[112:115], v[140:143], v[192:195], v[112:115]
	v_mfma_f32_16x16x32_bf16 v[108:111], v[132:135], v[200:203], v[108:111]
	v_mfma_f32_16x16x32_bf16 v[104:107], v[140:143], v[200:203], v[104:107]
	v_mfma_f32_16x16x32_bf16 v[100:103], v[132:135], v[208:211], v[100:103]
	v_mfma_f32_16x16x32_bf16 v[96:99], v[140:143], v[208:211], v[96:99]
	s_setprio 0
	s_setprio 1
	v_mfma_f32_16x16x32_bf16 v[60:63], v[158:161], v[180:183], v[60:63]
	v_mfma_f32_16x16x32_bf16 v[56:59], v[172:175], v[180:183], v[56:59]
	v_mfma_f32_16x16x32_bf16 v[52:55], v[158:161], v[188:191], v[52:55]
	v_mfma_f32_16x16x32_bf16 v[48:51], v[172:175], v[188:191], v[48:51]
	v_mfma_f32_16x16x32_bf16 v[44:47], v[158:161], v[196:199], v[44:47]
	v_mfma_f32_16x16x32_bf16 v[40:43], v[172:175], v[196:199], v[40:43]
	v_mfma_f32_16x16x32_bf16 v[36:39], v[158:161], v[204:207], v[36:39]
	v_mfma_f32_16x16x32_bf16 v[32:35], v[172:175], v[204:207], v[32:35]
	v_mfma_f32_16x16x32_bf16 v[60:63], v[162:165], v[184:187], v[60:63]
	v_mfma_f32_16x16x32_bf16 v[56:59], v[176:179], v[184:187], v[56:59]
	v_mfma_f32_16x16x32_bf16 v[52:55], v[162:165], v[192:195], v[52:55]
	v_mfma_f32_16x16x32_bf16 v[48:51], v[176:179], v[192:195], v[48:51]
	v_mfma_f32_16x16x32_bf16 v[44:47], v[162:165], v[200:203], v[44:47]
	v_mfma_f32_16x16x32_bf16 v[40:43], v[176:179], v[200:203], v[40:43]
	v_mfma_f32_16x16x32_bf16 v[36:39], v[162:165], v[208:211], v[36:39]
	v_mfma_f32_16x16x32_bf16 v[32:35], v[176:179], v[208:211], v[32:35]
	s_setprio 0
	s_barrier
	s_add_i32 s46, s72, s48
	v_lshl_add_u64 v[144:145], v[144:145], 0, s[4:5]
	s_mov_b32 m0, s46
	ds_read_b128 v[180:183], v171 offset:49152
	ds_read_b128 v[184:187], v171 offset:50176
	ds_read_b128 v[188:191], v171 offset:51200
	ds_read_b128 v[192:195], v171 offset:52224
	ds_read_b128 v[196:199], v171 offset:53248
	ds_read_b128 v[200:203], v171 offset:54272
	ds_read_b128 v[204:207], v171 offset:55296
	ds_read_b128 v[208:211], v171 offset:56320
	global_load_lds_dwordx4 v[144:145], off
	s_add_i32 m0, s46, 0x2000
	s_add_u32 s14, s14, 0x40080
	v_lshl_add_u64 v[144:145], v[166:167], 0, s[4:5]
	s_addc_u32 s15, s15, 0
	s_add_i32 s46, s73, s48
	global_load_lds_dwordx4 v[144:145], off
	v_lshl_add_u64 v[144:145], s[14:15], 0, v[148:149]
	s_mov_b32 m0, s46
	s_nop 0
	global_load_lds_dwordx4 v[144:145], off
	v_lshl_add_u64 v[144:145], s[14:15], 0, v[152:153]
	s_add_i32 m0, s46, 0x2000
	s_nop 0
	global_load_lds_dwordx4 v[144:145], off
	s_waitcnt vmcnt(4)
	s_waitcnt lgkmcnt(0)
	s_barrier
	s_setprio 1
	s_waitcnt lgkmcnt(0)
	v_mfma_f32_16x16x32_bf16 v[92:95], v[128:131], v[180:183], v[92:95]
	v_mfma_f32_16x16x32_bf16 v[88:91], v[136:139], v[180:183], v[88:91]
	v_mfma_f32_16x16x32_bf16 v[84:87], v[128:131], v[188:191], v[84:87]
	v_mfma_f32_16x16x32_bf16 v[80:83], v[136:139], v[188:191], v[80:83]
	v_mfma_f32_16x16x32_bf16 v[76:79], v[128:131], v[196:199], v[76:79]
	v_mfma_f32_16x16x32_bf16 v[72:75], v[136:139], v[196:199], v[72:75]
	v_mfma_f32_16x16x32_bf16 v[68:71], v[128:131], v[204:207], v[68:71]
	v_mfma_f32_16x16x32_bf16 v[64:67], v[136:139], v[204:207], v[64:67]
	v_mfma_f32_16x16x32_bf16 v[92:95], v[132:135], v[184:187], v[92:95]
	v_mfma_f32_16x16x32_bf16 v[88:91], v[140:143], v[184:187], v[88:91]
	v_mfma_f32_16x16x32_bf16 v[84:87], v[132:135], v[192:195], v[84:87]
	v_mfma_f32_16x16x32_bf16 v[80:83], v[140:143], v[192:195], v[80:83]
	v_mfma_f32_16x16x32_bf16 v[76:79], v[132:135], v[200:203], v[76:79]
	v_mfma_f32_16x16x32_bf16 v[72:75], v[140:143], v[200:203], v[72:75]
	v_mfma_f32_16x16x32_bf16 v[68:71], v[132:135], v[208:211], v[68:71]
	v_mfma_f32_16x16x32_bf16 v[64:67], v[140:143], v[208:211], v[64:67]
	s_setprio 0
	s_setprio 1
	v_mfma_f32_16x16x32_bf16 v[28:31], v[158:161], v[180:183], v[28:31]
	v_mfma_f32_16x16x32_bf16 v[24:27], v[172:175], v[180:183], v[24:27]
	v_mfma_f32_16x16x32_bf16 v[20:23], v[158:161], v[188:191], v[20:23]
	v_mfma_f32_16x16x32_bf16 v[16:19], v[172:175], v[188:191], v[16:19]
	v_mfma_f32_16x16x32_bf16 v[12:15], v[158:161], v[196:199], v[12:15]
	v_mfma_f32_16x16x32_bf16 v[8:11], v[172:175], v[196:199], v[8:11]
	v_mfma_f32_16x16x32_bf16 v[4:7], v[158:161], v[204:207], v[4:7]
	v_mfma_f32_16x16x32_bf16 v[0:3], v[172:175], v[204:207], v[0:3]
	v_mfma_f32_16x16x32_bf16 v[28:31], v[162:165], v[184:187], v[28:31]
	v_mfma_f32_16x16x32_bf16 v[24:27], v[176:179], v[184:187], v[24:27]
	v_mfma_f32_16x16x32_bf16 v[20:23], v[162:165], v[192:195], v[20:23]
	v_mfma_f32_16x16x32_bf16 v[16:19], v[176:179], v[192:195], v[16:19]
	v_mfma_f32_16x16x32_bf16 v[12:15], v[162:165], v[200:203], v[12:15]
	v_mfma_f32_16x16x32_bf16 v[8:11], v[176:179], v[200:203], v[8:11]
	v_mfma_f32_16x16x32_bf16 v[4:7], v[162:165], v[208:211], v[4:7]
	v_mfma_f32_16x16x32_bf16 v[0:3], v[176:179], v[208:211], v[0:3]
	s_setprio 0
	s_barrier
	s_add_i32 s71, s71, 2
	s_add_u32 s44, s44, 0x100
	s_addc_u32 s45, s45, 0
	s_add_u32 s65, s65, 0x100
	s_addc_u32 s70, s70, 0
	s_cmp_gt_u32 s71, 13
	s_cbranch_scc0 .LBB0_3466
	s_and_b64 vcc, exec, s[6:7]
	s_cbranch_vccz .LBB0_3469
	s_barrier

; #define G_STAGE(bufoff, gbase, voff) do { _Pragma("unroll") for (int _i = 0; _i < 2; ++_i) \
;         __builtin_amdgcn_global_load_lds((const unsigned*)((const char*)(gbase) + voff[_i]), (LAS unsigned*)(lds + (bufoff) + ldsw + _i * 8192), 16, 0, 0); } while (0)
; #define G_LDA(dst, b, h) do { _Pragma("unroll") for (int m = 0; m < 4; ++m) _Pragma("unroll") for (int k = 0; k < 2; ++k) dst[m][k] = *(const LAS bf16x8*)(lds + G_SA(b, h) + aoff + m * 2048 + k * 1024); } while (0)
; #define G_LDB(dst, b, h) do { _Pragma("unroll") for (int n = 0; n < 2; ++n) _Pragma("unroll") for (int k = 0; k < 2; ++k) dst[n][k] = *(const LAS bf16x8*)(lds + G_SB(b, h) + boff + n * 2048 + k * 1024); } while (0)
; #define G_MMA(ai, bj, At_, Bt_) do { __builtin_amdgcn_s_setprio(1); _Pragma("unroll") for (int m = 0; m < 4; ++m) _Pragma("unroll") for (int n = 0; n < 2; ++n) _Pragma("unroll") for (int k = 0; k < 2; ++k) \
;         acc[ai][bj][m][n] = __builtin_amdgcn_mfma_f32_16x16x32_bf16(Bt_[n][k], At_[m][k], acc[ai][bj][m][n], 0, 0, 0); __builtin_amdgcn_s_setprio(0); } while (0)
; #define WAIT_V(n) asm volatile("s_waitcnt vmcnt(" #n ")" ::: "memory")
; #define WAIT_L(n) asm volatile("s_waitcnt lgkmcnt(" #n ")" ::: "memory")
; #define BAR __builtin_amdgcn_s_barrier()
; #define SCHED __builtin_amdgcn_sched_barrier(0)
; template <class Get, class Epi>
; DI void gemm_loop(int ntiles, int ld, char* shm, const Get& get, const Epi& epi) {
;     ...
;         for (int t = 0; t < nt; t += 2) {
;             const bool last = (t == nt - 2);
;             const char* a1 = cA + (size_t)(t + 1) * kstep;
;             const char* a2 = last ? nA : cA + (size_t)(t + 2) * kstep; const char* b2 = last ? nB : cB + (size_t)(t + 2) * kstep;
;             const char* a3 = a2 + kstep; const char* b3 = b2 + kstep;
;             G_LDB(B0, 0, 0); G_LDB(B1, 0, 1); SCHED; G_LDA(At, 0, 0); G_STAGE(G_SA(1, 1), a1 + hstep, voffA);
;             WAIT_V(8); WAIT_L(0); BAR; G_MMA(0, 0, At, B0); G_MMA(0, 1, At, B1); BAR; SCHED;
;             G_LDA(At, 0, 1); G_STAGE(G_SB(0, 0), b2, voffB); G_STAGE(G_SB(0, 1), b2 + hstep, voffB); G_STAGE(G_SA(0, 0), a2, voffA);
;             WAIT_V(8); WAIT_L(0); BAR; G_MMA(1, 0, At, B0); G_MMA(1, 1, At, B1); BAR; SCHED;
.LBB0_3679:
	ds_read_b128 v[144:147], v141
	ds_read_b128 v[148:151], v141 offset:1024
	ds_read_b128 v[152:155], v141 offset:2048
	ds_read_b128 v[156:159], v141 offset:3072
	ds_read_b128 v[160:163], v142
	ds_read_b128 v[164:167], v142 offset:1024
	ds_read_b128 v[168:171], v142 offset:2048
	ds_read_b128 v[172:175], v142 offset:3072
	s_add_u32 s14, s34, 0xfffc0080
	s_addc_u32 s15, s35, -1
	s_cmp_eq_u32 s53, 12
	s_cselect_b32 s37, s9, s15
	s_cselect_b32 s36, s49, s14
	s_cselect_b32 s15, s11, s52
	s_cselect_b32 s14, s50, s51
	v_lshl_add_u64 v[208:209], s[34:35], 0, v[136:137]
	s_add_i32 m0, s25, 0xc000
	ds_read_b128 v[176:179], v143
	ds_read_b128 v[180:183], v143 offset:1024
	ds_read_b128 v[184:187], v143 offset:2048
	ds_read_b128 v[188:191], v143 offset:3072
	ds_read_b128 v[192:195], v143 offset:4096
	ds_read_b128 v[196:199], v143 offset:5120
	ds_read_b128 v[200:203], v143 offset:6144
	ds_read_b128 v[204:207], v143 offset:7168
	global_load_lds_dwordx4 v[208:209], off
	v_lshl_add_u64 v[208:209], s[34:35], 0, v[138:139]
	s_add_i32 m0, s25, 0xe000
	s_nop 0
	global_load_lds_dwordx4 v[208:209], off
	s_mov_b32 s98, 0xfffc0000
	s_mov_b32 s99, -1
	v_lshl_add_u64 v[208:209], s[34:35], 0, v[136:137]
	v_lshl_add_u64 v[208:209], v[208:209], 0, s[98:99]
	s_add_i32 m0, s25, 0x8000
	s_nop 0
	global_load_lds_dwordx4 v[208:209], off
	v_lshl_add_u64 v[208:209], s[34:35], 0, v[138:139]
	v_lshl_add_u64 v[208:209], v[208:209], 0, s[98:99]
	s_add_i32 m0, s25, 0xa000
	s_nop 0
	global_load_lds_dwordx4 v[208:209], off
	s_waitcnt vmcnt(8)
	s_waitcnt lgkmcnt(0)
	s_barrier
	s_setprio 1
	s_waitcnt lgkmcnt(0)
	v_mfma_f32_16x16x32_bf16 v[124:127], v[144:147], v[176:179], v[124:127]
	v_mfma_f32_16x16x32_bf16 v[120:123], v[152:155], v[176:179], v[120:123]
	v_mfma_f32_16x16x32_bf16 v[108:111], v[144:147], v[184:187], v[108:111]
	v_mfma_f32_16x16x32_bf16 v[104:107], v[152:155], v[184:187], v[104:107]
	v_mfma_f32_16x16x32_bf16 v[92:95], v[144:147], v[192:195], v[92:95]
	v_mfma_f32_16x16x32_bf16 v[88:91], v[152:155], v[192:195], v[88:91]
	v_mfma_f32_16x16x32_bf16 v[76:79], v[144:147], v[200:203], v[76:79]
	v_mfma_f32_16x16x32_bf16 v[72:75], v[152:155], v[200:203], v[72:75]
	v_mfma_f32_16x16x32_bf16 v[124:127], v[148:151], v[180:183], v[124:127]
	v_mfma_f32_16x16x32_bf16 v[120:123], v[156:159], v[180:183], v[120:123]
	v_mfma_f32_16x16x32_bf16 v[108:111], v[148:151], v[188:191], v[108:111]
	v_mfma_f32_16x16x32_bf16 v[104:107], v[156:159], v[188:191], v[104:107]
	v_mfma_f32_16x16x32_bf16 v[92:95], v[148:151], v[196:199], v[92:95]
	v_mfma_f32_16x16x32_bf16 v[88:91], v[156:159], v[196:199], v[88:91]
	v_mfma_f32_16x16x32_bf16 v[76:79], v[148:151], v[204:207], v[76:79]
	v_mfma_f32_16x16x32_bf16 v[72:75], v[156:159], v[204:207], v[72:75]
	s_setprio 0
	s_setprio 1
	v_mfma_f32_16x16x32_bf16 v[116:119], v[160:163], v[176:179], v[116:119]
	v_mfma_f32_16x16x32_bf16 v[112:115], v[168:171], v[176:179], v[112:115]
	v_mfma_f32_16x16x32_bf16 v[100:103], v[160:163], v[184:187], v[100:103]
	v_mfma_f32_16x16x32_bf16 v[96:99], v[168:171], v[184:187], v[96:99]
	v_mfma_f32_16x16x32_bf16 v[84:87], v[160:163], v[192:195], v[84:87]
	v_mfma_f32_16x16x32_bf16 v[80:83], v[168:171], v[192:195], v[80:83]
	v_mfma_f32_16x16x32_bf16 v[68:71], v[160:163], v[200:203], v[68:71]
	v_mfma_f32_16x16x32_bf16 v[64:67], v[168:171], v[200:203], v[64:67]
	v_mfma_f32_16x16x32_bf16 v[116:119], v[164:167], v[180:183], v[116:119]
	v_mfma_f32_16x16x32_bf16 v[112:115], v[172:175], v[180:183], v[112:115]
	v_mfma_f32_16x16x32_bf16 v[100:103], v[164:167], v[188:191], v[100:103]
	v_mfma_f32_16x16x32_bf16 v[96:99], v[172:175], v[188:191], v[96:99]
	v_mfma_f32_16x16x32_bf16 v[84:87], v[164:167], v[196:199], v[84:87]
	v_mfma_f32_16x16x32_bf16 v[80:83], v[172:175], v[196:199], v[80:83]
	v_mfma_f32_16x16x32_bf16 v[68:71], v[164:167], v[204:207], v[68:71]
	v_mfma_f32_16x16x32_bf16 v[64:67], v[172:175], v[204:207], v[64:67]
	s_setprio 0
	s_barrier
	s_add_i32 s54, s44, s38
	v_lshl_add_u64 v[208:209], s[14:15], 0, v[132:133]
	s_mov_b32 m0, s54
	ds_read_b128 v[176:179], v143 offset:16384
	ds_read_b128 v[180:183], v143 offset:17408
	ds_read_b128 v[184:187], v143 offset:18432
	ds_read_b128 v[188:191], v143 offset:19456
	ds_read_b128 v[192:195], v143 offset:20480
	ds_read_b128 v[196:199], v143 offset:21504
	ds_read_b128 v[200:203], v143 offset:22528
	ds_read_b128 v[204:207], v143 offset:23552
	global_load_lds_dwordx4 v[208:209], off
	s_add_i32 m0, s54, 0x2000
	s_add_u32 s54, s14, 0x40000
	v_lshl_add_u64 v[210:211], s[14:15], 0, v[128:129]
	s_addc_u32 s55, s15, 0
	s_add_i32 s56, s45, s38
	global_load_lds_dwordx4 v[210:211], off
	v_lshl_add_u64 v[212:213], s[54:55], 0, v[132:133]
	s_mov_b32 m0, s56
	v_lshl_add_u64 v[214:215], s[36:37], 0, v[130:131]
	global_load_lds_dwordx4 v[212:213], off
	v_lshl_add_u64 v[212:213], s[54:55], 0, v[128:129]
	s_add_i32 m0, s56, 0x2000
	s_nop 0
	global_load_lds_dwordx4 v[212:213], off
	v_lshl_add_u64 v[212:213], s[36:37], 0, v[134:135]
	s_waitcnt vmcnt(4)
	s_waitcnt lgkmcnt(0)
	s_barrier
; #define G_STAGE(bufoff, gbase, voff) do { _Pragma("unroll") for (int _i = 0; _i < 2; ++_i) \
;         __builtin_amdgcn_global_load_lds((const unsigned*)((const char*)(gbase) + voff[_i]), (LAS unsigned*)(lds + (bufoff) + ldsw + _i * 8192), 16, 0, 0); } while (0)
; #define G_LDA(dst, b, h) do { _Pragma("unroll") for (int m = 0; m < 4; ++m) _Pragma("unroll") for (int k = 0; k < 2; ++k) dst[m][k] = *(const LAS bf16x8*)(lds + G_SA(b, h) + aoff + m * 2048 + k * 1024); } while (0)
; #define G_LDB(dst, b, h) do { _Pragma("unroll") for (int n = 0; n < 2; ++n) _Pragma("unroll") for (int k = 0; k < 2; ++k) dst[n][k] = *(const LAS bf16x8*)(lds + G_SB(b, h) + boff + n * 2048 + k * 1024); } while (0)
; #define G_MMA(ai, bj, At_, Bt_) do { __builtin_amdgcn_s_setprio(1); _Pragma("unroll") for (int m = 0; m < 4; ++m) _Pragma("unroll") for (int n = 0; n < 2; ++n) _Pragma("unroll") for (int k = 0; k < 2; ++k) \
;         acc[ai][bj][m][n] = __builtin_amdgcn_mfma_f32_16x16x32_bf16(Bt_[n][k], At_[m][k], acc[ai][bj][m][n], 0, 0, 0); __builtin_amdgcn_s_setprio(0); } while (0)
; #define WAIT_V(n) asm volatile("s_waitcnt vmcnt(" #n ")" ::: "memory")
; #define WAIT_L(n) asm volatile("s_waitcnt lgkmcnt(" #n ")" ::: "memory")
; #define BAR __builtin_amdgcn_s_barrier()
; #define SCHED __builtin_amdgcn_sched_barrier(0)
; template <class Get, class Epi>
; DI void gemm_loop(int ntiles, int ld, char* shm, const Get& get, const Epi& epi) {
;     ...
;             WAIT_V(8); WAIT_L(0); BAR; G_MMA(1, 0, At, B0); G_MMA(1, 1, At, B1); BAR; SCHED;
;             G_LDB(B0, 1, 0); G_LDB(B1, 1, 1); SCHED; G_LDA(At, 1, 0); G_STAGE(G_SA(0, 1), a2 + hstep, voffA);
;             WAIT_V(8); WAIT_L(0); BAR; G_MMA(0, 0, At, B0); G_MMA(0, 1, At, B1); BAR; SCHED;
	s_setprio 1
	s_waitcnt lgkmcnt(0)
	v_mfma_f32_16x16x32_bf16 v[60:63], v[144:147], v[176:179], v[60:63]
	v_mfma_f32_16x16x32_bf16 v[56:59], v[152:155], v[176:179], v[56:59]
	v_mfma_f32_16x16x32_bf16 v[44:47], v[144:147], v[184:187], v[44:47]
	v_mfma_f32_16x16x32_bf16 v[40:43], v[152:155], v[184:187], v[40:43]
	v_mfma_f32_16x16x32_bf16 v[28:31], v[144:147], v[192:195], v[28:31]
	v_mfma_f32_16x16x32_bf16 v[24:27], v[152:155], v[192:195], v[24:27]
	v_mfma_f32_16x16x32_bf16 v[12:15], v[144:147], v[200:203], v[12:15]
	v_mfma_f32_16x16x32_bf16 v[8:11], v[152:155], v[200:203], v[8:11]
	v_mfma_f32_16x16x32_bf16 v[60:63], v[148:151], v[180:183], v[60:63]
	v_mfma_f32_16x16x32_bf16 v[56:59], v[156:159], v[180:183], v[56:59]
	v_mfma_f32_16x16x32_bf16 v[44:47], v[148:151], v[188:191], v[44:47]
	v_mfma_f32_16x16x32_bf16 v[40:43], v[156:159], v[188:191], v[40:43]
	v_mfma_f32_16x16x32_bf16 v[28:31], v[148:151], v[196:199], v[28:31]
	v_mfma_f32_16x16x32_bf16 v[24:27], v[156:159], v[196:199], v[24:27]
	v_mfma_f32_16x16x32_bf16 v[12:15], v[148:151], v[204:207], v[12:15]
	v_mfma_f32_16x16x32_bf16 v[8:11], v[156:159], v[204:207], v[8:11]
	s_setprio 0
	s_setprio 1
	v_mfma_f32_16x16x32_bf16 v[52:55], v[160:163], v[176:179], v[52:55]
	v_mfma_f32_16x16x32_bf16 v[48:51], v[168:171], v[176:179], v[48:51]
	v_mfma_f32_16x16x32_bf16 v[36:39], v[160:163], v[184:187], v[36:39]
	v_mfma_f32_16x16x32_bf16 v[32:35], v[168:171], v[184:187], v[32:35]
	v_mfma_f32_16x16x32_bf16 v[20:23], v[160:163], v[192:195], v[20:23]
	v_mfma_f32_16x16x32_bf16 v[16:19], v[168:171], v[192:195], v[16:19]
	v_mfma_f32_16x16x32_bf16 v[4:7], v[160:163], v[200:203], v[4:7]
	v_mfma_f32_16x16x32_bf16 v[0:3], v[168:171], v[200:203], v[0:3]
	v_mfma_f32_16x16x32_bf16 v[52:55], v[164:167], v[180:183], v[52:55]
	v_mfma_f32_16x16x32_bf16 v[48:51], v[172:175], v[180:183], v[48:51]
	v_mfma_f32_16x16x32_bf16 v[36:39], v[164:167], v[188:191], v[36:39]
	v_mfma_f32_16x16x32_bf16 v[32:35], v[172:175], v[188:191], v[32:35]
	v_mfma_f32_16x16x32_bf16 v[20:23], v[164:167], v[196:199], v[20:23]
	v_mfma_f32_16x16x32_bf16 v[16:19], v[172:175], v[196:199], v[16:19]
	v_mfma_f32_16x16x32_bf16 v[4:7], v[164:167], v[204:207], v[4:7]
	v_mfma_f32_16x16x32_bf16 v[0:3], v[172:175], v[204:207], v[0:3]
	s_setprio 0
	s_barrier
	s_add_i32 s54, 0, 0x18000
	s_add_i32 s55, 0, 0x1c000
	v_add_u32_e32 v156, s54, v140
	v_add_u32_e32 v172, s55, v140
	ds_read_b128 v[144:147], v156
	ds_read_b128 v[148:151], v156 offset:1024
	ds_read_b128 v[152:155], v156 offset:2048
	ds_read_b128 v[156:159], v156 offset:3072
	ds_read_b128 v[160:163], v172
	ds_read_b128 v[164:167], v172 offset:1024
	ds_read_b128 v[168:171], v172 offset:2048
	ds_read_b128 v[172:175], v172 offset:3072
	s_add_u32 s36, s36, 0x40000
	s_addc_u32 s37, s37, 0
	s_mov_b32 m0, s40
	v_lshl_add_u64 v[216:217], s[36:37], 0, v[134:135]
	ds_read_b128 v[176:179], v143 offset:32768
	ds_read_b128 v[180:183], v143 offset:33792
	ds_read_b128 v[184:187], v143 offset:34816
	ds_read_b128 v[188:191], v143 offset:35840
	ds_read_b128 v[192:195], v143 offset:36864
	ds_read_b128 v[196:199], v143 offset:37888
	ds_read_b128 v[200:203], v143 offset:38912
	ds_read_b128 v[204:207], v143 offset:39936
	global_load_lds_dwordx4 v[216:217], off
	v_lshl_add_u64 v[216:217], s[36:37], 0, v[130:131]
	s_mov_b32 m0, s41
	s_nop 0
	global_load_lds_dwordx4 v[216:217], off
	s_mov_b32 m0, s25
	s_nop 0
	global_load_lds_dwordx4 v[212:213], off
	s_mov_b32 m0, s31
	s_nop 0
	global_load_lds_dwordx4 v[214:215], off
	s_waitcnt vmcnt(8)
	s_waitcnt lgkmcnt(0)
	s_barrier
; #define G_STAGE(bufoff, gbase, voff) do { _Pragma("unroll") for (int _i = 0; _i < 2; ++_i) \
;         __builtin_amdgcn_global_load_lds((const unsigned*)((const char*)(gbase) + voff[_i]), (LAS unsigned*)(lds + (bufoff) + ldsw + _i * 8192), 16, 0, 0); } while (0)
; #define G_LDA(dst, b, h) do { _Pragma("unroll") for (int m = 0; m < 4; ++m) _Pragma("unroll") for (int k = 0; k < 2; ++k) dst[m][k] = *(const LAS bf16x8*)(lds + G_SA(b, h) + aoff + m * 2048 + k * 1024); } while (0)
; #define G_MMA(ai, bj, At_, Bt_) do { __builtin_amdgcn_s_setprio(1); _Pragma("unroll") for (int m = 0; m < 4; ++m) _Pragma("unroll") for (int n = 0; n < 2; ++n) _Pragma("unroll") for (int k = 0; k < 2; ++k) \
;         acc[ai][bj][m][n] = __builtin_amdgcn_mfma_f32_16x16x32_bf16(Bt_[n][k], At_[m][k], acc[ai][bj][m][n], 0, 0, 0); __builtin_amdgcn_s_setprio(0); } while (0)
; #define WAIT_V(n) asm volatile("s_waitcnt vmcnt(" #n ")" ::: "memory")
; #define WAIT_L(n) asm volatile("s_waitcnt lgkmcnt(" #n ")" ::: "memory")
; #define BAR __builtin_amdgcn_s_barrier()
; #define SCHED __builtin_amdgcn_sched_barrier(0)
; template <class Get, class Epi>
; DI void gemm_loop(int ntiles, int ld, char* shm, const Get& get, const Epi& epi) {
;     ...
;             WAIT_V(8); WAIT_L(0); BAR; G_MMA(0, 0, At, B0); G_MMA(0, 1, At, B1); BAR; SCHED;
;             G_LDA(At, 1, 1); G_STAGE(G_SB(1, 0), b3, voffB); G_STAGE(G_SB(1, 1), b3 + hstep, voffB); G_STAGE(G_SA(1, 0), a3, voffA);
;             WAIT_V(8); WAIT_L(0); BAR; G_MMA(1, 0, At, B0); G_MMA(1, 1, At, B1); BAR; SCHED;
;         }
;         if (wr == 0) BAR;
	s_setprio 1
	s_waitcnt lgkmcnt(0)
	v_mfma_f32_16x16x32_bf16 v[124:127], v[144:147], v[176:179], v[124:127]
	v_mfma_f32_16x16x32_bf16 v[120:123], v[152:155], v[176:179], v[120:123]
	v_mfma_f32_16x16x32_bf16 v[108:111], v[144:147], v[184:187], v[108:111]
	v_mfma_f32_16x16x32_bf16 v[104:107], v[152:155], v[184:187], v[104:107]
	v_mfma_f32_16x16x32_bf16 v[92:95], v[144:147], v[192:195], v[92:95]
	v_mfma_f32_16x16x32_bf16 v[88:91], v[152:155], v[192:195], v[88:91]
	v_mfma_f32_16x16x32_bf16 v[76:79], v[144:147], v[200:203], v[76:79]
	v_mfma_f32_16x16x32_bf16 v[72:75], v[152:155], v[200:203], v[72:75]
	v_mfma_f32_16x16x32_bf16 v[124:127], v[148:151], v[180:183], v[124:127]
	v_mfma_f32_16x16x32_bf16 v[120:123], v[156:159], v[180:183], v[120:123]
	v_mfma_f32_16x16x32_bf16 v[108:111], v[148:151], v[188:191], v[108:111]
	v_mfma_f32_16x16x32_bf16 v[104:107], v[156:159], v[188:191], v[104:107]
	v_mfma_f32_16x16x32_bf16 v[92:95], v[148:151], v[196:199], v[92:95]
	v_mfma_f32_16x16x32_bf16 v[88:91], v[156:159], v[196:199], v[88:91]
	v_mfma_f32_16x16x32_bf16 v[76:79], v[148:151], v[204:207], v[76:79]
	v_mfma_f32_16x16x32_bf16 v[72:75], v[156:159], v[204:207], v[72:75]
	s_setprio 0
	s_setprio 1
	v_mfma_f32_16x16x32_bf16 v[116:119], v[160:163], v[176:179], v[116:119]
	v_mfma_f32_16x16x32_bf16 v[112:115], v[168:171], v[176:179], v[112:115]
	v_mfma_f32_16x16x32_bf16 v[100:103], v[160:163], v[184:187], v[100:103]
	v_mfma_f32_16x16x32_bf16 v[96:99], v[168:171], v[184:187], v[96:99]
	v_mfma_f32_16x16x32_bf16 v[84:87], v[160:163], v[192:195], v[84:87]
	v_mfma_f32_16x16x32_bf16 v[80:83], v[168:171], v[192:195], v[80:83]
	v_mfma_f32_16x16x32_bf16 v[68:71], v[160:163], v[200:203], v[68:71]
	v_mfma_f32_16x16x32_bf16 v[64:67], v[168:171], v[200:203], v[64:67]
	v_mfma_f32_16x16x32_bf16 v[116:119], v[164:167], v[180:183], v[116:119]
	v_mfma_f32_16x16x32_bf16 v[112:115], v[172:175], v[180:183], v[112:115]
	v_mfma_f32_16x16x32_bf16 v[100:103], v[164:167], v[188:191], v[100:103]
	v_mfma_f32_16x16x32_bf16 v[96:99], v[172:175], v[188:191], v[96:99]
	v_mfma_f32_16x16x32_bf16 v[84:87], v[164:167], v[196:199], v[84:87]
	v_mfma_f32_16x16x32_bf16 v[80:83], v[172:175], v[196:199], v[80:83]
	v_mfma_f32_16x16x32_bf16 v[68:71], v[164:167], v[204:207], v[68:71]
	v_mfma_f32_16x16x32_bf16 v[64:67], v[172:175], v[204:207], v[64:67]
	s_setprio 0
	s_barrier
	s_add_i32 s36, s54, s38
	v_lshl_add_u64 v[208:209], v[208:209], 0, s[2:3]
	s_mov_b32 m0, s36
	ds_read_b128 v[176:179], v143 offset:49152
	ds_read_b128 v[180:183], v143 offset:50176
	ds_read_b128 v[184:187], v143 offset:51200
	ds_read_b128 v[188:191], v143 offset:52224
	ds_read_b128 v[192:195], v143 offset:53248
	ds_read_b128 v[196:199], v143 offset:54272
	ds_read_b128 v[200:203], v143 offset:55296
	ds_read_b128 v[204:207], v143 offset:56320
	global_load_lds_dwordx4 v[208:209], off
	s_add_i32 m0, s36, 0x2000
	s_add_u32 s14, s14, 0x40080
	v_lshl_add_u64 v[208:209], v[210:211], 0, s[2:3]
	s_addc_u32 s15, s15, 0
	s_add_i32 s36, s55, s38
	global_load_lds_dwordx4 v[208:209], off
	v_lshl_add_u64 v[208:209], s[14:15], 0, v[132:133]
	s_mov_b32 m0, s36
	s_nop 0
	global_load_lds_dwordx4 v[208:209], off
	v_lshl_add_u64 v[208:209], s[14:15], 0, v[128:129]
	s_add_i32 m0, s36, 0x2000
	s_nop 0
	global_load_lds_dwordx4 v[208:209], off
	s_waitcnt vmcnt(4)
	s_waitcnt lgkmcnt(0)
	s_barrier
	s_setprio 1
	s_waitcnt lgkmcnt(0)
	v_mfma_f32_16x16x32_bf16 v[60:63], v[144:147], v[176:179], v[60:63]
	v_mfma_f32_16x16x32_bf16 v[56:59], v[152:155], v[176:179], v[56:59]
	v_mfma_f32_16x16x32_bf16 v[44:47], v[144:147], v[184:187], v[44:47]
	v_mfma_f32_16x16x32_bf16 v[40:43], v[152:155], v[184:187], v[40:43]
	v_mfma_f32_16x16x32_bf16 v[28:31], v[144:147], v[192:195], v[28:31]
	v_mfma_f32_16x16x32_bf16 v[24:27], v[152:155], v[192:195], v[24:27]
	v_mfma_f32_16x16x32_bf16 v[12:15], v[144:147], v[200:203], v[12:15]
	v_mfma_f32_16x16x32_bf16 v[8:11], v[152:155], v[200:203], v[8:11]
	v_mfma_f32_16x16x32_bf16 v[60:63], v[148:151], v[180:183], v[60:63]
	v_mfma_f32_16x16x32_bf16 v[56:59], v[156:159], v[180:183], v[56:59]
	v_mfma_f32_16x16x32_bf16 v[44:47], v[148:151], v[188:191], v[44:47]
	v_mfma_f32_16x16x32_bf16 v[40:43], v[156:159], v[188:191], v[40:43]
	v_mfma_f32_16x16x32_bf16 v[28:31], v[148:151], v[196:199], v[28:31]
	v_mfma_f32_16x16x32_bf16 v[24:27], v[156:159], v[196:199], v[24:27]
	v_mfma_f32_16x16x32_bf16 v[12:15], v[148:151], v[204:207], v[12:15]
	v_mfma_f32_16x16x32_bf16 v[8:11], v[156:159], v[204:207], v[8:11]
	s_setprio 0
	s_setprio 1
	v_mfma_f32_16x16x32_bf16 v[52:55], v[160:163], v[176:179], v[52:55]
	v_mfma_f32_16x16x32_bf16 v[48:51], v[168:171], v[176:179], v[48:51]
	v_mfma_f32_16x16x32_bf16 v[36:39], v[160:163], v[184:187], v[36:39]
	v_mfma_f32_16x16x32_bf16 v[32:35], v[168:171], v[184:187], v[32:35]
	v_mfma_f32_16x16x32_bf16 v[20:23], v[160:163], v[192:195], v[20:23]
	v_mfma_f32_16x16x32_bf16 v[16:19], v[168:171], v[192:195], v[16:19]
	v_mfma_f32_16x16x32_bf16 v[4:7], v[160:163], v[200:203], v[4:7]
	v_mfma_f32_16x16x32_bf16 v[0:3], v[168:171], v[200:203], v[0:3]
	v_mfma_f32_16x16x32_bf16 v[52:55], v[164:167], v[180:183], v[52:55]
	v_mfma_f32_16x16x32_bf16 v[48:51], v[172:175], v[180:183], v[48:51]
	v_mfma_f32_16x16x32_bf16 v[36:39], v[164:167], v[188:191], v[36:39]
	v_mfma_f32_16x16x32_bf16 v[32:35], v[172:175], v[188:191], v[32:35]
	v_mfma_f32_16x16x32_bf16 v[20:23], v[164:167], v[196:199], v[20:23]
	v_mfma_f32_16x16x32_bf16 v[16:19], v[172:175], v[196:199], v[16:19]
	v_mfma_f32_16x16x32_bf16 v[4:7], v[164:167], v[204:207], v[4:7]
	v_mfma_f32_16x16x32_bf16 v[0:3], v[172:175], v[204:207], v[0:3]
	s_setprio 0
	s_barrier
	s_add_i32 s53, s53, 2
	s_add_u32 s34, s34, 0x100
	s_addc_u32 s35, s35, 0
	s_add_u32 s51, s51, 0x100
	s_addc_u32 s52, s52, 0
	s_cmp_gt_u32 s53, 13
	s_cbranch_scc0 .LBB0_3679
	s_and_b64 vcc, exec, s[4:5]
	s_cbranch_vccz .LBB0_3682
	s_barrier

; #define G_STAGE(bufoff, gbase, voff) do { _Pragma("unroll") for (int _i = 0; _i < 2; ++_i) \
;         __builtin_amdgcn_global_load_lds((const unsigned*)((const char*)(gbase) + voff[_i]), (LAS unsigned*)(lds + (bufoff) + ldsw + _i * 8192), 16, 0, 0); } while (0)
; #define G_LDA(dst, b, h) do { _Pragma("unroll") for (int m = 0; m < 4; ++m) _Pragma("unroll") for (int k = 0; k < 2; ++k) dst[m][k] = *(const LAS bf16x8*)(lds + G_SA(b, h) + aoff + m * 2048 + k * 1024); } while (0)
; #define G_LDB(dst, b, h) do { _Pragma("unroll") for (int n = 0; n < 2; ++n) _Pragma("unroll") for (int k = 0; k < 2; ++k) dst[n][k] = *(const LAS bf16x8*)(lds + G_SB(b, h) + boff + n * 2048 + k * 1024); } while (0)
; #define G_MMA(ai, bj, At_, Bt_) do { __builtin_amdgcn_s_setprio(1); _Pragma("unroll") for (int m = 0; m < 4; ++m) _Pragma("unroll") for (int n = 0; n < 2; ++n) _Pragma("unroll") for (int k = 0; k < 2; ++k) \
;         acc[ai][bj][m][n] = __builtin_amdgcn_mfma_f32_16x16x32_bf16(Bt_[n][k], At_[m][k], acc[ai][bj][m][n], 0, 0, 0); __builtin_amdgcn_s_setprio(0); } while (0)
; #define WAIT_V(n) asm volatile("s_waitcnt vmcnt(" #n ")" ::: "memory")
; #define WAIT_L(n) asm volatile("s_waitcnt lgkmcnt(" #n ")" ::: "memory")
; #define BAR __builtin_amdgcn_s_barrier()
; #define SCHED __builtin_amdgcn_sched_barrier(0)
; template <class Get, class Epi>
; DI void gemm_loop(int ntiles, int ld, char* shm, const Get& get, const Epi& epi) {
;     ...
;         for (int t = 0; t < nt; t += 2) {
;             const bool last = (t == nt - 2);
;             const char* a1 = cA + (size_t)(t + 1) * kstep;
;             const char* a2 = last ? nA : cA + (size_t)(t + 2) * kstep; const char* b2 = last ? nB : cB + (size_t)(t + 2) * kstep;
;             const char* a3 = a2 + kstep; const char* b3 = b2 + kstep;
;             G_LDB(B0, 0, 0); G_LDB(B1, 0, 1); SCHED; G_LDA(At, 0, 0); G_STAGE(G_SA(1, 1), a1 + hstep, voffA);
;             WAIT_V(8); WAIT_L(0); BAR; G_MMA(0, 0, At, B0); G_MMA(0, 1, At, B1); BAR; SCHED;
;             G_LDA(At, 0, 1); G_STAGE(G_SB(0, 0), b2, voffB); G_STAGE(G_SB(0, 1), b2 + hstep, voffB); G_STAGE(G_SA(0, 0), a2, voffA);
;             WAIT_V(8); WAIT_L(0); BAR; G_MMA(1, 0, At, B0); G_MMA(1, 1, At, B1); BAR; SCHED;
.LBB0_3759:
	ds_read_b128 v[128:131], v169
	ds_read_b128 v[132:135], v169 offset:1024
	ds_read_b128 v[136:139], v169 offset:2048
	ds_read_b128 v[140:143], v169 offset:3072
	ds_read_b128 v[158:161], v170
	ds_read_b128 v[162:165], v170 offset:1024
	ds_read_b128 v[172:175], v170 offset:2048
	ds_read_b128 v[176:179], v170 offset:3072
	s_add_u32 s24, s2, 0x100
	s_addc_u32 s25, s3, 0
	s_cmp_eq_u32 s54, 40
	s_cselect_b32 s35, s21, s25
	s_cselect_b32 s34, s20, s24
	s_cselect_b32 s31, s23, s53
	s_cselect_b32 s30, s22, s52
	v_lshl_add_u64 v[144:145], s[2:3], 0, v[154:155]
	s_add_i32 m0, s36, 0xc000
	ds_read_b128 v[180:183], v171
	ds_read_b128 v[184:187], v171 offset:1024
	ds_read_b128 v[188:191], v171 offset:2048
	ds_read_b128 v[192:195], v171 offset:3072
	ds_read_b128 v[196:199], v171 offset:4096
	ds_read_b128 v[200:203], v171 offset:5120
	ds_read_b128 v[204:207], v171 offset:6144
	ds_read_b128 v[208:211], v171 offset:7168
	global_load_lds_dwordx4 v[144:145], off
	v_lshl_add_u64 v[144:145], s[2:3], 0, v[156:157]
	s_add_i32 m0, s36, 0xe000
	s_nop 0
	global_load_lds_dwordx4 v[144:145], off
	s_mov_b32 s98, 0xfff50000
	s_mov_b32 s99, -1
	v_lshl_add_u64 v[144:145], s[2:3], 0, v[154:155]
	v_lshl_add_u64 v[144:145], v[144:145], 0, s[98:99]
	s_add_i32 m0, s36, 0x8000
	s_nop 0
	global_load_lds_dwordx4 v[144:145], off
	v_lshl_add_u64 v[144:145], s[2:3], 0, v[156:157]
	v_lshl_add_u64 v[144:145], v[144:145], 0, s[98:99]
	s_add_i32 m0, s36, 0xa000
	s_nop 0
	global_load_lds_dwordx4 v[144:145], off
	s_waitcnt vmcnt(8)
	s_waitcnt lgkmcnt(0)
	s_barrier
	s_setprio 1
	s_waitcnt lgkmcnt(0)
	v_mfma_f32_16x16x32_bf16 v[124:127], v[128:131], v[180:183], v[124:127]
	v_mfma_f32_16x16x32_bf16 v[120:123], v[136:139], v[180:183], v[120:123]
	v_mfma_f32_16x16x32_bf16 v[116:119], v[128:131], v[188:191], v[116:119]
	v_mfma_f32_16x16x32_bf16 v[112:115], v[136:139], v[188:191], v[112:115]
	v_mfma_f32_16x16x32_bf16 v[108:111], v[128:131], v[196:199], v[108:111]
	v_mfma_f32_16x16x32_bf16 v[104:107], v[136:139], v[196:199], v[104:107]
	v_mfma_f32_16x16x32_bf16 v[100:103], v[128:131], v[204:207], v[100:103]
	v_mfma_f32_16x16x32_bf16 v[96:99], v[136:139], v[204:207], v[96:99]
	v_mfma_f32_16x16x32_bf16 v[124:127], v[132:135], v[184:187], v[124:127]
	v_mfma_f32_16x16x32_bf16 v[120:123], v[140:143], v[184:187], v[120:123]
	v_mfma_f32_16x16x32_bf16 v[116:119], v[132:135], v[192:195], v[116:119]
	v_mfma_f32_16x16x32_bf16 v[112:115], v[140:143], v[192:195], v[112:115]
	v_mfma_f32_16x16x32_bf16 v[108:111], v[132:135], v[200:203], v[108:111]
	v_mfma_f32_16x16x32_bf16 v[104:107], v[140:143], v[200:203], v[104:107]
	v_mfma_f32_16x16x32_bf16 v[100:103], v[132:135], v[208:211], v[100:103]
	v_mfma_f32_16x16x32_bf16 v[96:99], v[140:143], v[208:211], v[96:99]
	s_setprio 0
	s_setprio 1
	v_mfma_f32_16x16x32_bf16 v[60:63], v[158:161], v[180:183], v[60:63]
	v_mfma_f32_16x16x32_bf16 v[56:59], v[172:175], v[180:183], v[56:59]
	v_mfma_f32_16x16x32_bf16 v[52:55], v[158:161], v[188:191], v[52:55]
	v_mfma_f32_16x16x32_bf16 v[48:51], v[172:175], v[188:191], v[48:51]
	v_mfma_f32_16x16x32_bf16 v[44:47], v[158:161], v[196:199], v[44:47]
	v_mfma_f32_16x16x32_bf16 v[40:43], v[172:175], v[196:199], v[40:43]
	v_mfma_f32_16x16x32_bf16 v[36:39], v[158:161], v[204:207], v[36:39]
	v_mfma_f32_16x16x32_bf16 v[32:35], v[172:175], v[204:207], v[32:35]
	v_mfma_f32_16x16x32_bf16 v[60:63], v[162:165], v[184:187], v[60:63]
	v_mfma_f32_16x16x32_bf16 v[56:59], v[176:179], v[184:187], v[56:59]
	v_mfma_f32_16x16x32_bf16 v[52:55], v[162:165], v[192:195], v[52:55]
	v_mfma_f32_16x16x32_bf16 v[48:51], v[176:179], v[192:195], v[48:51]
	v_mfma_f32_16x16x32_bf16 v[44:47], v[162:165], v[200:203], v[44:47]
	v_mfma_f32_16x16x32_bf16 v[40:43], v[176:179], v[200:203], v[40:43]
	v_mfma_f32_16x16x32_bf16 v[36:39], v[162:165], v[208:211], v[36:39]
	v_mfma_f32_16x16x32_bf16 v[32:35], v[176:179], v[208:211], v[32:35]
	s_setprio 0
	s_barrier
	s_add_i32 s2, s44, s33
	v_lshl_add_u64 v[144:145], s[30:31], 0, v[148:149]
	s_mov_b32 m0, s2
	ds_read_b128 v[180:183], v171 offset:16384
	ds_read_b128 v[184:187], v171 offset:17408
	ds_read_b128 v[188:191], v171 offset:18432
	ds_read_b128 v[192:195], v171 offset:19456
	ds_read_b128 v[196:199], v171 offset:20480
	ds_read_b128 v[200:203], v171 offset:21504
	ds_read_b128 v[204:207], v171 offset:22528
	ds_read_b128 v[208:211], v171 offset:23552
	global_load_lds_dwordx4 v[144:145], off
	s_add_i32 m0, s2, 0x2000
	s_add_u32 s2, s30, 0xb0000
	v_lshl_add_u64 v[166:167], s[30:31], 0, v[152:153]
	s_addc_u32 s3, s31, 0
	s_add_i32 s55, s45, s33
	global_load_lds_dwordx4 v[166:167], off
	v_lshl_add_u64 v[212:213], s[2:3], 0, v[148:149]
	s_mov_b32 m0, s55
	v_lshl_add_u64 v[214:215], s[34:35], 0, v[150:151]
	global_load_lds_dwordx4 v[212:213], off
	v_lshl_add_u64 v[212:213], s[2:3], 0, v[152:153]
	s_add_i32 m0, s55, 0x2000
	s_nop 0
	global_load_lds_dwordx4 v[212:213], off
	v_lshl_add_u64 v[212:213], s[34:35], 0, v[146:147]
	s_waitcnt vmcnt(4)
	s_waitcnt lgkmcnt(0)
	s_barrier
; #define G_STAGE(bufoff, gbase, voff) do { _Pragma("unroll") for (int _i = 0; _i < 2; ++_i) \
;         __builtin_amdgcn_global_load_lds((const unsigned*)((const char*)(gbase) + voff[_i]), (LAS unsigned*)(lds + (bufoff) + ldsw + _i * 8192), 16, 0, 0); } while (0)
; #define G_LDA(dst, b, h) do { _Pragma("unroll") for (int m = 0; m < 4; ++m) _Pragma("unroll") for (int k = 0; k < 2; ++k) dst[m][k] = *(const LAS bf16x8*)(lds + G_SA(b, h) + aoff + m * 2048 + k * 1024); } while (0)
; #define G_LDB(dst, b, h) do { _Pragma("unroll") for (int n = 0; n < 2; ++n) _Pragma("unroll") for (int k = 0; k < 2; ++k) dst[n][k] = *(const LAS bf16x8*)(lds + G_SB(b, h) + boff + n * 2048 + k * 1024); } while (0)
; #define G_MMA(ai, bj, At_, Bt_) do { __builtin_amdgcn_s_setprio(1); _Pragma("unroll") for (int m = 0; m < 4; ++m) _Pragma("unroll") for (int n = 0; n < 2; ++n) _Pragma("unroll") for (int k = 0; k < 2; ++k) \
;         acc[ai][bj][m][n] = __builtin_amdgcn_mfma_f32_16x16x32_bf16(Bt_[n][k], At_[m][k], acc[ai][bj][m][n], 0, 0, 0); __builtin_amdgcn_s_setprio(0); } while (0)
; #define WAIT_V(n) asm volatile("s_waitcnt vmcnt(" #n ")" ::: "memory")
; #define WAIT_L(n) asm volatile("s_waitcnt lgkmcnt(" #n ")" ::: "memory")
; #define BAR __builtin_amdgcn_s_barrier()
; #define SCHED __builtin_amdgcn_sched_barrier(0)
; template <class Get, class Epi>
; DI void gemm_loop(int ntiles, int ld, char* shm, const Get& get, const Epi& epi) {
;     ...
;             WAIT_V(8); WAIT_L(0); BAR; G_MMA(0, 0, At, B0); G_MMA(0, 1, At, B1); BAR; SCHED;
;             G_LDA(At, 0, 1); G_STAGE(G_SB(0, 0), b2, voffB); G_STAGE(G_SB(0, 1), b2 + hstep, voffB); G_STAGE(G_SA(0, 0), a2, voffA);
;             WAIT_V(8); WAIT_L(0); BAR; G_MMA(1, 0, At, B0); G_MMA(1, 1, At, B1); BAR; SCHED;
;             G_LDB(B0, 1, 0); G_LDB(B1, 1, 1); SCHED; G_LDA(At, 1, 0); G_STAGE(G_SA(0, 1), a2 + hstep, voffA);
;             WAIT_V(8); WAIT_L(0); BAR; G_MMA(0, 0, At, B0); G_MMA(0, 1, At, B1); BAR; SCHED;
;             G_LDA(At, 1, 1); G_STAGE(G_SB(1, 0), b3, voffB); G_STAGE(G_SB(1, 1), b3 + hstep, voffB); G_STAGE(G_SA(1, 0), a3, voffA);
	s_setprio 1
	s_waitcnt lgkmcnt(0)
	v_mfma_f32_16x16x32_bf16 v[92:95], v[128:131], v[180:183], v[92:95]
	v_mfma_f32_16x16x32_bf16 v[88:91], v[136:139], v[180:183], v[88:91]
	v_mfma_f32_16x16x32_bf16 v[84:87], v[128:131], v[188:191], v[84:87]
	v_mfma_f32_16x16x32_bf16 v[80:83], v[136:139], v[188:191], v[80:83]
	v_mfma_f32_16x16x32_bf16 v[76:79], v[128:131], v[196:199], v[76:79]
	v_mfma_f32_16x16x32_bf16 v[72:75], v[136:139], v[196:199], v[72:75]
	v_mfma_f32_16x16x32_bf16 v[68:71], v[128:131], v[204:207], v[68:71]
	v_mfma_f32_16x16x32_bf16 v[64:67], v[136:139], v[204:207], v[64:67]
	v_mfma_f32_16x16x32_bf16 v[92:95], v[132:135], v[184:187], v[92:95]
	v_mfma_f32_16x16x32_bf16 v[88:91], v[140:143], v[184:187], v[88:91]
	v_mfma_f32_16x16x32_bf16 v[84:87], v[132:135], v[192:195], v[84:87]
	v_mfma_f32_16x16x32_bf16 v[80:83], v[140:143], v[192:195], v[80:83]
	v_mfma_f32_16x16x32_bf16 v[76:79], v[132:135], v[200:203], v[76:79]
	v_mfma_f32_16x16x32_bf16 v[72:75], v[140:143], v[200:203], v[72:75]
	v_mfma_f32_16x16x32_bf16 v[68:71], v[132:135], v[208:211], v[68:71]
	v_mfma_f32_16x16x32_bf16 v[64:67], v[140:143], v[208:211], v[64:67]
	s_setprio 0
	s_setprio 1
	v_mfma_f32_16x16x32_bf16 v[28:31], v[158:161], v[180:183], v[28:31]
	v_mfma_f32_16x16x32_bf16 v[24:27], v[172:175], v[180:183], v[24:27]
	v_mfma_f32_16x16x32_bf16 v[20:23], v[158:161], v[188:191], v[20:23]
	v_mfma_f32_16x16x32_bf16 v[16:19], v[172:175], v[188:191], v[16:19]
	v_mfma_f32_16x16x32_bf16 v[12:15], v[158:161], v[196:199], v[12:15]
	v_mfma_f32_16x16x32_bf16 v[8:11], v[172:175], v[196:199], v[8:11]
	v_mfma_f32_16x16x32_bf16 v[4:7], v[158:161], v[204:207], v[4:7]
	v_mfma_f32_16x16x32_bf16 v[0:3], v[172:175], v[204:207], v[0:3]
	v_mfma_f32_16x16x32_bf16 v[28:31], v[162:165], v[184:187], v[28:31]
	v_mfma_f32_16x16x32_bf16 v[24:27], v[176:179], v[184:187], v[24:27]
	v_mfma_f32_16x16x32_bf16 v[20:23], v[162:165], v[192:195], v[20:23]
	v_mfma_f32_16x16x32_bf16 v[16:19], v[176:179], v[192:195], v[16:19]
	v_mfma_f32_16x16x32_bf16 v[12:15], v[162:165], v[200:203], v[12:15]
	v_mfma_f32_16x16x32_bf16 v[8:11], v[176:179], v[200:203], v[8:11]
	v_mfma_f32_16x16x32_bf16 v[4:7], v[162:165], v[208:211], v[4:7]
	v_mfma_f32_16x16x32_bf16 v[0:3], v[176:179], v[208:211], v[0:3]
	s_setprio 0
	s_barrier
	s_add_i32 s55, 0, 0x18000
	s_add_i32 s56, 0, 0x1c000
	v_add_u32_e32 v140, s55, v168
	v_add_u32_e32 v176, s56, v168
	ds_read_b128 v[128:131], v140
	ds_read_b128 v[132:135], v140 offset:1024
	ds_read_b128 v[136:139], v140 offset:2048
	ds_read_b128 v[140:143], v140 offset:3072
	ds_read_b128 v[158:161], v176
	ds_read_b128 v[162:165], v176 offset:1024
	ds_read_b128 v[172:175], v176 offset:2048
	ds_read_b128 v[176:179], v176 offset:3072
	s_add_u32 s2, s34, 0xb0000
	s_addc_u32 s3, s35, 0
	s_mov_b32 m0, s38
	v_lshl_add_u64 v[216:217], s[2:3], 0, v[146:147]
	ds_read_b128 v[180:183], v171 offset:32768
	ds_read_b128 v[184:187], v171 offset:33792
	ds_read_b128 v[188:191], v171 offset:34816
	ds_read_b128 v[192:195], v171 offset:35840
	ds_read_b128 v[196:199], v171 offset:36864
	ds_read_b128 v[200:203], v171 offset:37888
	ds_read_b128 v[204:207], v171 offset:38912
	ds_read_b128 v[208:211], v171 offset:39936
	global_load_lds_dwordx4 v[216:217], off
	v_lshl_add_u64 v[216:217], s[2:3], 0, v[150:151]
	s_mov_b32 m0, s39
	s_nop 0
	global_load_lds_dwordx4 v[216:217], off
	s_mov_b32 m0, s36
	s_nop 0
	global_load_lds_dwordx4 v[212:213], off
	s_mov_b32 m0, s37
	s_nop 0
	global_load_lds_dwordx4 v[214:215], off
	s_waitcnt vmcnt(8)
	s_waitcnt lgkmcnt(0)
	s_barrier
; #define G_STAGE(bufoff, gbase, voff) do { _Pragma("unroll") for (int _i = 0; _i < 2; ++_i) \
;         __builtin_amdgcn_global_load_lds((const unsigned*)((const char*)(gbase) + voff[_i]), (LAS unsigned*)(lds + (bufoff) + ldsw + _i * 8192), 16, 0, 0); } while (0)
; #define G_LDA(dst, b, h) do { _Pragma("unroll") for (int m = 0; m < 4; ++m) _Pragma("unroll") for (int k = 0; k < 2; ++k) dst[m][k] = *(const LAS bf16x8*)(lds + G_SA(b, h) + aoff + m * 2048 + k * 1024); } while (0)
; #define G_MMA(ai, bj, At_, Bt_) do { __builtin_amdgcn_s_setprio(1); _Pragma("unroll") for (int m = 0; m < 4; ++m) _Pragma("unroll") for (int n = 0; n < 2; ++n) _Pragma("unroll") for (int k = 0; k < 2; ++k) \
;         acc[ai][bj][m][n] = __builtin_amdgcn_mfma_f32_16x16x32_bf16(Bt_[n][k], At_[m][k], acc[ai][bj][m][n], 0, 0, 0); __builtin_amdgcn_s_setprio(0); } while (0)
; #define WAIT_V(n) asm volatile("s_waitcnt vmcnt(" #n ")" ::: "memory")
; #define WAIT_L(n) asm volatile("s_waitcnt lgkmcnt(" #n ")" ::: "memory")
; #define BAR __builtin_amdgcn_s_barrier()
; #define SCHED __builtin_amdgcn_sched_barrier(0)
; template <class Get, class Epi>
; DI void gemm_loop(int ntiles, int ld, char* shm, const Get& get, const Epi& epi) {
;     ...
;             WAIT_V(8); WAIT_L(0); BAR; G_MMA(0, 0, At, B0); G_MMA(0, 1, At, B1); BAR; SCHED;
;             G_LDA(At, 1, 1); G_STAGE(G_SB(1, 0), b3, voffB); G_STAGE(G_SB(1, 1), b3 + hstep, voffB); G_STAGE(G_SA(1, 0), a3, voffA);
;             WAIT_V(8); WAIT_L(0); BAR; G_MMA(1, 0, At, B0); G_MMA(1, 1, At, B1); BAR; SCHED;
;         }
	s_setprio 1
	s_waitcnt lgkmcnt(0)
	v_mfma_f32_16x16x32_bf16 v[124:127], v[128:131], v[180:183], v[124:127]
	v_mfma_f32_16x16x32_bf16 v[120:123], v[136:139], v[180:183], v[120:123]
	v_mfma_f32_16x16x32_bf16 v[116:119], v[128:131], v[188:191], v[116:119]
	v_mfma_f32_16x16x32_bf16 v[112:115], v[136:139], v[188:191], v[112:115]
	v_mfma_f32_16x16x32_bf16 v[108:111], v[128:131], v[196:199], v[108:111]
	v_mfma_f32_16x16x32_bf16 v[104:107], v[136:139], v[196:199], v[104:107]
	v_mfma_f32_16x16x32_bf16 v[100:103], v[128:131], v[204:207], v[100:103]
	v_mfma_f32_16x16x32_bf16 v[96:99], v[136:139], v[204:207], v[96:99]
	v_mfma_f32_16x16x32_bf16 v[124:127], v[132:135], v[184:187], v[124:127]
	v_mfma_f32_16x16x32_bf16 v[120:123], v[140:143], v[184:187], v[120:123]
	v_mfma_f32_16x16x32_bf16 v[116:119], v[132:135], v[192:195], v[116:119]
	v_mfma_f32_16x16x32_bf16 v[112:115], v[140:143], v[192:195], v[112:115]
	v_mfma_f32_16x16x32_bf16 v[108:111], v[132:135], v[200:203], v[108:111]
	v_mfma_f32_16x16x32_bf16 v[104:107], v[140:143], v[200:203], v[104:107]
	v_mfma_f32_16x16x32_bf16 v[100:103], v[132:135], v[208:211], v[100:103]
	v_mfma_f32_16x16x32_bf16 v[96:99], v[140:143], v[208:211], v[96:99]
	s_setprio 0
	s_setprio 1
	v_mfma_f32_16x16x32_bf16 v[60:63], v[158:161], v[180:183], v[60:63]
	v_mfma_f32_16x16x32_bf16 v[56:59], v[172:175], v[180:183], v[56:59]
	v_mfma_f32_16x16x32_bf16 v[52:55], v[158:161], v[188:191], v[52:55]
	v_mfma_f32_16x16x32_bf16 v[48:51], v[172:175], v[188:191], v[48:51]
	v_mfma_f32_16x16x32_bf16 v[44:47], v[158:161], v[196:199], v[44:47]
	v_mfma_f32_16x16x32_bf16 v[40:43], v[172:175], v[196:199], v[40:43]
	v_mfma_f32_16x16x32_bf16 v[36:39], v[158:161], v[204:207], v[36:39]
	v_mfma_f32_16x16x32_bf16 v[32:35], v[172:175], v[204:207], v[32:35]
	v_mfma_f32_16x16x32_bf16 v[60:63], v[162:165], v[184:187], v[60:63]
	v_mfma_f32_16x16x32_bf16 v[56:59], v[176:179], v[184:187], v[56:59]
	v_mfma_f32_16x16x32_bf16 v[52:55], v[162:165], v[192:195], v[52:55]
	v_mfma_f32_16x16x32_bf16 v[48:51], v[176:179], v[192:195], v[48:51]
	v_mfma_f32_16x16x32_bf16 v[44:47], v[162:165], v[200:203], v[44:47]
	v_mfma_f32_16x16x32_bf16 v[40:43], v[176:179], v[200:203], v[40:43]
	v_mfma_f32_16x16x32_bf16 v[36:39], v[162:165], v[208:211], v[36:39]
	v_mfma_f32_16x16x32_bf16 v[32:35], v[176:179], v[208:211], v[32:35]
	s_setprio 0
	s_barrier
	s_add_i32 s2, s55, s33
	v_lshl_add_u64 v[144:145], v[144:145], 0, s[6:7]
	s_mov_b32 m0, s2
	ds_read_b128 v[180:183], v171 offset:49152
	ds_read_b128 v[184:187], v171 offset:50176
	ds_read_b128 v[188:191], v171 offset:51200
	ds_read_b128 v[192:195], v171 offset:52224
	ds_read_b128 v[196:199], v171 offset:53248
	ds_read_b128 v[200:203], v171 offset:54272
	ds_read_b128 v[204:207], v171 offset:55296
	ds_read_b128 v[208:211], v171 offset:56320
	global_load_lds_dwordx4 v[144:145], off
	s_add_i32 m0, s2, 0x2000
	s_add_u32 s2, s30, 0xb0080
	v_lshl_add_u64 v[144:145], v[166:167], 0, s[6:7]
	s_addc_u32 s3, s31, 0
	s_add_i32 s30, s56, s33
	global_load_lds_dwordx4 v[144:145], off
	v_lshl_add_u64 v[144:145], s[2:3], 0, v[148:149]
	s_mov_b32 m0, s30
	s_nop 0
	global_load_lds_dwordx4 v[144:145], off
	v_lshl_add_u64 v[144:145], s[2:3], 0, v[152:153]
	s_add_i32 m0, s30, 0x2000
	s_nop 0
	global_load_lds_dwordx4 v[144:145], off
	s_waitcnt vmcnt(4)
	s_waitcnt lgkmcnt(0)
	s_barrier
	s_setprio 1
	s_waitcnt lgkmcnt(0)
	v_mfma_f32_16x16x32_bf16 v[92:95], v[128:131], v[180:183], v[92:95]
	v_mfma_f32_16x16x32_bf16 v[88:91], v[136:139], v[180:183], v[88:91]
	v_mfma_f32_16x16x32_bf16 v[84:87], v[128:131], v[188:191], v[84:87]
	v_mfma_f32_16x16x32_bf16 v[80:83], v[136:139], v[188:191], v[80:83]
	v_mfma_f32_16x16x32_bf16 v[76:79], v[128:131], v[196:199], v[76:79]
	v_mfma_f32_16x16x32_bf16 v[72:75], v[136:139], v[196:199], v[72:75]
	v_mfma_f32_16x16x32_bf16 v[68:71], v[128:131], v[204:207], v[68:71]
	v_mfma_f32_16x16x32_bf16 v[64:67], v[136:139], v[204:207], v[64:67]
	v_mfma_f32_16x16x32_bf16 v[92:95], v[132:135], v[184:187], v[92:95]
	v_mfma_f32_16x16x32_bf16 v[88:91], v[140:143], v[184:187], v[88:91]
	v_mfma_f32_16x16x32_bf16 v[84:87], v[132:135], v[192:195], v[84:87]
	v_mfma_f32_16x16x32_bf16 v[80:83], v[140:143], v[192:195], v[80:83]
	v_mfma_f32_16x16x32_bf16 v[76:79], v[132:135], v[200:203], v[76:79]
	v_mfma_f32_16x16x32_bf16 v[72:75], v[140:143], v[200:203], v[72:75]
	v_mfma_f32_16x16x32_bf16 v[68:71], v[132:135], v[208:211], v[68:71]
	v_mfma_f32_16x16x32_bf16 v[64:67], v[140:143], v[208:211], v[64:67]
	s_setprio 0
	s_setprio 1
	v_mfma_f32_16x16x32_bf16 v[28:31], v[158:161], v[180:183], v[28:31]
	v_mfma_f32_16x16x32_bf16 v[24:27], v[172:175], v[180:183], v[24:27]
	v_mfma_f32_16x16x32_bf16 v[20:23], v[158:161], v[188:191], v[20:23]
	v_mfma_f32_16x16x32_bf16 v[16:19], v[172:175], v[188:191], v[16:19]
	v_mfma_f32_16x16x32_bf16 v[12:15], v[158:161], v[196:199], v[12:15]
	v_mfma_f32_16x16x32_bf16 v[8:11], v[172:175], v[196:199], v[8:11]
	v_mfma_f32_16x16x32_bf16 v[4:7], v[158:161], v[204:207], v[4:7]
	v_mfma_f32_16x16x32_bf16 v[0:3], v[172:175], v[204:207], v[0:3]
	v_mfma_f32_16x16x32_bf16 v[28:31], v[162:165], v[184:187], v[28:31]
	v_mfma_f32_16x16x32_bf16 v[24:27], v[176:179], v[184:187], v[24:27]
	v_mfma_f32_16x16x32_bf16 v[20:23], v[162:165], v[192:195], v[20:23]
	v_mfma_f32_16x16x32_bf16 v[16:19], v[176:179], v[192:195], v[16:19]
	v_mfma_f32_16x16x32_bf16 v[12:15], v[162:165], v[200:203], v[12:15]
	v_mfma_f32_16x16x32_bf16 v[8:11], v[176:179], v[200:203], v[8:11]
	v_mfma_f32_16x16x32_bf16 v[4:7], v[162:165], v[208:211], v[4:7]
	v_mfma_f32_16x16x32_bf16 v[0:3], v[176:179], v[208:211], v[0:3]
	s_setprio 0
	s_barrier
	s_add_i32 s54, s54, 2
	s_add_u32 s52, s52, 0x100
	s_addc_u32 s53, s53, 0
	s_cmp_gt_u32 s54, 41
	s_mov_b64 s[2:3], s[24:25]
	s_cbranch_scc0 .LBB0_3759
	s_and_b64 vcc, exec, s[8:9]
	s_cbranch_vccz .LBB0_3762
	s_barrier
